# speedup vs baseline: 1.0032x; 1.0032x over previous
; __device__ __forceinline__ float wave_sum(float v) {
; #pragma unroll
;     for (int o = 1; o < 64; o <<= 1) v += __shfl_xor(v, o);
;     return v;
; }
; template <bool XB16>
; __device__ __forceinline__ void modulate_phase(const void* xv, const float* nw, const float* modl, const float* adab, bf16_t* H, bool perm, int wid_s_, bf16_t* XRo) {
;     ...
;     const int tid = tid_, lane = tid & 63, wid = tid >> 6, gw = blockIdx.x * 8 + wid, NGW = gridDim.x * 8;
;     f32x4 av[8], bv[8];
; #pragma unroll
;     for (int j = 0; j < 4; ++j)
; #pragma unroll
;         for (int q = 0; q < 2; ++q) { const int col = 512 * j + 8 * lane + 4 * q;
;             av[2 * j + q] = *(const f32x4*)(nw + col) * (*(const f32x4*)(modl + 2048 + col) + 1.0f); bv[2 * j + q] = *(const f32x4*)(modl + col); }
.LBB0_160:
	s_lshr_b32 s0, s2, 1
	v_writelane_b32 v255, s0, 42
	s_add_u32 s40, s28, 0x29400000
	s_mul_i32 s26, s2, 0x1800
	v_writelane_b32 v255, s1, 43
	s_addc_u32 s41, s29, 0
	s_lshl_b64 s[0:1], s[26:27], 2
	s_add_u32 s0, s28, s0
	s_addc_u32 s1, s29, s1
	s_add_u32 s0, s0, 0x1000
	s_addc_u32 s1, s1, 0
	v_writelane_b32 v255, s0, 44
	s_lshl_b32 s26, s2, 11
	v_readlane_b32 s4, v254, 23
	v_writelane_b32 v255, s1, 45
	s_lshl_b64 s[0:1], s[26:27], 2
	v_readlane_b32 s8, v254, 27
	v_readlane_b32 s9, v254, 28
	s_add_u32 s0, s8, s0
	s_addc_u32 s1, s9, s1
	v_writelane_b32 v255, s0, 46
	v_readlane_b32 s5, v254, 24
	v_readlane_b32 s6, v254, 25
	v_writelane_b32 v255, s1, 47
	v_writelane_b32 v255, s2, 48
	s_bitcmp1_b32 s2, 0
	s_cselect_b64 s[0:1], -1, 0
	v_writelane_b32 v255, s3, 49
	v_writelane_b32 v255, s40, 50
	s_and_b64 vcc, exec, s[0:1]
	s_mov_b64 s[2:3], 0
	s_mov_b64 s[0:1], -1
	v_writelane_b32 v255, s41, 51
	v_readlane_b32 s7, v254, 26
	v_readlane_b32 s10, v254, 29
	v_readlane_b32 s11, v254, 30
	v_readlane_b32 s12, v254, 31
	v_readlane_b32 s13, v254, 32
	v_readlane_b32 s14, v254, 33
	v_readlane_b32 s15, v254, 34
	v_readlane_b32 s16, v254, 35
	v_readlane_b32 s17, v254, 36
	v_readlane_b32 s18, v254, 37
	v_readlane_b32 s19, v254, 38
	s_cbranch_vccz .LBB0_754
	v_mbcnt_lo_u32_b32 v0, -1, 0
	v_mbcnt_hi_u32_b32 v0, -1, v0
	v_readlane_b32 s0, v254, 5
	s_nop 1
	v_add_u32_e32 v0, s0, v0
	v_readlane_b32 s0, v254, 47
	v_ashrrev_i32_e32 v45, 6, v0
	s_nop 0
	v_add_u32_e32 v44, s0, v45
	v_cmp_gt_i32_e32 vcc, s80, v44
	s_and_saveexec_b64 s[2:3], vcc
	s_cbranch_execz .LBB0_164
	v_readlane_b32 s4, v255, 44
	v_and_b32_e32 v66, 63, v0
	v_readlane_b32 s5, v255, 45
	s_add_u32 s0, s4, 0x2000
	s_addc_u32 s1, s5, 0
	v_lshlrev_b32_e32 v96, 5, v66
	v_readlane_b32 s6, v255, 46
	v_readlane_b32 s7, v255, 47
	v_lshl_add_u64 v[8:9], s[0:1], 0, v[96:97]
	s_nop 3
	global_load_dwordx4 v[4:7], v96, s[6:7] offset:16
	global_load_dwordx4 v[0:3], v96, s[6:7]
	v_lshl_add_u64 v[20:21], s[4:5], 0, v[96:97]
	global_load_dwordx4 v[8:11], v[8:9], off
	v_or_b32_e32 v16, 0x800, v96
	v_mov_b32_e32 v17, v97
	v_lshl_add_u64 v[16:17], s[0:1], 0, v[16:17]
	v_or_b32_e32 v28, 0x1000, v96
	v_mov_b32_e32 v29, v97
	v_lshl_add_u64 v[24:25], s[0:1], 0, v[28:29]
	v_or_b32_e32 v62, 0x1800, v96
	v_mov_b32_e32 v63, v97
	v_lshl_add_u64 v[58:59], s[0:1], 0, v[62:63]
	s_waitcnt vmcnt(0) lgkmcnt(0)
	v_pk_add_f32 v[8:9], v[8:9], 1.0 op_sel_hi:[1,0]
	s_nop 0
	v_pk_mul_f32 v[34:35], v[0:1], v[8:9]
	v_or_b32_e32 v8, 16, v96
	v_mov_b32_e32 v9, v97
	v_pk_add_f32 v[10:11], v[10:11], 1.0 op_sel_hi:[1,0]
	v_lshl_add_u64 v[8:9], s[0:1], 0, v[8:9]
	v_pk_mul_f32 v[32:33], v[2:3], v[10:11]
	global_load_dwordx4 v[0:3], v[20:21], off
	s_nop 0
	global_load_dwordx4 v[8:11], v[8:9], off
	s_waitcnt vmcnt(0) lgkmcnt(0)
	v_pk_add_f32 v[10:11], v[10:11], 1.0 op_sel_hi:[1,0]
	v_pk_add_f32 v[8:9], v[8:9], 1.0 op_sel_hi:[1,0]
	v_pk_mul_f32 v[36:37], v[6:7], v[10:11]
	v_pk_mul_f32 v[38:39], v[4:5], v[8:9]
	global_load_dwordx4 v[4:7], v[20:21], off offset:16
	global_load_dwordx4 v[12:15], v96, s[6:7] offset:2064
	global_load_dwordx4 v[8:11], v96, s[6:7] offset:2048
	s_nop 0
	global_load_dwordx4 v[16:19], v[16:17], off
	s_waitcnt vmcnt(0) lgkmcnt(0)
	v_pk_add_f32 v[16:17], v[16:17], 1.0 op_sel_hi:[1,0]
	s_nop 0
	v_pk_mul_f32 v[42:43], v[8:9], v[16:17]
	v_or_b32_e32 v16, 0x810, v96
	v_mov_b32_e32 v17, v97
	v_pk_add_f32 v[18:19], v[18:19], 1.0 op_sel_hi:[1,0]
	v_lshl_add_u64 v[16:17], s[0:1], 0, v[16:17]
	v_pk_mul_f32 v[40:41], v[10:11], v[18:19]
	global_load_dwordx4 v[8:11], v[20:21], off offset:2048
	s_nop 0
	global_load_dwordx4 v[16:19], v[16:17], off
	s_waitcnt vmcnt(0) lgkmcnt(0)
	v_pk_add_f32 v[18:19], v[18:19], 1.0 op_sel_hi:[1,0]
	v_pk_add_f32 v[16:17], v[16:17], 1.0 op_sel_hi:[1,0]
	v_pk_mul_f32 v[46:47], v[14:15], v[18:19]
	v_pk_mul_f32 v[48:49], v[12:13], v[16:17]
	global_load_dwordx4 v[12:15], v[20:21], off offset:2064
	s_nop 0
	global_load_dwordx4 v[20:23], v28, s[6:7] offset:16
	global_load_dwordx4 v[16:19], v28, s[6:7]
	s_nop 0
	global_load_dwordx4 v[24:27], v[24:25], off
	s_waitcnt vmcnt(0) lgkmcnt(0)
	v_pk_add_f32 v[24:25], v[24:25], 1.0 op_sel_hi:[1,0]
	s_nop 0
	v_pk_mul_f32 v[52:53], v[16:17], v[24:25]
	v_lshl_add_u64 v[16:17], s[4:5], 0, v[28:29]
	v_or_b32_e32 v28, 0x1010, v96
	v_pk_add_f32 v[26:27], v[26:27], 1.0 op_sel_hi:[1,0]
	v_lshl_add_u64 v[24:25], s[0:1], 0, v[28:29]
	v_pk_mul_f32 v[50:51], v[18:19], v[26:27]
	global_load_dwordx4 v[24:27], v[24:25], off
	v_or_b32_e32 v96, 0x1810, v96
	global_load_dwordx4 v[16:19], v[16:17], off
	s_waitcnt vmcnt(0) lgkmcnt(0)
	v_pk_add_f32 v[24:25], v[24:25], 1.0 op_sel_hi:[1,0]
	v_pk_add_f32 v[26:27], v[26:27], 1.0 op_sel_hi:[1,0]
	v_pk_mul_f32 v[56:57], v[20:21], v[24:25]
	v_lshl_add_u64 v[20:21], s[4:5], 0, v[28:29]
	v_pk_mul_f32 v[54:55], v[22:23], v[26:27]
	global_load_dwordx4 v[20:23], v[20:21], off
	s_nop 0
	global_load_dwordx4 v[28:31], v62, s[6:7] offset:16
	global_load_dwordx4 v[24:27], v62, s[6:7]
	s_mov_b64 s[6:7], 0
	global_load_dwordx4 v[58:61], v[58:59], off
	s_waitcnt vmcnt(0) lgkmcnt(0)
	v_pk_add_f32 v[60:61], v[60:61], 1.0 op_sel_hi:[1,0]
	v_pk_add_f32 v[64:65], v[58:59], 1.0 op_sel_hi:[1,0]
	v_pk_mul_f32 v[58:59], v[26:27], v[60:61]
	v_pk_mul_f32 v[60:61], v[24:25], v[64:65]
	v_lshl_add_u64 v[24:25], s[4:5], 0, v[62:63]
	v_lshl_add_u64 v[62:63], s[0:1], 0, v[96:97]
	global_load_dwordx4 v[62:65], v[62:63], off
	s_mov_b64 s[0:1], 0x8400000
	global_load_dwordx4 v[24:27], v[24:25], off
	s_waitcnt vmcnt(0) lgkmcnt(0)
	v_pk_add_f32 v[64:65], v[64:65], 1.0 op_sel_hi:[1,0]
	v_pk_add_f32 v[68:69], v[62:63], 1.0 op_sel_hi:[1,0]
	v_pk_mul_f32 v[62:63], v[30:31], v[64:65]
	v_pk_mul_f32 v[64:65], v[28:29], v[68:69]
	v_lshl_add_u64 v[28:29], s[4:5], 0, v[96:97]
	global_load_dwordx4 v[28:31], v[28:29], off
	v_xor_b32_e32 v68, 1, v190
	v_cmp_lt_i32_e32 vcc, v68, v192
	v_lshlrev_b32_e32 v96, 4, v66
	v_lshl_add_u64 v[66:67], s[40:41], 0, v[96:97]
	v_cndmask_b32_e32 v68, v190, v68, vcc
	v_lshlrev_b32_e32 v140, 2, v68
	v_xor_b32_e32 v68, 2, v190
	v_cmp_lt_i32_e32 vcc, v68, v192
	s_nop 1
	v_cndmask_b32_e32 v68, v190, v68, vcc
	v_lshlrev_b32_e32 v141, 2, v68
	v_xor_b32_e32 v68, 4, v190
	v_cmp_lt_i32_e32 vcc, v68, v192
	s_nop 1
	v_cndmask_b32_e32 v68, v190, v68, vcc
	v_lshlrev_b32_e32 v142, 2, v68
	v_xor_b32_e32 v68, 8, v190
	v_cmp_lt_i32_e32 vcc, v68, v192
	s_nop 1
	v_cndmask_b32_e32 v68, v190, v68, vcc
	v_lshlrev_b32_e32 v143, 2, v68
	v_xor_b32_e32 v68, 16, v190
	v_cmp_lt_i32_e32 vcc, v68, v192
	s_nop 1
	v_cndmask_b32_e32 v68, v190, v68, vcc
	v_lshlrev_b32_e32 v144, 2, v68
	v_xor_b32_e32 v68, 32, v190
	v_cmp_lt_i32_e32 vcc, v68, v192
	s_nop 1
	v_cndmask_b32_e32 v68, v190, v68, vcc
	v_lshlrev_b32_e32 v145, 2, v68
	v_lshl_add_u64 v[68:69], s[28:29], 0, v[96:97]
	v_lshl_add_u64 v[68:69], v[68:69], 0, s[0:1]
	v_readlane_b32 s0, v255, 30
	s_nop 1
	v_lshl_add_u32 v96, v45, 7, s0
; __device__ __forceinline__ float bflo(unsigned w) { return __uint_as_float(w << 16); }
; __device__ __forceinline__ float bfhi(unsigned w) { return __uint_as_float(w & 0xffff0000u); }
; template <bool XB16>
; __device__ __forceinline__ void modulate_phase(const void* xv, const float* nw, const float* modl, const float* adab, bf16_t* H, bool perm, int wid_s_, bf16_t* XRo) {
;     ...
;     for (int row = gw; row < S; row += 2 * NGW) {
;         const int row1 = row + NGW;
;         f32x4 v0[8], v1[8]; float s0 = 0.f, s1 = 0.f;
; #pragma unroll
;         for (int j = 0; j < 4; ++j) {
;             if (XB16) { const u32x4 a = ((const u32x4*)(xb + (size_t)row * D) + lane)[64 * j], b = ((const u32x4*)(xb + (size_t)row1 * D) + lane)[64 * j];
;                 v0[2 * j] = (f32x4){bflo(a.x), bfhi(a.x), bflo(a.y), bfhi(a.y)}; v0[2 * j + 1] = (f32x4){bflo(a.z), bfhi(a.z), bflo(a.w), bfhi(a.w)};
;                 v1[2 * j] = (f32x4){bflo(b.x), bfhi(b.x), bflo(b.y), bfhi(b.y)}; v1[2 * j + 1] = (f32x4){bflo(b.z), bfhi(b.z), bflo(b.w), bfhi(b.w)}; }
;             else { const f32x4* p0 = (const f32x4*)(x + (size_t)row * D + 512 * j + 8 * lane); const f32x4* p1 = (const f32x4*)(x + (size_t)row1 * D + 512 * j + 8 * lane);
;                 v0[2 * j] = p0[0]; v0[2 * j + 1] = p0[1]; v1[2 * j] = p1[0]; v1[2 * j + 1] = p1[1]; } }
; #pragma unroll
;         for (int j = 0; j < 8; ++j) { s0 += (v0[j][0] * v0[j][0] + v0[j][1] * v0[j][1]) + (v0[j][2] * v0[j][2] + v0[j][3] * v0[j][3]);
;                                       s1 += (v1[j][0] * v1[j][0] + v1[j][1] * v1[j][1]) + (v1[j][2] * v1[j][2] + v1[j][3] * v1[j][3]); }
.LBB0_163:
	v_add_u32_e32 v70, s92, v44
	v_ashrrev_i32_e32 v45, 31, v44
	v_lshlrev_b64 v[72:73], 12, v[44:45]
	v_ashrrev_i32_e32 v71, 31, v70
	v_lshl_add_u64 v[72:73], v[66:67], 0, v[72:73]
	v_lshlrev_b64 v[74:75], 12, v[70:71]
	v_lshl_add_u64 v[74:75], v[66:67], 0, v[74:75]
	global_load_dwordx4 v[98:101], v[72:73], off
	global_load_dwordx4 v[102:105], v[74:75], off
	global_load_dwordx4 v[124:127], v[72:73], off offset:1024
	global_load_dwordx4 v[128:131], v[74:75], off offset:1024
	global_load_dwordx4 v[134:137], v[72:73], off offset:2048
	global_load_dwordx4 v[146:149], v[74:75], off offset:2048
	global_load_dwordx4 v[150:153], v[72:73], off offset:3072
	global_load_dwordx4 v[154:157], v[74:75], off offset:3072
	v_ashrrev_i32_e32 v44, 7, v44
	s_waitcnt vmcnt(0) lgkmcnt(0)
	v_and_b32_e32 v113, 0xffff0000, v100
	v_and_b32_e32 v112, 0xffff0000, v98
	v_and_b32_e32 v123, 0xffff0000, v101
	v_and_b32_e32 v122, 0xffff0000, v99
	v_lshlrev_b32_e32 v111, 16, v100
	v_lshlrev_b32_e32 v110, 16, v98
	v_lshlrev_b32_e32 v121, 16, v101
	v_lshlrev_b32_e32 v120, 16, v99
	v_pk_mul_f32 v[94:95], v[112:113], v[112:113]
	v_pk_mul_f32 v[98:99], v[122:123], v[122:123]
	v_pk_fma_f32 v[94:95], v[110:111], v[110:111], v[94:95]
	v_pk_fma_f32 v[98:99], v[120:121], v[120:121], v[98:99]
	v_and_b32_e32 v109, 0xffff0000, v104
	v_and_b32_e32 v108, 0xffff0000, v102
	v_and_b32_e32 v117, 0xffff0000, v105
	v_and_b32_e32 v116, 0xffff0000, v103
	v_pk_add_f32 v[132:133], v[94:95], v[98:99]
	v_lshlrev_b32_e32 v107, 16, v104
	v_lshlrev_b32_e32 v106, 16, v102
	v_lshlrev_b32_e32 v115, 16, v105
	v_lshlrev_b32_e32 v114, 16, v103
	v_pk_mul_f32 v[94:95], v[108:109], v[108:109]
	v_pk_mul_f32 v[98:99], v[116:117], v[116:117]
	v_lshlrev_b32_e32 v92, 16, v126
	v_and_b32_e32 v93, 0xffff0000, v126
	v_lshlrev_b32_e32 v89, 16, v134
	v_pk_fma_f32 v[94:95], v[106:107], v[106:107], v[94:95]
	v_pk_fma_f32 v[98:99], v[114:115], v[114:115], v[98:99]
	v_and_b32_e32 v103, 0xffff0000, v125
	v_and_b32_e32 v102, 0xffff0000, v124
	v_and_b32_e32 v87, 0xffff0000, v134
	v_lshlrev_b32_e32 v84, 16, v135
	v_and_b32_e32 v85, 0xffff0000, v135
	v_pk_add_f32 v[134:135], v[94:95], v[98:99]
	v_lshlrev_b32_e32 v101, 16, v125
	v_lshlrev_b32_e32 v100, 16, v124
	v_pk_mul_f32 v[94:95], v[102:103], v[102:103]
	v_and_b32_e32 v99, 0xffff0000, v129
	v_and_b32_e32 v98, 0xffff0000, v128
	v_mul_f32_e32 v88, v92, v92
	v_mul_f32_e32 v126, v93, v93
	v_lshlrev_b32_e32 v118, 16, v127
	v_and_b32_e32 v119, 0xffff0000, v127
	v_mov_b32_e32 v127, v89
	v_pk_fma_f32 v[124:125], v[100:101], v[100:101], v[94:95]
	v_lshlrev_b32_e32 v95, 16, v129
	v_lshlrev_b32_e32 v94, 16, v128
	v_pk_mul_f32 v[104:105], v[98:99], v[98:99]
	v_pk_add_f32 v[126:127], v[88:89], v[126:127]
	v_pk_mul_f32 v[138:139], v[88:89], v[88:89]
	v_mul_f32_e32 v86, v119, v119
	v_lshlrev_b32_e32 v83, 16, v146
	v_and_b32_e32 v45, 0xffff0000, v146
	v_pk_fma_f32 v[128:129], v[94:95], v[94:95], v[104:105]
	v_lshlrev_b32_e32 v104, 16, v131
	v_and_b32_e32 v105, 0xffff0000, v131
	v_mul_f32_e32 v77, v87, v87
	v_mul_f32_e32 v131, v84, v84
	v_mul_f32_e32 v146, v85, v85
	v_mov_b32_e32 v127, v139
	v_pk_fma_f32 v[138:139], v[118:119], v[118:119], v[86:87] op_sel_hi:[1,1,0]
	v_pk_add_f32 v[132:133], v[132:133], v[132:133] op_sel:[0,1] op_sel_hi:[1,0]
	v_pk_add_f32 v[124:125], v[124:125], v[124:125] op_sel:[0,1] op_sel_hi:[1,0]
	v_mov_b32_e32 v139, v77
	v_mov_b32_e32 v133, v131
	v_mov_b32_e32 v125, v146
	v_lshlrev_b32_e32 v90, 16, v130
	v_and_b32_e32 v91, 0xffff0000, v130
	v_pk_add_f32 v[126:127], v[126:127], v[138:139]
	v_pk_add_f32 v[124:125], v[132:133], v[124:125]
	v_mul_f32_e32 v82, v90, v90
	v_mul_f32_e32 v130, v91, v91
	v_pk_add_f32 v[124:125], v[126:127], v[124:125]
	v_mov_b32_e32 v131, v83
	v_lshlrev_b32_e32 v80, 16, v147
	v_and_b32_e32 v81, 0xffff0000, v147
	v_pk_add_f32 v[146:147], v[124:125], v[124:125] op_sel_hi:[0,1]
	v_pk_add_f32 v[124:125], v[82:83], v[130:131]
	v_pk_mul_f32 v[126:127], v[82:83], v[82:83]
	v_mul_f32_e32 v82, v105, v105
	v_mul_f32_e32 v77, v45, v45
	v_mov_b32_e32 v125, v127
	v_pk_fma_f32 v[126:127], v[104:105], v[104:105], v[82:83] op_sel_hi:[1,1,0]
	v_mul_f32_e32 v86, v80, v80
	v_mov_b32_e32 v127, v77
	v_pk_add_f32 v[124:125], v[124:125], v[126:127]
	v_pk_add_f32 v[126:127], v[134:135], v[134:135] op_sel:[0,1] op_sel_hi:[1,0]
	v_lshlrev_b32_e32 v134, 16, v136
	v_mul_f32_e32 v88, v81, v81
	v_pk_add_f32 v[128:129], v[128:129], v[128:129] op_sel:[0,1] op_sel_hi:[1,0]
	v_and_b32_e32 v135, 0xffff0000, v136
	v_mul_f32_e32 v82, v134, v134
	v_lshlrev_b32_e32 v138, 16, v137
	v_lshlrev_b32_e32 v72, 16, v156
	v_and_b32_e32 v73, 0xffff0000, v156
	v_lshlrev_b32_e32 v74, 16, v157
	v_and_b32_e32 v75, 0xffff0000, v157
	v_mov_b32_e32 v127, v86
	v_mov_b32_e32 v129, v88
	v_pk_fma_f32 v[156:157], v[134:135], v[134:135], v[82:83] op_sel_hi:[1,1,0]
	v_and_b32_e32 v139, 0xffff0000, v137
	v_mul_f32_e32 v82, v138, v138
	v_lshlrev_b32_e32 v132, 16, v148
	v_pk_add_f32 v[126:127], v[126:127], v[128:129]
	v_pk_fma_f32 v[158:159], v[138:139], v[138:139], v[82:83] op_sel_hi:[1,1,0]
	v_and_b32_e32 v133, 0xffff0000, v148
	v_mul_f32_e32 v82, v132, v132
	v_lshlrev_b32_e32 v136, 16, v149
	v_pk_add_f32 v[124:125], v[124:125], v[126:127]
	v_pk_fma_f32 v[160:161], v[132:133], v[132:133], v[82:83] op_sel_hi:[1,1,0]
	v_and_b32_e32 v137, 0xffff0000, v149
	v_mul_f32_e32 v82, v136, v136
	v_lshlrev_b32_e32 v126, 16, v150
	v_lshlrev_b32_e32 v76, 16, v152
	v_pk_fma_f32 v[148:149], v[136:137], v[136:137], v[82:83] op_sel_hi:[1,1,0]
	v_and_b32_e32 v127, 0xffff0000, v150
	v_mul_f32_e32 v82, v126, v126
	v_lshlrev_b32_e32 v130, 16, v151
	v_pk_fma_f32 v[162:163], v[126:127], v[126:127], v[82:83] op_sel_hi:[1,1,0]
	v_and_b32_e32 v131, 0xffff0000, v151
	v_mul_f32_e32 v82, v130, v130
	v_mov_b32_e32 v77, v157
	v_mov_b32_e32 v166, v76
	v_mov_b32_e32 v167, v159
	v_and_b32_e32 v71, 0xffff0000, v152
	v_lshlrev_b32_e32 v78, 16, v153
	v_and_b32_e32 v79, 0xffff0000, v153
	v_pk_fma_f32 v[150:151], v[130:131], v[130:131], v[82:83] op_sel_hi:[1,1,0]
	v_pk_mul_f32 v[166:167], v[76:77], v[166:167]
	v_pk_add_f32 v[156:157], v[156:157], v[158:159]
	v_mul_f32_e32 v146, v71, v71
	v_mul_f32_e32 v162, v78, v78
	v_mul_f32_e32 v150, v79, v79
	v_mov_b32_e32 v167, v157
	v_pk_add_f32 v[152:153], v[124:125], v[124:125] op_sel_hi:[0,1]
	v_lshlrev_b32_e32 v124, 16, v154
	v_pk_add_f32 v[146:147], v[166:167], v[146:147]
	v_pk_add_f32 v[150:151], v[162:163], v[150:151]
	v_and_b32_e32 v125, 0xffff0000, v154
	v_mul_f32_e32 v82, v124, v124
	v_lshlrev_b32_e32 v128, 16, v155
	v_pk_add_f32 v[146:147], v[146:147], v[150:151]
	v_pk_fma_f32 v[164:165], v[124:125], v[124:125], v[82:83] op_sel_hi:[1,1,0]
	v_and_b32_e32 v129, 0xffff0000, v155
	v_mul_f32_e32 v82, v128, v128
	v_add_f32_e32 v77, v146, v147
	v_pk_fma_f32 v[154:155], v[128:129], v[128:129], v[82:83] op_sel_hi:[1,1,0]
	ds_bpermute_b32 v82, v140, v77
	v_pk_add_f32 v[148:149], v[160:161], v[148:149]
	v_mul_f32_e32 v152, v73, v73
	v_mul_f32_e32 v164, v74, v74
	v_mul_f32_e32 v154, v75, v75
	s_waitcnt lgkmcnt(0)
; template <bool XB16>
; __device__ __forceinline__ void modulate_phase(const void* xv, const float* nw, const float* modl, const float* adab, bf16_t* H, bool perm, int wid_s_, bf16_t* XRo) {
;     ...
;         const float r0 = 1.0f / sqrtf(wave_sum(s0) * (1.f / D) + NORM_EPS), r1 = 1.0f / sqrtf(wave_sum(s1) * (1.f / D) + NORM_EPS);
;     ...
;         for (int j = 0; j < 4; ++j) { const f32x4 ya = v0[2 * j] * r0 * av[2 * j] + bv[2 * j], yb = v0[2 * j + 1] * r0 * av[2 * j + 1] + bv[2 * j + 1];
;             const f32x4 yc = v1[2 * j] * r1 * av[2 * j] + bv[2 * j], yd = v1[2 * j + 1] * r1 * av[2 * j + 1] + bv[2 * j + 1];
	v_add_f32_e32 v77, v77, v82
	ds_bpermute_b32 v82, v141, v77
	v_mul_f32_e32 v146, v72, v72
	v_mov_b32_e32 v147, v149
	v_pk_add_f32 v[146:147], v[146:147], v[152:153]
	v_pk_add_f32 v[148:149], v[164:165], v[154:155]
	s_waitcnt lgkmcnt(0)
	v_add_f32_e32 v77, v77, v82
	ds_bpermute_b32 v82, v142, v77
	v_pk_add_f32 v[146:147], v[146:147], v[148:149]
	v_mov_b32_e32 v150, v110
	v_add_f32_e32 v86, v146, v147
	v_mov_b32_e32 v151, v112
	s_waitcnt lgkmcnt(0)
	v_add_f32_e32 v77, v77, v82
	ds_bpermute_b32 v82, v143, v77
	v_mov_b32_e32 v152, v120
	v_mov_b32_e32 v153, v122
	v_mov_b32_e32 v112, v111
	v_mov_b32_e32 v122, v121
	s_waitcnt lgkmcnt(0)
	v_add_f32_e32 v77, v77, v82
	ds_bpermute_b32 v82, v144, v77
	v_mov_b32_e32 v120, v106
	v_mov_b32_e32 v121, v108
	v_mov_b32_e32 v108, v107
	s_waitcnt lgkmcnt(0)
	v_add_f32_e32 v77, v77, v82
	ds_bpermute_b32 v82, v145, v77
	s_waitcnt lgkmcnt(0)
	v_add_f32_e32 v77, v77, v82
	v_fmamk_f32 v77, v77, 0x3a000000, v185
	v_cmp_gt_f32_e32 vcc, s36, v77
	v_mul_f32_e32 v82, 0x4f800000, v77
	s_nop 0
	v_cndmask_b32_e32 v77, v77, v82, vcc
	v_sqrt_f32_e32 v82, v77
	s_nop 0
	v_add_u32_e32 v88, -1, v82
	v_fma_f32 v146, -v88, v82, v77
	v_cmp_ge_f32_e64 s[0:1], 0, v146
	v_add_u32_e32 v146, 1, v82
	s_nop 0
	v_cndmask_b32_e64 v88, v82, v88, s[0:1]
	v_fma_f32 v82, -v146, v82, v77
	v_cmp_lt_f32_e64 s[0:1], 0, v82
	s_nop 1
	v_cndmask_b32_e64 v82, v88, v146, s[0:1]
	v_mul_f32_e32 v88, 0x37800000, v82
	v_cndmask_b32_e32 v82, v82, v88, vcc
	v_cmp_class_f32_e32 vcc, v77, v186
	s_nop 1
	v_cndmask_b32_e32 v77, v82, v77, vcc
	v_div_scale_f32 v82, s[0:1], v77, v77, 1.0
	v_rcp_f32_e32 v88, v82
	s_nop 0
	v_fma_f32 v146, -v82, v88, 1.0
	v_fmac_f32_e32 v88, v146, v88
	v_div_scale_f32 v146, vcc, 1.0, v77, 1.0
	v_mul_f32_e32 v147, v146, v88
	v_fma_f32 v148, -v82, v147, v146
	v_fmac_f32_e32 v147, v148, v88
	v_fma_f32 v82, -v82, v147, v146
	v_div_fmas_f32 v82, v82, v88, v147
	v_div_fixup_f32 v82, v82, v77, 1.0
	ds_bpermute_b32 v77, v140, v86
	v_pk_mul_f32 v[150:151], v[150:151], v[82:83] op_sel_hi:[1,0]
	v_pk_mul_f32 v[152:153], v[152:153], v[82:83] op_sel_hi:[1,0]
	v_pk_mul_f32 v[110:111], v[112:113], v[82:83] op_sel_hi:[1,0]
	v_pk_mul_f32 v[112:113], v[122:123], v[82:83] op_sel_hi:[1,0]
	s_waitcnt lgkmcnt(0)
	v_add_f32_e32 v77, v86, v77
	ds_bpermute_b32 v86, v141, v77
	v_mov_b32_e32 v122, v114
	v_mov_b32_e32 v123, v116
	v_mov_b32_e32 v116, v115
	v_pk_fma_f32 v[152:153], v[32:33], v[152:153], v[2:3]
	s_waitcnt lgkmcnt(0)
	v_add_f32_e32 v77, v77, v86
	ds_bpermute_b32 v86, v142, v77
	v_pk_fma_f32 v[150:151], v[34:35], v[150:151], v[0:1]
	v_pk_fma_f32 v[112:113], v[36:37], v[112:113], v[6:7]
	v_pk_fma_f32 v[110:111], v[38:39], v[110:111], v[4:5]
	v_pk_mul_f32 v[92:93], v[92:93], v[82:83] op_sel_hi:[1,0]
	s_waitcnt lgkmcnt(0)
	v_add_f32_e32 v77, v77, v86
	ds_bpermute_b32 v86, v143, v77
	v_pk_fma_f32 v[92:93], v[48:49], v[92:93], v[12:13]
	v_pk_mul_f32 v[84:85], v[84:85], v[82:83] op_sel_hi:[1,0]
	v_cvt_pk_bf16_f32 v92, v92, v93
	v_pk_mul_f32 v[78:79], v[78:79], v[82:83] op_sel_hi:[1,0]
	s_waitcnt lgkmcnt(0)
	v_add_f32_e32 v77, v77, v86
	ds_bpermute_b32 v86, v144, v77
	v_pk_fma_f32 v[78:79], v[62:63], v[78:79], v[30:31]
	s_waitcnt lgkmcnt(0)
	v_add_f32_e32 v77, v77, v86
	ds_bpermute_b32 v86, v145, v77
	s_waitcnt lgkmcnt(0)
; __device__ __forceinline__ unsigned cvtpk(float lo, float hi) { f32x2_t v = {lo, hi}; bf16x2_t b = __builtin_convertvector(v, bf16x2_t); return __builtin_bit_cast(unsigned, b); }
; template <bool XB16>
; __device__ __forceinline__ void modulate_phase(const void* xv, const float* nw, const float* modl, const float* adab, bf16_t* H, bool perm, int wid_s_, bf16_t* XRo) {
;     ...
;         const float r0 = 1.0f / sqrtf(wave_sum(s0) * (1.f / D) + NORM_EPS), r1 = 1.0f / sqrtf(wave_sum(s1) * (1.f / D) + NORM_EPS);
;         const int o0 = perm ? ((row & 127) * 128 + (row >> 7)) : row, o1 = perm ? ((row1 & 127) * 128 + (row1 >> 7)) : row1;
;         u32x4* p0 = (u32x4*)(H + (size_t)o0 * D) + lane; u32x4* p1 = (u32x4*)(H + (size_t)o1 * D) + lane;
;         if (!XB16) { u32x4* q0 = (u32x4*)(XRo + (size_t)row * D) + lane; u32x4* q1 = (u32x4*)(XRo + (size_t)row1 * D) + lane;
; #pragma unroll
;             for (int j = 0; j < 4; ++j) { u32x4 w; w.x = cvtpk(v0[2 * j][0], v0[2 * j][1]); w.y = cvtpk(v0[2 * j][2], v0[2 * j][3]); w.z = cvtpk(v0[2 * j + 1][0], v0[2 * j + 1][1]); w.w = cvtpk(v0[2 * j + 1][2], v0[2 * j + 1][3]); q0[64 * j] = w;
;                 w.x = cvtpk(v1[2 * j][0], v1[2 * j][1]); w.y = cvtpk(v1[2 * j][2], v1[2 * j][3]); w.z = cvtpk(v1[2 * j + 1][0], v1[2 * j + 1][1]); w.w = cvtpk(v1[2 * j + 1][2], v1[2 * j + 1][3]); q1[64 * j] = w; } }
; #pragma unroll
;         for (int j = 0; j < 4; ++j) { const f32x4 ya = v0[2 * j] * r0 * av[2 * j] + bv[2 * j], yb = v0[2 * j + 1] * r0 * av[2 * j + 1] + bv[2 * j + 1];
;             const f32x4 yc = v1[2 * j] * r1 * av[2 * j] + bv[2 * j], yd = v1[2 * j + 1] * r1 * av[2 * j + 1] + bv[2 * j + 1];
;             u32x4 w; w.x = cvtpk(ya[0], ya[1]); w.y = cvtpk(ya[2], ya[3]); w.z = cvtpk(yb[0], yb[1]); w.w = cvtpk(yb[2], yb[3]); p0[64 * j] = w;
;             w.x = cvtpk(yc[0], yc[1]); w.y = cvtpk(yc[2], yc[3]); w.z = cvtpk(yd[0], yd[1]); w.w = cvtpk(yd[2], yd[3]); p1[64 * j] = w; }
;     }
	v_add_f32_e32 v77, v77, v86
	v_fmamk_f32 v77, v77, 0x3a000000, v185
	v_cmp_gt_f32_e32 vcc, s36, v77
	v_mul_f32_e32 v86, 0x4f800000, v77
	s_nop 0
	v_cndmask_b32_e32 v77, v77, v86, vcc
	v_sqrt_f32_e32 v86, v77
	s_nop 0
	v_add_u32_e32 v88, -1, v86
	v_fma_f32 v146, -v88, v86, v77
	v_cmp_ge_f32_e64 s[0:1], 0, v146
	v_add_u32_e32 v146, 1, v86
	s_nop 0
	v_cndmask_b32_e64 v88, v86, v88, s[0:1]
	v_fma_f32 v86, -v146, v86, v77
	v_cmp_lt_f32_e64 s[0:1], 0, v86
	s_nop 1
	v_cndmask_b32_e64 v86, v88, v146, s[0:1]
	v_mul_f32_e32 v88, 0x37800000, v86
	v_cndmask_b32_e32 v86, v86, v88, vcc
	v_cmp_class_f32_e32 vcc, v77, v186
	s_nop 1
	v_cndmask_b32_e32 v77, v86, v77, vcc
	v_div_scale_f32 v86, s[0:1], v77, v77, 1.0
	v_rcp_f32_e32 v88, v86
	s_nop 0
	v_fma_f32 v146, -v86, v88, 1.0
	v_fmac_f32_e32 v88, v146, v88
	v_div_scale_f32 v146, vcc, 1.0, v77, 1.0
	v_mul_f32_e32 v147, v146, v88
	v_fma_f32 v148, -v86, v147, v146
	v_fmac_f32_e32 v147, v148, v88
	v_fma_f32 v86, -v86, v147, v146
	v_div_fmas_f32 v86, v86, v88, v147
	v_div_fixup_f32 v88, v86, v77, 1.0
	v_and_b32_e32 v77, 0x3f80, v96
	v_add_u32_e32 v146, v77, v44
	v_add_u32_e32 v44, s24, v96
	v_and_b32_e32 v44, 0x3f80, v44
	v_ashrrev_i32_e32 v77, 7, v70
	v_add_u32_e32 v148, v44, v77
	v_ashrrev_i32_e32 v147, 31, v146
	v_lshlrev_b64 v[146:147], 12, v[146:147]
	v_ashrrev_i32_e32 v149, 31, v148
	v_pk_mul_f32 v[120:121], v[88:89], v[120:121] op_sel_hi:[0,1]
	v_pk_mul_f32 v[122:123], v[88:89], v[122:123] op_sel_hi:[0,1]
	v_pk_mul_f32 v[106:107], v[88:89], v[108:109] op_sel_hi:[0,1]
	v_pk_mul_f32 v[108:109], v[88:89], v[116:117] op_sel_hi:[0,1]
	v_lshl_add_u64 v[146:147], v[68:69], 0, v[146:147]
	v_lshlrev_b64 v[148:149], 12, v[148:149]
	v_pk_fma_f32 v[122:123], v[32:33], v[122:123], v[2:3]
	v_pk_fma_f32 v[120:121], v[34:35], v[120:121], v[0:1]
	v_pk_fma_f32 v[114:115], v[36:37], v[108:109], v[6:7]
	v_pk_fma_f32 v[116:117], v[38:39], v[106:107], v[4:5]
	v_cvt_pk_bf16_f32 v106, v150, v151
	v_cvt_pk_bf16_f32 v107, v152, v153
	v_cvt_pk_bf16_f32 v108, v110, v111
	v_cvt_pk_bf16_f32 v109, v112, v113
	v_lshl_add_u64 v[148:149], v[68:69], 0, v[148:149]
	global_store_dwordx4 v[146:147], v[106:109], off
	v_pk_mul_f32 v[90:91], v[88:89], v[90:91] op_sel_hi:[0,1]
	v_pk_mul_f32 v[104:105], v[88:89], v[104:105] op_sel_hi:[0,1]
	v_cvt_pk_bf16_f32 v106, v120, v121
	v_cvt_pk_bf16_f32 v107, v122, v123
	v_cvt_pk_bf16_f32 v108, v116, v117
	v_cvt_pk_bf16_f32 v109, v114, v115
	global_store_dwordx4 v[148:149], v[106:109], off
	v_pk_fma_f32 v[104:105], v[46:47], v[104:105], v[14:15]
	v_mov_b32_e32 v86, v89
	v_mov_b32_e32 v106, v100
	v_mov_b32_e32 v107, v102
	v_pk_mul_f32 v[106:107], v[82:83], v[106:107] op_sel_hi:[0,1]
	v_mov_b32_e32 v102, v101
	v_pk_mul_f32 v[100:101], v[82:83], v[102:103] op_sel_hi:[0,1]
	v_pk_fma_f32 v[102:103], v[42:43], v[106:107], v[8:9]
	v_pk_mul_f32 v[106:107], v[118:119], v[82:83] op_sel_hi:[1,0]
	v_mov_b32_e32 v108, v94
	v_mov_b32_e32 v109, v98
	v_mov_b32_e32 v98, v95
	v_pk_fma_f32 v[100:101], v[40:41], v[100:101], v[10:11]
	v_pk_fma_f32 v[106:107], v[46:47], v[106:107], v[14:15]
	v_pk_mul_f32 v[108:109], v[88:89], v[108:109] op_sel_hi:[0,1]
	v_pk_mul_f32 v[94:95], v[88:89], v[98:99] op_sel_hi:[0,1]
	v_pk_fma_f32 v[94:95], v[40:41], v[94:95], v[10:11]
	v_pk_fma_f32 v[98:99], v[42:43], v[108:109], v[8:9]
	v_pk_fma_f32 v[108:109], v[48:49], v[90:91], v[12:13]
	v_cvt_pk_bf16_f32 v90, v102, v103
	v_cvt_pk_bf16_f32 v91, v100, v101
	v_cvt_pk_bf16_f32 v93, v106, v107
	global_store_dwordx4 v[146:147], v[90:93], off offset:1024
	v_pk_mul_f32 v[86:87], v[86:87], v[82:83] op_sel_hi:[1,0]
	v_mov_b32_e32 v44, v83
	v_cvt_pk_bf16_f32 v90, v98, v99
	v_cvt_pk_bf16_f32 v91, v94, v95
	v_cvt_pk_bf16_f32 v92, v108, v109
	v_cvt_pk_bf16_f32 v93, v104, v105
	global_store_dwordx4 v[148:149], v[90:93], off offset:1024
	v_pk_mul_f32 v[44:45], v[88:89], v[44:45] op_sel_hi:[0,1]
	v_pk_mul_f32 v[80:81], v[88:89], v[80:81] op_sel_hi:[0,1]
	v_pk_fma_f32 v[90:91], v[50:51], v[84:85], v[18:19]
	v_pk_fma_f32 v[84:85], v[52:53], v[86:87], v[16:17]
	v_pk_mul_f32 v[86:87], v[82:83], v[134:135] op_sel_hi:[0,1]
	v_pk_mul_f32 v[92:93], v[82:83], v[138:139] op_sel_hi:[0,1]
	v_pk_fma_f32 v[92:93], v[54:55], v[92:93], v[22:23]
	v_pk_fma_f32 v[86:87], v[56:57], v[86:87], v[20:21]
	v_pk_fma_f32 v[44:45], v[52:53], v[44:45], v[16:17]
	v_pk_mul_f32 v[94:95], v[88:89], v[132:133] op_sel_hi:[0,1]
	v_pk_mul_f32 v[98:99], v[88:89], v[136:137] op_sel_hi:[0,1]
	v_cvt_pk_bf16_f32 v84, v84, v85
	v_cvt_pk_bf16_f32 v85, v90, v91
	v_cvt_pk_bf16_f32 v86, v86, v87
	v_cvt_pk_bf16_f32 v87, v92, v93
	v_pk_fma_f32 v[80:81], v[50:51], v[80:81], v[18:19]
	v_pk_fma_f32 v[98:99], v[54:55], v[98:99], v[22:23]
	v_pk_fma_f32 v[94:95], v[56:57], v[94:95], v[20:21]
	global_store_dwordx4 v[146:147], v[84:87], off offset:2048
	v_mov_b32_e32 v77, v71
	v_pk_mul_f32 v[76:77], v[76:77], v[82:83] op_sel_hi:[1,0]
	v_cvt_pk_bf16_f32 v84, v44, v45
	v_pk_mul_f32 v[44:45], v[82:83], v[126:127] op_sel_hi:[0,1]
	v_cvt_pk_bf16_f32 v85, v80, v81
	v_cvt_pk_bf16_f32 v86, v94, v95
	v_cvt_pk_bf16_f32 v87, v98, v99
	v_pk_mul_f32 v[80:81], v[82:83], v[130:131] op_sel_hi:[0,1]
	v_pk_fma_f32 v[44:45], v[60:61], v[44:45], v[24:25]
	v_pk_mul_f32 v[72:73], v[88:89], v[72:73] op_sel_hi:[0,1]
	global_store_dwordx4 v[148:149], v[84:87], off offset:2048
	v_pk_fma_f32 v[80:81], v[58:59], v[80:81], v[26:27]
	v_pk_fma_f32 v[76:77], v[64:65], v[76:77], v[28:29]
	v_pk_mul_f32 v[82:83], v[88:89], v[124:125] op_sel_hi:[0,1]
	v_pk_mul_f32 v[84:85], v[88:89], v[128:129] op_sel_hi:[0,1]
	v_pk_mul_f32 v[74:75], v[88:89], v[74:75] op_sel_hi:[0,1]
	v_pk_fma_f32 v[88:89], v[64:65], v[72:73], v[28:29]
	v_cvt_pk_bf16_f32 v72, v44, v45
	v_add_u32_e32 v44, s92, v70
	v_pk_fma_f32 v[84:85], v[58:59], v[84:85], v[26:27]
	v_pk_fma_f32 v[82:83], v[60:61], v[82:83], v[24:25]
	v_pk_fma_f32 v[86:87], v[62:63], v[74:75], v[30:31]
	v_cvt_pk_bf16_f32 v73, v80, v81
	v_cvt_pk_bf16_f32 v74, v76, v77
	v_cvt_pk_bf16_f32 v75, v78, v79
	v_cmp_lt_i32_e32 vcc, s21, v44
	global_store_dwordx4 v[146:147], v[72:75], off offset:3072
	v_add_u32_e32 v96, s37, v96
	s_or_b64 s[6:7], vcc, s[6:7]
	v_cvt_pk_bf16_f32 v72, v82, v83
	v_cvt_pk_bf16_f32 v73, v84, v85
	v_cvt_pk_bf16_f32 v74, v88, v89
	v_cvt_pk_bf16_f32 v75, v86, v87
	global_store_dwordx4 v[148:149], v[72:75], off offset:3072
	s_andn2_b64 exec, exec, s[6:7]
	s_cbranch_execnz .LBB0_163

; __device__ __forceinline__ unsigned cvtpk(float lo, float hi) { f32x2_t v = {lo, hi}; bf16x2_t b = __builtin_convertvector(v, bf16x2_t); return __builtin_bit_cast(unsigned, b); }
; __device__ __forceinline__ float silu_f(float v) { return v * __builtin_amdgcn_rcpf(1.f + __builtin_amdgcn_exp2f(-LOG2E * v)); }
;     __device__ __forceinline__ void operator()(const f32x4 (&acc)[2][2][4][2], const Unit& u, int wr, int wc, int fr, int fq) const {
;     ...
;             for (int m = 0; m < 4; ++m) { bf16_t* rowp = O + (size_t)(row0 + ai * HALF + m * 16) * ldc + col0;
; #pragma unroll
;                 for (int bj = 0; bj < 2; ++bj) { f32x4 v0 = acc[ai][bj][m][0] * scale, v1 = acc[ai][bj][m][1] * scale;
;                     if (act) {
; #pragma unroll
;                         for (int i = 0; i < 4; ++i) { v0[i] = silu_f(v0[i]); v1[i] = silu_f(v1[i]); } }
;                     u32x4 w; w.x = cvtpk(v0[0], v0[1]); w.y = cvtpk(v0[2], v0[3]); w.z = cvtpk(v1[0], v1[1]); w.w = cvtpk(v1[2], v1[3]);
;                     *(u32x4*)(rowp + bj * HALF) = w; } }
.LBB0_271:
	s_sub_i32 s3, s84, s5
	v_lshl_add_u32 v158, s3, 8, v146
	v_ashrrev_i32_e32 v159, 31, v158
	v_or_b32_e32 v98, s2, v148
	v_lshlrev_b64 v[150:151], 12, v[158:159]
	v_ashrrev_i32_e32 v99, 31, v98
	v_lshl_add_u64 v[150:151], s[6:7], 0, v[150:151]
	v_lshl_add_u64 v[160:161], v[98:99], 1, v[150:151]
	v_cvt_pk_bf16_f32 v132, v132, v133
	v_cvt_pk_bf16_f32 v133, v134, v135
	v_cvt_pk_bf16_f32 v134, v136, v137
	v_cvt_pk_bf16_f32 v135, v138, v139
	global_store_dwordx4 v[160:161], v[132:135], off
	v_cndmask_b32_e64 v96, 0, 1, s[24:25]
	v_mov_b64_e32 v[138:139], v[110:111]
	v_mov_b64_e32 v[134:135], v[118:119]
	v_cmp_ne_u32_e64 s[2:3], 1, v96
	s_andn2_b64 vcc, exec, s[24:25]
	v_mov_b64_e32 v[132:133], v[116:117]
	v_mov_b64_e32 v[136:137], v[108:109]
	s_cbranch_vccnz .LBB0_273
	v_mul_f32_e32 v96, 0xbfb8aa3b, v116
	v_exp_f32_e32 v96, v96
	v_mul_f32_e32 v132, 0xbfb8aa3b, v108
	v_mul_f32_e32 v133, 0xbfb8aa3b, v117
	v_exp_f32_e32 v134, v132
	v_exp_f32_e32 v133, v133
	v_add_f32_e32 v96, 1.0, v96
	v_rcp_f32_e32 v132, v96
	v_add_f32_e32 v96, 1.0, v134
	v_rcp_f32_e32 v136, v96
	v_add_f32_e32 v96, 1.0, v133
	v_mul_f32_e32 v135, 0xbfb8aa3b, v110
	v_rcp_f32_e32 v133, v96
	v_mul_f32_e32 v96, 0xbfb8aa3b, v109
	v_mul_f32_e32 v134, 0xbfb8aa3b, v118
	v_exp_f32_e32 v135, v135
	v_mul_f32_e32 v137, 0xbfb8aa3b, v119
	v_mul_f32_e32 v138, 0xbfb8aa3b, v111
	v_exp_f32_e32 v96, v96
	v_exp_f32_e32 v134, v134
	v_exp_f32_e32 v137, v137
	v_exp_f32_e32 v139, v138
	v_add_f32_e32 v135, 1.0, v135
	v_add_f32_e32 v96, 1.0, v96
	v_add_f32_e32 v134, 1.0, v134
	v_rcp_f32_e32 v138, v135
	v_add_f32_e32 v135, 1.0, v137
	v_add_f32_e32 v137, 1.0, v139
	v_rcp_f32_e32 v134, v134
	v_rcp_f32_e32 v135, v135
	v_rcp_f32_e32 v139, v137
	v_rcp_f32_e32 v137, v96
	v_pk_mul_f32 v[132:133], v[116:117], v[132:133]
	v_pk_mul_f32 v[134:135], v[118:119], v[134:135]
	v_pk_mul_f32 v[138:139], v[110:111], v[138:139]
	v_pk_mul_f32 v[136:137], v[108:109], v[136:137]
.LBB0_273:
	v_cvt_pk_bf16_f32 v132, v132, v133
	v_cvt_pk_bf16_f32 v133, v134, v135
	v_cvt_pk_bf16_f32 v134, v136, v137
	v_cvt_pk_bf16_f32 v135, v138, v139
	global_store_dwordx4 v[160:161], v[132:135], off offset:256
	v_mov_b64_e32 v[138:139], v[114:115]
	s_and_b64 vcc, exec, s[2:3]
	v_mov_b64_e32 v[134:135], v[122:123]
	v_mov_b64_e32 v[132:133], v[120:121]
	v_mov_b64_e32 v[136:137], v[112:113]
	s_cbranch_vccnz .LBB0_275
	v_mul_f32_e32 v96, 0xbfb8aa3b, v120
	v_exp_f32_e32 v96, v96
	v_mul_f32_e32 v132, 0xbfb8aa3b, v112
	v_mul_f32_e32 v133, 0xbfb8aa3b, v121
	v_exp_f32_e32 v134, v132
	v_exp_f32_e32 v133, v133
	v_add_f32_e32 v96, 1.0, v96
	v_rcp_f32_e32 v132, v96
	v_add_f32_e32 v96, 1.0, v134
	v_rcp_f32_e32 v136, v96
	v_add_f32_e32 v96, 1.0, v133
	v_mul_f32_e32 v135, 0xbfb8aa3b, v114
	v_rcp_f32_e32 v133, v96
	v_mul_f32_e32 v96, 0xbfb8aa3b, v113
	v_mul_f32_e32 v134, 0xbfb8aa3b, v122
	v_exp_f32_e32 v135, v135
	v_mul_f32_e32 v137, 0xbfb8aa3b, v123
	v_mul_f32_e32 v138, 0xbfb8aa3b, v115
	v_exp_f32_e32 v96, v96
	v_exp_f32_e32 v134, v134
	v_exp_f32_e32 v137, v137
	v_exp_f32_e32 v139, v138
	v_add_f32_e32 v135, 1.0, v135
	v_add_f32_e32 v96, 1.0, v96
	v_add_f32_e32 v134, 1.0, v134
	v_rcp_f32_e32 v138, v135
	v_add_f32_e32 v135, 1.0, v137
	v_add_f32_e32 v137, 1.0, v139
	v_rcp_f32_e32 v134, v134
	v_rcp_f32_e32 v135, v135
	v_rcp_f32_e32 v139, v137
	v_rcp_f32_e32 v137, v96
	v_pk_mul_f32 v[132:133], v[120:121], v[132:133]
	v_pk_mul_f32 v[134:135], v[122:123], v[134:135]
	v_pk_mul_f32 v[138:139], v[114:115], v[138:139]
	v_pk_mul_f32 v[136:137], v[112:113], v[136:137]
.LBB0_275:
	v_or_b32_e32 v150, 16, v158
	v_ashrrev_i32_e32 v151, 31, v150
	v_lshlrev_b64 v[150:151], 12, v[150:151]
	v_lshl_add_u64 v[150:151], s[6:7], 0, v[150:151]
	v_lshl_add_u64 v[160:161], v[98:99], 1, v[150:151]
	v_cvt_pk_bf16_f32 v132, v132, v133
	v_cvt_pk_bf16_f32 v133, v134, v135
	v_cvt_pk_bf16_f32 v134, v136, v137
	v_cvt_pk_bf16_f32 v135, v138, v139
	global_store_dwordx4 v[160:161], v[132:135], off
	v_mov_b64_e32 v[138:139], v[90:91]
	s_and_b64 vcc, exec, s[2:3]
	v_mov_b64_e32 v[134:135], v[102:103]
	v_mov_b64_e32 v[132:133], v[100:101]
	v_mov_b64_e32 v[136:137], v[88:89]
	s_cbranch_vccnz .LBB0_277
	v_mul_f32_e32 v96, 0xbfb8aa3b, v100
	v_exp_f32_e32 v96, v96
	v_mul_f32_e32 v132, 0xbfb8aa3b, v88
	v_mul_f32_e32 v133, 0xbfb8aa3b, v101
	v_exp_f32_e32 v134, v132
	v_exp_f32_e32 v133, v133
	v_add_f32_e32 v96, 1.0, v96
	v_rcp_f32_e32 v132, v96
	v_add_f32_e32 v96, 1.0, v134
	v_rcp_f32_e32 v136, v96
	v_add_f32_e32 v96, 1.0, v133
	v_mul_f32_e32 v135, 0xbfb8aa3b, v90
	v_rcp_f32_e32 v133, v96
	v_mul_f32_e32 v96, 0xbfb8aa3b, v89
	v_mul_f32_e32 v134, 0xbfb8aa3b, v102
	v_exp_f32_e32 v135, v135
	v_mul_f32_e32 v137, 0xbfb8aa3b, v103
	v_mul_f32_e32 v138, 0xbfb8aa3b, v91
	v_exp_f32_e32 v96, v96
	v_exp_f32_e32 v134, v134
	v_exp_f32_e32 v137, v137
	v_exp_f32_e32 v139, v138
	v_add_f32_e32 v135, 1.0, v135
	v_add_f32_e32 v96, 1.0, v96
	v_add_f32_e32 v134, 1.0, v134
	v_rcp_f32_e32 v138, v135
	v_add_f32_e32 v135, 1.0, v137
	v_add_f32_e32 v137, 1.0, v139
	v_rcp_f32_e32 v134, v134
	v_rcp_f32_e32 v135, v135
	v_rcp_f32_e32 v139, v137
	v_rcp_f32_e32 v137, v96
	v_pk_mul_f32 v[132:133], v[100:101], v[132:133]
	v_pk_mul_f32 v[134:135], v[102:103], v[134:135]
	v_pk_mul_f32 v[138:139], v[90:91], v[138:139]
	v_pk_mul_f32 v[136:137], v[88:89], v[136:137]
; __device__ __forceinline__ unsigned cvtpk(float lo, float hi) { f32x2_t v = {lo, hi}; bf16x2_t b = __builtin_convertvector(v, bf16x2_t); return __builtin_bit_cast(unsigned, b); }
; __device__ __forceinline__ float silu_f(float v) { return v * __builtin_amdgcn_rcpf(1.f + __builtin_amdgcn_exp2f(-LOG2E * v)); }
;     __device__ __forceinline__ void operator()(const f32x4 (&acc)[2][2][4][2], const Unit& u, int wr, int wc, int fr, int fq) const {
;     ...
;             for (int m = 0; m < 4; ++m) { bf16_t* rowp = O + (size_t)(row0 + ai * HALF + m * 16) * ldc + col0;
; #pragma unroll
;                 for (int bj = 0; bj < 2; ++bj) { f32x4 v0 = acc[ai][bj][m][0] * scale, v1 = acc[ai][bj][m][1] * scale;
;                     if (act) {
; #pragma unroll
;                         for (int i = 0; i < 4; ++i) { v0[i] = silu_f(v0[i]); v1[i] = silu_f(v1[i]); } }
;                     u32x4 w; w.x = cvtpk(v0[0], v0[1]); w.y = cvtpk(v0[2], v0[3]); w.z = cvtpk(v1[0], v1[1]); w.w = cvtpk(v1[2], v1[3]);
;                     *(u32x4*)(rowp + bj * HALF) = w; } }
.LBB0_277:
	v_cvt_pk_bf16_f32 v132, v132, v133
	v_cvt_pk_bf16_f32 v133, v134, v135
	v_cvt_pk_bf16_f32 v134, v136, v137
	v_cvt_pk_bf16_f32 v135, v138, v139
	global_store_dwordx4 v[160:161], v[132:135], off offset:256
	v_mov_b64_e32 v[138:139], v[94:95]
	s_and_b64 vcc, exec, s[2:3]
	v_mov_b64_e32 v[134:135], v[106:107]
	v_mov_b64_e32 v[132:133], v[104:105]
	v_mov_b64_e32 v[136:137], v[92:93]
	s_cbranch_vccnz .LBB0_279
	v_mul_f32_e32 v96, 0xbfb8aa3b, v104
	v_exp_f32_e32 v96, v96
	v_mul_f32_e32 v132, 0xbfb8aa3b, v92
	v_mul_f32_e32 v133, 0xbfb8aa3b, v105
	v_exp_f32_e32 v134, v132
	v_exp_f32_e32 v133, v133
	v_add_f32_e32 v96, 1.0, v96
	v_rcp_f32_e32 v132, v96
	v_add_f32_e32 v96, 1.0, v134
	v_rcp_f32_e32 v136, v96
	v_add_f32_e32 v96, 1.0, v133
	v_mul_f32_e32 v135, 0xbfb8aa3b, v94
	v_rcp_f32_e32 v133, v96
	v_mul_f32_e32 v96, 0xbfb8aa3b, v93
	v_mul_f32_e32 v134, 0xbfb8aa3b, v106
	v_exp_f32_e32 v135, v135
	v_mul_f32_e32 v137, 0xbfb8aa3b, v107
	v_mul_f32_e32 v138, 0xbfb8aa3b, v95
	v_exp_f32_e32 v96, v96
	v_exp_f32_e32 v134, v134
	v_exp_f32_e32 v137, v137
	v_exp_f32_e32 v139, v138
	v_add_f32_e32 v135, 1.0, v135
	v_add_f32_e32 v96, 1.0, v96
	v_add_f32_e32 v134, 1.0, v134
	v_rcp_f32_e32 v138, v135
	v_add_f32_e32 v135, 1.0, v137
	v_add_f32_e32 v137, 1.0, v139
	v_rcp_f32_e32 v134, v134
	v_rcp_f32_e32 v135, v135
	v_rcp_f32_e32 v139, v137
	v_rcp_f32_e32 v137, v96
	v_pk_mul_f32 v[132:133], v[104:105], v[132:133]
	v_pk_mul_f32 v[134:135], v[106:107], v[134:135]
	v_pk_mul_f32 v[138:139], v[94:95], v[138:139]
	v_pk_mul_f32 v[136:137], v[92:93], v[136:137]
.LBB0_279:
	v_or_b32_e32 v150, 32, v158
	v_ashrrev_i32_e32 v151, 31, v150
	v_lshlrev_b64 v[150:151], 12, v[150:151]
	v_lshl_add_u64 v[150:151], s[6:7], 0, v[150:151]
	v_lshl_add_u64 v[160:161], v[98:99], 1, v[150:151]
	v_cvt_pk_bf16_f32 v132, v132, v133
	v_cvt_pk_bf16_f32 v133, v134, v135
	v_cvt_pk_bf16_f32 v134, v136, v137
	v_cvt_pk_bf16_f32 v135, v138, v139
	global_store_dwordx4 v[160:161], v[132:135], off
	v_mov_b64_e32 v[138:139], v[74:75]
	s_and_b64 vcc, exec, s[2:3]
	v_mov_b64_e32 v[134:135], v[82:83]
	v_mov_b64_e32 v[132:133], v[80:81]
	v_mov_b64_e32 v[136:137], v[72:73]
	s_cbranch_vccnz .LBB0_281
	v_mul_f32_e32 v96, 0xbfb8aa3b, v80
	v_exp_f32_e32 v96, v96
	v_mul_f32_e32 v132, 0xbfb8aa3b, v72
	v_mul_f32_e32 v133, 0xbfb8aa3b, v81
	v_exp_f32_e32 v134, v132
	v_exp_f32_e32 v133, v133
	v_add_f32_e32 v96, 1.0, v96
	v_rcp_f32_e32 v132, v96
	v_add_f32_e32 v96, 1.0, v134
	v_rcp_f32_e32 v136, v96
	v_add_f32_e32 v96, 1.0, v133
	v_mul_f32_e32 v135, 0xbfb8aa3b, v74
	v_rcp_f32_e32 v133, v96
	v_mul_f32_e32 v96, 0xbfb8aa3b, v73
	v_mul_f32_e32 v134, 0xbfb8aa3b, v82
	v_exp_f32_e32 v135, v135
	v_mul_f32_e32 v137, 0xbfb8aa3b, v83
	v_mul_f32_e32 v138, 0xbfb8aa3b, v75
	v_exp_f32_e32 v96, v96
	v_exp_f32_e32 v134, v134
	v_exp_f32_e32 v137, v137
	v_exp_f32_e32 v139, v138
	v_add_f32_e32 v135, 1.0, v135
	v_add_f32_e32 v96, 1.0, v96
	v_add_f32_e32 v134, 1.0, v134
	v_rcp_f32_e32 v138, v135
	v_add_f32_e32 v135, 1.0, v137
	v_add_f32_e32 v137, 1.0, v139
	v_rcp_f32_e32 v134, v134
	v_rcp_f32_e32 v135, v135
	v_rcp_f32_e32 v139, v137
	v_rcp_f32_e32 v137, v96
	v_pk_mul_f32 v[132:133], v[80:81], v[132:133]
	v_pk_mul_f32 v[134:135], v[82:83], v[134:135]
	v_pk_mul_f32 v[138:139], v[74:75], v[138:139]
	v_pk_mul_f32 v[136:137], v[72:73], v[136:137]
.LBB0_281:
	v_cvt_pk_bf16_f32 v132, v132, v133
	v_cvt_pk_bf16_f32 v133, v134, v135
	v_cvt_pk_bf16_f32 v134, v136, v137
	v_cvt_pk_bf16_f32 v135, v138, v139
	global_store_dwordx4 v[160:161], v[132:135], off offset:256
	v_mov_b64_e32 v[138:139], v[78:79]
	s_and_b64 vcc, exec, s[2:3]
	v_mov_b64_e32 v[134:135], v[86:87]
	v_mov_b64_e32 v[132:133], v[84:85]
	v_mov_b64_e32 v[136:137], v[76:77]
	s_cbranch_vccnz .LBB0_283
	v_mul_f32_e32 v96, 0xbfb8aa3b, v84
	v_exp_f32_e32 v96, v96
	v_mul_f32_e32 v132, 0xbfb8aa3b, v76
	v_mul_f32_e32 v133, 0xbfb8aa3b, v85
	v_exp_f32_e32 v134, v132
	v_exp_f32_e32 v133, v133
	v_add_f32_e32 v96, 1.0, v96
	v_rcp_f32_e32 v132, v96
	v_add_f32_e32 v96, 1.0, v134
	v_rcp_f32_e32 v136, v96
	v_add_f32_e32 v96, 1.0, v133
	v_mul_f32_e32 v135, 0xbfb8aa3b, v78
	v_rcp_f32_e32 v133, v96
	v_mul_f32_e32 v96, 0xbfb8aa3b, v77
	v_mul_f32_e32 v134, 0xbfb8aa3b, v86
	v_exp_f32_e32 v135, v135
	v_mul_f32_e32 v137, 0xbfb8aa3b, v87
	v_mul_f32_e32 v138, 0xbfb8aa3b, v79
	v_exp_f32_e32 v96, v96
	v_exp_f32_e32 v134, v134
	v_exp_f32_e32 v137, v137
	v_exp_f32_e32 v139, v138
	v_add_f32_e32 v135, 1.0, v135
	v_add_f32_e32 v96, 1.0, v96
	v_add_f32_e32 v134, 1.0, v134
	v_rcp_f32_e32 v138, v135
	v_add_f32_e32 v135, 1.0, v137
	v_add_f32_e32 v137, 1.0, v139
	v_rcp_f32_e32 v134, v134
	v_rcp_f32_e32 v135, v135
	v_rcp_f32_e32 v139, v137
	v_rcp_f32_e32 v137, v96
	v_pk_mul_f32 v[132:133], v[84:85], v[132:133]
	v_pk_mul_f32 v[134:135], v[86:87], v[134:135]
	v_pk_mul_f32 v[138:139], v[78:79], v[138:139]
	v_pk_mul_f32 v[136:137], v[76:77], v[136:137]
; __device__ __forceinline__ unsigned cvtpk(float lo, float hi) { f32x2_t v = {lo, hi}; bf16x2_t b = __builtin_convertvector(v, bf16x2_t); return __builtin_bit_cast(unsigned, b); }
; __device__ __forceinline__ float silu_f(float v) { return v * __builtin_amdgcn_rcpf(1.f + __builtin_amdgcn_exp2f(-LOG2E * v)); }
;     __device__ __forceinline__ void operator()(const f32x4 (&acc)[2][2][4][2], const Unit& u, int wr, int wc, int fr, int fq) const {
;         const int row0 = u.pm * BM + wr * 64 + fr, colt = u.pn * BM, col0 = colt + wc * 32 + 8 * fq;
;         const bool act = colt >= silu_from;
; #pragma unroll
;         for (int ai = 0; ai < 2; ++ai)
; #pragma unroll
;             for (int m = 0; m < 4; ++m) { bf16_t* rowp = O + (size_t)(row0 + ai * HALF + m * 16) * ldc + col0;
; #pragma unroll
;                 for (int bj = 0; bj < 2; ++bj) { f32x4 v0 = acc[ai][bj][m][0] * scale, v1 = acc[ai][bj][m][1] * scale;
;                     if (act) {
; #pragma unroll
;                         for (int i = 0; i < 4; ++i) { v0[i] = silu_f(v0[i]); v1[i] = silu_f(v1[i]); } }
;                     u32x4 w; w.x = cvtpk(v0[0], v0[1]); w.y = cvtpk(v0[2], v0[3]); w.z = cvtpk(v1[0], v1[1]); w.w = cvtpk(v1[2], v1[3]);
;                     *(u32x4*)(rowp + bj * HALF) = w; } }
;     __device__ __forceinline__ void operator()(const f32x4 (&acc)[2][2][4][2], const Unit& u, int wr, int wc, int fr, int fq) const {
;         if (u.pm >= TH) { const Unit v{u.pm - TH, u.pn - pnA}; ea(acc, v, wr, wc, fr, fq); }
;         else { const Unit v{u.pm - pmB, u.pn - TH}; eb(acc, v, wr, wc, fr, fq); }
.LBB0_283:
	v_or_b32_e32 v150, 48, v158
	v_ashrrev_i32_e32 v151, 31, v150
	v_lshlrev_b64 v[150:151], 12, v[150:151]
	v_lshl_add_u64 v[150:151], s[6:7], 0, v[150:151]
	v_lshl_add_u64 v[160:161], v[98:99], 1, v[150:151]
	v_cvt_pk_bf16_f32 v132, v132, v133
	v_cvt_pk_bf16_f32 v133, v134, v135
	v_cvt_pk_bf16_f32 v134, v136, v137
	v_cvt_pk_bf16_f32 v135, v138, v139
	global_store_dwordx4 v[160:161], v[132:135], off
	v_mov_b64_e32 v[138:139], v[66:67]
	s_and_b64 vcc, exec, s[2:3]
	v_mov_b64_e32 v[134:135], v[70:71]
	v_mov_b64_e32 v[132:133], v[68:69]
	v_mov_b64_e32 v[136:137], v[64:65]
	s_cbranch_vccnz .LBB0_285
	v_mul_f32_e32 v96, 0xbfb8aa3b, v68
	v_exp_f32_e32 v96, v96
	v_mul_f32_e32 v132, 0xbfb8aa3b, v64
	v_mul_f32_e32 v133, 0xbfb8aa3b, v69
	v_exp_f32_e32 v134, v132
	v_exp_f32_e32 v133, v133
	v_add_f32_e32 v96, 1.0, v96
	v_rcp_f32_e32 v132, v96
	v_add_f32_e32 v96, 1.0, v134
	v_rcp_f32_e32 v136, v96
	v_add_f32_e32 v96, 1.0, v133
	v_mul_f32_e32 v135, 0xbfb8aa3b, v66
	v_rcp_f32_e32 v133, v96
	v_mul_f32_e32 v96, 0xbfb8aa3b, v65
	v_mul_f32_e32 v134, 0xbfb8aa3b, v70
	v_exp_f32_e32 v135, v135
	v_mul_f32_e32 v137, 0xbfb8aa3b, v71
	v_mul_f32_e32 v138, 0xbfb8aa3b, v67
	v_exp_f32_e32 v96, v96
	v_exp_f32_e32 v134, v134
	v_exp_f32_e32 v137, v137
	v_exp_f32_e32 v139, v138
	v_add_f32_e32 v135, 1.0, v135
	v_add_f32_e32 v96, 1.0, v96
	v_add_f32_e32 v134, 1.0, v134
	v_rcp_f32_e32 v138, v135
	v_add_f32_e32 v135, 1.0, v137
	v_add_f32_e32 v137, 1.0, v139
	v_rcp_f32_e32 v134, v134
	v_rcp_f32_e32 v135, v135
	v_rcp_f32_e32 v139, v137
	v_rcp_f32_e32 v137, v96
	v_pk_mul_f32 v[132:133], v[68:69], v[132:133]
	v_pk_mul_f32 v[134:135], v[70:71], v[134:135]
	v_pk_mul_f32 v[138:139], v[66:67], v[138:139]
	v_pk_mul_f32 v[136:137], v[64:65], v[136:137]
.LBB0_285:
	v_cvt_pk_bf16_f32 v132, v132, v133
	v_cvt_pk_bf16_f32 v133, v134, v135
	v_cvt_pk_bf16_f32 v134, v136, v137
	v_cvt_pk_bf16_f32 v135, v138, v139
	global_store_dwordx4 v[160:161], v[132:135], off offset:256
	v_mov_b64_e32 v[138:139], v[58:59]
	s_and_b64 vcc, exec, s[2:3]
	v_mov_b64_e32 v[134:135], v[62:63]
	v_mov_b64_e32 v[132:133], v[60:61]
	v_mov_b64_e32 v[136:137], v[56:57]
	s_cbranch_vccnz .LBB0_287
	v_mul_f32_e32 v96, 0xbfb8aa3b, v60
	v_exp_f32_e32 v96, v96
	v_mul_f32_e32 v132, 0xbfb8aa3b, v56
	v_mul_f32_e32 v133, 0xbfb8aa3b, v61
	v_exp_f32_e32 v134, v132
	v_exp_f32_e32 v133, v133
	v_add_f32_e32 v96, 1.0, v96
	v_rcp_f32_e32 v132, v96
	v_add_f32_e32 v96, 1.0, v134
	v_rcp_f32_e32 v136, v96
	v_add_f32_e32 v96, 1.0, v133
	v_mul_f32_e32 v135, 0xbfb8aa3b, v58
	v_rcp_f32_e32 v133, v96
	v_mul_f32_e32 v96, 0xbfb8aa3b, v57
	v_mul_f32_e32 v134, 0xbfb8aa3b, v62
	v_exp_f32_e32 v135, v135
	v_mul_f32_e32 v137, 0xbfb8aa3b, v63
	v_mul_f32_e32 v138, 0xbfb8aa3b, v59
	v_exp_f32_e32 v96, v96
	v_exp_f32_e32 v134, v134
	v_exp_f32_e32 v137, v137
	v_exp_f32_e32 v139, v138
	v_add_f32_e32 v135, 1.0, v135
	v_add_f32_e32 v96, 1.0, v96
	v_add_f32_e32 v134, 1.0, v134
	v_rcp_f32_e32 v138, v135
	v_add_f32_e32 v135, 1.0, v137
	v_add_f32_e32 v137, 1.0, v139
	v_rcp_f32_e32 v134, v134
	v_rcp_f32_e32 v135, v135
	v_rcp_f32_e32 v139, v137
	v_rcp_f32_e32 v137, v96
	v_pk_mul_f32 v[132:133], v[60:61], v[132:133]
	v_pk_mul_f32 v[134:135], v[62:63], v[134:135]
	v_pk_mul_f32 v[138:139], v[58:59], v[138:139]
	v_pk_mul_f32 v[136:137], v[56:57], v[136:137]
.LBB0_287:
	v_lshlrev_b64 v[150:151], 12, v[158:159]
	v_lshl_add_u64 v[150:151], s[6:7], 0, v[150:151]
	v_lshl_add_u64 v[160:161], v[98:99], 1, v[150:151]
	v_cvt_pk_bf16_f32 v132, v132, v133
	v_cvt_pk_bf16_f32 v133, v134, v135
	v_cvt_pk_bf16_f32 v134, v136, v137
	v_add_co_u32_e32 v136, vcc, 0x80000, v160
	v_cvt_pk_bf16_f32 v135, v138, v139
	s_nop 0
	v_addc_co_u32_e32 v137, vcc, 0, v161, vcc
	global_store_dwordx4 v[136:137], v[132:135], off
	v_mov_b64_e32 v[138:139], v[42:43]
	s_and_b64 vcc, exec, s[2:3]
	v_mov_b64_e32 v[134:135], v[46:47]
	v_mov_b64_e32 v[132:133], v[44:45]
	v_mov_b64_e32 v[136:137], v[40:41]
	s_cbranch_vccnz .LBB0_289
	v_mul_f32_e32 v96, 0xbfb8aa3b, v44
	v_exp_f32_e32 v96, v96
	v_mul_f32_e32 v132, 0xbfb8aa3b, v40
	v_mul_f32_e32 v133, 0xbfb8aa3b, v45
	v_exp_f32_e32 v134, v132
	v_exp_f32_e32 v133, v133
	v_add_f32_e32 v96, 1.0, v96
	v_rcp_f32_e32 v132, v96
	v_add_f32_e32 v96, 1.0, v134
	v_rcp_f32_e32 v136, v96
	v_add_f32_e32 v96, 1.0, v133
	v_mul_f32_e32 v135, 0xbfb8aa3b, v42
	v_rcp_f32_e32 v133, v96
	v_mul_f32_e32 v96, 0xbfb8aa3b, v41
	v_mul_f32_e32 v134, 0xbfb8aa3b, v46
	v_exp_f32_e32 v135, v135
	v_mul_f32_e32 v137, 0xbfb8aa3b, v47
	v_mul_f32_e32 v138, 0xbfb8aa3b, v43
	v_exp_f32_e32 v96, v96
	v_exp_f32_e32 v134, v134
	v_exp_f32_e32 v137, v137
	v_exp_f32_e32 v139, v138
	v_add_f32_e32 v135, 1.0, v135
	v_add_f32_e32 v96, 1.0, v96
	v_add_f32_e32 v134, 1.0, v134
	v_rcp_f32_e32 v138, v135
	v_add_f32_e32 v135, 1.0, v137
	v_add_f32_e32 v137, 1.0, v139
	v_rcp_f32_e32 v134, v134
	v_rcp_f32_e32 v135, v135
	v_rcp_f32_e32 v139, v137
	v_rcp_f32_e32 v137, v96
	v_pk_mul_f32 v[132:133], v[44:45], v[132:133]
	v_pk_mul_f32 v[134:135], v[46:47], v[134:135]
	v_pk_mul_f32 v[138:139], v[42:43], v[138:139]
	v_pk_mul_f32 v[136:137], v[40:41], v[136:137]
; __device__ __forceinline__ unsigned cvtpk(float lo, float hi) { f32x2_t v = {lo, hi}; bf16x2_t b = __builtin_convertvector(v, bf16x2_t); return __builtin_bit_cast(unsigned, b); }
; __device__ __forceinline__ float silu_f(float v) { return v * __builtin_amdgcn_rcpf(1.f + __builtin_amdgcn_exp2f(-LOG2E * v)); }
;     __device__ __forceinline__ void operator()(const f32x4 (&acc)[2][2][4][2], const Unit& u, int wr, int wc, int fr, int fq) const {
;         const int row0 = u.pm * BM + wr * 64 + fr, colt = u.pn * BM, col0 = colt + wc * 32 + 8 * fq;
;         const bool act = colt >= silu_from;
; #pragma unroll
;         for (int ai = 0; ai < 2; ++ai)
; #pragma unroll
;             for (int m = 0; m < 4; ++m) { bf16_t* rowp = O + (size_t)(row0 + ai * HALF + m * 16) * ldc + col0;
; #pragma unroll
;                 for (int bj = 0; bj < 2; ++bj) { f32x4 v0 = acc[ai][bj][m][0] * scale, v1 = acc[ai][bj][m][1] * scale;
;                     if (act) {
; #pragma unroll
;                         for (int i = 0; i < 4; ++i) { v0[i] = silu_f(v0[i]); v1[i] = silu_f(v1[i]); } }
;                     u32x4 w; w.x = cvtpk(v0[0], v0[1]); w.y = cvtpk(v0[2], v0[3]); w.z = cvtpk(v1[0], v1[1]); w.w = cvtpk(v1[2], v1[3]);
;                     *(u32x4*)(rowp + bj * HALF) = w; } }
;     __device__ __forceinline__ void operator()(const f32x4 (&acc)[2][2][4][2], const Unit& u, int wr, int wc, int fr, int fq) const {
;         if (u.pm >= TH) { const Unit v{u.pm - TH, u.pn - pnA}; ea(acc, v, wr, wc, fr, fq); }
;         else { const Unit v{u.pm - pmB, u.pn - TH}; eb(acc, v, wr, wc, fr, fq); }
.LBB0_289:
	s_mov_b64 s[24:25], 0x80000
	v_lshl_add_u64 v[150:151], v[160:161], 0, s[24:25]
	v_cvt_pk_bf16_f32 v132, v132, v133
	v_cvt_pk_bf16_f32 v133, v134, v135
	v_cvt_pk_bf16_f32 v134, v136, v137
	v_cvt_pk_bf16_f32 v135, v138, v139
	global_store_dwordx4 v[150:151], v[132:135], off offset:256
	v_mov_b64_e32 v[138:139], v[50:51]
	s_and_b64 vcc, exec, s[2:3]
	v_mov_b64_e32 v[134:135], v[54:55]
	v_mov_b64_e32 v[132:133], v[52:53]
	v_mov_b64_e32 v[136:137], v[48:49]
	s_cbranch_vccnz .LBB0_291
	v_mul_f32_e32 v96, 0xbfb8aa3b, v52
	v_exp_f32_e32 v96, v96
	v_mul_f32_e32 v132, 0xbfb8aa3b, v48
	v_mul_f32_e32 v133, 0xbfb8aa3b, v53
	v_exp_f32_e32 v134, v132
	v_exp_f32_e32 v133, v133
	v_add_f32_e32 v96, 1.0, v96
	v_rcp_f32_e32 v132, v96
	v_add_f32_e32 v96, 1.0, v134
	v_rcp_f32_e32 v136, v96
	v_add_f32_e32 v96, 1.0, v133
	v_mul_f32_e32 v135, 0xbfb8aa3b, v50
	v_rcp_f32_e32 v133, v96
	v_mul_f32_e32 v96, 0xbfb8aa3b, v49
	v_mul_f32_e32 v134, 0xbfb8aa3b, v54
	v_exp_f32_e32 v135, v135
	v_mul_f32_e32 v137, 0xbfb8aa3b, v55
	v_mul_f32_e32 v138, 0xbfb8aa3b, v51
	v_exp_f32_e32 v96, v96
	v_exp_f32_e32 v134, v134
	v_exp_f32_e32 v137, v137
	v_exp_f32_e32 v139, v138
	v_add_f32_e32 v135, 1.0, v135
	v_add_f32_e32 v96, 1.0, v96
	v_add_f32_e32 v134, 1.0, v134
	v_rcp_f32_e32 v138, v135
	v_add_f32_e32 v135, 1.0, v137
	v_add_f32_e32 v137, 1.0, v139
	v_rcp_f32_e32 v134, v134
	v_rcp_f32_e32 v135, v135
	v_rcp_f32_e32 v139, v137
	v_rcp_f32_e32 v137, v96
	v_pk_mul_f32 v[132:133], v[52:53], v[132:133]
	v_pk_mul_f32 v[134:135], v[54:55], v[134:135]
	v_pk_mul_f32 v[138:139], v[50:51], v[138:139]
	v_pk_mul_f32 v[136:137], v[48:49], v[136:137]
.LBB0_291:
	v_lshlrev_b64 v[150:151], 12, v[158:159]
	v_lshl_add_u64 v[150:151], s[6:7], 0, v[150:151]
	v_lshl_add_u64 v[160:161], v[98:99], 1, v[150:151]
	v_cvt_pk_bf16_f32 v132, v132, v133
	v_cvt_pk_bf16_f32 v133, v134, v135
	v_cvt_pk_bf16_f32 v134, v136, v137
	v_add_co_u32_e32 v136, vcc, 0x90000, v160
	v_cvt_pk_bf16_f32 v135, v138, v139
	s_nop 0
	v_addc_co_u32_e32 v137, vcc, 0, v161, vcc
	global_store_dwordx4 v[136:137], v[132:135], off
	v_mov_b64_e32 v[138:139], v[26:27]
	s_and_b64 vcc, exec, s[2:3]
	v_mov_b64_e32 v[134:135], v[30:31]
	v_mov_b64_e32 v[132:133], v[28:29]
	v_mov_b64_e32 v[136:137], v[24:25]
	s_cbranch_vccnz .LBB0_293
	v_mul_f32_e32 v96, 0xbfb8aa3b, v28
	v_exp_f32_e32 v96, v96
	v_mul_f32_e32 v132, 0xbfb8aa3b, v24
	v_mul_f32_e32 v133, 0xbfb8aa3b, v29
	v_exp_f32_e32 v134, v132
	v_exp_f32_e32 v133, v133
	v_add_f32_e32 v96, 1.0, v96
	v_rcp_f32_e32 v132, v96
	v_add_f32_e32 v96, 1.0, v134
	v_rcp_f32_e32 v136, v96
	v_add_f32_e32 v96, 1.0, v133
	v_mul_f32_e32 v135, 0xbfb8aa3b, v26
	v_rcp_f32_e32 v133, v96
	v_mul_f32_e32 v96, 0xbfb8aa3b, v25
	v_mul_f32_e32 v134, 0xbfb8aa3b, v30
	v_exp_f32_e32 v135, v135
	v_mul_f32_e32 v137, 0xbfb8aa3b, v31
	v_mul_f32_e32 v138, 0xbfb8aa3b, v27
	v_exp_f32_e32 v96, v96
	v_exp_f32_e32 v134, v134
	v_exp_f32_e32 v137, v137
	v_exp_f32_e32 v139, v138
	v_add_f32_e32 v135, 1.0, v135
	v_add_f32_e32 v96, 1.0, v96
	v_add_f32_e32 v134, 1.0, v134
	v_rcp_f32_e32 v138, v135
	v_add_f32_e32 v135, 1.0, v137
	v_add_f32_e32 v137, 1.0, v139
	v_rcp_f32_e32 v134, v134
	v_rcp_f32_e32 v135, v135
	v_rcp_f32_e32 v139, v137
	v_rcp_f32_e32 v137, v96
	v_pk_mul_f32 v[132:133], v[28:29], v[132:133]
	v_pk_mul_f32 v[134:135], v[30:31], v[134:135]
	v_pk_mul_f32 v[138:139], v[26:27], v[138:139]
	v_pk_mul_f32 v[136:137], v[24:25], v[136:137]
.LBB0_293:
	s_mov_b64 s[24:25], 0x90000
	v_lshl_add_u64 v[150:151], v[160:161], 0, s[24:25]
	v_cvt_pk_bf16_f32 v132, v132, v133
	v_cvt_pk_bf16_f32 v133, v134, v135
	v_cvt_pk_bf16_f32 v134, v136, v137
	v_cvt_pk_bf16_f32 v135, v138, v139
	global_store_dwordx4 v[150:151], v[132:135], off offset:256
	v_mov_b64_e32 v[138:139], v[34:35]
	s_and_b64 vcc, exec, s[2:3]
	v_mov_b64_e32 v[134:135], v[38:39]
	v_mov_b64_e32 v[132:133], v[36:37]
	v_mov_b64_e32 v[136:137], v[32:33]
	s_cbranch_vccnz .LBB0_295
	v_mul_f32_e32 v96, 0xbfb8aa3b, v36
	v_exp_f32_e32 v96, v96
	v_mul_f32_e32 v132, 0xbfb8aa3b, v32
	v_mul_f32_e32 v133, 0xbfb8aa3b, v37
	v_exp_f32_e32 v134, v132
	v_exp_f32_e32 v133, v133
	v_add_f32_e32 v96, 1.0, v96
	v_rcp_f32_e32 v132, v96
	v_add_f32_e32 v96, 1.0, v134
	v_rcp_f32_e32 v136, v96
	v_add_f32_e32 v96, 1.0, v133
	v_mul_f32_e32 v135, 0xbfb8aa3b, v34
	v_rcp_f32_e32 v133, v96
	v_mul_f32_e32 v96, 0xbfb8aa3b, v33
	v_mul_f32_e32 v134, 0xbfb8aa3b, v38
	v_exp_f32_e32 v135, v135
	v_mul_f32_e32 v137, 0xbfb8aa3b, v39
	v_mul_f32_e32 v138, 0xbfb8aa3b, v35
	v_exp_f32_e32 v96, v96
	v_exp_f32_e32 v134, v134
	v_exp_f32_e32 v137, v137
	v_exp_f32_e32 v139, v138
	v_add_f32_e32 v135, 1.0, v135
	v_add_f32_e32 v96, 1.0, v96
	v_add_f32_e32 v134, 1.0, v134
	v_rcp_f32_e32 v138, v135
	v_add_f32_e32 v135, 1.0, v137
	v_add_f32_e32 v137, 1.0, v139
	v_rcp_f32_e32 v134, v134
	v_rcp_f32_e32 v135, v135
	v_rcp_f32_e32 v139, v137
	v_rcp_f32_e32 v137, v96
	v_pk_mul_f32 v[132:133], v[36:37], v[132:133]
	v_pk_mul_f32 v[134:135], v[38:39], v[134:135]
	v_pk_mul_f32 v[138:139], v[34:35], v[138:139]
	v_pk_mul_f32 v[136:137], v[32:33], v[136:137]
; __device__ __forceinline__ unsigned cvtpk(float lo, float hi) { f32x2_t v = {lo, hi}; bf16x2_t b = __builtin_convertvector(v, bf16x2_t); return __builtin_bit_cast(unsigned, b); }
; __device__ __forceinline__ float silu_f(float v) { return v * __builtin_amdgcn_rcpf(1.f + __builtin_amdgcn_exp2f(-LOG2E * v)); }
;     __device__ __forceinline__ void operator()(const f32x4 (&acc)[2][2][4][2], const Unit& u, int wr, int wc, int fr, int fq) const {
;         const int row0 = u.pm * BM + wr * 64 + fr, colt = u.pn * BM, col0 = colt + wc * 32 + 8 * fq;
;         const bool act = colt >= silu_from;
; #pragma unroll
;         for (int ai = 0; ai < 2; ++ai)
; #pragma unroll
;             for (int m = 0; m < 4; ++m) { bf16_t* rowp = O + (size_t)(row0 + ai * HALF + m * 16) * ldc + col0;
; #pragma unroll
;                 for (int bj = 0; bj < 2; ++bj) { f32x4 v0 = acc[ai][bj][m][0] * scale, v1 = acc[ai][bj][m][1] * scale;
;                     if (act) {
; #pragma unroll
;                         for (int i = 0; i < 4; ++i) { v0[i] = silu_f(v0[i]); v1[i] = silu_f(v1[i]); } }
;                     u32x4 w; w.x = cvtpk(v0[0], v0[1]); w.y = cvtpk(v0[2], v0[3]); w.z = cvtpk(v1[0], v1[1]); w.w = cvtpk(v1[2], v1[3]);
;                     *(u32x4*)(rowp + bj * HALF) = w; } }
;     __device__ __forceinline__ void operator()(const f32x4 (&acc)[2][2][4][2], const Unit& u, int wr, int wc, int fr, int fq) const {
;         if (u.pm >= TH) { const Unit v{u.pm - TH, u.pn - pnA}; ea(acc, v, wr, wc, fr, fq); }
;         else { const Unit v{u.pm - pmB, u.pn - TH}; eb(acc, v, wr, wc, fr, fq); }
.LBB0_295:
	v_lshlrev_b64 v[150:151], 12, v[158:159]
	v_lshl_add_u64 v[150:151], s[6:7], 0, v[150:151]
	v_lshl_add_u64 v[160:161], v[98:99], 1, v[150:151]
	v_cvt_pk_bf16_f32 v132, v132, v133
	v_cvt_pk_bf16_f32 v133, v134, v135
	v_cvt_pk_bf16_f32 v134, v136, v137
	v_add_co_u32_e32 v136, vcc, 0xa0000, v160
	v_cvt_pk_bf16_f32 v135, v138, v139
	s_nop 0
	v_addc_co_u32_e32 v137, vcc, 0, v161, vcc
	global_store_dwordx4 v[136:137], v[132:135], off
	v_mov_b64_e32 v[138:139], v[10:11]
	s_and_b64 vcc, exec, s[2:3]
	v_mov_b64_e32 v[134:135], v[14:15]
	v_mov_b64_e32 v[132:133], v[12:13]
	v_mov_b64_e32 v[136:137], v[8:9]
	s_cbranch_vccnz .LBB0_297
	v_mul_f32_e32 v96, 0xbfb8aa3b, v12
	v_exp_f32_e32 v96, v96
	v_mul_f32_e32 v132, 0xbfb8aa3b, v8
	v_mul_f32_e32 v133, 0xbfb8aa3b, v13
	v_exp_f32_e32 v134, v132
	v_exp_f32_e32 v133, v133
	v_add_f32_e32 v96, 1.0, v96
	v_rcp_f32_e32 v132, v96
	v_add_f32_e32 v96, 1.0, v134
	v_rcp_f32_e32 v136, v96
	v_add_f32_e32 v96, 1.0, v133
	v_mul_f32_e32 v135, 0xbfb8aa3b, v10
	v_rcp_f32_e32 v133, v96
	v_mul_f32_e32 v96, 0xbfb8aa3b, v9
	v_mul_f32_e32 v134, 0xbfb8aa3b, v14
	v_exp_f32_e32 v135, v135
	v_mul_f32_e32 v137, 0xbfb8aa3b, v15
	v_mul_f32_e32 v138, 0xbfb8aa3b, v11
	v_exp_f32_e32 v96, v96
	v_exp_f32_e32 v134, v134
	v_exp_f32_e32 v137, v137
	v_exp_f32_e32 v139, v138
	v_add_f32_e32 v135, 1.0, v135
	v_add_f32_e32 v96, 1.0, v96
	v_add_f32_e32 v134, 1.0, v134
	v_rcp_f32_e32 v138, v135
	v_add_f32_e32 v135, 1.0, v137
	v_add_f32_e32 v137, 1.0, v139
	v_rcp_f32_e32 v134, v134
	v_rcp_f32_e32 v135, v135
	v_rcp_f32_e32 v139, v137
	v_rcp_f32_e32 v137, v96
	v_pk_mul_f32 v[132:133], v[12:13], v[132:133]
	v_pk_mul_f32 v[134:135], v[14:15], v[134:135]
	v_pk_mul_f32 v[138:139], v[10:11], v[138:139]
	v_pk_mul_f32 v[136:137], v[8:9], v[136:137]
.LBB0_297:
	s_mov_b64 s[24:25], 0xa0000
	v_lshl_add_u64 v[150:151], v[160:161], 0, s[24:25]
	v_cvt_pk_bf16_f32 v132, v132, v133
	v_cvt_pk_bf16_f32 v133, v134, v135
	v_cvt_pk_bf16_f32 v134, v136, v137
	v_cvt_pk_bf16_f32 v135, v138, v139
	global_store_dwordx4 v[150:151], v[132:135], off offset:256
	v_mov_b64_e32 v[138:139], v[18:19]
	s_and_b64 vcc, exec, s[2:3]
	v_mov_b64_e32 v[134:135], v[22:23]
	v_mov_b64_e32 v[132:133], v[20:21]
	v_mov_b64_e32 v[136:137], v[16:17]
	s_cbranch_vccnz .LBB0_299
	v_mul_f32_e32 v96, 0xbfb8aa3b, v20
	v_exp_f32_e32 v96, v96
	v_mul_f32_e32 v132, 0xbfb8aa3b, v16
	v_mul_f32_e32 v133, 0xbfb8aa3b, v21
	v_exp_f32_e32 v134, v132
	v_exp_f32_e32 v133, v133
	v_add_f32_e32 v96, 1.0, v96
	v_rcp_f32_e32 v132, v96
	v_add_f32_e32 v96, 1.0, v134
	v_rcp_f32_e32 v136, v96
	v_add_f32_e32 v96, 1.0, v133
	v_mul_f32_e32 v135, 0xbfb8aa3b, v18
	v_rcp_f32_e32 v133, v96
	v_mul_f32_e32 v96, 0xbfb8aa3b, v17
	v_mul_f32_e32 v134, 0xbfb8aa3b, v22
	v_exp_f32_e32 v135, v135
	v_mul_f32_e32 v137, 0xbfb8aa3b, v23
	v_mul_f32_e32 v138, 0xbfb8aa3b, v19
	v_exp_f32_e32 v96, v96
	v_exp_f32_e32 v134, v134
	v_exp_f32_e32 v137, v137
	v_exp_f32_e32 v139, v138
	v_add_f32_e32 v135, 1.0, v135
	v_add_f32_e32 v96, 1.0, v96
	v_add_f32_e32 v134, 1.0, v134
	v_rcp_f32_e32 v138, v135
	v_add_f32_e32 v135, 1.0, v137
	v_add_f32_e32 v137, 1.0, v139
	v_rcp_f32_e32 v134, v134
	v_rcp_f32_e32 v135, v135
	v_rcp_f32_e32 v139, v137
	v_rcp_f32_e32 v137, v96
	v_pk_mul_f32 v[132:133], v[20:21], v[132:133]
	v_pk_mul_f32 v[134:135], v[22:23], v[134:135]
	v_pk_mul_f32 v[138:139], v[18:19], v[138:139]
	v_pk_mul_f32 v[136:137], v[16:17], v[136:137]
.LBB0_299:
	v_lshlrev_b64 v[150:151], 12, v[158:159]
	v_lshl_add_u64 v[150:151], s[6:7], 0, v[150:151]
	v_lshl_add_u64 v[98:99], v[98:99], 1, v[150:151]
	v_cvt_pk_bf16_f32 v132, v132, v133
	v_cvt_pk_bf16_f32 v133, v134, v135
	v_cvt_pk_bf16_f32 v134, v136, v137
	v_add_co_u32_e32 v136, vcc, 0xb0000, v98
	v_cvt_pk_bf16_f32 v135, v138, v139
	s_nop 0
	v_addc_co_u32_e32 v137, vcc, 0, v99, vcc
	global_store_dwordx4 v[136:137], v[132:135], off
	v_mov_b64_e32 v[138:139], v[2:3]
	s_and_b64 vcc, exec, s[2:3]
	v_mov_b64_e32 v[134:135], v[6:7]
	v_mov_b64_e32 v[136:137], v[0:1]
	v_mov_b64_e32 v[132:133], v[4:5]
	s_cbranch_vccnz .LBB0_301
	v_mul_f32_e32 v96, 0xbfb8aa3b, v4
	v_exp_f32_e32 v96, v96
	v_mul_f32_e32 v132, 0xbfb8aa3b, v0
	v_mul_f32_e32 v133, 0xbfb8aa3b, v5
	v_exp_f32_e32 v134, v132
	v_exp_f32_e32 v133, v133
	v_add_f32_e32 v96, 1.0, v96
	v_rcp_f32_e32 v132, v96
	v_add_f32_e32 v96, 1.0, v134
	v_rcp_f32_e32 v136, v96
	v_add_f32_e32 v96, 1.0, v133
	v_mul_f32_e32 v135, 0xbfb8aa3b, v2
	v_rcp_f32_e32 v133, v96
	v_mul_f32_e32 v96, 0xbfb8aa3b, v1
	v_mul_f32_e32 v134, 0xbfb8aa3b, v6
	v_exp_f32_e32 v135, v135
	v_mul_f32_e32 v137, 0xbfb8aa3b, v7
	v_mul_f32_e32 v138, 0xbfb8aa3b, v3
	v_exp_f32_e32 v96, v96
	v_exp_f32_e32 v134, v134
	v_exp_f32_e32 v137, v137
	v_exp_f32_e32 v139, v138
	v_add_f32_e32 v135, 1.0, v135
	v_add_f32_e32 v96, 1.0, v96
	v_add_f32_e32 v134, 1.0, v134
	v_rcp_f32_e32 v138, v135
	v_add_f32_e32 v135, 1.0, v137
	v_add_f32_e32 v137, 1.0, v139
	v_rcp_f32_e32 v134, v134
	v_rcp_f32_e32 v135, v135
	v_rcp_f32_e32 v139, v137
	v_rcp_f32_e32 v137, v96
	v_pk_mul_f32 v[132:133], v[4:5], v[132:133]
	v_pk_mul_f32 v[134:135], v[6:7], v[134:135]
	v_pk_mul_f32 v[138:139], v[2:3], v[138:139]
	v_pk_mul_f32 v[136:137], v[0:1], v[136:137]

; __device__ __forceinline__ unsigned cvtpk(float lo, float hi) { f32x2_t v = {lo, hi}; bf16x2_t b = __builtin_convertvector(v, bf16x2_t); return __builtin_bit_cast(unsigned, b); }
; __device__ __forceinline__ float silu_f(float v) { return v * __builtin_amdgcn_rcpf(1.f + __builtin_amdgcn_exp2f(-LOG2E * v)); }
;     __device__ __forceinline__ void operator()(const f32x4 (&acc)[2][2][4][2], const Unit& u, int wr, int wc, int fr, int fq) const {
;         const int row0 = u.pm * BM + wr * 64 + fr, colt = u.pn * BM, col0 = colt + wc * 32 + 8 * fq;
;         const bool act = colt >= silu_from;
; #pragma unroll
;         for (int ai = 0; ai < 2; ++ai)
; #pragma unroll
;             for (int m = 0; m < 4; ++m) { bf16_t* rowp = O + (size_t)(row0 + ai * HALF + m * 16) * ldc + col0;
; #pragma unroll
;                 for (int bj = 0; bj < 2; ++bj) { f32x4 v0 = acc[ai][bj][m][0] * scale, v1 = acc[ai][bj][m][1] * scale;
;                     if (act) {
; #pragma unroll
;                         for (int i = 0; i < 4; ++i) { v0[i] = silu_f(v0[i]); v1[i] = silu_f(v1[i]); } }
;                     u32x4 w; w.x = cvtpk(v0[0], v0[1]); w.y = cvtpk(v0[2], v0[3]); w.z = cvtpk(v1[0], v1[1]); w.w = cvtpk(v1[2], v1[3]);
;                     *(u32x4*)(rowp + bj * HALF) = w; } }
;     __device__ __forceinline__ void operator()(const f32x4 (&acc)[2][2][4][2], const Unit& u, int wr, int wc, int fr, int fq) const {
;         if (u.pm >= TH) { const Unit v{u.pm - TH, u.pn - pnA}; ea(acc, v, wr, wc, fr, fq); }
;         else { const Unit v{u.pm - pmB, u.pn - TH}; eb(acc, v, wr, wc, fr, fq); }
.LBB0_302:
	s_and_b64 vcc, exec, s[2:3]
	s_cbranch_vccz .LBB0_304
	s_sub_i32 s2, s83, s5
	v_lshl_add_u32 v132, s84, 8, v146
	v_lshl_or_b32 v98, s2, 8, v148
	v_ashrrev_i32_e32 v133, 31, v132
	v_ashrrev_i32_e32 v99, 31, v98
	v_lshlrev_b64 v[134:135], 15, v[132:133]
	v_lshl_add_u64 v[134:135], s[8:9], 0, v[134:135]
	v_lshlrev_b64 v[136:137], 1, v[98:99]
	v_lshl_add_u64 v[134:135], v[134:135], 0, v[136:137]
	v_or_b32_e32 v98, 16, v132
	s_mov_b64 s[2:3], 0x400000
	v_ashrrev_i32_e32 v99, 31, v98
	v_cvt_pk_bf16_f32 v68, v68, v69
	v_cvt_pk_bf16_f32 v69, v70, v71
	v_cvt_pk_bf16_f32 v70, v64, v65
	v_lshl_add_u64 v[64:65], v[134:135], 0, s[2:3]
	s_mov_b32 s2, 0x400000
	v_lshlrev_b64 v[98:99], 15, v[98:99]
	v_cvt_pk_bf16_f32 v60, v60, v61
	v_cvt_pk_bf16_f32 v61, v62, v63
	v_cvt_pk_bf16_f32 v62, v56, v57
	v_add_co_u32_e32 v56, vcc, s2, v134
	v_cvt_pk_bf16_f32 v44, v44, v45
	v_cvt_pk_bf16_f32 v45, v46, v47
	v_cvt_pk_bf16_f32 v46, v40, v41
	v_cvt_pk_bf16_f32 v47, v42, v43
	s_mov_b64 s[2:3], 0x480000
	v_cvt_pk_bf16_f32 v116, v116, v117
	v_cvt_pk_bf16_f32 v117, v118, v119
	v_cvt_pk_bf16_f32 v118, v108, v109
	v_cvt_pk_bf16_f32 v119, v110, v111
	v_lshl_add_u64 v[98:99], s[8:9], 0, v[98:99]
	v_addc_co_u32_e32 v57, vcc, 0, v135, vcc
	global_store_dwordx4 v[64:65], v[44:47], off offset:256
	global_store_dwordx4 v[134:135], v[116:119], off offset:256
	v_cvt_pk_bf16_f32 v28, v28, v29
	v_lshl_add_u64 v[44:45], v[134:135], 0, s[2:3]
	s_mov_b32 s2, 0x480000
	v_lshl_add_u64 v[116:117], v[98:99], 0, v[136:137]
	v_cvt_pk_bf16_f32 v98, v100, v101
	v_cvt_pk_bf16_f32 v100, v88, v89
	v_or_b32_e32 v88, 32, v132
	v_add_co_u32_e32 v46, vcc, s2, v134
	v_cvt_pk_bf16_f32 v29, v30, v31
	v_cvt_pk_bf16_f32 v30, v24, v25
	v_cvt_pk_bf16_f32 v31, v26, v27
	s_mov_b64 s[2:3], 0x500000
	v_ashrrev_i32_e32 v89, 31, v88
	v_cvt_pk_bf16_f32 v80, v80, v81
	v_cvt_pk_bf16_f32 v81, v82, v83
	v_cvt_pk_bf16_f32 v82, v72, v73
	v_or_b32_e32 v72, 48, v132
	v_addc_co_u32_e32 v47, vcc, 0, v135, vcc
	global_store_dwordx4 v[44:45], v[28:31], off offset:256
	v_lshlrev_b64 v[88:89], 15, v[88:89]
	v_ashrrev_i32_e32 v73, 31, v72
	v_lshl_add_u64 v[28:29], v[134:135], 0, s[2:3]
	s_mov_b32 s2, 0x500000
	v_add_co_u32_e32 v30, vcc, s2, v134
	v_cvt_pk_bf16_f32 v99, v102, v103
	v_cvt_pk_bf16_f32 v101, v90, v91
	v_lshl_add_u64 v[88:89], s[8:9], 0, v[88:89]
	v_lshlrev_b64 v[72:73], 15, v[72:73]
	v_addc_co_u32_e32 v31, vcc, 0, v135, vcc
	v_cvt_pk_bf16_f32 v12, v12, v13
	v_cvt_pk_bf16_f32 v13, v14, v15
	v_cvt_pk_bf16_f32 v14, v8, v9
	v_cvt_pk_bf16_f32 v15, v10, v11
	v_cvt_pk_bf16_f32 v128, v128, v129
	v_cvt_pk_bf16_f32 v129, v130, v131
	v_cvt_pk_bf16_f32 v130, v124, v125
	v_cvt_pk_bf16_f32 v131, v126, v127
	global_store_dwordx4 v[116:117], v[98:101], off offset:256
	v_cvt_pk_bf16_f32 v90, v92, v93
	v_cvt_pk_bf16_f32 v91, v94, v95
	v_lshl_add_u64 v[98:99], v[88:89], 0, v[136:137]
	v_cvt_pk_bf16_f32 v88, v104, v105
	v_cvt_pk_bf16_f32 v89, v106, v107
	v_cvt_pk_bf16_f32 v83, v74, v75
	v_lshl_add_u64 v[72:73], s[8:9], 0, v[72:73]
	global_store_dwordx4 v[28:29], v[12:15], off offset:256
	s_mov_b64 s[2:3], 0x580000
	global_store_dwordx4 v[134:135], v[128:131], off
	v_add_co_u32_e32 v12, vcc, 0x580000, v134
	v_cvt_pk_bf16_f32 v108, v120, v121
	v_cvt_pk_bf16_f32 v109, v122, v123
	v_cvt_pk_bf16_f32 v110, v112, v113
	v_cvt_pk_bf16_f32 v111, v114, v115
	global_store_dwordx4 v[98:99], v[88:91], off
	global_store_dwordx4 v[98:99], v[80:83], off offset:256
	v_cvt_pk_bf16_f32 v74, v76, v77
	v_cvt_pk_bf16_f32 v75, v78, v79
	v_lshl_add_u64 v[80:81], v[72:73], 0, v[136:137]
	v_cvt_pk_bf16_f32 v72, v84, v85
	v_cvt_pk_bf16_f32 v73, v86, v87
	v_cvt_pk_bf16_f32 v71, v66, v67
	v_cvt_pk_bf16_f32 v63, v58, v59
	v_cvt_pk_bf16_f32 v40, v52, v53
	v_cvt_pk_bf16_f32 v41, v54, v55
	v_cvt_pk_bf16_f32 v42, v48, v49
	v_cvt_pk_bf16_f32 v43, v50, v51
	v_cvt_pk_bf16_f32 v24, v36, v37
	v_cvt_pk_bf16_f32 v25, v38, v39
	v_cvt_pk_bf16_f32 v26, v32, v33
	v_cvt_pk_bf16_f32 v27, v34, v35
	v_lshl_add_u64 v[98:99], v[134:135], 0, s[2:3]
	v_cvt_pk_bf16_f32 v8, v20, v21
	v_cvt_pk_bf16_f32 v9, v22, v23
	v_cvt_pk_bf16_f32 v10, v16, v17
	v_cvt_pk_bf16_f32 v11, v18, v19
	v_addc_co_u32_e32 v13, vcc, 0, v135, vcc
	v_mov_b64_e32 v[134:135], v[6:7]
	v_mov_b64_e32 v[138:139], v[2:3]
	global_store_dwordx4 v[116:117], v[108:111], off
	global_store_dwordx4 v[80:81], v[72:75], off
	global_store_dwordx4 v[80:81], v[68:71], off offset:256
	global_store_dwordx4 v[56:57], v[60:63], off
	global_store_dwordx4 v[46:47], v[40:43], off
	global_store_dwordx4 v[30:31], v[24:27], off
	global_store_dwordx4 v[12:13], v[8:11], off
	v_mov_b64_e32 v[132:133], v[4:5]
	v_mov_b64_e32 v[136:137], v[0:1]
.LBB0_304:
	v_cvt_pk_bf16_f32 v0, v132, v133
	v_cvt_pk_bf16_f32 v1, v134, v135
	v_cvt_pk_bf16_f32 v2, v136, v137
	v_cvt_pk_bf16_f32 v3, v138, v139
	s_and_b64 vcc, exec, s[0:1]
	s_mov_b64 s[0:1], -1
	global_store_dwordx4 v[98:99], v[0:3], off offset:256
	s_cbranch_vccnz .LBB0_239
	v_readlane_b32 s0, v255, 54
	v_readlane_b32 s1, v255, 55
	s_andn2_b64 vcc, exec, s[0:1]
	s_cbranch_vccnz .LBB0_238
	s_barrier
	s_branch .LBB0_238

; __device__ __forceinline__ unsigned cvtpk(float lo, float hi) { f32x2_t v = {lo, hi}; bf16x2_t b = __builtin_convertvector(v, bf16x2_t); return __builtin_bit_cast(unsigned, b); }
;     __device__ __forceinline__ void operator()(const f32x4 (&acc)[2][2][4][2], const Unit& u, int wr, int wc, int fr_, int fq) const {
;         int fr = fr_; asm volatile("" : "+v"(fr));
;         const int s2 = wc * 32 + 8 * fq;
; #pragma unroll
;         for (int m = 0; m < 4; ++m) { const int k1 = wr * 64 + m * 16 + fr; const float* tw = TW + ((size_t)k1 * 128 + s2) * 2;
;             if (k1 < NK1) {
;                 const f32x4 t0 = *(const f32x4*)(tw), t1 = *(const f32x4*)(tw + 4), t2 = *(const f32x4*)(tw + 8), t3 = *(const f32x4*)(tw + 12);
; #pragma unroll
;                 for (int bj = 0; bj < 2; ++bj) { const int c = u.pn * 2 + bj; const f32x4 ra = acc[0][bj][m][0], rb = acc[0][bj][m][1], ia = acc[1][bj][m][0], ib = acc[1][bj][m][1];
;                     u32x4 wr4, wi4;
;                     wr4.x = cvtpk(ra[0] * t0[0] - ia[0] * t0[1], ra[1] * t0[2] - ia[1] * t0[3]); wi4.x = cvtpk(ra[0] * t0[1] + ia[0] * t0[0], ra[1] * t0[3] + ia[1] * t0[2]);
;                     wr4.y = cvtpk(ra[2] * t1[0] - ia[2] * t1[1], ra[3] * t1[2] - ia[3] * t1[3]); wi4.y = cvtpk(ra[2] * t1[1] + ia[2] * t1[0], ra[3] * t1[3] + ia[3] * t1[2]);
;                     wr4.z = cvtpk(rb[0] * t2[0] - ib[0] * t2[1], rb[1] * t2[2] - ib[1] * t2[3]); wi4.z = cvtpk(rb[0] * t2[1] + ib[0] * t2[0], rb[1] * t2[3] + ib[1] * t2[2]);
;                     wr4.w = cvtpk(rb[2] * t3[0] - ib[2] * t3[1], rb[3] * t3[2] - ib[3] * t3[3]); wi4.w = cvtpk(rb[2] * t3[1] + ib[2] * t3[0], rb[3] * t3[3] + ib[3] * t3[2]);
;                     bf16_t* p = Y1 + (((size_t)k1 * 2048 + c) * 2) * 128 + s2;
;                     *(u32x4*)p = wr4; *(u32x4*)(p + 128) = wi4; } } }
.LBB0_388:
	v_mov_b32_e32 v96, v146
	s_lshl_b32 s24, s17, 1
	v_add_u32_e32 v168, s5, v96
	s_movk_i32 s17, 0x42
	v_cmp_gt_i32_e32 vcc, s17, v168
	s_and_saveexec_b64 s[48:49], vcc
	s_cbranch_execz .LBB0_390
	v_ashrrev_i32_e32 v169, 31, v168
	v_lshlrev_b64 v[130:131], 10, v[168:169]
	v_lshl_add_u64 v[130:131], v[162:163], 0, v[130:131]
	global_load_dwordx4 v[142:145], v[130:131], off
	global_load_dwordx4 v[138:141], v[130:131], off offset:16
	global_load_dwordx4 v[134:137], v[130:131], off offset:32
	s_nop 0
	global_load_dwordx4 v[130:133], v[130:131], off offset:48
	v_lshlrev_b64 v[150:151], 20, v[168:169]
	s_ashr_i32 s25, s24, 31
	s_lshl_b64 s[78:79], s[24:25], 9
	v_lshlrev_b32_e32 v96, 1, v160
	s_or_b32 s80, s24, 1
	s_ashr_i32 s81, s80, 31
	s_waitcnt vmcnt(0) lgkmcnt(0)
	v_mov_b32_e32 v170, v142
	v_mov_b32_e32 v171, v144
	v_mov_b32_e32 v144, v143
	v_pk_mul_f32 v[142:143], v[126:127], v[144:145]
	v_pk_mul_f32 v[126:127], v[126:127], v[170:171]
	v_pk_fma_f32 v[142:143], v[122:123], v[170:171], v[142:143] neg_lo:[0,0,1] neg_hi:[0,0,1]
	v_pk_fma_f32 v[122:123], v[122:123], v[144:145], v[126:127]
	v_cvt_pk_bf16_f32 v172, v142, v143
	v_cvt_pk_bf16_f32 v126, v122, v123
	v_mov_b32_e32 v122, v138
	v_mov_b32_e32 v123, v140
	v_mov_b32_e32 v140, v139
	v_pk_mul_f32 v[138:139], v[128:129], v[140:141]
	v_pk_mul_f32 v[128:129], v[128:129], v[122:123]
	v_pk_fma_f32 v[138:139], v[124:125], v[122:123], v[138:139] neg_lo:[0,0,1] neg_hi:[0,0,1]
	v_pk_fma_f32 v[124:125], v[124:125], v[140:141], v[128:129]
	v_cvt_pk_bf16_f32 v173, v138, v139
	v_cvt_pk_bf16_f32 v127, v124, v125
	v_mov_b32_e32 v124, v134
	v_mov_b32_e32 v125, v136
	v_mov_b32_e32 v136, v135
	v_pk_mul_f32 v[128:129], v[114:115], v[136:137]
	v_pk_mul_f32 v[114:115], v[114:115], v[124:125]
	v_pk_fma_f32 v[128:129], v[118:119], v[124:125], v[128:129] neg_lo:[0,0,1] neg_hi:[0,0,1]
	v_pk_fma_f32 v[114:115], v[118:119], v[136:137], v[114:115]
	v_mov_b32_e32 v119, v132
	v_mov_b32_e32 v132, v131
	v_cvt_pk_bf16_f32 v174, v128, v129
	v_cvt_pk_bf16_f32 v128, v114, v115
	v_mov_b32_e32 v118, v130
	v_pk_mul_f32 v[114:115], v[116:117], v[132:133]
	s_nop 0
	v_pk_fma_f32 v[114:115], v[120:121], v[118:119], v[114:115] neg_lo:[0,0,1] neg_hi:[0,0,1]
	s_nop 0
	v_cvt_pk_bf16_f32 v175, v114, v115
	v_pk_mul_f32 v[114:115], v[116:117], v[118:119]
	s_nop 0
	v_pk_fma_f32 v[114:115], v[120:121], v[132:133], v[114:115]
	v_lshl_add_u64 v[120:121], s[12:13], 0, v[150:151]
	v_cvt_pk_bf16_f32 v129, v114, v115
	v_lshl_add_u64 v[114:115], v[120:121], 0, s[78:79]
	v_lshl_add_u64 v[114:115], v[114:115], 0, v[96:97]
	global_store_dwordx4 v[114:115], v[172:175], off
	global_store_dwordx4 v[114:115], v[126:129], off offset:256
	v_pk_mul_f32 v[114:115], v[106:107], v[144:145]
	v_pk_mul_f32 v[106:107], v[106:107], v[170:171]
	v_pk_fma_f32 v[114:115], v[110:111], v[170:171], v[114:115] neg_lo:[0,0,1] neg_hi:[0,0,1]
	v_pk_fma_f32 v[106:107], v[110:111], v[144:145], v[106:107]
	v_pk_mul_f32 v[110:111], v[108:109], v[140:141]
	v_pk_mul_f32 v[108:109], v[108:109], v[122:123]
	v_cvt_pk_bf16_f32 v106, v106, v107
	v_pk_fma_f32 v[108:109], v[112:113], v[140:141], v[108:109]
	s_lshl_b64 s[78:79], s[80:81], 9
	v_cvt_pk_bf16_f32 v107, v108, v109
	v_pk_mul_f32 v[108:109], v[98:99], v[136:137]
	v_pk_mul_f32 v[98:99], v[98:99], v[124:125]
	v_pk_fma_f32 v[108:109], v[102:103], v[124:125], v[108:109] neg_lo:[0,0,1] neg_hi:[0,0,1]
	v_pk_fma_f32 v[98:99], v[102:103], v[136:137], v[98:99]
	v_cvt_pk_bf16_f32 v116, v108, v109
	v_cvt_pk_bf16_f32 v108, v98, v99
	v_pk_mul_f32 v[98:99], v[100:101], v[132:133]
	v_pk_fma_f32 v[110:111], v[112:113], v[122:123], v[110:111] neg_lo:[0,0,1] neg_hi:[0,0,1]
	v_pk_fma_f32 v[98:99], v[104:105], v[118:119], v[98:99] neg_lo:[0,0,1] neg_hi:[0,0,1]
	v_cvt_pk_bf16_f32 v114, v114, v115
	v_cvt_pk_bf16_f32 v117, v98, v99
	v_pk_mul_f32 v[98:99], v[100:101], v[118:119]
	v_cvt_pk_bf16_f32 v115, v110, v111
	v_pk_fma_f32 v[98:99], v[104:105], v[132:133], v[98:99]
	s_movk_i32 s80, 0x4000
	v_cvt_pk_bf16_f32 v109, v98, v99
	v_lshl_add_u64 v[98:99], v[120:121], 0, s[78:79]
	v_lshl_add_u64 v[98:99], v[98:99], 0, v[96:97]
	global_store_dwordx4 v[98:99], v[114:117], off
	global_store_dwordx4 v[98:99], v[106:109], off offset:256
.LBB0_390:
	s_or_b64 exec, exec, s[48:49]
	v_add_u32_e32 v114, 16, v168
	v_cmp_gt_i32_e32 vcc, s17, v114
	s_and_saveexec_b64 s[48:49], vcc
	s_cbranch_execz .LBB0_392
; __device__ __forceinline__ unsigned cvtpk(float lo, float hi) { f32x2_t v = {lo, hi}; bf16x2_t b = __builtin_convertvector(v, bf16x2_t); return __builtin_bit_cast(unsigned, b); }
;     __device__ __forceinline__ void operator()(const f32x4 (&acc)[2][2][4][2], const Unit& u, int wr, int wc, int fr_, int fq) const {
;         int fr = fr_; asm volatile("" : "+v"(fr));
;         const int s2 = wc * 32 + 8 * fq;
; #pragma unroll
;         for (int m = 0; m < 4; ++m) { const int k1 = wr * 64 + m * 16 + fr; const float* tw = TW + ((size_t)k1 * 128 + s2) * 2;
;             if (k1 < NK1) {
;                 const f32x4 t0 = *(const f32x4*)(tw), t1 = *(const f32x4*)(tw + 4), t2 = *(const f32x4*)(tw + 8), t3 = *(const f32x4*)(tw + 12);
; #pragma unroll
;                 for (int bj = 0; bj < 2; ++bj) { const int c = u.pn * 2 + bj; const f32x4 ra = acc[0][bj][m][0], rb = acc[0][bj][m][1], ia = acc[1][bj][m][0], ib = acc[1][bj][m][1];
;                     u32x4 wr4, wi4;
;                     wr4.x = cvtpk(ra[0] * t0[0] - ia[0] * t0[1], ra[1] * t0[2] - ia[1] * t0[3]); wi4.x = cvtpk(ra[0] * t0[1] + ia[0] * t0[0], ra[1] * t0[3] + ia[1] * t0[2]);
;                     wr4.y = cvtpk(ra[2] * t1[0] - ia[2] * t1[1], ra[3] * t1[2] - ia[3] * t1[3]); wi4.y = cvtpk(ra[2] * t1[1] + ia[2] * t1[0], ra[3] * t1[3] + ia[3] * t1[2]);
;                     wr4.z = cvtpk(rb[0] * t2[0] - ib[0] * t2[1], rb[1] * t2[2] - ib[1] * t2[3]); wi4.z = cvtpk(rb[0] * t2[1] + ib[0] * t2[0], rb[1] * t2[3] + ib[1] * t2[2]);
;                     wr4.w = cvtpk(rb[2] * t3[0] - ib[2] * t3[1], rb[3] * t3[2] - ib[3] * t3[3]); wi4.w = cvtpk(rb[2] * t3[1] + ib[2] * t3[0], rb[3] * t3[3] + ib[3] * t3[2]);
;                     bf16_t* p = Y1 + (((size_t)k1 * 2048 + c) * 2) * 128 + s2;
;                     *(u32x4*)p = wr4; *(u32x4*)(p + 128) = wi4; } } }
	v_ashrrev_i32_e32 v115, 31, v114
	v_lshlrev_b64 v[98:99], 10, v[114:115]
	v_lshl_add_u64 v[98:99], v[162:163], 0, v[98:99]
	global_load_dwordx4 v[110:113], v[98:99], off
	global_load_dwordx4 v[106:109], v[98:99], off offset:16
	global_load_dwordx4 v[102:105], v[98:99], off offset:32
	s_nop 0
	global_load_dwordx4 v[98:101], v[98:99], off offset:48
	v_lshlrev_b64 v[120:121], 20, v[114:115]
	s_ashr_i32 s25, s24, 31
	s_lshl_b64 s[78:79], s[24:25], 9
	v_lshlrev_b32_e32 v96, 1, v160
	s_or_b32 s80, s24, 1
	s_ashr_i32 s81, s80, 31
	s_waitcnt vmcnt(0) lgkmcnt(0)
	v_mov_b32_e32 v114, v110
	v_mov_b32_e32 v115, v112
	v_mov_b32_e32 v112, v111
	v_pk_mul_f32 v[110:111], v[88:89], v[112:113]
	v_pk_mul_f32 v[88:89], v[88:89], v[114:115]
	v_pk_fma_f32 v[110:111], v[92:93], v[114:115], v[110:111] neg_lo:[0,0,1] neg_hi:[0,0,1]
	v_pk_fma_f32 v[88:89], v[92:93], v[112:113], v[88:89]
	v_cvt_pk_bf16_f32 v116, v110, v111
	v_cvt_pk_bf16_f32 v92, v88, v89
	v_mov_b32_e32 v88, v106
	v_mov_b32_e32 v89, v108
	v_mov_b32_e32 v108, v107
	v_pk_mul_f32 v[106:107], v[90:91], v[108:109]
	v_pk_mul_f32 v[90:91], v[90:91], v[88:89]
	v_pk_fma_f32 v[106:107], v[94:95], v[88:89], v[106:107] neg_lo:[0,0,1] neg_hi:[0,0,1]
	v_pk_fma_f32 v[90:91], v[94:95], v[108:109], v[90:91]
	v_cvt_pk_bf16_f32 v117, v106, v107
	v_cvt_pk_bf16_f32 v93, v90, v91
	v_mov_b32_e32 v90, v102
	v_mov_b32_e32 v91, v104
	v_mov_b32_e32 v104, v103
	v_pk_mul_f32 v[94:95], v[80:81], v[104:105]
	v_pk_mul_f32 v[80:81], v[80:81], v[90:91]
	v_pk_fma_f32 v[94:95], v[84:85], v[90:91], v[94:95] neg_lo:[0,0,1] neg_hi:[0,0,1]
	v_pk_fma_f32 v[80:81], v[84:85], v[104:105], v[80:81]
	v_mov_b32_e32 v85, v100
	v_mov_b32_e32 v100, v99
	v_cvt_pk_bf16_f32 v118, v94, v95
	v_cvt_pk_bf16_f32 v94, v80, v81
	v_mov_b32_e32 v84, v98
	v_pk_mul_f32 v[80:81], v[82:83], v[100:101]
	s_nop 0
	v_pk_fma_f32 v[80:81], v[86:87], v[84:85], v[80:81] neg_lo:[0,0,1] neg_hi:[0,0,1]
	s_nop 0
	v_cvt_pk_bf16_f32 v119, v80, v81
	v_pk_mul_f32 v[80:81], v[82:83], v[84:85]
	s_nop 0
	v_pk_fma_f32 v[80:81], v[86:87], v[100:101], v[80:81]
	v_lshl_add_u64 v[86:87], s[12:13], 0, v[120:121]
	v_cvt_pk_bf16_f32 v95, v80, v81
	v_lshl_add_u64 v[80:81], v[86:87], 0, s[78:79]
	v_lshl_add_u64 v[80:81], v[80:81], 0, v[96:97]
	global_store_dwordx4 v[80:81], v[116:119], off
	global_store_dwordx4 v[80:81], v[92:95], off offset:256
	v_pk_mul_f32 v[80:81], v[72:73], v[112:113]
	v_pk_mul_f32 v[72:73], v[72:73], v[114:115]
	v_pk_fma_f32 v[80:81], v[76:77], v[114:115], v[80:81] neg_lo:[0,0,1] neg_hi:[0,0,1]
	v_pk_fma_f32 v[72:73], v[76:77], v[112:113], v[72:73]
	v_pk_mul_f32 v[76:77], v[74:75], v[108:109]
	v_pk_mul_f32 v[74:75], v[74:75], v[88:89]
	v_cvt_pk_bf16_f32 v72, v72, v73
	v_pk_fma_f32 v[74:75], v[78:79], v[108:109], v[74:75]
	s_lshl_b64 s[78:79], s[80:81], 9
	v_cvt_pk_bf16_f32 v73, v74, v75
	v_pk_mul_f32 v[74:75], v[64:65], v[104:105]
	v_pk_mul_f32 v[64:65], v[64:65], v[90:91]
	v_pk_fma_f32 v[74:75], v[68:69], v[90:91], v[74:75] neg_lo:[0,0,1] neg_hi:[0,0,1]
	v_pk_fma_f32 v[64:65], v[68:69], v[104:105], v[64:65]
	v_cvt_pk_bf16_f32 v82, v74, v75
	v_cvt_pk_bf16_f32 v74, v64, v65
	v_pk_mul_f32 v[64:65], v[66:67], v[100:101]
	v_pk_fma_f32 v[76:77], v[78:79], v[88:89], v[76:77] neg_lo:[0,0,1] neg_hi:[0,0,1]
	v_pk_fma_f32 v[64:65], v[70:71], v[84:85], v[64:65] neg_lo:[0,0,1] neg_hi:[0,0,1]
	v_cvt_pk_bf16_f32 v80, v80, v81
	v_cvt_pk_bf16_f32 v83, v64, v65
	v_pk_mul_f32 v[64:65], v[66:67], v[84:85]
	v_cvt_pk_bf16_f32 v81, v76, v77
	v_pk_fma_f32 v[64:65], v[70:71], v[100:101], v[64:65]
	s_movk_i32 s80, 0x4000
	v_cvt_pk_bf16_f32 v75, v64, v65
	v_lshl_add_u64 v[64:65], v[86:87], 0, s[78:79]
	v_lshl_add_u64 v[64:65], v[64:65], 0, v[96:97]
	global_store_dwordx4 v[64:65], v[80:83], off
	global_store_dwordx4 v[64:65], v[72:75], off offset:256
.LBB0_392:
	s_or_b64 exec, exec, s[48:49]
	v_add_u32_e32 v80, 32, v168
	v_cmp_gt_i32_e32 vcc, s17, v80
	s_and_saveexec_b64 s[48:49], vcc
	s_cbranch_execz .LBB0_394
	v_ashrrev_i32_e32 v81, 31, v80
	v_lshlrev_b64 v[64:65], 10, v[80:81]
	v_lshl_add_u64 v[64:65], v[162:163], 0, v[64:65]
	global_load_dwordx4 v[76:79], v[64:65], off
	global_load_dwordx4 v[72:75], v[64:65], off offset:16
	global_load_dwordx4 v[68:71], v[64:65], off offset:32
	s_nop 0
	global_load_dwordx4 v[64:67], v[64:65], off offset:48
	v_lshlrev_b64 v[86:87], 20, v[80:81]
	s_ashr_i32 s25, s24, 31
	s_lshl_b64 s[78:79], s[24:25], 9
	v_lshlrev_b32_e32 v96, 1, v160
	s_or_b32 s80, s24, 1
	s_ashr_i32 s81, s80, 31
	s_waitcnt vmcnt(0) lgkmcnt(0)
; __device__ __forceinline__ unsigned cvtpk(float lo, float hi) { f32x2_t v = {lo, hi}; bf16x2_t b = __builtin_convertvector(v, bf16x2_t); return __builtin_bit_cast(unsigned, b); }
;     __device__ __forceinline__ void operator()(const f32x4 (&acc)[2][2][4][2], const Unit& u, int wr, int wc, int fr_, int fq) const {
;         int fr = fr_; asm volatile("" : "+v"(fr));
;         const int s2 = wc * 32 + 8 * fq;
; #pragma unroll
;         for (int m = 0; m < 4; ++m) { const int k1 = wr * 64 + m * 16 + fr; const float* tw = TW + ((size_t)k1 * 128 + s2) * 2;
;             if (k1 < NK1) {
;                 const f32x4 t0 = *(const f32x4*)(tw), t1 = *(const f32x4*)(tw + 4), t2 = *(const f32x4*)(tw + 8), t3 = *(const f32x4*)(tw + 12);
; #pragma unroll
;                 for (int bj = 0; bj < 2; ++bj) { const int c = u.pn * 2 + bj; const f32x4 ra = acc[0][bj][m][0], rb = acc[0][bj][m][1], ia = acc[1][bj][m][0], ib = acc[1][bj][m][1];
;                     u32x4 wr4, wi4;
;                     wr4.x = cvtpk(ra[0] * t0[0] - ia[0] * t0[1], ra[1] * t0[2] - ia[1] * t0[3]); wi4.x = cvtpk(ra[0] * t0[1] + ia[0] * t0[0], ra[1] * t0[3] + ia[1] * t0[2]);
;                     wr4.y = cvtpk(ra[2] * t1[0] - ia[2] * t1[1], ra[3] * t1[2] - ia[3] * t1[3]); wi4.y = cvtpk(ra[2] * t1[1] + ia[2] * t1[0], ra[3] * t1[3] + ia[3] * t1[2]);
;                     wr4.z = cvtpk(rb[0] * t2[0] - ib[0] * t2[1], rb[1] * t2[2] - ib[1] * t2[3]); wi4.z = cvtpk(rb[0] * t2[1] + ib[0] * t2[0], rb[1] * t2[3] + ib[1] * t2[2]);
;                     wr4.w = cvtpk(rb[2] * t3[0] - ib[2] * t3[1], rb[3] * t3[2] - ib[3] * t3[3]); wi4.w = cvtpk(rb[2] * t3[1] + ib[2] * t3[0], rb[3] * t3[3] + ib[3] * t3[2]);
;                     bf16_t* p = Y1 + (((size_t)k1 * 2048 + c) * 2) * 128 + s2;
;                     *(u32x4*)p = wr4; *(u32x4*)(p + 128) = wi4; } } }
	v_mov_b32_e32 v80, v76
	v_mov_b32_e32 v81, v78
	v_mov_b32_e32 v78, v77
	v_pk_mul_f32 v[76:77], v[56:57], v[78:79]
	v_pk_mul_f32 v[56:57], v[56:57], v[80:81]
	v_pk_fma_f32 v[76:77], v[60:61], v[80:81], v[76:77] neg_lo:[0,0,1] neg_hi:[0,0,1]
	v_pk_fma_f32 v[56:57], v[60:61], v[78:79], v[56:57]
	v_cvt_pk_bf16_f32 v82, v76, v77
	v_cvt_pk_bf16_f32 v60, v56, v57
	v_mov_b32_e32 v56, v72
	v_mov_b32_e32 v57, v74
	v_mov_b32_e32 v74, v73
	v_pk_mul_f32 v[72:73], v[58:59], v[74:75]
	v_pk_mul_f32 v[58:59], v[58:59], v[56:57]
	v_pk_fma_f32 v[72:73], v[62:63], v[56:57], v[72:73] neg_lo:[0,0,1] neg_hi:[0,0,1]
	v_pk_fma_f32 v[58:59], v[62:63], v[74:75], v[58:59]
	v_cvt_pk_bf16_f32 v83, v72, v73
	v_cvt_pk_bf16_f32 v61, v58, v59
	v_mov_b32_e32 v58, v68
	v_mov_b32_e32 v59, v70
	v_mov_b32_e32 v70, v69
	v_pk_mul_f32 v[62:63], v[48:49], v[70:71]
	v_pk_mul_f32 v[48:49], v[48:49], v[58:59]
	v_pk_fma_f32 v[62:63], v[52:53], v[58:59], v[62:63] neg_lo:[0,0,1] neg_hi:[0,0,1]
	v_pk_fma_f32 v[48:49], v[52:53], v[70:71], v[48:49]
	v_mov_b32_e32 v53, v66
	v_mov_b32_e32 v66, v65
	v_cvt_pk_bf16_f32 v84, v62, v63
	v_cvt_pk_bf16_f32 v62, v48, v49
	v_mov_b32_e32 v52, v64
	v_pk_mul_f32 v[48:49], v[50:51], v[66:67]
	s_nop 0
	v_pk_fma_f32 v[48:49], v[54:55], v[52:53], v[48:49] neg_lo:[0,0,1] neg_hi:[0,0,1]
	s_nop 0
	v_cvt_pk_bf16_f32 v85, v48, v49
	v_pk_mul_f32 v[48:49], v[50:51], v[52:53]
	s_nop 0
	v_pk_fma_f32 v[48:49], v[54:55], v[66:67], v[48:49]
	v_lshl_add_u64 v[54:55], s[12:13], 0, v[86:87]
	v_cvt_pk_bf16_f32 v63, v48, v49
	v_lshl_add_u64 v[48:49], v[54:55], 0, s[78:79]
	v_lshl_add_u64 v[48:49], v[48:49], 0, v[96:97]
	global_store_dwordx4 v[48:49], v[82:85], off
	global_store_dwordx4 v[48:49], v[60:63], off offset:256
	v_pk_mul_f32 v[48:49], v[40:41], v[78:79]
	v_pk_mul_f32 v[40:41], v[40:41], v[80:81]
	v_pk_fma_f32 v[48:49], v[44:45], v[80:81], v[48:49] neg_lo:[0,0,1] neg_hi:[0,0,1]
	v_pk_fma_f32 v[40:41], v[44:45], v[78:79], v[40:41]
	v_pk_mul_f32 v[44:45], v[42:43], v[74:75]
	v_pk_mul_f32 v[42:43], v[42:43], v[56:57]
	v_cvt_pk_bf16_f32 v40, v40, v41
	v_pk_fma_f32 v[42:43], v[46:47], v[74:75], v[42:43]
	s_lshl_b64 s[78:79], s[80:81], 9
	v_cvt_pk_bf16_f32 v41, v42, v43
	v_pk_mul_f32 v[42:43], v[32:33], v[70:71]
	v_pk_mul_f32 v[32:33], v[32:33], v[58:59]
	v_pk_fma_f32 v[42:43], v[36:37], v[58:59], v[42:43] neg_lo:[0,0,1] neg_hi:[0,0,1]
	v_pk_fma_f32 v[32:33], v[36:37], v[70:71], v[32:33]
	v_cvt_pk_bf16_f32 v50, v42, v43
	v_cvt_pk_bf16_f32 v42, v32, v33
	v_pk_mul_f32 v[32:33], v[34:35], v[66:67]
	v_pk_fma_f32 v[44:45], v[46:47], v[56:57], v[44:45] neg_lo:[0,0,1] neg_hi:[0,0,1]
	v_pk_fma_f32 v[32:33], v[38:39], v[52:53], v[32:33] neg_lo:[0,0,1] neg_hi:[0,0,1]
	v_cvt_pk_bf16_f32 v48, v48, v49
	v_cvt_pk_bf16_f32 v51, v32, v33
	v_pk_mul_f32 v[32:33], v[34:35], v[52:53]
	v_cvt_pk_bf16_f32 v49, v44, v45
	v_pk_fma_f32 v[32:33], v[38:39], v[66:67], v[32:33]
	s_movk_i32 s80, 0x4000
	v_cvt_pk_bf16_f32 v43, v32, v33
	v_lshl_add_u64 v[32:33], v[54:55], 0, s[78:79]
	v_lshl_add_u64 v[32:33], v[32:33], 0, v[96:97]
	global_store_dwordx4 v[32:33], v[48:51], off
	global_store_dwordx4 v[32:33], v[40:43], off offset:256
.LBB0_394:
	s_or_b64 exec, exec, s[48:49]
	v_add_u32_e32 v48, 48, v168
	v_cmp_gt_i32_e32 vcc, s17, v48
	s_and_saveexec_b64 s[48:49], vcc
	s_cbranch_execz .LBB0_396
	v_ashrrev_i32_e32 v49, 31, v48
	v_lshlrev_b64 v[32:33], 10, v[48:49]
	v_lshl_add_u64 v[32:33], v[162:163], 0, v[32:33]
	global_load_dwordx4 v[44:47], v[32:33], off
	global_load_dwordx4 v[40:43], v[32:33], off offset:16
	global_load_dwordx4 v[36:39], v[32:33], off offset:32
	s_nop 0
	global_load_dwordx4 v[32:35], v[32:33], off offset:48
	v_lshlrev_b64 v[54:55], 20, v[48:49]
	s_ashr_i32 s25, s24, 31
	s_lshl_b64 s[78:79], s[24:25], 9
	v_lshlrev_b32_e32 v96, 1, v160
	s_or_b32 s24, s24, 1
	s_ashr_i32 s25, s24, 31
	s_lshl_b64 s[24:25], s[24:25], 9
	s_waitcnt vmcnt(0) lgkmcnt(0)
	v_mov_b32_e32 v48, v44
	v_mov_b32_e32 v49, v46
	v_mov_b32_e32 v46, v45
	v_pk_mul_f32 v[44:45], v[24:25], v[46:47]
	v_pk_mul_f32 v[24:25], v[24:25], v[48:49]
	v_pk_fma_f32 v[44:45], v[28:29], v[48:49], v[44:45] neg_lo:[0,0,1] neg_hi:[0,0,1]
	v_pk_fma_f32 v[24:25], v[28:29], v[46:47], v[24:25]
	v_cvt_pk_bf16_f32 v50, v44, v45
	v_cvt_pk_bf16_f32 v28, v24, v25
	v_mov_b32_e32 v24, v40
	v_mov_b32_e32 v25, v42
	v_mov_b32_e32 v42, v41
	v_pk_mul_f32 v[40:41], v[26:27], v[42:43]
	v_pk_mul_f32 v[26:27], v[26:27], v[24:25]
	v_pk_fma_f32 v[40:41], v[30:31], v[24:25], v[40:41] neg_lo:[0,0,1] neg_hi:[0,0,1]
	v_pk_fma_f32 v[26:27], v[30:31], v[42:43], v[26:27]
	v_cvt_pk_bf16_f32 v51, v40, v41
	v_cvt_pk_bf16_f32 v29, v26, v27
	v_mov_b32_e32 v26, v36
	v_mov_b32_e32 v27, v38
	v_mov_b32_e32 v38, v37
	v_pk_mul_f32 v[30:31], v[16:17], v[38:39]
	v_pk_mul_f32 v[16:17], v[16:17], v[26:27]
	v_pk_fma_f32 v[30:31], v[20:21], v[26:27], v[30:31] neg_lo:[0,0,1] neg_hi:[0,0,1]
	v_pk_fma_f32 v[16:17], v[20:21], v[38:39], v[16:17]
	v_mov_b32_e32 v21, v34
	v_mov_b32_e32 v34, v33
	v_cvt_pk_bf16_f32 v52, v30, v31
	v_cvt_pk_bf16_f32 v30, v16, v17
	v_mov_b32_e32 v20, v32
	v_pk_mul_f32 v[16:17], v[18:19], v[34:35]
	s_nop 0
	v_pk_fma_f32 v[16:17], v[22:23], v[20:21], v[16:17] neg_lo:[0,0,1] neg_hi:[0,0,1]
	s_nop 0
	v_cvt_pk_bf16_f32 v53, v16, v17
	v_pk_mul_f32 v[16:17], v[18:19], v[20:21]
	s_nop 0
	v_pk_fma_f32 v[16:17], v[22:23], v[34:35], v[16:17]
	v_lshl_add_u64 v[22:23], s[12:13], 0, v[54:55]
	v_cvt_pk_bf16_f32 v31, v16, v17
	v_lshl_add_u64 v[16:17], v[22:23], 0, s[78:79]
	v_lshl_add_u64 v[16:17], v[16:17], 0, v[96:97]
	global_store_dwordx4 v[16:17], v[50:53], off
	global_store_dwordx4 v[16:17], v[28:31], off offset:256
	v_pk_mul_f32 v[16:17], v[8:9], v[46:47]
	v_pk_mul_f32 v[8:9], v[8:9], v[48:49]
	v_pk_fma_f32 v[16:17], v[12:13], v[48:49], v[16:17] neg_lo:[0,0,1] neg_hi:[0,0,1]
	v_pk_fma_f32 v[8:9], v[12:13], v[46:47], v[8:9]
	v_pk_mul_f32 v[12:13], v[10:11], v[42:43]
	v_pk_mul_f32 v[10:11], v[10:11], v[24:25]
	v_cvt_pk_bf16_f32 v8, v8, v9
	v_pk_fma_f32 v[10:11], v[14:15], v[42:43], v[10:11]
	v_pk_fma_f32 v[12:13], v[14:15], v[24:25], v[12:13] neg_lo:[0,0,1] neg_hi:[0,0,1]
	v_cvt_pk_bf16_f32 v9, v10, v11
	v_pk_mul_f32 v[10:11], v[0:1], v[38:39]
	v_pk_mul_f32 v[0:1], v[0:1], v[26:27]
	v_pk_fma_f32 v[10:11], v[4:5], v[26:27], v[10:11] neg_lo:[0,0,1] neg_hi:[0,0,1]
	v_pk_fma_f32 v[0:1], v[4:5], v[38:39], v[0:1]
	v_cvt_pk_bf16_f32 v18, v10, v11
	v_cvt_pk_bf16_f32 v10, v0, v1
	v_pk_mul_f32 v[0:1], v[2:3], v[34:35]
	v_cvt_pk_bf16_f32 v16, v16, v17
	v_pk_fma_f32 v[0:1], v[6:7], v[20:21], v[0:1] neg_lo:[0,0,1] neg_hi:[0,0,1]
	v_cvt_pk_bf16_f32 v17, v12, v13
	v_cvt_pk_bf16_f32 v19, v0, v1
	v_pk_mul_f32 v[0:1], v[2:3], v[20:21]
	s_nop 0
	v_pk_fma_f32 v[0:1], v[6:7], v[34:35], v[0:1]
	s_nop 0
	v_cvt_pk_bf16_f32 v11, v0, v1
	v_lshl_add_u64 v[0:1], v[22:23], 0, s[24:25]
	v_lshl_add_u64 v[0:1], v[0:1], 0, v[96:97]
	global_store_dwordx4 v[0:1], v[16:19], off
	global_store_dwordx4 v[0:1], v[8:11], off offset:256

; __device__ __forceinline__ unsigned cvtpk(float lo, float hi) { f32x2_t v = {lo, hi}; bf16x2_t b = __builtin_convertvector(v, bf16x2_t); return __builtin_bit_cast(unsigned, b); }
;     __device__ __forceinline__ void operator()(const f32x4 (&acc)[2][2][4][2], const Unit& u, int wr, int wc, int fr, int fq) const {
;         const int n0 = u.pn * BM + wc * 32 + 8 * fq;
; #pragma unroll
;         for (int bj = 0; bj < 2; ++bj) { const int n = n0 + bj * HALF, k1 = n >> 11, c = n & 2047, g = c >> 9, cc = c & 511;
; #pragma unroll
;             for (int ai = 0; ai < 2; ++ai)
; #pragma unroll
;                 for (int m = 0; m < 4; ++m) { const int k2 = wr * 64 + m * 16 + fr;
;                     const f32x4 v0 = acc[ai][bj][m][0], v1 = acc[ai][bj][m][1];
;                     u32x4 w; w.x = cvtpk(v0[0], v0[1]); w.y = cvtpk(v0[2], v0[3]); w.z = cvtpk(v1[0], v1[1]); w.w = cvtpk(v1[2], v1[3]);
;                     *(u32x4*)(X + ((size_t)g * XROWS + k1 * 128 + k2) * 1024 + ai * 512 + cc) = w; } }
.LBB0_470:
	s_lshl_b32 s24, s90, 8
	s_and_b32 s24, s24, 0x100
	v_or_b32_e32 v96, s24, v147
	s_lshl_b32 s24, s90, 4
	s_bfe_u32 s25, s90, 0x20001
	s_and_b32 s24, s24, 0xffffff80
	s_mulk_i32 s25, 0x2100
	s_ashr_i32 s26, s24, 31
	s_add_u32 s24, s25, s24
	s_addc_u32 s25, 0, s26
	v_cvt_pk_bf16_f32 v122, v122, v123
	v_cvt_pk_bf16_f32 v123, v124, v125
	v_cvt_pk_bf16_f32 v124, v126, v127
	v_lshl_add_u64 v[126:127], s[24:25], 0, v[138:139]
	v_cvt_pk_bf16_f32 v118, v118, v119
	v_cvt_pk_bf16_f32 v119, v120, v121
	v_cvt_pk_bf16_f32 v120, v114, v115
	v_lshl_add_u64 v[114:115], s[24:25], 0, v[140:141]
	v_cvt_pk_bf16_f32 v110, v110, v111
	v_cvt_pk_bf16_f32 v111, v112, v113
	v_cvt_pk_bf16_f32 v112, v106, v107
	v_lshl_add_u64 v[106:107], s[24:25], 0, v[142:143]
	v_cvt_pk_bf16_f32 v102, v102, v103
	v_cvt_pk_bf16_f32 v103, v104, v105
	v_cvt_pk_bf16_f32 v104, v98, v99
	v_lshl_add_u64 v[98:99], s[24:25], 0, v[144:145]
	v_lshlrev_b64 v[126:127], 11, v[126:127]
	v_lshlrev_b64 v[114:115], 11, v[114:115]
	v_lshlrev_b64 v[106:107], 11, v[106:107]
	v_lshlrev_b64 v[98:99], 11, v[98:99]
	v_lshl_add_u64 v[126:127], s[10:11], 0, v[126:127]
	v_lshlrev_b32_e32 v96, 1, v96
	v_lshl_add_u64 v[114:115], s[10:11], 0, v[114:115]
	v_lshl_add_u64 v[106:107], s[10:11], 0, v[106:107]
	v_lshl_add_u64 v[98:99], s[10:11], 0, v[98:99]
	v_cvt_pk_bf16_f32 v125, v128, v129
	v_lshl_add_u64 v[126:127], v[126:127], 0, v[96:97]
	v_cvt_pk_bf16_f32 v121, v116, v117
	v_lshl_add_u64 v[114:115], v[114:115], 0, v[96:97]
	v_cvt_pk_bf16_f32 v113, v108, v109
	v_lshl_add_u64 v[106:107], v[106:107], 0, v[96:97]
	v_cvt_pk_bf16_f32 v105, v100, v101
	v_lshl_add_u64 v[98:99], v[98:99], 0, v[96:97]
	v_cvt_pk_bf16_f32 v92, v92, v93
	v_cvt_pk_bf16_f32 v93, v94, v95
	v_cvt_pk_bf16_f32 v94, v88, v89
	v_cvt_pk_bf16_f32 v95, v90, v91
	v_cvt_pk_bf16_f32 v84, v84, v85
	v_cvt_pk_bf16_f32 v85, v86, v87
	v_cvt_pk_bf16_f32 v86, v80, v81
	v_cvt_pk_bf16_f32 v87, v82, v83
	v_cvt_pk_bf16_f32 v76, v76, v77
	v_cvt_pk_bf16_f32 v77, v78, v79
	v_cvt_pk_bf16_f32 v78, v72, v73
	v_cvt_pk_bf16_f32 v79, v74, v75
	v_cvt_pk_bf16_f32 v68, v68, v69
	v_cvt_pk_bf16_f32 v69, v70, v71
	v_cvt_pk_bf16_f32 v70, v64, v65
	v_cvt_pk_bf16_f32 v71, v66, v67
	v_cvt_pk_bf16_f32 v60, v60, v61
	v_cvt_pk_bf16_f32 v61, v62, v63
	v_cvt_pk_bf16_f32 v62, v56, v57
	v_cvt_pk_bf16_f32 v63, v58, v59
	v_cvt_pk_bf16_f32 v52, v52, v53
	v_cvt_pk_bf16_f32 v53, v54, v55
	v_cvt_pk_bf16_f32 v54, v48, v49
	v_cvt_pk_bf16_f32 v55, v50, v51
	v_cvt_pk_bf16_f32 v44, v44, v45
	v_cvt_pk_bf16_f32 v45, v46, v47
	v_cvt_pk_bf16_f32 v46, v40, v41
	v_cvt_pk_bf16_f32 v47, v42, v43
	v_cvt_pk_bf16_f32 v36, v36, v37
	v_cvt_pk_bf16_f32 v37, v38, v39
	v_cvt_pk_bf16_f32 v38, v32, v33
	v_cvt_pk_bf16_f32 v39, v34, v35
	v_cvt_pk_bf16_f32 v28, v28, v29
	v_cvt_pk_bf16_f32 v29, v30, v31
	v_cvt_pk_bf16_f32 v30, v24, v25
	v_cvt_pk_bf16_f32 v31, v26, v27
	v_cvt_pk_bf16_f32 v20, v20, v21
	v_cvt_pk_bf16_f32 v21, v22, v23
	v_cvt_pk_bf16_f32 v22, v16, v17
	v_cvt_pk_bf16_f32 v23, v18, v19
	v_cvt_pk_bf16_f32 v12, v12, v13
	v_cvt_pk_bf16_f32 v13, v14, v15
	v_cvt_pk_bf16_f32 v14, v8, v9
	v_cvt_pk_bf16_f32 v15, v10, v11
	v_cvt_pk_bf16_f32 v4, v4, v5
	v_cvt_pk_bf16_f32 v5, v6, v7
	v_cvt_pk_bf16_f32 v6, v0, v1
	v_cvt_pk_bf16_f32 v7, v2, v3
	s_and_b64 vcc, exec, s[0:1]
	s_mov_b64 s[0:1], -1
	global_store_dwordx4 v[126:127], v[122:125], off
	global_store_dwordx4 v[114:115], v[118:121], off
	global_store_dwordx4 v[106:107], v[110:113], off
	global_store_dwordx4 v[98:99], v[102:105], off
	global_store_dwordx4 v[126:127], v[92:95], off offset:1024
	global_store_dwordx4 v[114:115], v[84:87], off offset:1024
	global_store_dwordx4 v[106:107], v[76:79], off offset:1024
	global_store_dwordx4 v[98:99], v[68:71], off offset:1024
	global_store_dwordx4 v[126:127], v[60:63], off offset:256
	global_store_dwordx4 v[114:115], v[52:55], off offset:256
	global_store_dwordx4 v[106:107], v[44:47], off offset:256
	global_store_dwordx4 v[98:99], v[36:39], off offset:256
	global_store_dwordx4 v[126:127], v[28:31], off offset:1280
	global_store_dwordx4 v[114:115], v[20:23], off offset:1280
	global_store_dwordx4 v[106:107], v[12:15], off offset:1280
	global_store_dwordx4 v[98:99], v[4:7], off offset:1280
	s_cbranch_vccnz .LBB0_457
	s_andn2_b64 vcc, exec, s[16:17]
	s_cbranch_vccnz .LBB0_456
	s_barrier
	s_branch .LBB0_456

; __device__ __forceinline__ float bflo(unsigned w) { return __uint_as_float(w << 16); }
; __device__ __forceinline__ float bfhi(unsigned w) { return __uint_as_float(w & 0xffff0000u); }
; __device__ __forceinline__ unsigned cvtpk(float lo, float hi) { f32x2_t v = {lo, hi}; bf16x2_t b = __builtin_convertvector(v, bf16x2_t); return __builtin_bit_cast(unsigned, b); }
;     __device__ __forceinline__ void operator()(const f32x4 (&acc)[2][2][4][2], const Unit& u, int wr, int wc, int fr, int fq) const {
;         const int g = u.pn >> 2, nt = u.pn & 3, mir = nt >> 1;
;         const int rg0 = (u.pm - g * 33) * BM + wr * 64 + fr, col0 = g * 512 + (nt & 1) * 256 + wc * 32 + 8 * fq;
; #pragma unroll
;         for (int ai = 0; ai < 2; ++ai)
; #pragma unroll
;             for (int m = 0; m < 4; ++m) { const int rg = rg0 + ai * HALF + m * 16, k1 = rg >> 7, k2 = rg & 127, kd = k2 * 128 + k1;
;                 const bool ok = mir ? (k1 >= 1 && k1 <= 63) : (k1 <= 64);
;                 const int k = mir ? ((S - kd) & (S - 1)) : kd, kp = (k & 127) * 128 + (k >> 7);
;                 if (ok) {
; #pragma unroll
;                 for (int bj = 0; bj < 2; ++bj) { const int col = col0 + bj * HALF;
;                     const u32x4 sg = *(const u32x4*)(GP + (size_t)kp * D + col);
;                     f32x4 v0 = acc[ai][bj][m][0], v1 = acc[ai][bj][m][1];
;                     v0[0] *= bflo(sg.x); v0[1] *= bfhi(sg.x); v0[2] *= bflo(sg.y); v0[3] *= bfhi(sg.y);
;                     v1[0] *= bflo(sg.z); v1[1] *= bfhi(sg.z); v1[2] *= bflo(sg.w); v1[3] *= bfhi(sg.w);
;                     u32x4 w; w.x = cvtpk(v0[0], v0[1]); w.y = cvtpk(v0[2], v0[3]); w.z = cvtpk(v1[0], v1[1]); w.w = cvtpk(v1[2], v1[3]);
;                     *(u32x4*)(Y + (size_t)k * D + col) = w; } } }
.LBB0_544:
	s_ashr_i32 s2, s5, 2
	s_mul_i32 s3, s2, 0xffffffdf
	s_add_i32 s3, s3, s4
	s_lshl_b32 s4, s3, 8
	s_add_i32 s4, s4, s86
	s_lshl_b32 s3, s5, 8
	s_lshl_b32 s2, s2, 9
	s_and_b32 s3, s3, 0x100
	s_and_b32 s13, s5, 2
	s_ashr_i32 s5, s4, 7
	s_or_b32 s12, s2, s3
	s_add_i32 s2, s5, -1
	s_cmp_lt_u32 s2, 63
	s_cselect_b64 s[2:3], -1, 0
	s_cmpk_lt_i32 s5, 0x41
	s_cselect_b64 s[48:49], -1, 0
	s_cmp_eq_u32 s13, 0
	v_cndmask_b32_e64 v140, 0, 1, s[48:49]
	v_cndmask_b32_e64 v141, 0, 1, s[2:3]
	s_cselect_b64 s[2:3], -1, 0
	v_cndmask_b32_e64 v140, v141, v140, s[2:3]
	v_and_b32_e32 v140, 1, v140
	v_cmp_eq_u32_e32 vcc, 0, v140
	v_or_b32_e32 v140, s12, v145
	s_cbranch_vccnz .LBB0_546
	v_add_u32_e32 v141, s5, v146
	v_sub_u32_e32 v142, 0, v141
	v_and_b32_e32 v142, 0x3fff, v142
	v_cndmask_b32_e64 v142, v142, v141, s[2:3]
	v_lshlrev_b32_e32 v141, 7, v142
	v_and_b32_e32 v141, 0x3f80, v141
	v_ashrrev_i32_e32 v143, 7, v142
	v_add_u32_e32 v152, v141, v143
	v_ashrrev_i32_e32 v153, 31, v152
	v_lshlrev_b64 v[152:153], 12, v[152:153]
	v_ashrrev_i32_e32 v143, 31, v142
	v_ashrrev_i32_e32 v141, 31, v140
	v_lshlrev_b64 v[156:157], 12, v[142:143]
	v_lshl_add_u64 v[152:153], s[6:7], 0, v[152:153]
	v_lshlrev_b64 v[142:143], 1, v[140:141]
	v_lshl_add_u64 v[158:159], v[152:153], 0, v[142:143]
	global_load_dwordx4 v[152:155], v[158:159], off
	s_waitcnt vmcnt(0) lgkmcnt(0)
	v_lshlrev_b32_e32 v160, 16, v152
	v_and_b32_e32 v161, 0xffff0000, v152
	v_lshlrev_b32_e32 v152, 16, v153
	v_and_b32_e32 v153, 0xffff0000, v153
	v_pk_mul_f32 v[128:129], v[128:129], v[152:153]
	v_lshlrev_b32_e32 v152, 16, v154
	v_and_b32_e32 v153, 0xffff0000, v154
	v_pk_mul_f32 v[126:127], v[126:127], v[160:161]
	v_pk_mul_f32 v[152:153], v[122:123], v[152:153]
	v_lshlrev_b32_e32 v122, 16, v155
	v_and_b32_e32 v123, 0xffff0000, v155
	v_pk_mul_f32 v[154:155], v[124:125], v[122:123]
	v_cvt_pk_bf16_f32 v122, v126, v127
	v_lshl_add_u64 v[126:127], s[8:9], 0, v[156:157]
	v_cvt_pk_bf16_f32 v123, v128, v129
	v_cvt_pk_bf16_f32 v124, v152, v153
	v_cvt_pk_bf16_f32 v125, v154, v155
	v_lshl_add_u64 v[126:127], v[126:127], 0, v[142:143]
	global_store_dwordx4 v[126:127], v[122:125], off
	global_load_dwordx4 v[122:125], v[158:159], off offset:256
	s_waitcnt vmcnt(0) lgkmcnt(0)
	v_lshlrev_b32_e32 v128, 16, v122
	v_and_b32_e32 v129, 0xffff0000, v122
	v_lshlrev_b32_e32 v122, 16, v123
	v_and_b32_e32 v123, 0xffff0000, v123
	v_pk_mul_f32 v[120:121], v[120:121], v[122:123]
	v_lshlrev_b32_e32 v122, 16, v124
	v_and_b32_e32 v123, 0xffff0000, v124
	v_pk_mul_f32 v[122:123], v[114:115], v[122:123]
	v_lshlrev_b32_e32 v114, 16, v125
	v_and_b32_e32 v115, 0xffff0000, v125
	v_pk_mul_f32 v[118:119], v[118:119], v[128:129]
	v_pk_mul_f32 v[124:125], v[116:117], v[114:115]
	v_cvt_pk_bf16_f32 v114, v118, v119
	v_cvt_pk_bf16_f32 v115, v120, v121
	v_cvt_pk_bf16_f32 v116, v122, v123
	v_cvt_pk_bf16_f32 v117, v124, v125
	global_store_dwordx4 v[126:127], v[114:117], off offset:256
	s_nop 1
	v_add_u32_e32 v114, s5, v147
	v_sub_u32_e32 v115, 0, v114
	v_and_b32_e32 v115, 0x3fff, v115
	v_cndmask_b32_e64 v114, v115, v114, s[2:3]
	v_lshlrev_b32_e32 v115, 7, v114
	v_and_b32_e32 v115, 0x3f80, v115
	v_ashrrev_i32_e32 v116, 7, v114
	v_add_u32_e32 v116, v115, v116
	v_ashrrev_i32_e32 v117, 31, v116
	v_lshlrev_b64 v[116:117], 12, v[116:117]
	v_ashrrev_i32_e32 v115, 31, v114
	v_lshlrev_b64 v[118:119], 12, v[114:115]
	v_lshl_add_u64 v[114:115], s[6:7], 0, v[116:117]
	v_lshl_add_u64 v[120:121], v[114:115], 0, v[142:143]
	global_load_dwordx4 v[114:117], v[120:121], off
	s_waitcnt vmcnt(0) lgkmcnt(0)
	v_lshlrev_b32_e32 v122, 16, v114
	v_and_b32_e32 v123, 0xffff0000, v114
	v_lshlrev_b32_e32 v114, 16, v115
	v_and_b32_e32 v115, 0xffff0000, v115
	v_pk_mul_f32 v[112:113], v[112:113], v[114:115]
	v_lshlrev_b32_e32 v114, 16, v116
	v_and_b32_e32 v115, 0xffff0000, v116
	v_pk_mul_f32 v[110:111], v[110:111], v[122:123]
	v_pk_mul_f32 v[114:115], v[106:107], v[114:115]
	v_lshlrev_b32_e32 v106, 16, v117
	v_and_b32_e32 v107, 0xffff0000, v117
	v_pk_mul_f32 v[116:117], v[108:109], v[106:107]
	v_cvt_pk_bf16_f32 v106, v110, v111
	v_lshl_add_u64 v[110:111], s[8:9], 0, v[118:119]
	v_cvt_pk_bf16_f32 v107, v112, v113
	v_cvt_pk_bf16_f32 v108, v114, v115
	v_cvt_pk_bf16_f32 v109, v116, v117
	v_lshl_add_u64 v[110:111], v[110:111], 0, v[142:143]
	global_store_dwordx4 v[110:111], v[106:109], off
	global_load_dwordx4 v[106:109], v[120:121], off offset:256
	s_waitcnt vmcnt(0) lgkmcnt(0)
	v_lshlrev_b32_e32 v112, 16, v106
	v_and_b32_e32 v113, 0xffff0000, v106
	v_lshlrev_b32_e32 v106, 16, v107
	v_and_b32_e32 v107, 0xffff0000, v107
	v_pk_mul_f32 v[104:105], v[104:105], v[106:107]
	v_lshlrev_b32_e32 v106, 16, v108
	v_and_b32_e32 v107, 0xffff0000, v108
	v_pk_mul_f32 v[106:107], v[98:99], v[106:107]
	v_lshlrev_b32_e32 v98, 16, v109
	v_and_b32_e32 v99, 0xffff0000, v109
	v_pk_mul_f32 v[102:103], v[102:103], v[112:113]
	v_pk_mul_f32 v[108:109], v[100:101], v[98:99]
	v_cvt_pk_bf16_f32 v98, v102, v103
	v_cvt_pk_bf16_f32 v99, v104, v105
	v_cvt_pk_bf16_f32 v100, v106, v107
	v_cvt_pk_bf16_f32 v101, v108, v109
	global_store_dwordx4 v[110:111], v[98:101], off offset:256
	s_nop 1
	v_add_u32_e32 v98, s5, v148
	v_sub_u32_e32 v99, 0, v98
	v_and_b32_e32 v99, 0x3fff, v99
	v_cndmask_b32_e64 v98, v99, v98, s[2:3]
	v_lshlrev_b32_e32 v99, 7, v98
	v_and_b32_e32 v99, 0x3f80, v99
	v_ashrrev_i32_e32 v100, 7, v98
	v_add_u32_e32 v100, v99, v100
	v_ashrrev_i32_e32 v101, 31, v100
	v_lshlrev_b64 v[100:101], 12, v[100:101]
	v_ashrrev_i32_e32 v99, 31, v98
	v_lshlrev_b64 v[102:103], 12, v[98:99]
	v_lshl_add_u64 v[98:99], s[6:7], 0, v[100:101]
	v_lshl_add_u64 v[104:105], v[98:99], 0, v[142:143]
	global_load_dwordx4 v[98:101], v[104:105], off
	s_waitcnt vmcnt(0) lgkmcnt(0)
; __device__ __forceinline__ float bflo(unsigned w) { return __uint_as_float(w << 16); }
; __device__ __forceinline__ float bfhi(unsigned w) { return __uint_as_float(w & 0xffff0000u); }
; __device__ __forceinline__ unsigned cvtpk(float lo, float hi) { f32x2_t v = {lo, hi}; bf16x2_t b = __builtin_convertvector(v, bf16x2_t); return __builtin_bit_cast(unsigned, b); }
;     __device__ __forceinline__ void operator()(const f32x4 (&acc)[2][2][4][2], const Unit& u, int wr, int wc, int fr, int fq) const {
;         const int g = u.pn >> 2, nt = u.pn & 3, mir = nt >> 1;
;         const int rg0 = (u.pm - g * 33) * BM + wr * 64 + fr, col0 = g * 512 + (nt & 1) * 256 + wc * 32 + 8 * fq;
; #pragma unroll
;         for (int ai = 0; ai < 2; ++ai)
; #pragma unroll
;             for (int m = 0; m < 4; ++m) { const int rg = rg0 + ai * HALF + m * 16, k1 = rg >> 7, k2 = rg & 127, kd = k2 * 128 + k1;
;                 const bool ok = mir ? (k1 >= 1 && k1 <= 63) : (k1 <= 64);
;                 const int k = mir ? ((S - kd) & (S - 1)) : kd, kp = (k & 127) * 128 + (k >> 7);
;                 if (ok) {
; #pragma unroll
;                 for (int bj = 0; bj < 2; ++bj) { const int col = col0 + bj * HALF;
;                     const u32x4 sg = *(const u32x4*)(GP + (size_t)kp * D + col);
;                     f32x4 v0 = acc[ai][bj][m][0], v1 = acc[ai][bj][m][1];
;                     v0[0] *= bflo(sg.x); v0[1] *= bfhi(sg.x); v0[2] *= bflo(sg.y); v0[3] *= bfhi(sg.y);
;                     v1[0] *= bflo(sg.z); v1[1] *= bfhi(sg.z); v1[2] *= bflo(sg.w); v1[3] *= bfhi(sg.w);
;                     u32x4 w; w.x = cvtpk(v0[0], v0[1]); w.y = cvtpk(v0[2], v0[3]); w.z = cvtpk(v1[0], v1[1]); w.w = cvtpk(v1[2], v1[3]);
;                     *(u32x4*)(Y + (size_t)k * D + col) = w; } } }
	v_lshlrev_b32_e32 v106, 16, v98
	v_and_b32_e32 v107, 0xffff0000, v98
	v_lshlrev_b32_e32 v98, 16, v99
	v_and_b32_e32 v99, 0xffff0000, v99
	v_pk_mul_f32 v[94:95], v[94:95], v[98:99]
	v_lshlrev_b32_e32 v98, 16, v100
	v_and_b32_e32 v99, 0xffff0000, v100
	v_pk_mul_f32 v[92:93], v[92:93], v[106:107]
	v_pk_mul_f32 v[98:99], v[88:89], v[98:99]
	v_lshlrev_b32_e32 v88, 16, v101
	v_and_b32_e32 v89, 0xffff0000, v101
	v_pk_mul_f32 v[100:101], v[90:91], v[88:89]
	v_cvt_pk_bf16_f32 v88, v92, v93
	v_lshl_add_u64 v[92:93], s[8:9], 0, v[102:103]
	v_cvt_pk_bf16_f32 v89, v94, v95
	v_cvt_pk_bf16_f32 v90, v98, v99
	v_cvt_pk_bf16_f32 v91, v100, v101
	v_lshl_add_u64 v[92:93], v[92:93], 0, v[142:143]
	global_store_dwordx4 v[92:93], v[88:91], off
	global_load_dwordx4 v[88:91], v[104:105], off offset:256
	s_waitcnt vmcnt(0) lgkmcnt(0)
	v_lshlrev_b32_e32 v94, 16, v88
	v_and_b32_e32 v95, 0xffff0000, v88
	v_lshlrev_b32_e32 v88, 16, v89
	v_and_b32_e32 v89, 0xffff0000, v89
	v_pk_mul_f32 v[86:87], v[86:87], v[88:89]
	v_lshlrev_b32_e32 v88, 16, v90
	v_and_b32_e32 v89, 0xffff0000, v90
	v_pk_mul_f32 v[88:89], v[80:81], v[88:89]
	v_lshlrev_b32_e32 v80, 16, v91
	v_and_b32_e32 v81, 0xffff0000, v91
	v_pk_mul_f32 v[84:85], v[84:85], v[94:95]
	v_pk_mul_f32 v[90:91], v[82:83], v[80:81]
	v_cvt_pk_bf16_f32 v80, v84, v85
	v_cvt_pk_bf16_f32 v81, v86, v87
	v_cvt_pk_bf16_f32 v82, v88, v89
	v_cvt_pk_bf16_f32 v83, v90, v91
	global_store_dwordx4 v[92:93], v[80:83], off offset:256
	s_nop 1
	v_add_u32_e32 v80, s5, v149
	v_sub_u32_e32 v81, 0, v80
	v_and_b32_e32 v81, 0x3fff, v81
	v_cndmask_b32_e64 v80, v81, v80, s[2:3]
	v_lshlrev_b32_e32 v81, 7, v80
	v_and_b32_e32 v81, 0x3f80, v81
	v_ashrrev_i32_e32 v82, 7, v80
	v_add_u32_e32 v82, v81, v82
	v_ashrrev_i32_e32 v83, 31, v82
	v_lshlrev_b64 v[82:83], 12, v[82:83]
	v_ashrrev_i32_e32 v81, 31, v80
	v_lshlrev_b64 v[84:85], 12, v[80:81]
	v_lshl_add_u64 v[80:81], s[6:7], 0, v[82:83]
	v_lshl_add_u64 v[86:87], v[80:81], 0, v[142:143]
	global_load_dwordx4 v[80:83], v[86:87], off
	s_waitcnt vmcnt(0) lgkmcnt(0)
	v_lshlrev_b32_e32 v88, 16, v80
	v_and_b32_e32 v89, 0xffff0000, v80
	v_lshlrev_b32_e32 v80, 16, v81
	v_and_b32_e32 v81, 0xffff0000, v81
	v_pk_mul_f32 v[78:79], v[78:79], v[80:81]
	v_lshlrev_b32_e32 v80, 16, v82
	v_and_b32_e32 v81, 0xffff0000, v82
	v_pk_mul_f32 v[76:77], v[76:77], v[88:89]
	v_pk_mul_f32 v[72:73], v[72:73], v[80:81]
	v_lshlrev_b32_e32 v80, 16, v83
	v_and_b32_e32 v81, 0xffff0000, v83
	v_pk_mul_f32 v[80:81], v[74:75], v[80:81]
	v_cvt_pk_bf16_f32 v74, v76, v77
	v_cvt_pk_bf16_f32 v76, v72, v73
	v_lshl_add_u64 v[72:73], s[8:9], 0, v[84:85]
	v_cvt_pk_bf16_f32 v75, v78, v79
	v_cvt_pk_bf16_f32 v77, v80, v81
	v_lshl_add_u64 v[72:73], v[72:73], 0, v[142:143]
	global_store_dwordx4 v[72:73], v[74:77], off
	global_load_dwordx4 v[74:77], v[86:87], off offset:256
	s_waitcnt vmcnt(0) lgkmcnt(0)
	v_lshlrev_b32_e32 v78, 16, v74
	v_and_b32_e32 v79, 0xffff0000, v74
	v_lshlrev_b32_e32 v74, 16, v75
	v_and_b32_e32 v75, 0xffff0000, v75
	v_pk_mul_f32 v[70:71], v[70:71], v[74:75]
	v_lshlrev_b32_e32 v74, 16, v76
	v_and_b32_e32 v75, 0xffff0000, v76
	v_pk_mul_f32 v[74:75], v[64:65], v[74:75]
	v_lshlrev_b32_e32 v64, 16, v77
	v_and_b32_e32 v65, 0xffff0000, v77
	v_pk_mul_f32 v[68:69], v[68:69], v[78:79]
	v_pk_mul_f32 v[76:77], v[66:67], v[64:65]
	v_cvt_pk_bf16_f32 v64, v68, v69
	v_cvt_pk_bf16_f32 v65, v70, v71
	v_cvt_pk_bf16_f32 v66, v74, v75
	v_cvt_pk_bf16_f32 v67, v76, v77
	global_store_dwordx4 v[72:73], v[64:67], off offset:256
.LBB0_546:
	s_addk_i32 s4, 0x80
	s_ashr_i32 s4, s4, 7
	s_add_i32 s5, s4, -1
	s_cmp_lt_u32 s5, 63
	s_cselect_b64 s[48:49], -1, 0
	s_cmpk_lt_i32 s4, 0x41
	v_cndmask_b32_e64 v64, 0, 1, s[48:49]
	s_cselect_b64 s[48:49], -1, 0
	v_cndmask_b32_e64 v65, 0, 1, s[48:49]
	v_cndmask_b32_e64 v64, v64, v65, s[2:3]
	v_and_b32_e32 v64, 1, v64
	v_cmp_eq_u32_e32 vcc, 0, v64
	s_cbranch_vccnz .LBB0_548
	v_add_u32_e32 v64, s4, v146
	v_sub_u32_e32 v65, 0, v64
	v_and_b32_e32 v65, 0x3fff, v65
	v_cndmask_b32_e64 v64, v65, v64, s[2:3]
	v_lshlrev_b32_e32 v65, 7, v64
	v_and_b32_e32 v65, 0x3f80, v65
	v_ashrrev_i32_e32 v66, 7, v64
	v_add_u32_e32 v66, v65, v66
	v_ashrrev_i32_e32 v67, 31, v66
	v_lshlrev_b64 v[66:67], 12, v[66:67]
	v_ashrrev_i32_e32 v65, 31, v64
	v_ashrrev_i32_e32 v141, 31, v140
	v_lshlrev_b64 v[70:71], 12, v[64:65]
	v_lshl_add_u64 v[66:67], s[6:7], 0, v[66:67]
	v_lshlrev_b64 v[64:65], 1, v[140:141]
	v_lshl_add_u64 v[72:73], v[66:67], 0, v[64:65]
	global_load_dwordx4 v[66:69], v[72:73], off
	s_waitcnt vmcnt(0) lgkmcnt(0)
	v_lshlrev_b32_e32 v74, 16, v66
	v_and_b32_e32 v75, 0xffff0000, v66
	v_lshlrev_b32_e32 v66, 16, v67
	v_and_b32_e32 v67, 0xffff0000, v67
	v_pk_mul_f32 v[62:63], v[62:63], v[66:67]
	v_lshlrev_b32_e32 v66, 16, v68
	v_and_b32_e32 v67, 0xffff0000, v68
	v_pk_mul_f32 v[60:61], v[60:61], v[74:75]
	v_pk_mul_f32 v[66:67], v[56:57], v[66:67]
	v_lshlrev_b32_e32 v56, 16, v69
	v_and_b32_e32 v57, 0xffff0000, v69
	v_pk_mul_f32 v[68:69], v[58:59], v[56:57]
	v_cvt_pk_bf16_f32 v56, v60, v61
	v_lshl_add_u64 v[60:61], s[8:9], 0, v[70:71]
	v_cvt_pk_bf16_f32 v57, v62, v63
	v_cvt_pk_bf16_f32 v58, v66, v67
	v_cvt_pk_bf16_f32 v59, v68, v69
	v_lshl_add_u64 v[60:61], v[60:61], 0, v[64:65]
	global_store_dwordx4 v[60:61], v[56:59], off
	global_load_dwordx4 v[56:59], v[72:73], off offset:256
	s_waitcnt vmcnt(0) lgkmcnt(0)
; __device__ __forceinline__ float bflo(unsigned w) { return __uint_as_float(w << 16); }
; __device__ __forceinline__ float bfhi(unsigned w) { return __uint_as_float(w & 0xffff0000u); }
; __device__ __forceinline__ unsigned cvtpk(float lo, float hi) { f32x2_t v = {lo, hi}; bf16x2_t b = __builtin_convertvector(v, bf16x2_t); return __builtin_bit_cast(unsigned, b); }
;     __device__ __forceinline__ void operator()(const f32x4 (&acc)[2][2][4][2], const Unit& u, int wr, int wc, int fr, int fq) const {
;         const int g = u.pn >> 2, nt = u.pn & 3, mir = nt >> 1;
;         const int rg0 = (u.pm - g * 33) * BM + wr * 64 + fr, col0 = g * 512 + (nt & 1) * 256 + wc * 32 + 8 * fq;
; #pragma unroll
;         for (int ai = 0; ai < 2; ++ai)
; #pragma unroll
;             for (int m = 0; m < 4; ++m) { const int rg = rg0 + ai * HALF + m * 16, k1 = rg >> 7, k2 = rg & 127, kd = k2 * 128 + k1;
;                 const bool ok = mir ? (k1 >= 1 && k1 <= 63) : (k1 <= 64);
;                 const int k = mir ? ((S - kd) & (S - 1)) : kd, kp = (k & 127) * 128 + (k >> 7);
;                 if (ok) {
; #pragma unroll
;                 for (int bj = 0; bj < 2; ++bj) { const int col = col0 + bj * HALF;
;                     const u32x4 sg = *(const u32x4*)(GP + (size_t)kp * D + col);
;                     f32x4 v0 = acc[ai][bj][m][0], v1 = acc[ai][bj][m][1];
;                     v0[0] *= bflo(sg.x); v0[1] *= bfhi(sg.x); v0[2] *= bflo(sg.y); v0[3] *= bfhi(sg.y);
;                     v1[0] *= bflo(sg.z); v1[1] *= bfhi(sg.z); v1[2] *= bflo(sg.w); v1[3] *= bfhi(sg.w);
;                     u32x4 w; w.x = cvtpk(v0[0], v0[1]); w.y = cvtpk(v0[2], v0[3]); w.z = cvtpk(v1[0], v1[1]); w.w = cvtpk(v1[2], v1[3]);
;                     *(u32x4*)(Y + (size_t)k * D + col) = w; } } }
	v_lshlrev_b32_e32 v62, 16, v56
	v_and_b32_e32 v63, 0xffff0000, v56
	v_lshlrev_b32_e32 v56, 16, v57
	v_and_b32_e32 v57, 0xffff0000, v57
	v_pk_mul_f32 v[54:55], v[54:55], v[56:57]
	v_lshlrev_b32_e32 v56, 16, v58
	v_and_b32_e32 v57, 0xffff0000, v58
	v_pk_mul_f32 v[56:57], v[48:49], v[56:57]
	v_lshlrev_b32_e32 v48, 16, v59
	v_and_b32_e32 v49, 0xffff0000, v59
	v_pk_mul_f32 v[52:53], v[52:53], v[62:63]
	v_pk_mul_f32 v[58:59], v[50:51], v[48:49]
	v_cvt_pk_bf16_f32 v48, v52, v53
	v_cvt_pk_bf16_f32 v49, v54, v55
	v_cvt_pk_bf16_f32 v50, v56, v57
	v_cvt_pk_bf16_f32 v51, v58, v59
	global_store_dwordx4 v[60:61], v[48:51], off offset:256
	s_nop 1
	v_add_u32_e32 v48, s4, v147
	v_sub_u32_e32 v49, 0, v48
	v_and_b32_e32 v49, 0x3fff, v49
	v_cndmask_b32_e64 v48, v49, v48, s[2:3]
	v_lshlrev_b32_e32 v49, 7, v48
	v_and_b32_e32 v49, 0x3f80, v49
	v_ashrrev_i32_e32 v50, 7, v48
	v_add_u32_e32 v50, v49, v50
	v_ashrrev_i32_e32 v51, 31, v50
	v_lshlrev_b64 v[50:51], 12, v[50:51]
	v_ashrrev_i32_e32 v49, 31, v48
	v_lshlrev_b64 v[52:53], 12, v[48:49]
	v_lshl_add_u64 v[48:49], s[6:7], 0, v[50:51]
	v_lshl_add_u64 v[54:55], v[48:49], 0, v[64:65]
	global_load_dwordx4 v[48:51], v[54:55], off
	s_waitcnt vmcnt(0) lgkmcnt(0)
	v_lshlrev_b32_e32 v56, 16, v48
	v_and_b32_e32 v57, 0xffff0000, v48
	v_lshlrev_b32_e32 v48, 16, v49
	v_and_b32_e32 v49, 0xffff0000, v49
	v_pk_mul_f32 v[46:47], v[46:47], v[48:49]
	v_lshlrev_b32_e32 v48, 16, v50
	v_and_b32_e32 v49, 0xffff0000, v50
	v_pk_mul_f32 v[44:45], v[44:45], v[56:57]
	v_pk_mul_f32 v[48:49], v[40:41], v[48:49]
	v_lshlrev_b32_e32 v40, 16, v51
	v_and_b32_e32 v41, 0xffff0000, v51
	v_pk_mul_f32 v[50:51], v[42:43], v[40:41]
	v_cvt_pk_bf16_f32 v40, v44, v45
	v_lshl_add_u64 v[44:45], s[8:9], 0, v[52:53]
	v_cvt_pk_bf16_f32 v41, v46, v47
	v_cvt_pk_bf16_f32 v42, v48, v49
	v_cvt_pk_bf16_f32 v43, v50, v51
	v_lshl_add_u64 v[44:45], v[44:45], 0, v[64:65]
	global_store_dwordx4 v[44:45], v[40:43], off
	global_load_dwordx4 v[40:43], v[54:55], off offset:256
	s_waitcnt vmcnt(0) lgkmcnt(0)
	v_lshlrev_b32_e32 v46, 16, v40
	v_and_b32_e32 v47, 0xffff0000, v40
	v_lshlrev_b32_e32 v40, 16, v41
	v_and_b32_e32 v41, 0xffff0000, v41
	v_pk_mul_f32 v[38:39], v[38:39], v[40:41]
	v_lshlrev_b32_e32 v40, 16, v42
	v_and_b32_e32 v41, 0xffff0000, v42
	v_pk_mul_f32 v[40:41], v[32:33], v[40:41]
	v_lshlrev_b32_e32 v32, 16, v43
	v_and_b32_e32 v33, 0xffff0000, v43
	v_pk_mul_f32 v[36:37], v[36:37], v[46:47]
	v_pk_mul_f32 v[42:43], v[34:35], v[32:33]
	v_cvt_pk_bf16_f32 v32, v36, v37
	v_cvt_pk_bf16_f32 v33, v38, v39
	v_cvt_pk_bf16_f32 v34, v40, v41
	v_cvt_pk_bf16_f32 v35, v42, v43
	global_store_dwordx4 v[44:45], v[32:35], off offset:256
	s_nop 1
	v_add_u32_e32 v32, s4, v148
	v_sub_u32_e32 v33, 0, v32
	v_and_b32_e32 v33, 0x3fff, v33
	v_cndmask_b32_e64 v32, v33, v32, s[2:3]
	v_lshlrev_b32_e32 v33, 7, v32
	v_and_b32_e32 v33, 0x3f80, v33
	v_ashrrev_i32_e32 v34, 7, v32
	v_add_u32_e32 v34, v33, v34
	v_ashrrev_i32_e32 v35, 31, v34
	v_lshlrev_b64 v[34:35], 12, v[34:35]
	v_ashrrev_i32_e32 v33, 31, v32
	v_lshlrev_b64 v[36:37], 12, v[32:33]
	v_lshl_add_u64 v[32:33], s[6:7], 0, v[34:35]
	v_lshl_add_u64 v[38:39], v[32:33], 0, v[64:65]
	global_load_dwordx4 v[32:35], v[38:39], off
	s_waitcnt vmcnt(0) lgkmcnt(0)
	v_lshlrev_b32_e32 v40, 16, v32
	v_and_b32_e32 v41, 0xffff0000, v32
	v_lshlrev_b32_e32 v32, 16, v33
	v_and_b32_e32 v33, 0xffff0000, v33
	v_pk_mul_f32 v[30:31], v[30:31], v[32:33]
	v_lshlrev_b32_e32 v32, 16, v34
	v_and_b32_e32 v33, 0xffff0000, v34
	v_pk_mul_f32 v[28:29], v[28:29], v[40:41]
	v_pk_mul_f32 v[32:33], v[24:25], v[32:33]
	v_lshlrev_b32_e32 v24, 16, v35
	v_and_b32_e32 v25, 0xffff0000, v35
	v_pk_mul_f32 v[34:35], v[26:27], v[24:25]
	v_cvt_pk_bf16_f32 v24, v28, v29
	v_lshl_add_u64 v[28:29], s[8:9], 0, v[36:37]
	v_cvt_pk_bf16_f32 v25, v30, v31
	v_cvt_pk_bf16_f32 v26, v32, v33
	v_cvt_pk_bf16_f32 v27, v34, v35
	v_lshl_add_u64 v[28:29], v[28:29], 0, v[64:65]
	global_store_dwordx4 v[28:29], v[24:27], off
	global_load_dwordx4 v[24:27], v[38:39], off offset:256
	s_waitcnt vmcnt(0) lgkmcnt(0)
	v_lshlrev_b32_e32 v30, 16, v24
	v_and_b32_e32 v31, 0xffff0000, v24
	v_lshlrev_b32_e32 v24, 16, v25
	v_and_b32_e32 v25, 0xffff0000, v25
	v_pk_mul_f32 v[22:23], v[22:23], v[24:25]
	v_lshlrev_b32_e32 v24, 16, v26
	v_and_b32_e32 v25, 0xffff0000, v26
	v_pk_mul_f32 v[24:25], v[16:17], v[24:25]
	v_lshlrev_b32_e32 v16, 16, v27
	v_and_b32_e32 v17, 0xffff0000, v27
	v_pk_mul_f32 v[20:21], v[20:21], v[30:31]
	v_pk_mul_f32 v[26:27], v[18:19], v[16:17]
	v_cvt_pk_bf16_f32 v16, v20, v21
	v_cvt_pk_bf16_f32 v17, v22, v23
	v_cvt_pk_bf16_f32 v18, v24, v25
	v_cvt_pk_bf16_f32 v19, v26, v27
	global_store_dwordx4 v[28:29], v[16:19], off offset:256
	s_nop 1
	v_add_u32_e32 v16, s4, v149
	v_sub_u32_e32 v17, 0, v16
	v_and_b32_e32 v17, 0x3fff, v17
	v_cndmask_b32_e64 v16, v17, v16, s[2:3]
	v_lshlrev_b32_e32 v17, 7, v16
	v_and_b32_e32 v17, 0x3f80, v17
	v_ashrrev_i32_e32 v18, 7, v16
	v_add_u32_e32 v18, v17, v18
	v_ashrrev_i32_e32 v19, 31, v18
	v_lshlrev_b64 v[18:19], 12, v[18:19]
	v_ashrrev_i32_e32 v17, 31, v16
	v_lshlrev_b64 v[20:21], 12, v[16:17]
	v_lshl_add_u64 v[16:17], s[6:7], 0, v[18:19]
	v_lshl_add_u64 v[22:23], v[16:17], 0, v[64:65]
	global_load_dwordx4 v[16:19], v[22:23], off
	s_waitcnt vmcnt(0) lgkmcnt(0)
	v_lshlrev_b32_e32 v24, 16, v16
	v_and_b32_e32 v25, 0xffff0000, v16
	v_lshlrev_b32_e32 v16, 16, v17
	v_and_b32_e32 v17, 0xffff0000, v17
	v_pk_mul_f32 v[14:15], v[14:15], v[16:17]
	v_lshlrev_b32_e32 v16, 16, v18
	v_and_b32_e32 v17, 0xffff0000, v18
	v_pk_mul_f32 v[12:13], v[12:13], v[24:25]
	v_pk_mul_f32 v[8:9], v[8:9], v[16:17]
	v_lshlrev_b32_e32 v16, 16, v19
	v_and_b32_e32 v17, 0xffff0000, v19
	v_pk_mul_f32 v[16:17], v[10:11], v[16:17]
	v_cvt_pk_bf16_f32 v10, v12, v13
	v_cvt_pk_bf16_f32 v12, v8, v9
	v_lshl_add_u64 v[8:9], s[8:9], 0, v[20:21]
	v_cvt_pk_bf16_f32 v11, v14, v15
	v_cvt_pk_bf16_f32 v13, v16, v17
	v_lshl_add_u64 v[8:9], v[8:9], 0, v[64:65]
	global_store_dwordx4 v[8:9], v[10:13], off
	global_load_dwordx4 v[10:13], v[22:23], off offset:256
	s_waitcnt vmcnt(0) lgkmcnt(0)
	v_lshlrev_b32_e32 v14, 16, v10
	v_and_b32_e32 v15, 0xffff0000, v10
	v_lshlrev_b32_e32 v10, 16, v11
	v_and_b32_e32 v11, 0xffff0000, v11
	v_pk_mul_f32 v[6:7], v[6:7], v[10:11]
	v_lshlrev_b32_e32 v10, 16, v12
	v_and_b32_e32 v11, 0xffff0000, v12
	v_pk_mul_f32 v[10:11], v[0:1], v[10:11]
	v_lshlrev_b32_e32 v0, 16, v13
	v_and_b32_e32 v1, 0xffff0000, v13
	v_pk_mul_f32 v[4:5], v[4:5], v[14:15]
	v_pk_mul_f32 v[12:13], v[2:3], v[0:1]
	v_cvt_pk_bf16_f32 v0, v4, v5
	v_cvt_pk_bf16_f32 v1, v6, v7
	v_cvt_pk_bf16_f32 v2, v10, v11
	v_cvt_pk_bf16_f32 v3, v12, v13
	global_store_dwordx4 v[8:9], v[0:3], off offset:256

; __device__ __forceinline__ float bflo(unsigned w) { return __uint_as_float(w << 16); }
; __device__ __forceinline__ float bfhi(unsigned w) { return __uint_as_float(w & 0xffff0000u); }
; __device__ __forceinline__ unsigned cvtpk(float lo, float hi) { f32x2_t v = {lo, hi}; bf16x2_t b = __builtin_convertvector(v, bf16x2_t); return __builtin_bit_cast(unsigned, b); }
;     __device__ __forceinline__ void operator()(const f32x4 (&acc)[2][2][4][2], const Unit& u, int wr, int wc, int fr, int fq) const {
;         const int row0 = u.pm * BM + wr * 64 + fr, col0 = u.pn * BM + wc * 32 + 8 * fq;
; #pragma unroll
;         for (int bj = 0; bj < 2; ++bj) { const int col = col0 + bj * HALF;
;             const f32x4 g0 = *(const f32x4*)(gm + col), g1 = *(const f32x4*)(gm + col + 4);
; #pragma unroll
;             for (int ai = 0; ai < 2; ++ai)
; #pragma unroll
;                 for (int m = 0; m < 4; ++m) { const size_t off = (size_t)(row0 + ai * HALF + m * 16) * D + col;
;                     const u32x4 w = *(const u32x4*)(xr + off);
;                     const f32x4 y0 = (f32x4){bflo(w.x), bfhi(w.x), bflo(w.y), bfhi(w.y)} + g0 * acc[ai][bj][m][0], y1 = (f32x4){bflo(w.z), bfhi(w.z), bflo(w.w), bfhi(w.w)} + g1 * acc[ai][bj][m][1];
;                     if (xout_f) { *(f32x4*)(xout_f + off) = y0; *(f32x4*)(xout_f + off + 4) = y1; }
;                     else { u32x4 o; o.x = cvtpk(y0[0], y0[1]); o.y = cvtpk(y0[2], y0[3]); o.z = cvtpk(y1[0], y1[1]); o.w = cvtpk(y1[2], y1[3]); *(u32x4*)(xr + off) = o; } } }
.LBB0_632:
	v_lshl_add_u32 v160, s15, 8, v146
	v_lshl_or_b32 v154, s14, 8, v148
	v_ashrrev_i32_e32 v161, 31, v160
	v_ashrrev_i32_e32 v155, 31, v154
	v_lshlrev_b64 v[156:157], 11, v[160:161]
	v_lshl_add_u64 v[150:151], v[156:157], 0, v[154:155]
	v_lshl_add_u64 v[122:123], v[154:155], 2, s[18:19]
	v_lshl_add_u64 v[162:163], v[150:151], 1, s[78:79]
	global_load_dwordx4 v[126:129], v[122:123], off
	s_nop 0
	global_load_dwordx4 v[122:125], v[122:123], off offset:16
	s_andn2_b64 vcc, exec, s[24:25]
	global_load_dwordx4 v[164:167], v[162:163], off
	s_waitcnt vmcnt(0) lgkmcnt(0)
	v_lshlrev_b32_e32 v158, 16, v164
	v_and_b32_e32 v159, 0xffff0000, v164
	v_lshlrev_b32_e32 v164, 16, v165
	v_and_b32_e32 v165, 0xffff0000, v165
	v_pk_fma_f32 v[134:135], v[134:135], v[126:127], v[158:159]
	v_lshlrev_b32_e32 v158, 16, v166
	v_and_b32_e32 v159, 0xffff0000, v166
	v_pk_fma_f32 v[136:137], v[136:137], v[128:129], v[164:165]
	v_lshlrev_b32_e32 v164, 16, v167
	v_and_b32_e32 v165, 0xffff0000, v167
	v_pk_fma_f32 v[130:131], v[130:131], v[122:123], v[158:159]
	v_cndmask_b32_e64 v158, 0, 1, s[24:25]
	v_pk_fma_f32 v[132:133], v[132:133], v[124:125], v[164:165]
	v_cmp_ne_u32_e64 s[2:3], 1, v158
	v_lshl_add_u64 v[158:159], v[150:151], 2, s[16:17]
	s_cbranch_vccnz .LBB0_683
	global_store_dwordx4 v[158:159], v[134:137], off
	global_store_dwordx4 v[158:159], v[130:133], off offset:16
	s_cbranch_execnz .LBB0_635
.LBB0_634:
	v_cvt_pk_bf16_f32 v134, v134, v135
	v_cvt_pk_bf16_f32 v135, v136, v137
	v_cvt_pk_bf16_f32 v136, v130, v131
	v_cvt_pk_bf16_f32 v137, v132, v133
	global_store_dwordx4 v[162:163], v[134:137], off
.LBB0_635:
	s_nop 0
	v_or_b32_e32 v130, 16, v160
	v_ashrrev_i32_e32 v131, 31, v130
	v_lshlrev_b64 v[132:133], 11, v[130:131]
	v_lshl_add_u64 v[130:131], v[132:133], 0, v[154:155]
	v_lshl_add_u64 v[134:135], v[130:131], 1, s[78:79]
	global_load_dwordx4 v[162:165], v[134:135], off
	s_and_b64 vcc, exec, s[2:3]
	v_lshl_add_u64 v[130:131], v[130:131], 2, s[16:17]
	s_waitcnt vmcnt(0) lgkmcnt(0)
	v_lshlrev_b32_e32 v136, 16, v162
	v_and_b32_e32 v137, 0xffff0000, v162
	v_lshlrev_b32_e32 v150, 16, v163
	v_and_b32_e32 v151, 0xffff0000, v163
	v_pk_fma_f32 v[120:121], v[120:121], v[128:129], v[150:151]
	v_pk_fma_f32 v[118:119], v[118:119], v[126:127], v[136:137]
	v_lshlrev_b32_e32 v136, 16, v164
	v_and_b32_e32 v137, 0xffff0000, v164
	v_lshlrev_b32_e32 v150, 16, v165
	v_and_b32_e32 v151, 0xffff0000, v165
	v_pk_fma_f32 v[116:117], v[116:117], v[124:125], v[150:151]
	v_pk_fma_f32 v[114:115], v[114:115], v[122:123], v[136:137]
	s_cbranch_vccnz .LBB0_684
	global_store_dwordx4 v[130:131], v[118:121], off
	global_store_dwordx4 v[130:131], v[114:117], off offset:16
	s_cbranch_execnz .LBB0_638
.LBB0_637:
	v_cvt_pk_bf16_f32 v118, v118, v119
	v_cvt_pk_bf16_f32 v119, v120, v121
	v_cvt_pk_bf16_f32 v120, v114, v115
	v_cvt_pk_bf16_f32 v121, v116, v117
	global_store_dwordx4 v[134:135], v[118:121], off
.LBB0_638:
	s_nop 0
	v_or_b32_e32 v114, 32, v160
	v_ashrrev_i32_e32 v115, 31, v114
	v_lshlrev_b64 v[116:117], 11, v[114:115]
	v_lshl_add_u64 v[114:115], v[116:117], 0, v[154:155]
	v_lshl_add_u64 v[118:119], v[114:115], 1, s[78:79]
	global_load_dwordx4 v[134:137], v[118:119], off
	s_and_b64 vcc, exec, s[2:3]
	v_lshl_add_u64 v[114:115], v[114:115], 2, s[16:17]
	s_waitcnt vmcnt(0) lgkmcnt(0)
	v_lshlrev_b32_e32 v120, 16, v134
	v_and_b32_e32 v121, 0xffff0000, v134
	v_lshlrev_b32_e32 v134, 16, v135
	v_and_b32_e32 v135, 0xffff0000, v135
	v_pk_fma_f32 v[112:113], v[112:113], v[128:129], v[134:135]
	v_pk_fma_f32 v[110:111], v[110:111], v[126:127], v[120:121]
	v_lshlrev_b32_e32 v120, 16, v136
	v_and_b32_e32 v121, 0xffff0000, v136
	v_lshlrev_b32_e32 v134, 16, v137
	v_and_b32_e32 v135, 0xffff0000, v137
	v_pk_fma_f32 v[108:109], v[108:109], v[124:125], v[134:135]
	v_pk_fma_f32 v[106:107], v[106:107], v[122:123], v[120:121]
	s_cbranch_vccnz .LBB0_685
	global_store_dwordx4 v[114:115], v[110:113], off
	global_store_dwordx4 v[114:115], v[106:109], off offset:16
	s_cbranch_execnz .LBB0_641
.LBB0_640:
	v_cvt_pk_bf16_f32 v110, v110, v111
	v_cvt_pk_bf16_f32 v111, v112, v113
	v_cvt_pk_bf16_f32 v112, v106, v107
	v_cvt_pk_bf16_f32 v113, v108, v109
	global_store_dwordx4 v[118:119], v[110:113], off
.LBB0_641:
	s_nop 0
	v_or_b32_e32 v106, 48, v160
	v_ashrrev_i32_e32 v107, 31, v106
	v_lshlrev_b64 v[108:109], 11, v[106:107]
	v_lshl_add_u64 v[106:107], v[108:109], 0, v[154:155]
	v_lshl_add_u64 v[110:111], v[106:107], 1, s[78:79]
	global_load_dwordx4 v[118:121], v[110:111], off
	s_and_b64 vcc, exec, s[2:3]
	v_lshl_add_u64 v[106:107], v[106:107], 2, s[16:17]
	s_waitcnt vmcnt(0) lgkmcnt(0)
	v_lshlrev_b32_e32 v112, 16, v118
	v_and_b32_e32 v113, 0xffff0000, v118
	v_lshlrev_b32_e32 v118, 16, v119
	v_and_b32_e32 v119, 0xffff0000, v119
	v_pk_fma_f32 v[104:105], v[104:105], v[128:129], v[118:119]
	v_pk_fma_f32 v[102:103], v[102:103], v[126:127], v[112:113]
	v_lshlrev_b32_e32 v112, 16, v120
	v_and_b32_e32 v113, 0xffff0000, v120
	v_lshlrev_b32_e32 v118, 16, v121
	v_and_b32_e32 v119, 0xffff0000, v121
	v_pk_fma_f32 v[100:101], v[100:101], v[124:125], v[118:119]
	v_pk_fma_f32 v[98:99], v[98:99], v[122:123], v[112:113]
	s_cbranch_vccnz .LBB0_686
	global_store_dwordx4 v[106:107], v[102:105], off
	global_store_dwordx4 v[106:107], v[98:101], off offset:16
	s_cbranch_execnz .LBB0_644
.LBB0_643:
	v_cvt_pk_bf16_f32 v102, v102, v103
	v_cvt_pk_bf16_f32 v103, v104, v105
	v_cvt_pk_bf16_f32 v104, v98, v99
	v_cvt_pk_bf16_f32 v105, v100, v101
	global_store_dwordx4 v[110:111], v[102:105], off
; __device__ __forceinline__ float bflo(unsigned w) { return __uint_as_float(w << 16); }
; __device__ __forceinline__ float bfhi(unsigned w) { return __uint_as_float(w & 0xffff0000u); }
; __device__ __forceinline__ unsigned cvtpk(float lo, float hi) { f32x2_t v = {lo, hi}; bf16x2_t b = __builtin_convertvector(v, bf16x2_t); return __builtin_bit_cast(unsigned, b); }
;     __device__ __forceinline__ void operator()(const f32x4 (&acc)[2][2][4][2], const Unit& u, int wr, int wc, int fr, int fq) const {
;         const int row0 = u.pm * BM + wr * 64 + fr, col0 = u.pn * BM + wc * 32 + 8 * fq;
; #pragma unroll
;         for (int bj = 0; bj < 2; ++bj) { const int col = col0 + bj * HALF;
;             const f32x4 g0 = *(const f32x4*)(gm + col), g1 = *(const f32x4*)(gm + col + 4);
; #pragma unroll
;             for (int ai = 0; ai < 2; ++ai)
; #pragma unroll
;                 for (int m = 0; m < 4; ++m) { const size_t off = (size_t)(row0 + ai * HALF + m * 16) * D + col;
;                     const u32x4 w = *(const u32x4*)(xr + off);
;                     const f32x4 y0 = (f32x4){bflo(w.x), bfhi(w.x), bflo(w.y), bfhi(w.y)} + g0 * acc[ai][bj][m][0], y1 = (f32x4){bflo(w.z), bfhi(w.z), bflo(w.w), bfhi(w.w)} + g1 * acc[ai][bj][m][1];
;                     if (xout_f) { *(f32x4*)(xout_f + off) = y0; *(f32x4*)(xout_f + off + 4) = y1; }
;                     else { u32x4 o; o.x = cvtpk(y0[0], y0[1]); o.y = cvtpk(y0[2], y0[3]); o.z = cvtpk(y1[0], y1[1]); o.w = cvtpk(y1[2], y1[3]); *(u32x4*)(xr + off) = o; } } }
.LBB0_644:
	s_nop 0
	v_lshlrev_b64 v[98:99], 11, v[160:161]
	s_mov_b64 s[14:15], 0x40000
	v_lshl_add_u64 v[100:101], v[98:99], 0, s[14:15]
	v_lshl_add_u64 v[98:99], v[100:101], 0, v[154:155]
	v_lshl_add_u64 v[102:103], v[98:99], 1, s[78:79]
	global_load_dwordx4 v[110:113], v[102:103], off
	s_and_b64 vcc, exec, s[2:3]
	v_lshl_add_u64 v[98:99], v[98:99], 2, s[16:17]
	s_waitcnt vmcnt(0) lgkmcnt(0)
	v_lshlrev_b32_e32 v104, 16, v110
	v_and_b32_e32 v105, 0xffff0000, v110
	v_lshlrev_b32_e32 v110, 16, v111
	v_and_b32_e32 v111, 0xffff0000, v111
	v_pk_fma_f32 v[94:95], v[94:95], v[128:129], v[110:111]
	v_pk_fma_f32 v[92:93], v[92:93], v[126:127], v[104:105]
	v_lshlrev_b32_e32 v104, 16, v112
	v_and_b32_e32 v105, 0xffff0000, v112
	v_lshlrev_b32_e32 v110, 16, v113
	v_and_b32_e32 v111, 0xffff0000, v113
	v_pk_fma_f32 v[90:91], v[90:91], v[124:125], v[110:111]
	v_pk_fma_f32 v[88:89], v[88:89], v[122:123], v[104:105]
	s_cbranch_vccnz .LBB0_687
	global_store_dwordx4 v[98:99], v[92:95], off
	global_store_dwordx4 v[98:99], v[88:91], off offset:16
	s_cbranch_execnz .LBB0_647
.LBB0_646:
	v_cvt_pk_bf16_f32 v92, v92, v93
	v_cvt_pk_bf16_f32 v93, v94, v95
	v_cvt_pk_bf16_f32 v94, v88, v89
	v_cvt_pk_bf16_f32 v95, v90, v91
	global_store_dwordx4 v[102:103], v[92:95], off
.LBB0_647:
	s_nop 0
	v_lshlrev_b64 v[88:89], 11, v[160:161]
	s_mov_b64 s[14:15], 0x48000
	v_lshl_add_u64 v[90:91], v[88:89], 0, s[14:15]
	v_lshl_add_u64 v[88:89], v[90:91], 0, v[154:155]
	v_lshl_add_u64 v[92:93], v[88:89], 1, s[78:79]
	global_load_dwordx4 v[102:105], v[92:93], off
	s_and_b64 vcc, exec, s[2:3]
	v_lshl_add_u64 v[88:89], v[88:89], 2, s[16:17]
	s_waitcnt vmcnt(0) lgkmcnt(0)
	v_lshlrev_b32_e32 v94, 16, v102
	v_and_b32_e32 v95, 0xffff0000, v102
	v_lshlrev_b32_e32 v102, 16, v103
	v_and_b32_e32 v103, 0xffff0000, v103
	v_pk_fma_f32 v[86:87], v[86:87], v[128:129], v[102:103]
	v_pk_fma_f32 v[84:85], v[84:85], v[126:127], v[94:95]
	v_lshlrev_b32_e32 v94, 16, v104
	v_and_b32_e32 v95, 0xffff0000, v104
	v_lshlrev_b32_e32 v102, 16, v105
	v_and_b32_e32 v103, 0xffff0000, v105
	v_pk_fma_f32 v[82:83], v[82:83], v[124:125], v[102:103]
	v_pk_fma_f32 v[80:81], v[80:81], v[122:123], v[94:95]
	s_cbranch_vccnz .LBB0_688
	global_store_dwordx4 v[88:89], v[84:87], off
	global_store_dwordx4 v[88:89], v[80:83], off offset:16
	s_cbranch_execnz .LBB0_650
.LBB0_649:
	v_cvt_pk_bf16_f32 v84, v84, v85
	v_cvt_pk_bf16_f32 v85, v86, v87
	v_cvt_pk_bf16_f32 v86, v80, v81
	v_cvt_pk_bf16_f32 v87, v82, v83
	global_store_dwordx4 v[92:93], v[84:87], off
.LBB0_650:
	s_nop 0
	v_lshlrev_b64 v[80:81], 11, v[160:161]
	s_mov_b64 s[14:15], 0x50000
	v_lshl_add_u64 v[82:83], v[80:81], 0, s[14:15]
	v_lshl_add_u64 v[80:81], v[82:83], 0, v[154:155]
	v_lshl_add_u64 v[84:85], v[80:81], 1, s[78:79]
	global_load_dwordx4 v[92:95], v[84:85], off
	s_and_b64 vcc, exec, s[2:3]
	v_lshl_add_u64 v[80:81], v[80:81], 2, s[16:17]
	s_waitcnt vmcnt(0) lgkmcnt(0)
	v_lshlrev_b32_e32 v86, 16, v92
	v_and_b32_e32 v87, 0xffff0000, v92
	v_lshlrev_b32_e32 v92, 16, v93
	v_and_b32_e32 v93, 0xffff0000, v93
	v_pk_fma_f32 v[78:79], v[78:79], v[128:129], v[92:93]
	v_pk_fma_f32 v[76:77], v[76:77], v[126:127], v[86:87]
	v_lshlrev_b32_e32 v86, 16, v94
	v_and_b32_e32 v87, 0xffff0000, v94
	v_lshlrev_b32_e32 v92, 16, v95
	v_and_b32_e32 v93, 0xffff0000, v95
	v_pk_fma_f32 v[74:75], v[74:75], v[124:125], v[92:93]
	v_pk_fma_f32 v[72:73], v[72:73], v[122:123], v[86:87]
	s_cbranch_vccnz .LBB0_689
	global_store_dwordx4 v[80:81], v[76:79], off
	global_store_dwordx4 v[80:81], v[72:75], off offset:16
	s_cbranch_execnz .LBB0_653
.LBB0_652:
	v_cvt_pk_bf16_f32 v76, v76, v77
	v_cvt_pk_bf16_f32 v77, v78, v79
	v_cvt_pk_bf16_f32 v78, v72, v73
	v_cvt_pk_bf16_f32 v79, v74, v75
	global_store_dwordx4 v[84:85], v[76:79], off
.LBB0_653:
	s_nop 0
	v_lshlrev_b64 v[72:73], 11, v[160:161]
	s_mov_b64 s[14:15], 0x58000
	v_lshl_add_u64 v[74:75], v[72:73], 0, s[14:15]
	v_lshl_add_u64 v[72:73], v[74:75], 0, v[154:155]
	v_lshl_add_u64 v[76:77], v[72:73], 1, s[78:79]
	global_load_dwordx4 v[84:87], v[76:77], off
	s_and_b64 vcc, exec, s[2:3]
	v_lshl_add_u64 v[72:73], v[72:73], 2, s[16:17]
	s_waitcnt vmcnt(0) lgkmcnt(0)
	v_lshlrev_b32_e32 v78, 16, v84
	v_and_b32_e32 v79, 0xffff0000, v84
	v_lshlrev_b32_e32 v84, 16, v85
	v_and_b32_e32 v85, 0xffff0000, v85
	v_pk_fma_f32 v[70:71], v[70:71], v[128:129], v[84:85]
	v_pk_fma_f32 v[68:69], v[68:69], v[126:127], v[78:79]
	v_lshlrev_b32_e32 v78, 16, v86
	v_and_b32_e32 v79, 0xffff0000, v86
	v_lshlrev_b32_e32 v84, 16, v87
	v_and_b32_e32 v85, 0xffff0000, v87
	v_pk_fma_f32 v[66:67], v[66:67], v[124:125], v[84:85]
	v_pk_fma_f32 v[64:65], v[64:65], v[122:123], v[78:79]
	s_cbranch_vccnz .LBB0_690
	global_store_dwordx4 v[72:73], v[68:71], off
	global_store_dwordx4 v[72:73], v[64:67], off offset:16
	s_cbranch_execnz .LBB0_656
.LBB0_655:
	v_cvt_pk_bf16_f32 v68, v68, v69
	v_cvt_pk_bf16_f32 v69, v70, v71
	v_cvt_pk_bf16_f32 v70, v64, v65
	v_cvt_pk_bf16_f32 v71, v66, v67
	global_store_dwordx4 v[76:77], v[68:71], off
.LBB0_656:
	v_or_b32_e32 v76, 0x80, v154
	v_ashrrev_i32_e32 v77, 31, v76
	v_lshl_add_u64 v[78:79], v[156:157], 0, v[76:77]
	v_lshl_add_u64 v[64:65], v[76:77], 2, s[18:19]
	v_lshl_add_u64 v[78:79], v[78:79], 1, s[78:79]
	global_load_dwordx4 v[68:71], v[64:65], off
	s_nop 0
	global_load_dwordx4 v[64:67], v[64:65], off offset:16
	s_and_b64 vcc, exec, s[2:3]
	global_load_dwordx4 v[84:87], v[78:79], off
	s_waitcnt vmcnt(0) lgkmcnt(0)
	v_lshlrev_b32_e32 v92, 16, v84
	v_and_b32_e32 v93, 0xffff0000, v84
	v_lshlrev_b32_e32 v84, 16, v85
	v_and_b32_e32 v85, 0xffff0000, v85
	v_pk_fma_f32 v[62:63], v[62:63], v[70:71], v[84:85]
	v_lshlrev_b32_e32 v84, 16, v86
	v_and_b32_e32 v85, 0xffff0000, v86
	v_lshlrev_b32_e32 v86, 16, v87
	v_and_b32_e32 v87, 0xffff0000, v87
	v_pk_fma_f32 v[60:61], v[60:61], v[68:69], v[92:93]
	v_pk_fma_f32 v[58:59], v[58:59], v[66:67], v[86:87]
	v_pk_fma_f32 v[56:57], v[56:57], v[64:65], v[84:85]
	s_cbranch_vccnz .LBB0_691
	global_store_dwordx4 v[158:159], v[60:63], off offset:512
	global_store_dwordx4 v[158:159], v[56:59], off offset:528
	s_cbranch_execnz .LBB0_659
; __device__ __forceinline__ float bflo(unsigned w) { return __uint_as_float(w << 16); }
; __device__ __forceinline__ float bfhi(unsigned w) { return __uint_as_float(w & 0xffff0000u); }
; __device__ __forceinline__ unsigned cvtpk(float lo, float hi) { f32x2_t v = {lo, hi}; bf16x2_t b = __builtin_convertvector(v, bf16x2_t); return __builtin_bit_cast(unsigned, b); }
;     __device__ __forceinline__ void operator()(const f32x4 (&acc)[2][2][4][2], const Unit& u, int wr, int wc, int fr, int fq) const {
;         const int row0 = u.pm * BM + wr * 64 + fr, col0 = u.pn * BM + wc * 32 + 8 * fq;
; #pragma unroll
;         for (int bj = 0; bj < 2; ++bj) { const int col = col0 + bj * HALF;
;             const f32x4 g0 = *(const f32x4*)(gm + col), g1 = *(const f32x4*)(gm + col + 4);
; #pragma unroll
;             for (int ai = 0; ai < 2; ++ai)
; #pragma unroll
;                 for (int m = 0; m < 4; ++m) { const size_t off = (size_t)(row0 + ai * HALF + m * 16) * D + col;
;                     const u32x4 w = *(const u32x4*)(xr + off);
;                     const f32x4 y0 = (f32x4){bflo(w.x), bfhi(w.x), bflo(w.y), bfhi(w.y)} + g0 * acc[ai][bj][m][0], y1 = (f32x4){bflo(w.z), bfhi(w.z), bflo(w.w), bfhi(w.w)} + g1 * acc[ai][bj][m][1];
;                     if (xout_f) { *(f32x4*)(xout_f + off) = y0; *(f32x4*)(xout_f + off + 4) = y1; }
;                     else { u32x4 o; o.x = cvtpk(y0[0], y0[1]); o.y = cvtpk(y0[2], y0[3]); o.z = cvtpk(y1[0], y1[1]); o.w = cvtpk(y1[2], y1[3]); *(u32x4*)(xr + off) = o; } } }
.LBB0_658:
	v_cvt_pk_bf16_f32 v60, v60, v61
	v_cvt_pk_bf16_f32 v61, v62, v63
	v_cvt_pk_bf16_f32 v62, v56, v57
	v_cvt_pk_bf16_f32 v63, v58, v59
	global_store_dwordx4 v[78:79], v[60:63], off
.LBB0_659:
	s_nop 0
	v_lshl_add_u64 v[56:57], v[132:133], 0, v[76:77]
	v_lshl_add_u64 v[56:57], v[56:57], 1, s[78:79]
	global_load_dwordx4 v[58:61], v[56:57], off
	s_and_b64 vcc, exec, s[2:3]
	s_waitcnt vmcnt(0) lgkmcnt(0)
	v_lshlrev_b32_e32 v62, 16, v58
	v_and_b32_e32 v63, 0xffff0000, v58
	v_lshlrev_b32_e32 v58, 16, v59
	v_and_b32_e32 v59, 0xffff0000, v59
	v_pk_fma_f32 v[54:55], v[54:55], v[70:71], v[58:59]
	v_lshlrev_b32_e32 v58, 16, v60
	v_and_b32_e32 v59, 0xffff0000, v60
	v_lshlrev_b32_e32 v60, 16, v61
	v_and_b32_e32 v61, 0xffff0000, v61
	v_pk_fma_f32 v[52:53], v[52:53], v[68:69], v[62:63]
	v_pk_fma_f32 v[50:51], v[50:51], v[66:67], v[60:61]
	v_pk_fma_f32 v[48:49], v[48:49], v[64:65], v[58:59]
	s_cbranch_vccnz .LBB0_692
	global_store_dwordx4 v[130:131], v[52:55], off offset:512
	global_store_dwordx4 v[130:131], v[48:51], off offset:528
	s_cbranch_execnz .LBB0_662
.LBB0_661:
	v_cvt_pk_bf16_f32 v52, v52, v53
	v_cvt_pk_bf16_f32 v53, v54, v55
	v_cvt_pk_bf16_f32 v54, v48, v49
	v_cvt_pk_bf16_f32 v55, v50, v51
	global_store_dwordx4 v[56:57], v[52:55], off
.LBB0_662:
	s_nop 0
	v_lshl_add_u64 v[48:49], v[116:117], 0, v[76:77]
	v_lshl_add_u64 v[48:49], v[48:49], 1, s[78:79]
	global_load_dwordx4 v[50:53], v[48:49], off
	s_and_b64 vcc, exec, s[2:3]
	s_waitcnt vmcnt(0) lgkmcnt(0)
	v_lshlrev_b32_e32 v54, 16, v50
	v_and_b32_e32 v55, 0xffff0000, v50
	v_lshlrev_b32_e32 v50, 16, v51
	v_and_b32_e32 v51, 0xffff0000, v51
	v_pk_fma_f32 v[46:47], v[46:47], v[70:71], v[50:51]
	v_lshlrev_b32_e32 v50, 16, v52
	v_and_b32_e32 v51, 0xffff0000, v52
	v_lshlrev_b32_e32 v52, 16, v53
	v_and_b32_e32 v53, 0xffff0000, v53
	v_pk_fma_f32 v[44:45], v[44:45], v[68:69], v[54:55]
	v_pk_fma_f32 v[42:43], v[42:43], v[66:67], v[52:53]
	v_pk_fma_f32 v[40:41], v[40:41], v[64:65], v[50:51]
	s_cbranch_vccnz .LBB0_693
	global_store_dwordx4 v[114:115], v[44:47], off offset:512
	global_store_dwordx4 v[114:115], v[40:43], off offset:528
	s_cbranch_execnz .LBB0_665
.LBB0_664:
	v_cvt_pk_bf16_f32 v44, v44, v45
	v_cvt_pk_bf16_f32 v45, v46, v47
	v_cvt_pk_bf16_f32 v46, v40, v41
	v_cvt_pk_bf16_f32 v47, v42, v43
	global_store_dwordx4 v[48:49], v[44:47], off
.LBB0_665:
	s_nop 0
	v_lshl_add_u64 v[40:41], v[108:109], 0, v[76:77]
	v_lshl_add_u64 v[40:41], v[40:41], 1, s[78:79]
	global_load_dwordx4 v[42:45], v[40:41], off
	s_and_b64 vcc, exec, s[2:3]
	s_waitcnt vmcnt(0) lgkmcnt(0)
	v_lshlrev_b32_e32 v46, 16, v42
	v_and_b32_e32 v47, 0xffff0000, v42
	v_lshlrev_b32_e32 v42, 16, v43
	v_and_b32_e32 v43, 0xffff0000, v43
	v_pk_fma_f32 v[38:39], v[38:39], v[70:71], v[42:43]
	v_lshlrev_b32_e32 v42, 16, v44
	v_and_b32_e32 v43, 0xffff0000, v44
	v_lshlrev_b32_e32 v44, 16, v45
	v_and_b32_e32 v45, 0xffff0000, v45
	v_pk_fma_f32 v[36:37], v[36:37], v[68:69], v[46:47]
	v_pk_fma_f32 v[34:35], v[34:35], v[66:67], v[44:45]
	v_pk_fma_f32 v[32:33], v[32:33], v[64:65], v[42:43]
	s_cbranch_vccnz .LBB0_694
	global_store_dwordx4 v[106:107], v[36:39], off offset:512
	global_store_dwordx4 v[106:107], v[32:35], off offset:528
	s_cbranch_execnz .LBB0_668
.LBB0_667:
	v_cvt_pk_bf16_f32 v36, v36, v37
	v_cvt_pk_bf16_f32 v37, v38, v39
	v_cvt_pk_bf16_f32 v38, v32, v33
	v_cvt_pk_bf16_f32 v39, v34, v35
	global_store_dwordx4 v[40:41], v[36:39], off
; __device__ __forceinline__ float bflo(unsigned w) { return __uint_as_float(w << 16); }
; __device__ __forceinline__ float bfhi(unsigned w) { return __uint_as_float(w & 0xffff0000u); }
; __device__ __forceinline__ unsigned cvtpk(float lo, float hi) { f32x2_t v = {lo, hi}; bf16x2_t b = __builtin_convertvector(v, bf16x2_t); return __builtin_bit_cast(unsigned, b); }
;     __device__ __forceinline__ void operator()(const f32x4 (&acc)[2][2][4][2], const Unit& u, int wr, int wc, int fr, int fq) const {
;         const int row0 = u.pm * BM + wr * 64 + fr, col0 = u.pn * BM + wc * 32 + 8 * fq;
; #pragma unroll
;         for (int bj = 0; bj < 2; ++bj) { const int col = col0 + bj * HALF;
;             const f32x4 g0 = *(const f32x4*)(gm + col), g1 = *(const f32x4*)(gm + col + 4);
; #pragma unroll
;             for (int ai = 0; ai < 2; ++ai)
; #pragma unroll
;                 for (int m = 0; m < 4; ++m) { const size_t off = (size_t)(row0 + ai * HALF + m * 16) * D + col;
;                     const u32x4 w = *(const u32x4*)(xr + off);
;                     const f32x4 y0 = (f32x4){bflo(w.x), bfhi(w.x), bflo(w.y), bfhi(w.y)} + g0 * acc[ai][bj][m][0], y1 = (f32x4){bflo(w.z), bfhi(w.z), bflo(w.w), bfhi(w.w)} + g1 * acc[ai][bj][m][1];
;                     if (xout_f) { *(f32x4*)(xout_f + off) = y0; *(f32x4*)(xout_f + off + 4) = y1; }
;                     else { u32x4 o; o.x = cvtpk(y0[0], y0[1]); o.y = cvtpk(y0[2], y0[3]); o.z = cvtpk(y1[0], y1[1]); o.w = cvtpk(y1[2], y1[3]); *(u32x4*)(xr + off) = o; } } }
.LBB0_668:
	s_nop 0
	v_lshl_add_u64 v[32:33], v[100:101], 0, v[76:77]
	v_lshl_add_u64 v[32:33], v[32:33], 1, s[78:79]
	global_load_dwordx4 v[34:37], v[32:33], off
	s_and_b64 vcc, exec, s[2:3]
	s_waitcnt vmcnt(0) lgkmcnt(0)
	v_lshlrev_b32_e32 v38, 16, v34
	v_and_b32_e32 v39, 0xffff0000, v34
	v_lshlrev_b32_e32 v34, 16, v35
	v_and_b32_e32 v35, 0xffff0000, v35
	v_pk_fma_f32 v[30:31], v[30:31], v[70:71], v[34:35]
	v_lshlrev_b32_e32 v34, 16, v36
	v_and_b32_e32 v35, 0xffff0000, v36
	v_lshlrev_b32_e32 v36, 16, v37
	v_and_b32_e32 v37, 0xffff0000, v37
	v_pk_fma_f32 v[28:29], v[28:29], v[68:69], v[38:39]
	v_pk_fma_f32 v[26:27], v[26:27], v[66:67], v[36:37]
	v_pk_fma_f32 v[24:25], v[24:25], v[64:65], v[34:35]
	s_cbranch_vccnz .LBB0_695
	global_store_dwordx4 v[98:99], v[28:31], off offset:512
	global_store_dwordx4 v[98:99], v[24:27], off offset:528
	s_cbranch_execnz .LBB0_671
.LBB0_670:
	v_cvt_pk_bf16_f32 v28, v28, v29
	v_cvt_pk_bf16_f32 v29, v30, v31
	v_cvt_pk_bf16_f32 v30, v24, v25
	v_cvt_pk_bf16_f32 v31, v26, v27
	global_store_dwordx4 v[32:33], v[28:31], off
.LBB0_671:
	s_nop 0
	v_lshl_add_u64 v[24:25], v[90:91], 0, v[76:77]
	v_lshl_add_u64 v[24:25], v[24:25], 1, s[78:79]
	global_load_dwordx4 v[26:29], v[24:25], off
	s_and_b64 vcc, exec, s[2:3]
	s_waitcnt vmcnt(0) lgkmcnt(0)
	v_lshlrev_b32_e32 v30, 16, v26
	v_and_b32_e32 v31, 0xffff0000, v26
	v_lshlrev_b32_e32 v26, 16, v27
	v_and_b32_e32 v27, 0xffff0000, v27
	v_pk_fma_f32 v[22:23], v[22:23], v[70:71], v[26:27]
	v_lshlrev_b32_e32 v26, 16, v28
	v_and_b32_e32 v27, 0xffff0000, v28
	v_lshlrev_b32_e32 v28, 16, v29
	v_and_b32_e32 v29, 0xffff0000, v29
	v_pk_fma_f32 v[20:21], v[20:21], v[68:69], v[30:31]
	v_pk_fma_f32 v[18:19], v[18:19], v[66:67], v[28:29]
	v_pk_fma_f32 v[16:17], v[16:17], v[64:65], v[26:27]
	s_cbranch_vccnz .LBB0_696
	global_store_dwordx4 v[88:89], v[20:23], off offset:512
	global_store_dwordx4 v[88:89], v[16:19], off offset:528
	s_cbranch_execnz .LBB0_674
.LBB0_673:
	v_cvt_pk_bf16_f32 v20, v20, v21
	v_cvt_pk_bf16_f32 v21, v22, v23
	v_cvt_pk_bf16_f32 v22, v16, v17
	v_cvt_pk_bf16_f32 v23, v18, v19
	global_store_dwordx4 v[24:25], v[20:23], off
.LBB0_674:
	s_nop 0
	v_lshl_add_u64 v[16:17], v[82:83], 0, v[76:77]
	v_lshl_add_u64 v[16:17], v[16:17], 1, s[78:79]
	global_load_dwordx4 v[18:21], v[16:17], off
	s_and_b64 vcc, exec, s[2:3]
	s_waitcnt vmcnt(0) lgkmcnt(0)
	v_lshlrev_b32_e32 v22, 16, v18
	v_and_b32_e32 v23, 0xffff0000, v18
	v_lshlrev_b32_e32 v18, 16, v19
	v_and_b32_e32 v19, 0xffff0000, v19
	v_pk_fma_f32 v[14:15], v[14:15], v[70:71], v[18:19]
	v_lshlrev_b32_e32 v18, 16, v20
	v_and_b32_e32 v19, 0xffff0000, v20
	v_lshlrev_b32_e32 v20, 16, v21
	v_and_b32_e32 v21, 0xffff0000, v21
	v_pk_fma_f32 v[12:13], v[12:13], v[68:69], v[22:23]
	v_pk_fma_f32 v[10:11], v[10:11], v[66:67], v[20:21]
	v_pk_fma_f32 v[8:9], v[8:9], v[64:65], v[18:19]
	s_cbranch_vccnz .LBB0_697
	global_store_dwordx4 v[80:81], v[12:15], off offset:512
	global_store_dwordx4 v[80:81], v[8:11], off offset:528
	s_cbranch_execnz .LBB0_677
.LBB0_676:
	v_cvt_pk_bf16_f32 v12, v12, v13
	v_cvt_pk_bf16_f32 v13, v14, v15
	v_cvt_pk_bf16_f32 v14, v8, v9
	v_cvt_pk_bf16_f32 v15, v10, v11
	global_store_dwordx4 v[16:17], v[12:15], off
.LBB0_677:
	s_nop 0
	v_lshl_add_u64 v[8:9], v[74:75], 0, v[76:77]
	v_lshl_add_u64 v[8:9], v[8:9], 1, s[78:79]
	global_load_dwordx4 v[10:13], v[8:9], off
	s_and_b64 vcc, exec, s[2:3]
	s_waitcnt vmcnt(0) lgkmcnt(0)
	v_lshlrev_b32_e32 v14, 16, v10
	v_and_b32_e32 v15, 0xffff0000, v10
	v_lshlrev_b32_e32 v10, 16, v11
	v_and_b32_e32 v11, 0xffff0000, v11
	v_pk_fma_f32 v[6:7], v[6:7], v[70:71], v[10:11]
	v_lshlrev_b32_e32 v10, 16, v12
	v_and_b32_e32 v11, 0xffff0000, v12
	v_lshlrev_b32_e32 v12, 16, v13
	v_and_b32_e32 v13, 0xffff0000, v13
	v_pk_fma_f32 v[4:5], v[4:5], v[68:69], v[14:15]
	v_pk_fma_f32 v[2:3], v[2:3], v[66:67], v[12:13]
	v_pk_fma_f32 v[0:1], v[0:1], v[64:65], v[10:11]
	s_cbranch_vccnz .LBB0_698
	global_store_dwordx4 v[72:73], v[4:7], off offset:512
	global_store_dwordx4 v[72:73], v[0:3], off offset:528
	s_cbranch_execnz .LBB0_680
.LBB0_679:
	v_cvt_pk_bf16_f32 v4, v4, v5
	v_cvt_pk_bf16_f32 v5, v6, v7
	v_cvt_pk_bf16_f32 v6, v0, v1
	v_cvt_pk_bf16_f32 v7, v2, v3
	global_store_dwordx4 v[8:9], v[4:7], off

; template <bool XB16>
; __device__ __forceinline__ void modulate_phase(const void* xv, const float* nw, const float* modl, const float* adab, bf16_t* H, bool perm, int wid_s_, bf16_t* XRo) {
;     ...
;     const int tid = tid_, lane = tid & 63, wid = tid >> 6, gw = blockIdx.x * 8 + wid, NGW = gridDim.x * 8;
;     f32x4 av[8], bv[8];
; #pragma unroll
;     for (int j = 0; j < 4; ++j)
; #pragma unroll
;         for (int q = 0; q < 2; ++q) { const int col = 512 * j + 8 * lane + 4 * q;
;             av[2 * j + q] = *(const f32x4*)(nw + col) * (*(const f32x4*)(modl + 2048 + col) + 1.0f); bv[2 * j + q] = *(const f32x4*)(modl + col); }
.LBB0_754:
	s_and_b64 vcc, exec, s[0:1]
	s_cbranch_vccz .LBB0_1453
	v_readlane_b32 s0, v255, 48
	s_cmp_eq_u32 s0, 0
	v_readlane_b32 s4, v255, 44
	s_cselect_b64 s[2:3], -1, 0
	v_readlane_b32 s5, v255, 45
	s_add_u32 s6, s4, 0x2000
	v_readlane_b32 s1, v255, 49
	s_addc_u32 s7, s5, 0
	s_cmp_lg_u32 s0, 0
	s_mov_b64 s[0:1], -1
	v_readlane_b32 s26, v255, 32
	v_readlane_b32 s37, v255, 33
	s_movk_i32 s12, 0x1000
	s_mov_b64 s[14:15], 0x1000
	s_cbranch_scc0 .LBB0_760
	v_mbcnt_lo_u32_b32 v0, -1, 0
	v_mbcnt_hi_u32_b32 v0, -1, v0
	v_readlane_b32 s0, v254, 5
	s_nop 1
	v_add_u32_e32 v0, s0, v0
	v_readlane_b32 s0, v254, 47
	v_ashrrev_i32_e32 v1, 6, v0
	s_nop 0
	v_add_u32_e32 v68, s0, v1
	v_cmp_gt_i32_e32 vcc, s80, v68
	s_and_saveexec_b64 s[8:9], vcc
	s_cbranch_execz .LBB0_759
	v_and_b32_e32 v66, 63, v0
	v_lshlrev_b32_e32 v96, 5, v66
	v_readlane_b32 s4, v255, 46
	v_readlane_b32 s5, v255, 47
	v_lshl_add_u64 v[8:9], s[6:7], 0, v[96:97]
	s_nop 3
	global_load_dwordx4 v[4:7], v96, s[4:5] offset:16
	global_load_dwordx4 v[0:3], v96, s[4:5]
	v_readlane_b32 s0, v255, 44
	global_load_dwordx4 v[8:11], v[8:9], off
	v_readlane_b32 s1, v255, 45
	v_or_b32_e32 v16, 0x800, v96
	v_mov_b32_e32 v17, v97
	v_lshl_add_u64 v[20:21], s[0:1], 0, v[96:97]
	v_lshl_add_u64 v[16:17], s[6:7], 0, v[16:17]
	v_or_b32_e32 v28, 0x1000, v96
	v_mov_b32_e32 v29, v97
	v_lshl_add_u64 v[24:25], s[6:7], 0, v[28:29]
	v_or_b32_e32 v60, 0x1800, v96
	v_mov_b32_e32 v61, v97
	v_lshl_add_u64 v[56:57], s[6:7], 0, v[60:61]
	s_mov_b64 s[10:11], 0
	s_waitcnt vmcnt(0) lgkmcnt(0)
	v_pk_add_f32 v[8:9], v[8:9], 1.0 op_sel_hi:[1,0]
	s_nop 0
	v_pk_mul_f32 v[34:35], v[0:1], v[8:9]
	v_or_b32_e32 v8, 16, v96
	v_mov_b32_e32 v9, v97
	v_pk_add_f32 v[10:11], v[10:11], 1.0 op_sel_hi:[1,0]
	v_lshl_add_u64 v[8:9], s[6:7], 0, v[8:9]
	v_pk_mul_f32 v[32:33], v[2:3], v[10:11]
	global_load_dwordx4 v[0:3], v[20:21], off
	s_nop 0
	global_load_dwordx4 v[8:11], v[8:9], off
	s_waitcnt vmcnt(0) lgkmcnt(0)
	v_pk_add_f32 v[10:11], v[10:11], 1.0 op_sel_hi:[1,0]
	v_pk_add_f32 v[8:9], v[8:9], 1.0 op_sel_hi:[1,0]
	v_pk_mul_f32 v[36:37], v[6:7], v[10:11]
	v_pk_mul_f32 v[38:39], v[4:5], v[8:9]
	global_load_dwordx4 v[4:7], v[20:21], off offset:16
	global_load_dwordx4 v[12:15], v96, s[4:5] offset:2064
	global_load_dwordx4 v[8:11], v96, s[4:5] offset:2048
	s_nop 0
	global_load_dwordx4 v[16:19], v[16:17], off
	s_waitcnt vmcnt(0) lgkmcnt(0)
	v_pk_add_f32 v[16:17], v[16:17], 1.0 op_sel_hi:[1,0]
	s_nop 0
	v_pk_mul_f32 v[42:43], v[8:9], v[16:17]
	v_or_b32_e32 v16, 0x810, v96
	v_mov_b32_e32 v17, v97
	v_pk_add_f32 v[18:19], v[18:19], 1.0 op_sel_hi:[1,0]
	v_lshl_add_u64 v[16:17], s[6:7], 0, v[16:17]
	v_pk_mul_f32 v[40:41], v[10:11], v[18:19]
	global_load_dwordx4 v[8:11], v[20:21], off offset:2048
	s_nop 0
	global_load_dwordx4 v[16:19], v[16:17], off
	s_waitcnt vmcnt(0) lgkmcnt(0)
	v_pk_add_f32 v[18:19], v[18:19], 1.0 op_sel_hi:[1,0]
	v_pk_add_f32 v[16:17], v[16:17], 1.0 op_sel_hi:[1,0]
	v_pk_mul_f32 v[44:45], v[14:15], v[18:19]
	v_pk_mul_f32 v[46:47], v[12:13], v[16:17]
	global_load_dwordx4 v[12:15], v[20:21], off offset:2064
	s_nop 0
	global_load_dwordx4 v[20:23], v28, s[4:5] offset:16
	global_load_dwordx4 v[16:19], v28, s[4:5]
	s_nop 0
	global_load_dwordx4 v[24:27], v[24:25], off
	s_waitcnt vmcnt(0) lgkmcnt(0)
	v_pk_add_f32 v[24:25], v[24:25], 1.0 op_sel_hi:[1,0]
	s_nop 0
	v_pk_mul_f32 v[50:51], v[16:17], v[24:25]
	v_lshl_add_u64 v[16:17], s[0:1], 0, v[28:29]
	v_or_b32_e32 v28, 0x1010, v96
	v_pk_add_f32 v[26:27], v[26:27], 1.0 op_sel_hi:[1,0]
	v_lshl_add_u64 v[24:25], s[6:7], 0, v[28:29]
	v_pk_mul_f32 v[48:49], v[18:19], v[26:27]
	global_load_dwordx4 v[24:27], v[24:25], off
	v_or_b32_e32 v96, 0x1810, v96
	global_load_dwordx4 v[16:19], v[16:17], off
	s_waitcnt vmcnt(0) lgkmcnt(0)
	v_pk_add_f32 v[24:25], v[24:25], 1.0 op_sel_hi:[1,0]
	v_pk_add_f32 v[26:27], v[26:27], 1.0 op_sel_hi:[1,0]
	v_pk_mul_f32 v[54:55], v[20:21], v[24:25]
	v_lshl_add_u64 v[20:21], s[0:1], 0, v[28:29]
	v_pk_mul_f32 v[52:53], v[22:23], v[26:27]
	global_load_dwordx4 v[20:23], v[20:21], off
	s_nop 0
	global_load_dwordx4 v[28:31], v60, s[4:5] offset:16
	global_load_dwordx4 v[24:27], v60, s[4:5]
	s_nop 0
	global_load_dwordx4 v[56:59], v[56:57], off
	s_waitcnt vmcnt(0) lgkmcnt(0)
	v_pk_add_f32 v[58:59], v[58:59], 1.0 op_sel_hi:[1,0]
	v_pk_add_f32 v[62:63], v[56:57], 1.0 op_sel_hi:[1,0]
	v_pk_mul_f32 v[56:57], v[26:27], v[58:59]
	v_pk_mul_f32 v[58:59], v[24:25], v[62:63]
	v_lshl_add_u64 v[24:25], s[0:1], 0, v[60:61]
	v_lshl_add_u64 v[60:61], s[6:7], 0, v[96:97]
	global_load_dwordx4 v[60:63], v[60:61], off
	s_waitcnt vmcnt(0) lgkmcnt(0)
	v_pk_add_f32 v[62:63], v[62:63], 1.0 op_sel_hi:[1,0]
	v_pk_add_f32 v[64:65], v[60:61], 1.0 op_sel_hi:[1,0]
	v_pk_mul_f32 v[60:61], v[30:31], v[62:63]
	v_pk_mul_f32 v[62:63], v[28:29], v[64:65]
	v_lshl_add_u64 v[28:29], s[0:1], 0, v[96:97]
	global_load_dwordx4 v[24:27], v[24:25], off
	v_lshlrev_b32_e32 v96, 4, v66
	global_load_dwordx4 v[28:31], v[28:29], off
	v_xor_b32_e32 v66, 1, v190
	v_cmp_lt_i32_e32 vcc, v66, v192
	s_mov_b64 s[0:1], 0x8400000
	v_lshl_add_u64 v[64:65], s[40:41], 0, v[96:97]
	v_cndmask_b32_e32 v66, v190, v66, vcc
	v_lshlrev_b32_e32 v98, 2, v66
	v_xor_b32_e32 v66, 2, v190
	v_cmp_lt_i32_e32 vcc, v66, v192
	s_nop 1
	v_cndmask_b32_e32 v66, v190, v66, vcc
	v_lshlrev_b32_e32 v99, 2, v66
	v_xor_b32_e32 v66, 4, v190
	v_cmp_lt_i32_e32 vcc, v66, v192
	s_nop 1
	v_cndmask_b32_e32 v66, v190, v66, vcc
	v_lshlrev_b32_e32 v100, 2, v66
	v_xor_b32_e32 v66, 8, v190
	v_cmp_lt_i32_e32 vcc, v66, v192
	s_nop 1
	v_cndmask_b32_e32 v66, v190, v66, vcc
	v_lshlrev_b32_e32 v101, 2, v66
	v_xor_b32_e32 v66, 16, v190
	v_cmp_lt_i32_e32 vcc, v66, v192
	s_nop 1
	v_cndmask_b32_e32 v66, v190, v66, vcc
	v_lshlrev_b32_e32 v102, 2, v66
	v_xor_b32_e32 v66, 32, v190
	v_cmp_lt_i32_e32 vcc, v66, v192
	s_nop 1
	v_cndmask_b32_e32 v66, v190, v66, vcc
	v_lshlrev_b32_e32 v103, 2, v66
	v_lshl_add_u64 v[66:67], s[28:29], 0, v[96:97]
	v_lshl_add_u64 v[66:67], v[66:67], 0, s[0:1]
; __device__ __forceinline__ float bflo(unsigned w) { return __uint_as_float(w << 16); }
; __device__ __forceinline__ float bfhi(unsigned w) { return __uint_as_float(w & 0xffff0000u); }
; template <bool XB16>
; __device__ __forceinline__ void modulate_phase(const void* xv, const float* nw, const float* modl, const float* adab, bf16_t* H, bool perm, int wid_s_, bf16_t* XRo) {
;     ...
;     for (int row = gw; row < S; row += 2 * NGW) {
;         const int row1 = row + NGW;
;         f32x4 v0[8], v1[8]; float s0 = 0.f, s1 = 0.f;
; #pragma unroll
;         for (int j = 0; j < 4; ++j) {
;             if (XB16) { const u32x4 a = ((const u32x4*)(xb + (size_t)row * D) + lane)[64 * j], b = ((const u32x4*)(xb + (size_t)row1 * D) + lane)[64 * j];
;                 v0[2 * j] = (f32x4){bflo(a.x), bfhi(a.x), bflo(a.y), bfhi(a.y)}; v0[2 * j + 1] = (f32x4){bflo(a.z), bfhi(a.z), bflo(a.w), bfhi(a.w)};
;                 v1[2 * j] = (f32x4){bflo(b.x), bfhi(b.x), bflo(b.y), bfhi(b.y)}; v1[2 * j + 1] = (f32x4){bflo(b.z), bfhi(b.z), bflo(b.w), bfhi(b.w)}; }
;             else { const f32x4* p0 = (const f32x4*)(x + (size_t)row * D + 512 * j + 8 * lane); const f32x4* p1 = (const f32x4*)(x + (size_t)row1 * D + 512 * j + 8 * lane);
;                 v0[2 * j] = p0[0]; v0[2 * j + 1] = p0[1]; v1[2 * j] = p1[0]; v1[2 * j + 1] = p1[1]; } }
; #pragma unroll
;         for (int j = 0; j < 8; ++j) { s0 += (v0[j][0] * v0[j][0] + v0[j][1] * v0[j][1]) + (v0[j][2] * v0[j][2] + v0[j][3] * v0[j][3]);
;                                       s1 += (v1[j][0] * v1[j][0] + v1[j][1] * v1[j][1]) + (v1[j][2] * v1[j][2] + v1[j][3] * v1[j][3]); }
.LBB0_758:
	v_add_u32_e32 v70, s92, v68
	v_ashrrev_i32_e32 v69, 31, v68
	v_lshlrev_b64 v[94:95], 12, v[68:69]
	v_ashrrev_i32_e32 v71, 31, v70
	v_lshl_add_u64 v[68:69], v[64:65], 0, v[94:95]
	v_lshlrev_b64 v[136:137], 12, v[70:71]
	v_lshl_add_u64 v[72:73], v[64:65], 0, v[136:137]
	global_load_dwordx4 v[104:107], v[68:69], off
	global_load_dwordx4 v[108:111], v[72:73], off
	global_load_dwordx4 v[112:115], v[68:69], off offset:1024
	global_load_dwordx4 v[116:119], v[72:73], off offset:1024
	global_load_dwordx4 v[120:123], v[68:69], off offset:2048
	global_load_dwordx4 v[124:127], v[72:73], off offset:2048
	global_load_dwordx4 v[128:131], v[68:69], off offset:3072
	global_load_dwordx4 v[132:135], v[72:73], off offset:3072
	v_lshl_add_u64 v[94:95], v[66:67], 0, v[94:95]
	s_waitcnt vmcnt(0) lgkmcnt(0)
	v_and_b32_e32 v139, 0xffff0000, v110
	v_and_b32_e32 v138, 0xffff0000, v108
	v_lshlrev_b32_e32 v84, 16, v121
	v_and_b32_e32 v85, 0xffff0000, v121
	v_lshlrev_b32_e32 v83, 16, v124
	v_and_b32_e32 v81, 0xffff0000, v124
	v_lshlrev_b32_e32 v78, 16, v125
	v_and_b32_e32 v79, 0xffff0000, v125
	v_lshlrev_b32_e32 v76, 16, v131
	v_and_b32_e32 v77, 0xffff0000, v131
	v_lshlrev_b32_e32 v121, 16, v106
	v_and_b32_e32 v125, 0xffff0000, v106
	v_and_b32_e32 v124, 0xffff0000, v104
	v_lshlrev_b32_e32 v131, 16, v107
	v_and_b32_e32 v107, 0xffff0000, v107
	v_and_b32_e32 v106, 0xffff0000, v105
	v_lshlrev_b32_e32 v89, 16, v120
	v_and_b32_e32 v87, 0xffff0000, v120
	v_lshlrev_b32_e32 v74, 16, v130
	v_and_b32_e32 v71, 0xffff0000, v130
	v_lshlrev_b32_e32 v68, 16, v134
	v_and_b32_e32 v69, 0xffff0000, v134
	v_lshlrev_b32_e32 v72, 16, v135
	v_and_b32_e32 v73, 0xffff0000, v135
	v_lshlrev_b32_e32 v120, 16, v104
	v_lshlrev_b32_e32 v130, 16, v105
	v_pk_mul_f32 v[104:105], v[124:125], v[124:125]
	v_pk_mul_f32 v[134:135], v[106:107], v[106:107]
	v_pk_fma_f32 v[104:105], v[120:121], v[120:121], v[104:105]
	v_pk_fma_f32 v[134:135], v[130:131], v[130:131], v[134:135]
	v_lshlrev_b32_e32 v141, 16, v111
	v_pk_add_f32 v[104:105], v[104:105], v[134:135]
	v_lshlrev_b32_e32 v135, 16, v110
	v_and_b32_e32 v111, 0xffff0000, v111
	v_and_b32_e32 v110, 0xffff0000, v109
	v_lshlrev_b32_e32 v134, 16, v108
	v_lshlrev_b32_e32 v140, 16, v109
	v_pk_mul_f32 v[108:109], v[138:139], v[138:139]
	v_pk_mul_f32 v[142:143], v[110:111], v[110:111]
	v_pk_fma_f32 v[108:109], v[134:135], v[134:135], v[108:109]
	v_pk_fma_f32 v[142:143], v[140:141], v[140:141], v[142:143]
	v_lshlrev_b32_e32 v92, 16, v114
	v_and_b32_e32 v93, 0xffff0000, v114
	v_pk_add_f32 v[108:109], v[108:109], v[142:143]
	v_lshlrev_b32_e32 v143, 16, v113
	v_lshlrev_b32_e32 v142, 16, v112
	v_and_b32_e32 v113, 0xffff0000, v113
	v_and_b32_e32 v112, 0xffff0000, v112
	v_pk_mul_f32 v[144:145], v[112:113], v[112:113]
	v_mul_f32_e32 v88, v92, v92
	v_mul_f32_e32 v114, v93, v93
	v_lshlrev_b32_e32 v150, 16, v115
	v_and_b32_e32 v151, 0xffff0000, v115
	v_mov_b32_e32 v115, v89
	v_pk_fma_f32 v[144:145], v[142:143], v[142:143], v[144:145]
	v_pk_add_f32 v[114:115], v[88:89], v[114:115]
	v_pk_mul_f32 v[154:155], v[88:89], v[88:89]
	v_mul_f32_e32 v80, v151, v151
	v_mul_f32_e32 v75, v87, v87
	v_mul_f32_e32 v86, v84, v84
	v_mul_f32_e32 v96, v85, v85
	v_mov_b32_e32 v115, v155
	v_pk_fma_f32 v[154:155], v[150:151], v[150:151], v[80:81] op_sel_hi:[1,1,0]
	v_pk_add_f32 v[104:105], v[104:105], v[104:105] op_sel:[0,1] op_sel_hi:[1,0]
	v_pk_add_f32 v[144:145], v[144:145], v[144:145] op_sel:[0,1] op_sel_hi:[1,0]
	v_lshlrev_b32_e32 v90, 16, v118
	v_and_b32_e32 v91, 0xffff0000, v118
	v_mov_b32_e32 v155, v75
	v_mov_b32_e32 v105, v86
	v_mov_b32_e32 v145, v96
	v_mul_f32_e32 v82, v90, v90
	v_mul_f32_e32 v118, v91, v91
	v_lshlrev_b32_e32 v152, 16, v119
	v_and_b32_e32 v153, 0xffff0000, v119
	v_pk_add_f32 v[114:115], v[114:115], v[154:155]
	v_pk_add_f32 v[104:105], v[104:105], v[144:145]
	v_mov_b32_e32 v119, v83
	v_lshlrev_b32_e32 v147, 16, v117
	v_lshlrev_b32_e32 v146, 16, v116
	v_and_b32_e32 v117, 0xffff0000, v117
	v_and_b32_e32 v116, 0xffff0000, v116
	v_pk_add_f32 v[104:105], v[114:115], v[104:105]
	v_pk_add_f32 v[114:115], v[82:83], v[118:119]
	v_pk_mul_f32 v[118:119], v[82:83], v[82:83]
	v_mul_f32_e32 v80, v153, v153
	v_pk_mul_f32 v[148:149], v[116:117], v[116:117]
	v_mul_f32_e32 v75, v81, v81
	v_mov_b32_e32 v115, v119
	v_pk_fma_f32 v[118:119], v[152:153], v[152:153], v[80:81] op_sel_hi:[1,1,0]
	v_pk_fma_f32 v[148:149], v[146:147], v[146:147], v[148:149]
	v_mov_b32_e32 v119, v75
	v_mul_f32_e32 v86, v78, v78
	v_mul_f32_e32 v88, v79, v79
	v_pk_add_f32 v[114:115], v[114:115], v[118:119]
	v_pk_add_f32 v[108:109], v[108:109], v[108:109] op_sel:[0,1] op_sel_hi:[1,0]
	v_pk_add_f32 v[118:119], v[148:149], v[148:149] op_sel:[0,1] op_sel_hi:[1,0]
	v_mov_b32_e32 v109, v86
	v_mov_b32_e32 v119, v88
	v_pk_add_f32 v[108:109], v[108:109], v[118:119]
	v_lshlrev_b32_e32 v148, 16, v126
	v_pk_add_f32 v[108:109], v[114:115], v[108:109]
	v_lshlrev_b32_e32 v114, 16, v122
	v_and_b32_e32 v115, 0xffff0000, v122
	v_mul_f32_e32 v80, v114, v114
	v_lshlrev_b32_e32 v122, 16, v123
	v_pk_fma_f32 v[118:119], v[114:115], v[114:115], v[80:81] op_sel_hi:[1,1,0]
	v_and_b32_e32 v123, 0xffff0000, v123
	v_mul_f32_e32 v80, v122, v122
	v_pk_fma_f32 v[144:145], v[122:123], v[122:123], v[80:81] op_sel_hi:[1,1,0]
	v_and_b32_e32 v149, 0xffff0000, v126
	v_mul_f32_e32 v80, v148, v148
	v_lshlrev_b32_e32 v126, 16, v127
	v_pk_fma_f32 v[154:155], v[148:149], v[148:149], v[80:81] op_sel_hi:[1,1,0]
	v_and_b32_e32 v127, 0xffff0000, v127
	v_mul_f32_e32 v80, v126, v126
	v_lshlrev_b32_e32 v158, 16, v128
	v_pk_fma_f32 v[156:157], v[126:127], v[126:127], v[80:81] op_sel_hi:[1,1,0]
	v_and_b32_e32 v159, 0xffff0000, v128
	v_mul_f32_e32 v80, v158, v158
	v_lshlrev_b32_e32 v128, 16, v129
	v_pk_fma_f32 v[160:161], v[158:159], v[158:159], v[80:81] op_sel_hi:[1,1,0]
	v_and_b32_e32 v129, 0xffff0000, v129
	v_mul_f32_e32 v80, v128, v128
	v_mov_b32_e32 v75, v119
	v_mov_b32_e32 v170, v74
	v_mov_b32_e32 v171, v145
	v_pk_add_f32 v[104:105], v[104:105], v[104:105] op_sel_hi:[0,1]
	v_pk_fma_f32 v[162:163], v[128:129], v[128:129], v[80:81] op_sel_hi:[1,1,0]
	v_pk_mul_f32 v[170:171], v[74:75], v[170:171]
	v_pk_add_f32 v[118:119], v[118:119], v[144:145]
	v_mul_f32_e32 v104, v71, v71
	v_mul_f32_e32 v160, v76, v76
	v_mul_f32_e32 v162, v77, v77
	v_mov_b32_e32 v171, v119
	v_pk_add_f32 v[104:105], v[170:171], v[104:105]
	v_pk_add_f32 v[118:119], v[160:161], v[162:163]
	v_lshlrev_b32_e32 v164, 16, v132
	v_pk_add_f32 v[104:105], v[104:105], v[118:119]
	v_and_b32_e32 v165, 0xffff0000, v132
	v_add_f32_e32 v75, v104, v105
	ds_bpermute_b32 v82, v98, v75
	v_mul_f32_e32 v80, v164, v164
	v_lshlrev_b32_e32 v132, 16, v133
	v_pk_fma_f32 v[166:167], v[164:165], v[164:165], v[80:81] op_sel_hi:[1,1,0]
	v_and_b32_e32 v133, 0xffff0000, v133
	s_waitcnt lgkmcnt(0)
; template <bool XB16>
; __device__ __forceinline__ void modulate_phase(const void* xv, const float* nw, const float* modl, const float* adab, bf16_t* H, bool perm, int wid_s_, bf16_t* XRo) {
;     ...
;         const float r0 = 1.0f / sqrtf(wave_sum(s0) * (1.f / D) + NORM_EPS), r1 = 1.0f / sqrtf(wave_sum(s1) * (1.f / D) + NORM_EPS);
;         const int o0 = perm ? ((row & 127) * 128 + (row >> 7)) : row, o1 = perm ? ((row1 & 127) * 128 + (row1 >> 7)) : row1;
;     ...
;         for (int j = 0; j < 4; ++j) { const f32x4 ya = v0[2 * j] * r0 * av[2 * j] + bv[2 * j], yb = v0[2 * j + 1] * r0 * av[2 * j + 1] + bv[2 * j + 1];
;             const f32x4 yc = v1[2 * j] * r1 * av[2 * j] + bv[2 * j], yd = v1[2 * j + 1] * r1 * av[2 * j + 1] + bv[2 * j + 1];
	v_add_f32_e32 v75, v75, v82
	ds_bpermute_b32 v82, v99, v75
	v_mul_f32_e32 v80, v132, v132
	v_pk_add_f32 v[108:109], v[108:109], v[108:109] op_sel_hi:[0,1]
	v_pk_fma_f32 v[168:169], v[132:133], v[132:133], v[80:81] op_sel_hi:[1,1,0]
	v_pk_add_f32 v[118:119], v[154:155], v[156:157]
	s_waitcnt lgkmcnt(0)
	v_add_f32_e32 v75, v75, v82
	ds_bpermute_b32 v82, v100, v75
	v_mul_f32_e32 v108, v69, v69
	v_mul_f32_e32 v166, v72, v72
	v_mul_f32_e32 v168, v73, v73
	v_mul_f32_e32 v104, v68, v68
	s_waitcnt lgkmcnt(0)
	v_add_f32_e32 v75, v75, v82
	ds_bpermute_b32 v82, v101, v75
	v_mov_b32_e32 v105, v119
	v_pk_add_f32 v[104:105], v[104:105], v[108:109]
	v_pk_add_f32 v[108:109], v[166:167], v[168:169]
	v_mov_b32_e32 v119, v106
	s_waitcnt lgkmcnt(0)
	v_add_f32_e32 v75, v75, v82
	ds_bpermute_b32 v82, v102, v75
	v_pk_add_f32 v[104:105], v[104:105], v[108:109]
	v_mov_b32_e32 v106, v131
	v_add_f32_e32 v80, v104, v105
	v_mov_b32_e32 v105, v124
	s_waitcnt lgkmcnt(0)
	v_add_f32_e32 v75, v75, v82
	ds_bpermute_b32 v82, v103, v75
	v_mov_b32_e32 v124, v121
	v_mov_b32_e32 v118, v130
	v_mov_b32_e32 v130, v140
	v_mov_b32_e32 v131, v110
	s_waitcnt lgkmcnt(0)
	v_add_f32_e32 v75, v75, v82
	v_fmamk_f32 v75, v75, 0x3a000000, v185
	v_cmp_gt_f32_e32 vcc, s36, v75
	v_mul_f32_e32 v82, 0x4f800000, v75
	v_mov_b32_e32 v110, v141
	v_cndmask_b32_e32 v75, v75, v82, vcc
	v_sqrt_f32_e32 v82, v75
	v_lshl_add_u64 v[108:109], v[66:67], 0, v[136:137]
	v_add_u32_e32 v86, -1, v82
	v_fma_f32 v88, -v86, v82, v75
	v_cmp_ge_f32_e64 s[0:1], 0, v88
	v_add_u32_e32 v88, 1, v82
	s_nop 0
	v_cndmask_b32_e64 v86, v82, v86, s[0:1]
	v_fma_f32 v82, -v88, v82, v75
	v_cmp_lt_f32_e64 s[0:1], 0, v82
	s_nop 1
	v_cndmask_b32_e64 v82, v86, v88, s[0:1]
	v_mul_f32_e32 v86, 0x37800000, v82
	v_cndmask_b32_e32 v82, v82, v86, vcc
	v_cmp_class_f32_e32 vcc, v75, v186
	s_nop 1
	v_cndmask_b32_e32 v75, v82, v75, vcc
	v_div_scale_f32 v82, s[0:1], v75, v75, 1.0
	v_rcp_f32_e32 v86, v82
	s_nop 0
	v_fma_f32 v88, -v82, v86, 1.0
	v_fmac_f32_e32 v86, v88, v86
	v_div_scale_f32 v88, vcc, 1.0, v75, 1.0
	v_mul_f32_e32 v96, v88, v86
	v_fma_f32 v104, -v82, v96, v88
	v_fmac_f32_e32 v96, v104, v86
	v_fma_f32 v82, -v82, v96, v88
	v_div_fmas_f32 v82, v82, v86, v96
	v_div_fixup_f32 v82, v82, v75, 1.0
	ds_bpermute_b32 v75, v98, v80
	v_pk_mul_f32 v[106:107], v[106:107], v[82:83] op_sel_hi:[1,0]
	v_pk_mul_f32 v[118:119], v[118:119], v[82:83] op_sel_hi:[1,0]
	v_pk_mul_f32 v[92:93], v[92:93], v[82:83] op_sel_hi:[1,0]
	v_pk_fma_f32 v[118:119], v[32:33], v[118:119], v[2:3]
	s_waitcnt lgkmcnt(0)
	v_add_f32_e32 v75, v80, v75
	ds_bpermute_b32 v80, v99, v75
	v_pk_fma_f32 v[92:93], v[46:47], v[92:93], v[12:13]
	v_pk_mul_f32 v[84:85], v[84:85], v[82:83] op_sel_hi:[1,0]
	v_cvt_pk_bf16_f32 v92, v92, v93
	v_pk_fma_f32 v[84:85], v[48:49], v[84:85], v[18:19]
	s_waitcnt lgkmcnt(0)
	v_add_f32_e32 v75, v75, v80
	ds_bpermute_b32 v80, v100, v75
	v_pk_mul_f32 v[76:77], v[76:77], v[82:83] op_sel_hi:[1,0]
	s_waitcnt lgkmcnt(0)
	v_add_f32_e32 v75, v75, v80
	ds_bpermute_b32 v80, v101, v75
	v_pk_fma_f32 v[76:77], v[60:61], v[76:77], v[30:31]
	s_waitcnt lgkmcnt(0)
	v_add_f32_e32 v75, v75, v80
	ds_bpermute_b32 v80, v102, v75
	s_waitcnt lgkmcnt(0)
	v_add_f32_e32 v75, v75, v80
	ds_bpermute_b32 v80, v103, v75
	s_waitcnt lgkmcnt(0)
; __device__ __forceinline__ unsigned cvtpk(float lo, float hi) { f32x2_t v = {lo, hi}; bf16x2_t b = __builtin_convertvector(v, bf16x2_t); return __builtin_bit_cast(unsigned, b); }
; template <bool XB16>
; __device__ __forceinline__ void modulate_phase(const void* xv, const float* nw, const float* modl, const float* adab, bf16_t* H, bool perm, int wid_s_, bf16_t* XRo) {
;     ...
;         const float r0 = 1.0f / sqrtf(wave_sum(s0) * (1.f / D) + NORM_EPS), r1 = 1.0f / sqrtf(wave_sum(s1) * (1.f / D) + NORM_EPS);
;         const int o0 = perm ? ((row & 127) * 128 + (row >> 7)) : row, o1 = perm ? ((row1 & 127) * 128 + (row1 >> 7)) : row1;
;         u32x4* p0 = (u32x4*)(H + (size_t)o0 * D) + lane; u32x4* p1 = (u32x4*)(H + (size_t)o1 * D) + lane;
;         if (!XB16) { u32x4* q0 = (u32x4*)(XRo + (size_t)row * D) + lane; u32x4* q1 = (u32x4*)(XRo + (size_t)row1 * D) + lane;
; #pragma unroll
;             for (int j = 0; j < 4; ++j) { u32x4 w; w.x = cvtpk(v0[2 * j][0], v0[2 * j][1]); w.y = cvtpk(v0[2 * j][2], v0[2 * j][3]); w.z = cvtpk(v0[2 * j + 1][0], v0[2 * j + 1][1]); w.w = cvtpk(v0[2 * j + 1][2], v0[2 * j + 1][3]); q0[64 * j] = w;
;                 w.x = cvtpk(v1[2 * j][0], v1[2 * j][1]); w.y = cvtpk(v1[2 * j][2], v1[2 * j][3]); w.z = cvtpk(v1[2 * j + 1][0], v1[2 * j + 1][1]); w.w = cvtpk(v1[2 * j + 1][2], v1[2 * j + 1][3]); q1[64 * j] = w; } }
; #pragma unroll
;         for (int j = 0; j < 4; ++j) { const f32x4 ya = v0[2 * j] * r0 * av[2 * j] + bv[2 * j], yb = v0[2 * j + 1] * r0 * av[2 * j + 1] + bv[2 * j + 1];
;             const f32x4 yc = v1[2 * j] * r1 * av[2 * j] + bv[2 * j], yd = v1[2 * j + 1] * r1 * av[2 * j + 1] + bv[2 * j + 1];
;             u32x4 w; w.x = cvtpk(ya[0], ya[1]); w.y = cvtpk(ya[2], ya[3]); w.z = cvtpk(yb[0], yb[1]); w.w = cvtpk(yb[2], yb[3]); p0[64 * j] = w;
;             w.x = cvtpk(yc[0], yc[1]); w.y = cvtpk(yc[2], yc[3]); w.z = cvtpk(yd[0], yd[1]); w.w = cvtpk(yd[2], yd[3]); p1[64 * j] = w; }
	v_add_f32_e32 v75, v75, v80
	v_fmamk_f32 v75, v75, 0x3a000000, v185
	v_cmp_gt_f32_e32 vcc, s36, v75
	v_mul_f32_e32 v80, 0x4f800000, v75
	s_nop 0
	v_cndmask_b32_e32 v75, v75, v80, vcc
	v_sqrt_f32_e32 v80, v75
	s_nop 0
	v_add_u32_e32 v86, -1, v80
	v_fma_f32 v88, -v86, v80, v75
	v_cmp_ge_f32_e64 s[0:1], 0, v88
	v_add_u32_e32 v88, 1, v80
	s_nop 0
	v_cndmask_b32_e64 v86, v80, v86, s[0:1]
	v_fma_f32 v80, -v88, v80, v75
	v_cmp_lt_f32_e64 s[0:1], 0, v80
	s_nop 1
	v_cndmask_b32_e64 v80, v86, v88, s[0:1]
	v_mul_f32_e32 v86, 0x37800000, v80
	v_cndmask_b32_e32 v80, v80, v86, vcc
	v_cmp_class_f32_e32 vcc, v75, v186
	s_nop 1
	v_cndmask_b32_e32 v75, v80, v75, vcc
	v_div_scale_f32 v80, s[0:1], v75, v75, 1.0
	v_rcp_f32_e32 v86, v80
	s_nop 0
	v_fma_f32 v88, -v80, v86, 1.0
	v_fmac_f32_e32 v86, v88, v86
	v_div_scale_f32 v88, vcc, 1.0, v75, 1.0
	v_mul_f32_e32 v96, v88, v86
	v_fma_f32 v104, -v80, v96, v88
	v_fmac_f32_e32 v96, v104, v86
	v_fma_f32 v80, -v80, v96, v88
	v_div_fmas_f32 v80, v80, v86, v96
	v_mov_b32_e32 v104, v120
	v_pk_mul_f32 v[120:121], v[124:125], v[82:83] op_sel_hi:[1,0]
	v_div_fixup_f32 v88, v80, v75, 1.0
	v_pk_mul_f32 v[104:105], v[104:105], v[82:83] op_sel_hi:[1,0]
	v_pk_fma_f32 v[124:125], v[36:37], v[106:107], v[6:7]
	v_pk_fma_f32 v[106:107], v[38:39], v[120:121], v[4:5]
	v_mov_b32_e32 v120, v134
	v_mov_b32_e32 v121, v138
	v_mov_b32_e32 v138, v135
	v_pk_fma_f32 v[104:105], v[34:35], v[104:105], v[0:1]
	v_pk_mul_f32 v[120:121], v[88:89], v[120:121] op_sel_hi:[0,1]
	v_pk_mul_f32 v[130:131], v[88:89], v[130:131] op_sel_hi:[0,1]
	v_pk_mul_f32 v[134:135], v[88:89], v[138:139] op_sel_hi:[0,1]
	v_pk_mul_f32 v[110:111], v[88:89], v[110:111] op_sel_hi:[0,1]
	v_pk_fma_f32 v[130:131], v[32:33], v[130:131], v[2:3]
	v_pk_fma_f32 v[120:121], v[34:35], v[120:121], v[0:1]
	v_pk_fma_f32 v[110:111], v[36:37], v[110:111], v[6:7]
	v_pk_fma_f32 v[134:135], v[38:39], v[134:135], v[4:5]
	v_cvt_pk_bf16_f32 v104, v104, v105
	v_cvt_pk_bf16_f32 v105, v118, v119
	v_cvt_pk_bf16_f32 v106, v106, v107
	v_cvt_pk_bf16_f32 v107, v124, v125
	global_store_dwordx4 v[94:95], v[104:107], off
	v_pk_mul_f32 v[90:91], v[88:89], v[90:91] op_sel_hi:[0,1]
	v_pk_mul_f32 v[118:119], v[88:89], v[152:153] op_sel_hi:[0,1]
	v_cvt_pk_bf16_f32 v104, v120, v121
	v_cvt_pk_bf16_f32 v105, v130, v131
	v_cvt_pk_bf16_f32 v106, v134, v135
	v_cvt_pk_bf16_f32 v107, v110, v111
	global_store_dwordx4 v[108:109], v[104:107], off
	v_pk_mul_f32 v[110:111], v[150:151], v[82:83] op_sel_hi:[1,0]
	v_pk_fma_f32 v[118:119], v[44:45], v[118:119], v[14:15]
	v_mov_b32_e32 v104, v142
	v_mov_b32_e32 v105, v112
	v_mov_b32_e32 v112, v143
	v_pk_mul_f32 v[104:105], v[82:83], v[104:105] op_sel_hi:[0,1]
	v_pk_mul_f32 v[106:107], v[82:83], v[112:113] op_sel_hi:[0,1]
	v_mov_b32_e32 v112, v146
	v_mov_b32_e32 v113, v116
	v_mov_b32_e32 v116, v147
	v_pk_fma_f32 v[106:107], v[40:41], v[106:107], v[10:11]
	v_pk_fma_f32 v[104:105], v[42:43], v[104:105], v[8:9]
	v_pk_fma_f32 v[110:111], v[44:45], v[110:111], v[14:15]
	v_pk_mul_f32 v[112:113], v[88:89], v[112:113] op_sel_hi:[0,1]
	v_pk_mul_f32 v[116:117], v[88:89], v[116:117] op_sel_hi:[0,1]
	v_pk_fma_f32 v[116:117], v[40:41], v[116:117], v[10:11]
	v_pk_fma_f32 v[112:113], v[42:43], v[112:113], v[8:9]
	v_pk_fma_f32 v[120:121], v[46:47], v[90:91], v[12:13]
	v_cvt_pk_bf16_f32 v90, v104, v105
	v_cvt_pk_bf16_f32 v91, v106, v107
	v_cvt_pk_bf16_f32 v93, v110, v111
	global_store_dwordx4 v[94:95], v[90:93], off offset:1024
	v_mov_b32_e32 v86, v89
	v_mov_b32_e32 v80, v83
	v_cvt_pk_bf16_f32 v90, v112, v113
	v_cvt_pk_bf16_f32 v91, v116, v117
	v_cvt_pk_bf16_f32 v92, v120, v121
	v_cvt_pk_bf16_f32 v93, v118, v119
	global_store_dwordx4 v[108:109], v[90:93], off offset:1024
	v_pk_mul_f32 v[86:87], v[86:87], v[82:83] op_sel_hi:[1,0]
	v_pk_mul_f32 v[80:81], v[88:89], v[80:81] op_sel_hi:[0,1]
	v_pk_mul_f32 v[90:91], v[82:83], v[114:115] op_sel_hi:[0,1]
	v_pk_mul_f32 v[92:93], v[82:83], v[122:123] op_sel_hi:[0,1]
	v_pk_mul_f32 v[78:79], v[88:89], v[78:79] op_sel_hi:[0,1]
	v_pk_fma_f32 v[86:87], v[50:51], v[86:87], v[16:17]
	v_pk_fma_f32 v[92:93], v[52:53], v[92:93], v[22:23]
	v_pk_fma_f32 v[90:91], v[54:55], v[90:91], v[20:21]
	v_pk_fma_f32 v[104:105], v[48:49], v[78:79], v[18:19]
	v_pk_fma_f32 v[106:107], v[50:51], v[80:81], v[16:17]
	v_pk_mul_f32 v[78:79], v[88:89], v[148:149] op_sel_hi:[0,1]
	v_pk_mul_f32 v[80:81], v[88:89], v[126:127] op_sel_hi:[0,1]
	v_pk_fma_f32 v[110:111], v[52:53], v[80:81], v[22:23]
	v_pk_fma_f32 v[112:113], v[54:55], v[78:79], v[20:21]
	v_cvt_pk_bf16_f32 v78, v86, v87
	v_cvt_pk_bf16_f32 v79, v84, v85
	v_cvt_pk_bf16_f32 v80, v90, v91
	v_cvt_pk_bf16_f32 v81, v92, v93
	global_store_dwordx4 v[94:95], v[78:81], off offset:2048
	v_mov_b32_e32 v75, v71
	v_pk_mul_f32 v[74:75], v[74:75], v[82:83] op_sel_hi:[1,0]
	v_cvt_pk_bf16_f32 v78, v106, v107
	v_cvt_pk_bf16_f32 v79, v104, v105
	v_cvt_pk_bf16_f32 v80, v112, v113
	v_cvt_pk_bf16_f32 v81, v110, v111
	global_store_dwordx4 v[108:109], v[78:81], off offset:2048
	v_pk_fma_f32 v[74:75], v[62:63], v[74:75], v[28:29]
	v_pk_mul_f32 v[68:69], v[88:89], v[68:69] op_sel_hi:[0,1]
	v_pk_mul_f32 v[78:79], v[82:83], v[158:159] op_sel_hi:[0,1]
	v_pk_mul_f32 v[80:81], v[82:83], v[128:129] op_sel_hi:[0,1]
	v_pk_fma_f32 v[80:81], v[56:57], v[80:81], v[26:27]
	v_pk_fma_f32 v[78:79], v[58:59], v[78:79], v[24:25]
	v_pk_mul_f32 v[72:73], v[88:89], v[72:73] op_sel_hi:[0,1]
	v_pk_fma_f32 v[86:87], v[60:61], v[72:73], v[30:31]
	v_pk_fma_f32 v[68:69], v[62:63], v[68:69], v[28:29]
	v_cvt_pk_bf16_f32 v72, v78, v79
	v_cvt_pk_bf16_f32 v73, v80, v81
	v_cvt_pk_bf16_f32 v74, v74, v75
	v_cvt_pk_bf16_f32 v75, v76, v77
	v_pk_mul_f32 v[82:83], v[88:89], v[164:165] op_sel_hi:[0,1]
	v_pk_mul_f32 v[84:85], v[88:89], v[132:133] op_sel_hi:[0,1]
	global_store_dwordx4 v[94:95], v[72:75], off offset:3072
	v_pk_fma_f32 v[84:85], v[56:57], v[84:85], v[26:27]
	v_pk_fma_f32 v[82:83], v[58:59], v[82:83], v[24:25]
	v_cvt_pk_bf16_f32 v74, v68, v69
	v_add_u32_e32 v68, s92, v70
	v_cmp_lt_i32_e32 vcc, s21, v68
	v_cvt_pk_bf16_f32 v72, v82, v83
	v_cvt_pk_bf16_f32 v73, v84, v85
	v_cvt_pk_bf16_f32 v75, v86, v87
	s_or_b64 s[10:11], vcc, s[10:11]
	global_store_dwordx4 v[108:109], v[72:75], off offset:3072
	s_andn2_b64 exec, exec, s[10:11]
	s_cbranch_execnz .LBB0_758

; template <bool XB16>
; __device__ __forceinline__ void modulate_phase(const void* xv, const float* nw, const float* modl, const float* adab, bf16_t* H, bool perm, int wid_s_, bf16_t* XRo) {
;     ...
;     const int tid = tid_, lane = tid & 63, wid = tid >> 6, gw = blockIdx.x * 8 + wid, NGW = gridDim.x * 8;
;     f32x4 av[8], bv[8];
; #pragma unroll
;     for (int j = 0; j < 4; ++j)
; #pragma unroll
;         for (int q = 0; q < 2; ++q) { const int col = 512 * j + 8 * lane + 4 * q;
;             av[2 * j + q] = *(const f32x4*)(nw + col) * (*(const f32x4*)(modl + 2048 + col) + 1.0f); bv[2 * j + q] = *(const f32x4*)(modl + col); }
.LBB0_760:
	s_andn2_b64 vcc, exec, s[0:1]
	v_readlane_b32 s92, v255, 24
	s_cbranch_vccnz .LBB0_765
	v_mbcnt_lo_u32_b32 v0, -1, 0
	v_mbcnt_hi_u32_b32 v0, -1, v0
	v_readlane_b32 s0, v254, 5
	s_nop 1
	v_add_u32_e32 v0, s0, v0
	v_readlane_b32 s0, v254, 47
	v_ashrrev_i32_e32 v1, 6, v0
	s_nop 0
	v_add_u32_e32 v136, s0, v1
	v_cmp_gt_i32_e32 vcc, s80, v136
	s_and_saveexec_b64 s[8:9], vcc
	s_mov_b64 s[10:11], 0x1800
	s_cbranch_execz .LBB0_764
	v_and_b32_e32 v48, 63, v0
	v_lshlrev_b32_e32 v96, 5, v48
	v_lshl_add_u64 v[0:1], s[6:7], 0, v[96:97]
	global_load_dwordx4 v[4:7], v[0:1], off
	v_readlane_b32 s4, v255, 46
	v_or_b32_e32 v0, 16, v96
	v_mov_b32_e32 v1, v97
	v_readlane_b32 s5, v255, 47
	v_lshl_add_u64 v[0:1], s[6:7], 0, v[0:1]
	s_nop 3
	global_load_dwordx4 v[8:11], v96, s[4:5] offset:16
	global_load_dwordx4 v[12:15], v96, s[4:5]
	global_load_dwordx4 v[16:19], v[0:1], off
	v_or_b32_e32 v0, 0x800, v96
	v_mov_b32_e32 v1, v97
	v_lshl_add_u64 v[0:1], s[6:7], 0, v[0:1]
	global_load_dwordx4 v[20:23], v[0:1], off
	v_or_b32_e32 v0, 0x810, v96
	v_mov_b32_e32 v1, v97
	v_lshl_add_u64 v[0:1], s[6:7], 0, v[0:1]
	global_load_dwordx4 v[24:27], v[0:1], off
	global_load_dwordx4 v[30:33], v96, s[4:5] offset:2048
	global_load_dwordx4 v[34:37], v96, s[4:5] offset:2064
	v_readlane_b32 s0, v255, 44
	v_mov_b32_e32 v43, v97
	v_readlane_b32 s1, v255, 45
	v_or_b32_e32 v42, 0x1000, v96
	v_mov_b32_e32 v45, v97
	v_lshl_add_u64 v[28:29], s[0:1], 0, v[96:97]
	v_or_b32_e32 v44, 0x1010, v96
	v_lshl_add_u64 v[46:47], s[6:7], 0, v[42:43]
	global_load_dwordx4 v[0:3], v[28:29], off
	global_load_dwordx4 v[38:41], v42, s[4:5]
	v_readlane_b32 s80, v254, 23
	v_readlane_b32 s81, v254, 24
	v_readlane_b32 s82, v254, 25
	v_readlane_b32 s83, v254, 26
	v_lshl_add_u64 v[130:131], s[80:81], 0, v[96:97]
	v_readlane_b32 s92, v254, 35
	v_readlane_b32 s93, v254, 36
	v_readlane_b32 s82, v255, 38
	v_readlane_b32 s92, v255, 24
	v_readlane_b32 s83, v255, 39
	v_readlane_b32 s93, v255, 35
	s_movk_i32 s80, 0x4000
	v_readlane_b32 s84, v254, 27
	v_readlane_b32 s85, v254, 28
	v_readlane_b32 s86, v254, 29
	v_readlane_b32 s87, v254, 30
	v_readlane_b32 s88, v254, 31
	v_readlane_b32 s89, v254, 32
	v_readlane_b32 s90, v254, 33
	v_readlane_b32 s91, v254, 34
	v_readlane_b32 s94, v254, 37
	v_readlane_b32 s95, v254, 38
	s_waitcnt vmcnt(0) lgkmcnt(0)
	v_pk_add_f32 v[6:7], v[6:7], 1.0 op_sel_hi:[1,0]
	v_pk_add_f32 v[4:5], v[4:5], 1.0 op_sel_hi:[1,0]
	v_pk_mul_f32 v[98:99], v[14:15], v[6:7]
	v_pk_add_f32 v[16:17], v[16:17], 1.0 op_sel_hi:[1,0]
	v_pk_mul_f32 v[100:101], v[12:13], v[4:5]
	v_pk_add_f32 v[18:19], v[18:19], 1.0 op_sel_hi:[1,0]
	global_load_dwordx4 v[12:15], v[46:47], off
	v_pk_mul_f32 v[104:105], v[8:9], v[16:17]
	v_lshl_add_u64 v[8:9], s[6:7], 0, v[44:45]
	v_pk_mul_f32 v[102:103], v[10:11], v[18:19]
	v_pk_add_f32 v[20:21], v[20:21], 1.0 op_sel_hi:[1,0]
	global_load_dwordx4 v[16:19], v[8:9], off
	v_pk_add_f32 v[10:11], v[22:23], 1.0 op_sel_hi:[1,0]
	v_pk_mul_f32 v[108:109], v[30:31], v[20:21]
	global_load_dwordx4 v[20:23], v42, s[4:5] offset:16
	v_pk_add_f32 v[24:25], v[24:25], 1.0 op_sel_hi:[1,0]
	v_mov_b32_e32 v31, v97
	v_pk_mul_f32 v[112:113], v[34:35], v[24:25]
	v_or_b32_e32 v30, 0x1800, v96
	v_lshl_add_u64 v[24:25], s[0:1], 0, v[44:45]
	global_load_dwordx4 v[4:7], v[28:29], off offset:2064
	v_pk_add_f32 v[26:27], v[26:27], 1.0 op_sel_hi:[1,0]
	v_pk_mul_f32 v[106:107], v[32:33], v[10:11]
	v_pk_mul_f32 v[110:111], v[36:37], v[26:27]
	s_waitcnt vmcnt(0) lgkmcnt(0)
	v_pk_add_f32 v[14:15], v[14:15], 1.0 op_sel_hi:[1,0]
	v_pk_add_f32 v[12:13], v[12:13], 1.0 op_sel_hi:[1,0]
	v_pk_mul_f32 v[114:115], v[40:41], v[14:15]
	v_pk_mul_f32 v[116:117], v[38:39], v[12:13]
	global_load_dwordx4 v[12:15], v[24:25], off
	v_pk_add_f32 v[18:19], v[18:19], 1.0 op_sel_hi:[1,0]
	v_pk_add_f32 v[16:17], v[16:17], 1.0 op_sel_hi:[1,0]
	v_lshl_add_u64 v[24:25], s[6:7], 0, v[30:31]
	v_pk_mul_f32 v[118:119], v[22:23], v[18:19]
	v_pk_mul_f32 v[120:121], v[20:21], v[16:17]
	global_load_dwordx4 v[20:23], v[24:25], off
	v_lshl_add_u64 v[8:9], s[0:1], 0, v[42:43]
	v_lshl_add_u64 v[16:17], s[0:1], 0, v[30:31]
	global_load_dwordx4 v[8:11], v[8:9], off
	s_waitcnt vmcnt(0) lgkmcnt(0)
	v_pk_add_f32 v[24:25], v[22:23], 1.0 op_sel_hi:[1,0]
	v_pk_add_f32 v[26:27], v[20:21], 1.0 op_sel_hi:[1,0]
	global_load_dwordx4 v[20:23], v30, s[4:5]
	s_waitcnt vmcnt(0)
	v_pk_mul_f32 v[124:125], v[20:21], v[26:27]
	v_mov_b32_e32 v21, v97
	v_or_b32_e32 v20, 0x1810, v96
	v_pk_mul_f32 v[122:123], v[22:23], v[24:25]
	v_lshl_add_u64 v[22:23], s[6:7], 0, v[20:21]
	v_lshl_add_u64 v[20:21], s[0:1], 0, v[20:21]
	global_load_dwordx4 v[16:19], v[16:17], off
	s_nop 0
	global_load_dwordx4 v[24:27], v[22:23], off
	s_nop 0
	global_load_dwordx4 v[20:23], v[20:21], off
	v_lshlrev_b32_e32 v96, 4, v48
	s_mov_b64 s[0:1], 0x8400000
	v_readlane_b32 s6, v255, 34
	s_waitcnt vmcnt(0) lgkmcnt(0)
	v_pk_add_f32 v[32:33], v[26:27], 1.0 op_sel_hi:[1,0]
	v_pk_add_f32 v[34:35], v[24:25], 1.0 op_sel_hi:[1,0]
	global_load_dwordx4 v[24:27], v30, s[4:5] offset:16
	s_mov_b64 s[4:5], 0
	s_waitcnt vmcnt(0)
	v_pk_mul_f32 v[128:129], v[24:25], v[34:35]
	v_xor_b32_e32 v24, 1, v190
	v_cmp_lt_i32_e32 vcc, v24, v192
	v_pk_mul_f32 v[126:127], v[26:27], v[32:33]
	s_nop 0
	v_cndmask_b32_e32 v24, v190, v24, vcc
	v_lshlrev_b32_e32 v140, 2, v24
	v_xor_b32_e32 v24, 2, v190
	v_cmp_lt_i32_e32 vcc, v24, v192
	s_nop 1
	v_cndmask_b32_e32 v24, v190, v24, vcc
	v_lshlrev_b32_e32 v141, 2, v24
	v_xor_b32_e32 v24, 4, v190
	v_cmp_lt_i32_e32 vcc, v24, v192
	s_nop 1
	v_cndmask_b32_e32 v24, v190, v24, vcc
	v_lshlrev_b32_e32 v142, 2, v24
	v_xor_b32_e32 v24, 8, v190
	v_cmp_lt_i32_e32 vcc, v24, v192
	s_nop 1
	v_cndmask_b32_e32 v24, v190, v24, vcc
	v_lshlrev_b32_e32 v143, 2, v24
	v_xor_b32_e32 v24, 16, v190
	v_cmp_lt_i32_e32 vcc, v24, v192
	s_nop 1
	v_cndmask_b32_e32 v24, v190, v24, vcc
	v_lshlrev_b32_e32 v144, 2, v24
	v_xor_b32_e32 v24, 32, v190
	v_cmp_lt_i32_e32 vcc, v24, v192
	s_nop 1
	v_cndmask_b32_e32 v24, v190, v24, vcc
	v_lshlrev_b32_e32 v145, 2, v24
	v_lshl_add_u64 v[24:25], s[28:29], 0, v[96:97]
	v_lshl_add_u64 v[132:133], v[24:25], 0, s[0:1]
	global_load_dwordx4 v[24:27], v[28:29], off offset:16
	s_nop 0
	global_load_dwordx4 v[28:31], v[28:29], off offset:2048
	v_readlane_b32 s0, v255, 50
	v_readlane_b32 s1, v255, 51
	s_nop 1
	v_lshl_add_u64 v[134:135], s[0:1], 0, v[96:97]
; __device__ __forceinline__ float bflo(unsigned w) { return __uint_as_float(w << 16); }
; __device__ __forceinline__ float bfhi(unsigned w) { return __uint_as_float(w & 0xffff0000u); }
; template <bool XB16>
; __device__ __forceinline__ void modulate_phase(const void* xv, const float* nw, const float* modl, const float* adab, bf16_t* H, bool perm, int wid_s_, bf16_t* XRo) {
;     ...
;     for (int row = gw; row < S; row += 2 * NGW) {
;         const int row1 = row + NGW;
;         f32x4 v0[8], v1[8]; float s0 = 0.f, s1 = 0.f;
; #pragma unroll
;         for (int j = 0; j < 4; ++j) {
;             if (XB16) { const u32x4 a = ((const u32x4*)(xb + (size_t)row * D) + lane)[64 * j], b = ((const u32x4*)(xb + (size_t)row1 * D) + lane)[64 * j];
;                 v0[2 * j] = (f32x4){bflo(a.x), bfhi(a.x), bflo(a.y), bfhi(a.y)}; v0[2 * j + 1] = (f32x4){bflo(a.z), bfhi(a.z), bflo(a.w), bfhi(a.w)};
;                 v1[2 * j] = (f32x4){bflo(b.x), bfhi(b.x), bflo(b.y), bfhi(b.y)}; v1[2 * j + 1] = (f32x4){bflo(b.z), bfhi(b.z), bflo(b.w), bfhi(b.w)}; }
;             else { const f32x4* p0 = (const f32x4*)(x + (size_t)row * D + 512 * j + 8 * lane); const f32x4* p1 = (const f32x4*)(x + (size_t)row1 * D + 512 * j + 8 * lane);
;                 v0[2 * j] = p0[0]; v0[2 * j + 1] = p0[1]; v1[2 * j] = p1[0]; v1[2 * j + 1] = p1[1]; } }
; #pragma unroll
;         for (int j = 0; j < 8; ++j) { s0 += (v0[j][0] * v0[j][0] + v0[j][1] * v0[j][1]) + (v0[j][2] * v0[j][2] + v0[j][3] * v0[j][3]);
;                                       s1 += (v1[j][0] * v1[j][0] + v1[j][1] * v1[j][1]) + (v1[j][2] * v1[j][2] + v1[j][3] * v1[j][3]); }
.LBB0_763:
	v_add_u32_e32 v138, s6, v136
	v_ashrrev_i32_e32 v137, 31, v136
	v_lshlrev_b64 v[32:33], 13, v[136:137]
	v_ashrrev_i32_e32 v139, 31, v138
	v_lshl_add_u64 v[32:33], v[130:131], 0, v[32:33]
	v_lshlrev_b64 v[34:35], 13, v[138:139]
	v_lshl_add_u64 v[34:35], v[130:131], 0, v[34:35]
	global_load_dwordx4 v[92:95], v[32:33], off
	global_load_dwordx4 v[88:91], v[32:33], off offset:16
	global_load_dwordx4 v[84:87], v[34:35], off
	global_load_dwordx4 v[80:83], v[34:35], off offset:16
	global_load_dwordx4 v[76:79], v[32:33], off offset:2048
	global_load_dwordx4 v[72:75], v[32:33], off offset:2064
	global_load_dwordx4 v[68:71], v[34:35], off offset:2048
	global_load_dwordx4 v[64:67], v[34:35], off offset:2064
	v_add_co_u32_e32 v40, vcc, s12, v32
	v_lshl_add_u64 v[36:37], v[32:33], 0, s[14:15]
	s_nop 0
	v_addc_co_u32_e32 v41, vcc, 0, v33, vcc
	global_load_dwordx4 v[60:63], v[40:41], off
	global_load_dwordx4 v[56:59], v[36:37], off offset:16
	v_add_co_u32_e32 v36, vcc, s12, v34
	v_lshl_add_u64 v[38:39], v[34:35], 0, s[14:15]
	s_nop 0
	v_addc_co_u32_e32 v37, vcc, 0, v35, vcc
	global_load_dwordx4 v[52:55], v[36:37], off
	global_load_dwordx4 v[48:51], v[38:39], off offset:16
	v_lshl_add_u64 v[32:33], v[32:33], 0, s[10:11]
	v_lshl_add_u64 v[34:35], v[34:35], 0, s[10:11]
	global_load_dwordx4 v[44:47], v[40:41], off offset:2048
	s_nop 0
	global_load_dwordx4 v[40:43], v[32:33], off offset:16
	s_nop 0
	global_load_dwordx4 v[36:39], v[36:37], off offset:2048
	s_nop 0
	global_load_dwordx4 v[32:35], v[34:35], off offset:16
	v_lshlrev_b64 v[136:137], 12, v[136:137]
	s_waitcnt vmcnt(0)
	v_mov_b32_e32 v148, v93
	v_mov_b32_e32 v149, v89
	v_mov_b32_e32 v146, v92
	v_mov_b32_e32 v147, v88
	v_pk_mul_f32 v[148:149], v[148:149], v[148:149]
	v_mov_b32_e32 v150, v95
	v_mov_b32_e32 v151, v91
	v_pk_fma_f32 v[146:147], v[146:147], v[146:147], v[148:149]
	v_mov_b32_e32 v148, v94
	v_mov_b32_e32 v149, v90
	v_pk_mul_f32 v[150:151], v[150:151], v[150:151]
	v_mov_b32_e32 v152, v87
	v_pk_fma_f32 v[148:149], v[148:149], v[148:149], v[150:151]
	v_mov_b32_e32 v150, v85
	v_mov_b32_e32 v151, v81
	v_pk_add_f32 v[146:147], v[146:147], v[148:149]
	v_mov_b32_e32 v148, v84
	v_mov_b32_e32 v149, v80
	v_pk_mul_f32 v[150:151], v[150:151], v[150:151]
	v_mov_b32_e32 v153, v83
	v_pk_fma_f32 v[148:149], v[148:149], v[148:149], v[150:151]
	v_mov_b32_e32 v150, v86
	v_mov_b32_e32 v151, v82
	v_pk_mul_f32 v[152:153], v[152:153], v[152:153]
	v_mul_f32_e32 v96, v60, v60
	v_pk_fma_f32 v[150:151], v[150:151], v[150:151], v[152:153]
	v_pk_mul_f32 v[152:153], v[76:77], v[76:77]
	v_pk_add_f32 v[148:149], v[148:149], v[150:151]
	v_pk_mul_f32 v[150:151], v[78:79], v[78:79]
	v_pk_add_f32 v[146:147], v[146:147], v[146:147] op_sel:[0,1] op_sel_hi:[1,0]
	v_pk_mov_b32 v[154:155], v[152:153], v[150:151] op_sel:[1,0]
	v_mov_b32_e32 v153, v151
	v_pk_add_f32 v[150:151], v[154:155], v[152:153]
	v_pk_mul_f32 v[152:153], v[70:71], v[70:71]
	v_pk_mul_f32 v[154:155], v[68:69], v[68:69]
	v_pk_add_f32 v[150:151], v[150:151], v[150:151] op_sel:[0,1] op_sel_hi:[1,0]
	v_pk_mov_b32 v[156:157], v[154:155], v[152:153] op_sel:[1,0]
	v_mov_b32_e32 v155, v153
	v_pk_add_f32 v[152:153], v[156:157], v[154:155]
	v_mul_f32_e32 v154, v61, v61
	v_mov_b32_e32 v147, v96
	v_mov_b32_e32 v151, v154
	v_mul_f32_e32 v96, v73, v73
	v_mul_f32_e32 v155, v62, v62
	v_pk_add_f32 v[146:147], v[146:147], v[150:151]
	v_pk_fma_f32 v[150:151], v[72:73], v[72:73], v[96:97] op_sel_hi:[1,1,0]
	v_mul_f32_e32 v96, v75, v75
	v_mul_f32_e32 v156, v63, v63
	v_mov_b32_e32 v151, v155
	v_pk_fma_f32 v[154:155], v[74:75], v[74:75], v[96:97] op_sel_hi:[1,1,0]
	v_mul_f32_e32 v96, v52, v52
	v_mov_b32_e32 v155, v156
	v_pk_add_f32 v[150:151], v[150:151], v[154:155]
	v_mul_f32_e32 v154, v53, v53
	v_pk_add_f32 v[146:147], v[146:147], v[150:151]
	v_pk_add_f32 v[148:149], v[148:149], v[148:149] op_sel:[0,1] op_sel_hi:[1,0]
	v_pk_add_f32 v[150:151], v[152:153], v[152:153] op_sel:[0,1] op_sel_hi:[1,0]
	v_mov_b32_e32 v149, v96
	v_mov_b32_e32 v151, v154
	v_mul_f32_e32 v96, v65, v65
	v_pk_add_f32 v[148:149], v[148:149], v[150:151]
	v_pk_fma_f32 v[150:151], v[64:65], v[64:65], v[96:97] op_sel_hi:[1,1,0]
	v_mul_f32_e32 v96, v67, v67
	v_mul_f32_e32 v155, v54, v54
	v_mul_f32_e32 v156, v55, v55
	v_pk_fma_f32 v[152:153], v[66:67], v[66:67], v[96:97] op_sel_hi:[1,1,0]
	v_mov_b32_e32 v151, v155
	v_mov_b32_e32 v153, v156
	v_pk_add_f32 v[150:151], v[150:151], v[152:153]
	v_pk_mul_f32 v[152:153], v[56:57], v[56:57]
	v_pk_add_f32 v[148:149], v[148:149], v[150:151]
	v_pk_mul_f32 v[150:151], v[58:59], v[58:59]
	v_mul_f32_e32 v96, v40, v40
	v_pk_mov_b32 v[154:155], v[152:153], v[150:151] op_sel:[1,0]
	v_mov_b32_e32 v153, v151
	v_pk_add_f32 v[150:151], v[154:155], v[152:153]
	v_pk_mul_f32 v[152:153], v[50:51], v[50:51]
	v_pk_mul_f32 v[154:155], v[48:49], v[48:49]
	v_pk_add_f32 v[146:147], v[146:147], v[146:147] op_sel:[0,1] op_sel_hi:[1,0]
	v_pk_mov_b32 v[156:157], v[154:155], v[152:153] op_sel:[1,0]
	v_mov_b32_e32 v155, v153
	v_pk_add_f32 v[152:153], v[156:157], v[154:155]
	v_mul_f32_e32 v154, v41, v41
	v_pk_add_f32 v[150:151], v[150:151], v[150:151] op_sel:[0,1] op_sel_hi:[1,0]
	v_mov_b32_e32 v147, v96
	v_mov_b32_e32 v151, v154
	v_mul_f32_e32 v96, v45, v45
	v_mul_f32_e32 v155, v42, v42
	v_pk_add_f32 v[146:147], v[146:147], v[150:151]
	v_pk_fma_f32 v[150:151], v[44:45], v[44:45], v[96:97] op_sel_hi:[1,1,0]
	v_mul_f32_e32 v96, v47, v47
	v_mul_f32_e32 v156, v43, v43
	v_mov_b32_e32 v151, v155
	v_pk_fma_f32 v[154:155], v[46:47], v[46:47], v[96:97] op_sel_hi:[1,1,0]
	v_mul_f32_e32 v96, v32, v32
	v_mov_b32_e32 v155, v156
	v_pk_add_f32 v[150:151], v[150:151], v[154:155]
	v_mul_f32_e32 v155, v35, v35
	v_pk_add_f32 v[146:147], v[146:147], v[150:151]
	v_mul_f32_e32 v150, v33, v33
	v_add_f32_e32 v154, v146, v147
	v_pk_add_f32 v[146:147], v[148:149], v[148:149] op_sel:[0,1] op_sel_hi:[1,0]
	v_pk_add_f32 v[148:149], v[152:153], v[152:153] op_sel:[0,1] op_sel_hi:[1,0]
	v_mov_b32_e32 v147, v96
	v_mov_b32_e32 v149, v150
	v_mul_f32_e32 v96, v37, v37
	v_mul_f32_e32 v151, v34, v34
	v_pk_add_f32 v[146:147], v[146:147], v[148:149]
	v_pk_fma_f32 v[148:149], v[36:37], v[36:37], v[96:97] op_sel_hi:[1,1,0]
	v_mul_f32_e32 v96, v39, v39
	v_mov_b32_e32 v149, v151
	v_pk_fma_f32 v[150:151], v[38:39], v[38:39], v[96:97] op_sel_hi:[1,1,0]
	ds_bpermute_b32 v96, v140, v154
	v_mov_b32_e32 v151, v155
	v_pk_add_f32 v[148:149], v[148:149], v[150:151]
	v_lshlrev_b64 v[152:153], 12, v[138:139]
	v_pk_add_f32 v[146:147], v[146:147], v[148:149]
	s_waitcnt lgkmcnt(0)
; __device__ __forceinline__ unsigned cvtpk(float lo, float hi) { f32x2_t v = {lo, hi}; bf16x2_t b = __builtin_convertvector(v, bf16x2_t); return __builtin_bit_cast(unsigned, b); }
; template <bool XB16>
; __device__ __forceinline__ void modulate_phase(const void* xv, const float* nw, const float* modl, const float* adab, bf16_t* H, bool perm, int wid_s_, bf16_t* XRo) {
;     ...
;         const float r0 = 1.0f / sqrtf(wave_sum(s0) * (1.f / D) + NORM_EPS), r1 = 1.0f / sqrtf(wave_sum(s1) * (1.f / D) + NORM_EPS);
;         const int o0 = perm ? ((row & 127) * 128 + (row >> 7)) : row, o1 = perm ? ((row1 & 127) * 128 + (row1 >> 7)) : row1;
;         u32x4* p0 = (u32x4*)(H + (size_t)o0 * D) + lane; u32x4* p1 = (u32x4*)(H + (size_t)o1 * D) + lane;
;         if (!XB16) { u32x4* q0 = (u32x4*)(XRo + (size_t)row * D) + lane; u32x4* q1 = (u32x4*)(XRo + (size_t)row1 * D) + lane;
; #pragma unroll
;             for (int j = 0; j < 4; ++j) { u32x4 w; w.x = cvtpk(v0[2 * j][0], v0[2 * j][1]); w.y = cvtpk(v0[2 * j][2], v0[2 * j][3]); w.z = cvtpk(v0[2 * j + 1][0], v0[2 * j + 1][1]); w.w = cvtpk(v0[2 * j + 1][2], v0[2 * j + 1][3]); q0[64 * j] = w;
;                 w.x = cvtpk(v1[2 * j][0], v1[2 * j][1]); w.y = cvtpk(v1[2 * j][2], v1[2 * j][3]); w.z = cvtpk(v1[2 * j + 1][0], v1[2 * j + 1][1]); w.w = cvtpk(v1[2 * j + 1][2], v1[2 * j + 1][3]); q1[64 * j] = w; } }
	v_add_f32_e32 v96, v154, v96
	v_add_f32_e32 v146, v146, v147
	ds_bpermute_b32 v147, v141, v96
	v_lshl_add_u64 v[154:155], v[134:135], 0, v[136:137]
	v_cvt_pk_bf16_f32 v150, v88, v89
	v_cvt_pk_bf16_f32 v151, v90, v91
	v_lshl_add_u64 v[156:157], v[134:135], 0, v[152:153]
	s_waitcnt lgkmcnt(0)
	v_add_f32_e32 v96, v96, v147
	ds_bpermute_b32 v147, v142, v96
	v_lshl_add_u64 v[136:137], v[132:133], 0, v[136:137]
	s_waitcnt lgkmcnt(0)
	v_add_f32_e32 v96, v96, v147
	ds_bpermute_b32 v147, v143, v96
	s_waitcnt lgkmcnt(0)
	v_add_f32_e32 v96, v96, v147
	ds_bpermute_b32 v147, v144, v96
	s_waitcnt lgkmcnt(0)
	v_add_f32_e32 v96, v96, v147
	ds_bpermute_b32 v147, v145, v96
	s_waitcnt lgkmcnt(0)
	v_add_f32_e32 v96, v96, v147
	v_fmamk_f32 v96, v96, 0x3a000000, v185
	v_cmp_gt_f32_e32 vcc, s36, v96
	v_mul_f32_e32 v147, 0x4f800000, v96
	s_nop 0
	v_cndmask_b32_e32 v96, v96, v147, vcc
	v_sqrt_f32_e32 v147, v96
	s_nop 0
	v_add_u32_e32 v148, -1, v147
	v_fma_f32 v149, -v148, v147, v96
	v_cmp_ge_f32_e64 s[0:1], 0, v149
	v_add_u32_e32 v149, 1, v147
	s_nop 0
	v_cndmask_b32_e64 v148, v147, v148, s[0:1]
	v_fma_f32 v147, -v149, v147, v96
	v_cmp_lt_f32_e64 s[0:1], 0, v147
	s_nop 1
	v_cndmask_b32_e64 v147, v148, v149, s[0:1]
	v_mul_f32_e32 v148, 0x37800000, v147
	v_cndmask_b32_e32 v147, v147, v148, vcc
	v_cmp_class_f32_e32 vcc, v96, v186
	s_nop 1
	v_cndmask_b32_e32 v96, v147, v96, vcc
	ds_bpermute_b32 v147, v140, v146
	s_waitcnt lgkmcnt(0)
	v_add_f32_e32 v146, v146, v147
	ds_bpermute_b32 v147, v141, v146
	s_waitcnt lgkmcnt(0)
	v_add_f32_e32 v146, v146, v147
	ds_bpermute_b32 v147, v142, v146
	s_waitcnt lgkmcnt(0)
	v_add_f32_e32 v146, v146, v147
	ds_bpermute_b32 v147, v143, v146
	s_waitcnt lgkmcnt(0)
	v_add_f32_e32 v146, v146, v147
	ds_bpermute_b32 v147, v144, v146
	s_waitcnt lgkmcnt(0)
	v_add_f32_e32 v146, v146, v147
	ds_bpermute_b32 v147, v145, v146
	s_waitcnt lgkmcnt(0)
	v_add_f32_e32 v146, v146, v147
	v_fmamk_f32 v146, v146, 0x3a000000, v185
	v_cmp_gt_f32_e32 vcc, s36, v146
	v_mul_f32_e32 v147, 0x4f800000, v146
	s_nop 0
	v_cndmask_b32_e32 v146, v146, v147, vcc
	v_sqrt_f32_e32 v147, v146
	s_nop 0
	v_add_u32_e32 v148, -1, v147
	v_fma_f32 v149, -v148, v147, v146
	v_cmp_ge_f32_e64 s[0:1], 0, v149
	v_add_u32_e32 v149, 1, v147
	s_nop 0
	v_cndmask_b32_e64 v148, v147, v148, s[0:1]
	v_fma_f32 v147, -v149, v147, v146
	v_cmp_lt_f32_e64 s[0:1], 0, v147
	s_nop 1
	v_cndmask_b32_e64 v147, v148, v149, s[0:1]
	v_mul_f32_e32 v148, 0x37800000, v147
	v_cndmask_b32_e32 v147, v147, v148, vcc
	v_cvt_pk_bf16_f32 v148, v92, v93
	v_cvt_pk_bf16_f32 v149, v94, v95
	global_store_dwordx4 v[154:155], v[148:151], off
	v_cmp_class_f32_e32 vcc, v146, v186
	v_div_scale_f32 v139, s[0:1], v96, v96, 1.0
	v_cvt_pk_bf16_f32 v148, v84, v85
	v_cvt_pk_bf16_f32 v149, v86, v87
	v_cvt_pk_bf16_f32 v150, v80, v81
	v_cvt_pk_bf16_f32 v151, v82, v83
	global_store_dwordx4 v[156:157], v[148:151], off
	v_cndmask_b32_e32 v146, v147, v146, vcc
	v_rcp_f32_e32 v147, v139
	v_cvt_pk_bf16_f32 v148, v76, v77
	v_cvt_pk_bf16_f32 v149, v78, v79
	v_cvt_pk_bf16_f32 v150, v72, v73
	v_cvt_pk_bf16_f32 v151, v74, v75
	global_store_dwordx4 v[154:155], v[148:151], off offset:1024
	s_nop 1
	v_cvt_pk_bf16_f32 v148, v68, v69
	v_cvt_pk_bf16_f32 v149, v70, v71
	v_cvt_pk_bf16_f32 v150, v64, v65
	v_cvt_pk_bf16_f32 v151, v66, v67
	global_store_dwordx4 v[156:157], v[148:151], off offset:1024
	s_nop 1
	v_cvt_pk_bf16_f32 v148, v60, v61
	v_cvt_pk_bf16_f32 v149, v62, v63
	v_cvt_pk_bf16_f32 v150, v56, v57
	v_cvt_pk_bf16_f32 v151, v58, v59
	global_store_dwordx4 v[154:155], v[148:151], off offset:2048
	s_nop 1
	v_cvt_pk_bf16_f32 v148, v52, v53
	v_cvt_pk_bf16_f32 v149, v54, v55
	v_cvt_pk_bf16_f32 v150, v48, v49
	v_cvt_pk_bf16_f32 v151, v50, v51
	global_store_dwordx4 v[156:157], v[148:151], off offset:2048
	s_nop 1
	v_cvt_pk_bf16_f32 v148, v44, v45
	v_cvt_pk_bf16_f32 v149, v46, v47
	v_cvt_pk_bf16_f32 v150, v40, v41
	v_cvt_pk_bf16_f32 v151, v42, v43
	global_store_dwordx4 v[154:155], v[148:151], off offset:3072
	s_nop 1
	v_cvt_pk_bf16_f32 v148, v36, v37
	v_cvt_pk_bf16_f32 v149, v38, v39
	v_cvt_pk_bf16_f32 v150, v32, v33
	v_cvt_pk_bf16_f32 v151, v34, v35
	global_store_dwordx4 v[156:157], v[148:151], off offset:3072
	s_nop 1
	v_fma_f32 v148, -v139, v147, 1.0
	v_fmac_f32_e32 v147, v148, v147
	v_div_scale_f32 v148, vcc, 1.0, v96, 1.0
	v_mul_f32_e32 v149, v148, v147
	v_fma_f32 v150, -v139, v149, v148
	v_fmac_f32_e32 v149, v150, v147
	v_fma_f32 v139, -v139, v149, v148
	v_div_fmas_f32 v139, v139, v147, v149
	v_div_fixup_f32 v96, v139, v96, 1.0
	v_div_scale_f32 v139, s[0:1], v146, v146, 1.0
	v_rcp_f32_e32 v147, v139
	v_pk_mul_f32 v[92:93], v[92:93], v[96:97] op_sel_hi:[1,0]
	v_pk_mul_f32 v[94:95], v[94:95], v[96:97] op_sel_hi:[1,0]
	v_pk_mul_f32 v[88:89], v[88:89], v[96:97] op_sel_hi:[1,0]
	v_fma_f32 v148, -v139, v147, 1.0
	v_fmac_f32_e32 v147, v148, v147
	v_div_scale_f32 v148, vcc, 1.0, v146, 1.0
	v_mul_f32_e32 v149, v148, v147
	v_fma_f32 v150, -v139, v149, v148
	v_fmac_f32_e32 v149, v150, v147
	v_fma_f32 v139, -v139, v149, v148
	v_div_fmas_f32 v139, v139, v147, v149
	v_div_fixup_f32 v146, v139, v146, 1.0
	v_pk_mul_f32 v[90:91], v[90:91], v[96:97] op_sel_hi:[1,0]
; __device__ __forceinline__ unsigned cvtpk(float lo, float hi) { f32x2_t v = {lo, hi}; bf16x2_t b = __builtin_convertvector(v, bf16x2_t); return __builtin_bit_cast(unsigned, b); }
; template <bool XB16>
; __device__ __forceinline__ void modulate_phase(const void* xv, const float* nw, const float* modl, const float* adab, bf16_t* H, bool perm, int wid_s_, bf16_t* XRo) {
;     ...
; #pragma unroll
;         for (int j = 0; j < 4; ++j) { const f32x4 ya = v0[2 * j] * r0 * av[2 * j] + bv[2 * j], yb = v0[2 * j + 1] * r0 * av[2 * j + 1] + bv[2 * j + 1];
;             const f32x4 yc = v1[2 * j] * r1 * av[2 * j] + bv[2 * j], yd = v1[2 * j + 1] * r1 * av[2 * j + 1] + bv[2 * j + 1];
;             u32x4 w; w.x = cvtpk(ya[0], ya[1]); w.y = cvtpk(ya[2], ya[3]); w.z = cvtpk(yb[0], yb[1]); w.w = cvtpk(yb[2], yb[3]); p0[64 * j] = w;
;             w.x = cvtpk(yc[0], yc[1]); w.y = cvtpk(yc[2], yc[3]); w.z = cvtpk(yd[0], yd[1]); w.w = cvtpk(yd[2], yd[3]); p1[64 * j] = w; }
	v_pk_fma_f32 v[94:95], v[98:99], v[94:95], v[2:3]
	v_pk_fma_f32 v[92:93], v[100:101], v[92:93], v[0:1]
	v_pk_fma_f32 v[90:91], v[102:103], v[90:91], v[26:27]
	v_pk_fma_f32 v[88:89], v[104:105], v[88:89], v[24:25]
	v_pk_mul_f32 v[84:85], v[84:85], v[146:147] op_sel_hi:[1,0]
	v_pk_mul_f32 v[86:87], v[86:87], v[146:147] op_sel_hi:[1,0]
	v_pk_mul_f32 v[80:81], v[80:81], v[146:147] op_sel_hi:[1,0]
	v_pk_mul_f32 v[82:83], v[82:83], v[146:147] op_sel_hi:[1,0]
	v_lshl_add_u64 v[148:149], v[132:133], 0, v[152:153]
	v_pk_fma_f32 v[86:87], v[98:99], v[86:87], v[2:3]
	v_pk_fma_f32 v[84:85], v[100:101], v[84:85], v[0:1]
	v_pk_fma_f32 v[150:151], v[102:103], v[82:83], v[26:27]
	v_pk_fma_f32 v[152:153], v[104:105], v[80:81], v[24:25]
	v_cvt_pk_bf16_f32 v80, v92, v93
	v_cvt_pk_bf16_f32 v81, v94, v95
	v_cvt_pk_bf16_f32 v82, v88, v89
	v_cvt_pk_bf16_f32 v83, v90, v91
	v_pk_mul_f32 v[76:77], v[76:77], v[96:97] op_sel_hi:[1,0]
	v_pk_mul_f32 v[78:79], v[78:79], v[96:97] op_sel_hi:[1,0]
	v_pk_mul_f32 v[72:73], v[72:73], v[96:97] op_sel_hi:[1,0]
	v_pk_mul_f32 v[74:75], v[74:75], v[96:97] op_sel_hi:[1,0]
	global_store_dwordx4 v[136:137], v[80:83], off
	v_pk_fma_f32 v[78:79], v[106:107], v[78:79], v[30:31]
	v_pk_fma_f32 v[76:77], v[108:109], v[76:77], v[28:29]
	v_cvt_pk_bf16_f32 v80, v84, v85
	v_cvt_pk_bf16_f32 v81, v86, v87
	v_cvt_pk_bf16_f32 v82, v152, v153
	v_cvt_pk_bf16_f32 v83, v150, v151
	v_pk_fma_f32 v[74:75], v[110:111], v[74:75], v[6:7]
	v_pk_fma_f32 v[72:73], v[112:113], v[72:73], v[4:5]
	v_pk_mul_f32 v[68:69], v[68:69], v[146:147] op_sel_hi:[1,0]
	v_pk_mul_f32 v[70:71], v[70:71], v[146:147] op_sel_hi:[1,0]
	v_pk_mul_f32 v[64:65], v[64:65], v[146:147] op_sel_hi:[1,0]
	v_pk_mul_f32 v[66:67], v[66:67], v[146:147] op_sel_hi:[1,0]
	global_store_dwordx4 v[148:149], v[80:83], off
	v_pk_fma_f32 v[70:71], v[106:107], v[70:71], v[30:31]
	v_pk_fma_f32 v[68:69], v[108:109], v[68:69], v[28:29]
	v_pk_fma_f32 v[80:81], v[110:111], v[66:67], v[6:7]
	v_pk_fma_f32 v[82:83], v[112:113], v[64:65], v[4:5]
	v_cvt_pk_bf16_f32 v64, v76, v77
	v_cvt_pk_bf16_f32 v65, v78, v79
	v_cvt_pk_bf16_f32 v66, v72, v73
	v_cvt_pk_bf16_f32 v67, v74, v75
	v_pk_mul_f32 v[60:61], v[60:61], v[96:97] op_sel_hi:[1,0]
	v_pk_mul_f32 v[62:63], v[62:63], v[96:97] op_sel_hi:[1,0]
	v_pk_mul_f32 v[56:57], v[56:57], v[96:97] op_sel_hi:[1,0]
	v_pk_mul_f32 v[58:59], v[58:59], v[96:97] op_sel_hi:[1,0]
	global_store_dwordx4 v[136:137], v[64:67], off offset:1024
	v_pk_fma_f32 v[62:63], v[114:115], v[62:63], v[10:11]
	v_pk_fma_f32 v[60:61], v[116:117], v[60:61], v[8:9]
	v_cvt_pk_bf16_f32 v64, v68, v69
	v_cvt_pk_bf16_f32 v65, v70, v71
	v_cvt_pk_bf16_f32 v66, v82, v83
	v_cvt_pk_bf16_f32 v67, v80, v81
	v_pk_fma_f32 v[58:59], v[118:119], v[58:59], v[14:15]
	v_pk_fma_f32 v[56:57], v[120:121], v[56:57], v[12:13]
	v_pk_mul_f32 v[52:53], v[52:53], v[146:147] op_sel_hi:[1,0]
	v_pk_mul_f32 v[54:55], v[54:55], v[146:147] op_sel_hi:[1,0]
	v_pk_mul_f32 v[48:49], v[48:49], v[146:147] op_sel_hi:[1,0]
	v_pk_mul_f32 v[50:51], v[50:51], v[146:147] op_sel_hi:[1,0]
	global_store_dwordx4 v[148:149], v[64:67], off offset:1024
	v_pk_fma_f32 v[54:55], v[114:115], v[54:55], v[10:11]
	v_pk_fma_f32 v[52:53], v[116:117], v[52:53], v[8:9]
	v_pk_fma_f32 v[64:65], v[118:119], v[50:51], v[14:15]
	v_pk_fma_f32 v[66:67], v[120:121], v[48:49], v[12:13]
	v_cvt_pk_bf16_f32 v48, v60, v61
	v_cvt_pk_bf16_f32 v49, v62, v63
	v_cvt_pk_bf16_f32 v50, v56, v57
	v_cvt_pk_bf16_f32 v51, v58, v59
	v_pk_mul_f32 v[44:45], v[44:45], v[96:97] op_sel_hi:[1,0]
	v_pk_mul_f32 v[46:47], v[46:47], v[96:97] op_sel_hi:[1,0]
	v_pk_mul_f32 v[40:41], v[40:41], v[96:97] op_sel_hi:[1,0]
	v_pk_mul_f32 v[42:43], v[42:43], v[96:97] op_sel_hi:[1,0]
	global_store_dwordx4 v[136:137], v[48:51], off offset:2048
	v_pk_fma_f32 v[46:47], v[122:123], v[46:47], v[18:19]
	v_pk_fma_f32 v[44:45], v[124:125], v[44:45], v[16:17]
	v_cvt_pk_bf16_f32 v48, v52, v53
	v_cvt_pk_bf16_f32 v49, v54, v55
	v_cvt_pk_bf16_f32 v50, v66, v67
	v_cvt_pk_bf16_f32 v51, v64, v65
	v_pk_fma_f32 v[42:43], v[126:127], v[42:43], v[22:23]
	v_pk_fma_f32 v[40:41], v[128:129], v[40:41], v[20:21]
	v_pk_mul_f32 v[32:33], v[32:33], v[146:147] op_sel_hi:[1,0]
	v_pk_mul_f32 v[34:35], v[34:35], v[146:147] op_sel_hi:[1,0]
	global_store_dwordx4 v[148:149], v[48:51], off offset:2048
	v_pk_mul_f32 v[36:37], v[36:37], v[146:147] op_sel_hi:[1,0]
	v_pk_mul_f32 v[38:39], v[38:39], v[146:147] op_sel_hi:[1,0]
	v_pk_fma_f32 v[48:49], v[126:127], v[34:35], v[22:23]
	v_pk_fma_f32 v[50:51], v[128:129], v[32:33], v[20:21]
	v_cvt_pk_bf16_f32 v32, v44, v45
	v_cvt_pk_bf16_f32 v33, v46, v47
	v_cvt_pk_bf16_f32 v34, v40, v41
	v_cvt_pk_bf16_f32 v35, v42, v43
	global_store_dwordx4 v[136:137], v[32:35], off offset:3072
	v_add_u32_e32 v136, s6, v138
	v_pk_fma_f32 v[38:39], v[122:123], v[38:39], v[18:19]
	v_pk_fma_f32 v[36:37], v[124:125], v[36:37], v[16:17]
	v_cmp_lt_i32_e32 vcc, s21, v136
	v_cvt_pk_bf16_f32 v32, v36, v37
	v_cvt_pk_bf16_f32 v33, v38, v39
	v_cvt_pk_bf16_f32 v34, v50, v51
	v_cvt_pk_bf16_f32 v35, v48, v49
	s_or_b64 s[4:5], vcc, s[4:5]
	global_store_dwordx4 v[148:149], v[32:35], off offset:3072
	s_andn2_b64 exec, exec, s[4:5]
	s_cbranch_execnz .LBB0_763

; __device__ __forceinline__ unsigned cvtpk(float lo, float hi) { f32x2_t v = {lo, hi}; bf16x2_t b = __builtin_convertvector(v, bf16x2_t); return __builtin_bit_cast(unsigned, b); }
;     __device__ __forceinline__ void operator()(const f32x4 (&acc)[2][2][4][2], const Unit& u, int wr, int wc, int fr, int fq) const {
;     ...
;             for (int m = 0; m < 4; ++m) { const int row = row0 + ai * HALF + m * 16, jg = row >> 9, d = row & 511;
; #pragma unroll
;                 for (int bj = 0; bj < 2; ++bj) { const int n = col0 + bj * HALF, half = n >> 10;
;                     const f32x4 v0 = acc[ai][bj][m][0] * scale, v1 = acc[ai][bj][m][1] * scale;
;                     u32x4 w; w.x = cvtpk(v0[0], v0[1]); w.y = cvtpk(v0[2], v0[3]); w.z = cvtpk(v1[0], v1[1]); w.w = cvtpk(v1[2], v1[3]);
;                     *(u32x4*)(O + ((size_t)(jg * 2 + half) * 512 + d) * 1024 + (n & 1023)) = w; } }
.LBB0_792:
	s_lshl_b32 s8, s84, 8
	s_add_i32 s8, s8, s83
	v_or_b32_e32 v150, s8, v146
	s_ashr_i32 s8, s8, 8
	s_lshl_b32 s9, s90, 8
	s_ashr_i32 s18, s90, 2
	s_and_b32 s8, s8, -2
	s_and_b32 s9, s9, 0x300
	s_add_i32 s8, s8, s18
	v_or_b32_e32 v26, s9, v148
	s_ashr_i32 s9, s8, 31
	s_lshl_b64 s[8:9], s[8:9], 20
	s_add_u32 s8, s10, s8
	v_lshlrev_b32_e32 v24, 11, v150
	s_addc_u32 s9, s11, s9
	v_and_b32_e32 v96, 0xe7800, v24
	v_lshl_add_u64 v[24:25], s[8:9], 0, v[96:97]
	v_lshlrev_b32_e32 v96, 1, v26
	v_cvt_pk_bf16_f32 v16, v126, v127
	v_cvt_pk_bf16_f32 v17, v128, v129
	v_cvt_pk_bf16_f32 v18, v122, v123
	v_cvt_pk_bf16_f32 v19, v124, v125
	v_lshl_add_u64 v[26:27], v[24:25], 0, v[96:97]
	global_store_dwordx4 v[26:27], v[16:19], off
	s_mov_b64 s[8:9], 0x8000
	s_mov_b64 s[20:21], 0x10000
	v_cvt_pk_bf16_f32 v16, v144, v145
	v_cvt_pk_bf16_f32 v17, v142, v143
	v_cvt_pk_bf16_f32 v18, v154, v155
	v_cvt_pk_bf16_f32 v19, v152, v153
	global_store_dwordx4 v[26:27], v[16:19], off offset:256
	v_lshl_add_u64 v[26:27], v[24:25], 0, s[8:9]
	s_mov_b64 s[78:79], 0x18000
	v_cvt_pk_bf16_f32 v16, v104, v105
	v_cvt_pk_bf16_f32 v17, v102, v103
	v_cvt_pk_bf16_f32 v18, v112, v113
	v_cvt_pk_bf16_f32 v19, v110, v111
	v_lshl_add_u64 v[102:103], v[26:27], 0, v[96:97]
	global_store_dwordx4 v[102:103], v[16:19], off
	v_or_b32_e32 v102, 0x100, v96
	v_mov_b32_e32 v103, v97
	v_cvt_pk_bf16_f32 v16, v116, v117
	v_cvt_pk_bf16_f32 v17, v114, v115
	v_cvt_pk_bf16_f32 v18, v120, v121
	v_cvt_pk_bf16_f32 v19, v118, v119
	v_lshl_add_u64 v[26:27], v[26:27], 0, v[102:103]
	global_store_dwordx4 v[26:27], v[16:19], off
	v_lshl_add_u64 v[26:27], v[24:25], 0, s[20:21]
	v_lshl_add_u64 v[24:25], v[24:25], 0, s[78:79]
	v_cvt_pk_bf16_f32 v16, v86, v87
	v_cvt_pk_bf16_f32 v17, v84, v85
	v_cvt_pk_bf16_f32 v18, v94, v95
	v_cvt_pk_bf16_f32 v19, v92, v93
	v_lshl_add_u64 v[84:85], v[26:27], 0, v[96:97]
	global_store_dwordx4 v[84:85], v[16:19], off
	v_lshl_add_u64 v[26:27], v[26:27], 0, v[102:103]
	v_cvt_pk_bf16_f32 v4, v4, v5
	v_cvt_pk_bf16_f32 v16, v100, v101
	v_cvt_pk_bf16_f32 v17, v98, v99
	v_cvt_pk_bf16_f32 v18, v108, v109
	v_cvt_pk_bf16_f32 v19, v106, v107
	global_store_dwordx4 v[26:27], v[16:19], off
	v_lshl_add_u64 v[26:27], v[24:25], 0, v[96:97]
	v_lshl_add_u64 v[24:25], v[24:25], 0, v[102:103]
	v_cvt_pk_bf16_f32 v16, v74, v75
	v_cvt_pk_bf16_f32 v17, v72, v73
	v_cvt_pk_bf16_f32 v18, v78, v79
	v_cvt_pk_bf16_f32 v19, v76, v77
	global_store_dwordx4 v[26:27], v[16:19], off
	v_add_u32_e32 v26, 0x80, v150
	v_mov_b32_e32 v27, v97
	v_cvt_pk_bf16_f32 v16, v68, v69
	v_cvt_pk_bf16_f32 v17, v70, v71
	v_cvt_pk_bf16_f32 v18, v64, v65
	v_cvt_pk_bf16_f32 v19, v66, v67
	global_store_dwordx4 v[24:25], v[16:19], off
	v_cvt_pk_bf16_f32 v5, v6, v7
	v_cvt_pk_bf16_f32 v6, v0, v1
	v_ashrrev_i32_e32 v16, 8, v26
	v_and_b32_e32 v16, -2, v16
	v_add_u32_e32 v16, s18, v16
	v_ashrrev_i32_e32 v17, 31, v16
	v_lshlrev_b64 v[24:25], 20, v[16:17]
	v_lshlrev_b32_e32 v26, 11, v26
	v_lshl_add_u64 v[24:25], s[10:11], 0, v[24:25]
	v_and_b32_e32 v26, 0xe7800, v26
	v_lshl_add_u64 v[24:25], v[24:25], 0, v[26:27]
	v_cvt_pk_bf16_f32 v16, v60, v61
	v_cvt_pk_bf16_f32 v17, v62, v63
	v_cvt_pk_bf16_f32 v18, v56, v57
	v_cvt_pk_bf16_f32 v19, v58, v59
	v_lshl_add_u64 v[26:27], v[24:25], 0, v[96:97]
	global_store_dwordx4 v[26:27], v[16:19], off
	v_cvt_pk_bf16_f32 v7, v2, v3
	s_and_b64 vcc, exec, s[0:1]
	v_cvt_pk_bf16_f32 v16, v82, v83
	v_cvt_pk_bf16_f32 v17, v80, v81
	v_cvt_pk_bf16_f32 v18, v90, v91
	v_cvt_pk_bf16_f32 v19, v88, v89
	global_store_dwordx4 v[26:27], v[16:19], off offset:256
	v_lshl_add_u64 v[26:27], v[24:25], 0, s[8:9]
	s_mov_b64 s[0:1], -1
	v_cvt_pk_bf16_f32 v16, v38, v39
	v_cvt_pk_bf16_f32 v17, v36, v37
	v_cvt_pk_bf16_f32 v18, v46, v47
	v_cvt_pk_bf16_f32 v19, v44, v45
	v_lshl_add_u64 v[36:37], v[26:27], 0, v[96:97]
	global_store_dwordx4 v[36:37], v[16:19], off
	v_lshl_add_u64 v[26:27], v[26:27], 0, v[102:103]
	s_nop 0
	v_cvt_pk_bf16_f32 v16, v50, v51
	v_cvt_pk_bf16_f32 v17, v48, v49
	v_cvt_pk_bf16_f32 v18, v54, v55
	v_cvt_pk_bf16_f32 v19, v52, v53
	global_store_dwordx4 v[26:27], v[16:19], off
	s_nop 1
	v_cvt_pk_bf16_f32 v17, v20, v21
	v_lshl_add_u64 v[20:21], v[24:25], 0, s[20:21]
	v_cvt_pk_bf16_f32 v16, v22, v23
	v_cvt_pk_bf16_f32 v18, v30, v31
	v_cvt_pk_bf16_f32 v19, v28, v29
	v_lshl_add_u64 v[22:23], v[20:21], 0, v[96:97]
	global_store_dwordx4 v[22:23], v[16:19], off
	v_lshl_add_u64 v[20:21], v[20:21], 0, v[102:103]
	s_nop 0
	v_cvt_pk_bf16_f32 v16, v34, v35
	v_cvt_pk_bf16_f32 v17, v32, v33
	v_cvt_pk_bf16_f32 v18, v42, v43
	v_cvt_pk_bf16_f32 v19, v40, v41
	global_store_dwordx4 v[20:21], v[16:19], off
	s_nop 1
	v_cvt_pk_bf16_f32 v17, v8, v9
	v_lshl_add_u64 v[8:9], v[24:25], 0, s[78:79]
	v_cvt_pk_bf16_f32 v16, v10, v11
	v_cvt_pk_bf16_f32 v18, v14, v15
	v_cvt_pk_bf16_f32 v19, v12, v13
	v_lshl_add_u64 v[10:11], v[8:9], 0, v[96:97]
	v_lshl_add_u64 v[0:1], v[8:9], 0, v[102:103]
	global_store_dwordx4 v[10:11], v[16:19], off
	global_store_dwordx4 v[0:1], v[4:7], off
	s_cbranch_vccnz .LBB0_775
	s_andn2_b64 vcc, exec, s[94:95]
	s_cbranch_vccnz .LBB0_774
	s_barrier
	s_branch .LBB0_774

; __device__ __forceinline__ unsigned cvtpk(float lo, float hi) { f32x2_t v = {lo, hi}; bf16x2_t b = __builtin_convertvector(v, bf16x2_t); return __builtin_bit_cast(unsigned, b); }
; __device__ __forceinline__ float silu_f(float v) { return v * __builtin_amdgcn_rcpf(1.f + __builtin_amdgcn_exp2f(-LOG2E * v)); }
;     __device__ __forceinline__ void operator()(const f32x4 (&acc)[2][2][4][2], const Unit& u, int wr, int wc, int fr, int fq) const {
;     ...
;             for (int m = 0; m < 4; ++m) { bf16_t* rowp = O + (size_t)(row0 + ai * HALF + m * 16) * ldc + col0;
; #pragma unroll
;                 for (int bj = 0; bj < 2; ++bj) { f32x4 v0 = acc[ai][bj][m][0] * scale, v1 = acc[ai][bj][m][1] * scale;
;                     if (act) {
; #pragma unroll
;                         for (int i = 0; i < 4; ++i) { v0[i] = silu_f(v0[i]); v1[i] = silu_f(v1[i]); } }
;                     u32x4 w; w.x = cvtpk(v0[0], v0[1]); w.y = cvtpk(v0[2], v0[3]); w.z = cvtpk(v1[0], v1[1]); w.w = cvtpk(v1[2], v1[3]);
;                     *(u32x4*)(rowp + bj * HALF) = w; } }
.LBB0_895:
	s_sub_i32 s2, s84, s23
	v_lshl_add_u32 v96, s2, 8, v146
	v_lshl_or_b32 v98, s51, 8, v148
	v_mov_b64_e32 v[158:159], s[78:79]
	v_ashrrev_i32_e32 v99, 31, v98
	v_mad_i64_i32 v[158:159], s[2:3], v96, s33, v[158:159]
	v_lshl_add_u64 v[158:159], v[98:99], 1, v[158:159]
	v_cvt_pk_bf16_f32 v132, v132, v133
	v_cvt_pk_bf16_f32 v133, v134, v135
	v_cvt_pk_bf16_f32 v134, v136, v137
	v_cvt_pk_bf16_f32 v135, v138, v139
	global_store_dwordx4 v[158:159], v[132:135], off
	v_mov_b64_e32 v[138:139], v[110:111]
	s_andn2_b64 vcc, exec, s[18:19]
	v_cndmask_b32_e64 v132, 0, 1, s[18:19]
	v_cmp_ne_u32_e64 s[2:3], 1, v132
	v_mov_b64_e32 v[134:135], v[118:119]
	v_mov_b64_e32 v[132:133], v[116:117]
	v_mov_b64_e32 v[136:137], v[108:109]
	s_cbranch_vccnz .LBB0_897
	v_mul_f32_e32 v133, 0xbfb8aa3b, v108
	v_mul_f32_e32 v134, 0xbfb8aa3b, v117
	v_exp_f32_e32 v133, v133
	v_exp_f32_e32 v134, v134
	v_mul_f32_e32 v135, 0xbfb8aa3b, v118
	v_mul_f32_e32 v137, 0xbfb8aa3b, v110
	v_add_f32_e32 v133, 1.0, v133
	v_rcp_f32_e32 v136, v133
	v_add_f32_e32 v133, 1.0, v134
	v_mul_f32_e32 v134, 0xbfb8aa3b, v109
	v_exp_f32_e32 v134, v134
	v_exp_f32_e32 v135, v135
	v_exp_f32_e32 v137, v137
	v_mul_f32_e32 v132, 0xbfb8aa3b, v116
	v_add_f32_e32 v151, 1.0, v134
	v_add_f32_e32 v134, 1.0, v135
	v_add_f32_e32 v135, 1.0, v137
	v_mul_f32_e32 v137, 0xbfb8aa3b, v119
	v_mul_f32_e32 v138, 0xbfb8aa3b, v111
	v_exp_f32_e32 v132, v132
	v_exp_f32_e32 v137, v137
	v_exp_f32_e32 v139, v138
	v_rcp_f32_e32 v138, v135
	v_add_f32_e32 v132, 1.0, v132
	v_add_f32_e32 v135, 1.0, v137
	v_add_f32_e32 v137, 1.0, v139
	v_rcp_f32_e32 v132, v132
	v_rcp_f32_e32 v133, v133
	v_rcp_f32_e32 v134, v134
	v_rcp_f32_e32 v135, v135
	v_rcp_f32_e32 v139, v137
	v_rcp_f32_e32 v137, v151
	v_pk_mul_f32 v[132:133], v[116:117], v[132:133]
	v_pk_mul_f32 v[134:135], v[118:119], v[134:135]
	v_pk_mul_f32 v[138:139], v[110:111], v[138:139]
	v_pk_mul_f32 v[136:137], v[108:109], v[136:137]
.LBB0_897:
	v_cvt_pk_bf16_f32 v132, v132, v133
	v_cvt_pk_bf16_f32 v133, v134, v135
	v_cvt_pk_bf16_f32 v134, v136, v137
	v_cvt_pk_bf16_f32 v135, v138, v139
	global_store_dwordx4 v[158:159], v[132:135], off offset:256
	v_mov_b64_e32 v[138:139], v[114:115]
	s_and_b64 vcc, exec, s[2:3]
	v_mov_b64_e32 v[134:135], v[122:123]
	v_mov_b64_e32 v[132:133], v[120:121]
	v_mov_b64_e32 v[136:137], v[112:113]
	s_cbranch_vccnz .LBB0_899
	v_mul_f32_e32 v133, 0xbfb8aa3b, v112
	v_mul_f32_e32 v134, 0xbfb8aa3b, v121
	v_exp_f32_e32 v133, v133
	v_exp_f32_e32 v134, v134
	v_mul_f32_e32 v135, 0xbfb8aa3b, v122
	v_mul_f32_e32 v137, 0xbfb8aa3b, v114
	v_add_f32_e32 v133, 1.0, v133
	v_rcp_f32_e32 v136, v133
	v_add_f32_e32 v133, 1.0, v134
	v_mul_f32_e32 v134, 0xbfb8aa3b, v113
	v_exp_f32_e32 v134, v134
	v_exp_f32_e32 v135, v135
	v_exp_f32_e32 v137, v137
	v_mul_f32_e32 v132, 0xbfb8aa3b, v120
	v_add_f32_e32 v151, 1.0, v134
	v_add_f32_e32 v134, 1.0, v135
	v_add_f32_e32 v135, 1.0, v137
	v_mul_f32_e32 v137, 0xbfb8aa3b, v123
	v_mul_f32_e32 v138, 0xbfb8aa3b, v115
	v_exp_f32_e32 v132, v132
	v_exp_f32_e32 v137, v137
	v_exp_f32_e32 v139, v138
	v_rcp_f32_e32 v138, v135
	v_add_f32_e32 v132, 1.0, v132
	v_add_f32_e32 v135, 1.0, v137
	v_add_f32_e32 v137, 1.0, v139
	v_rcp_f32_e32 v132, v132
	v_rcp_f32_e32 v133, v133
	v_rcp_f32_e32 v134, v134
	v_rcp_f32_e32 v135, v135
	v_rcp_f32_e32 v139, v137
	v_rcp_f32_e32 v137, v151
	v_pk_mul_f32 v[132:133], v[120:121], v[132:133]
	v_pk_mul_f32 v[134:135], v[122:123], v[134:135]
	v_pk_mul_f32 v[138:139], v[114:115], v[138:139]
	v_pk_mul_f32 v[136:137], v[112:113], v[136:137]
.LBB0_899:
	v_or_b32_e32 v151, 16, v96
	v_mov_b64_e32 v[158:159], s[78:79]
	v_mad_i64_i32 v[158:159], s[18:19], v151, s33, v[158:159]
	v_lshl_add_u64 v[158:159], v[98:99], 1, v[158:159]
	v_cvt_pk_bf16_f32 v132, v132, v133
	v_cvt_pk_bf16_f32 v133, v134, v135
	v_cvt_pk_bf16_f32 v134, v136, v137
	v_cvt_pk_bf16_f32 v135, v138, v139
	global_store_dwordx4 v[158:159], v[132:135], off
	v_mov_b64_e32 v[138:139], v[90:91]
	s_and_b64 vcc, exec, s[2:3]
	v_mov_b64_e32 v[134:135], v[102:103]
	v_mov_b64_e32 v[132:133], v[100:101]
	v_mov_b64_e32 v[136:137], v[88:89]
	s_cbranch_vccnz .LBB0_901
	v_mul_f32_e32 v133, 0xbfb8aa3b, v88
	v_mul_f32_e32 v134, 0xbfb8aa3b, v101
	v_exp_f32_e32 v133, v133
	v_exp_f32_e32 v134, v134
	v_mul_f32_e32 v135, 0xbfb8aa3b, v102
	v_mul_f32_e32 v137, 0xbfb8aa3b, v90
	v_add_f32_e32 v133, 1.0, v133
	v_rcp_f32_e32 v136, v133
	v_add_f32_e32 v133, 1.0, v134
	v_mul_f32_e32 v134, 0xbfb8aa3b, v89
	v_exp_f32_e32 v134, v134
	v_exp_f32_e32 v135, v135
	v_exp_f32_e32 v137, v137
	v_mul_f32_e32 v132, 0xbfb8aa3b, v100
	v_add_f32_e32 v151, 1.0, v134
	v_add_f32_e32 v134, 1.0, v135
	v_add_f32_e32 v135, 1.0, v137
	v_mul_f32_e32 v137, 0xbfb8aa3b, v103
	v_mul_f32_e32 v138, 0xbfb8aa3b, v91
	v_exp_f32_e32 v132, v132
	v_exp_f32_e32 v137, v137
	v_exp_f32_e32 v139, v138
	v_rcp_f32_e32 v138, v135
	v_add_f32_e32 v132, 1.0, v132
	v_add_f32_e32 v135, 1.0, v137
	v_add_f32_e32 v137, 1.0, v139
	v_rcp_f32_e32 v132, v132
	v_rcp_f32_e32 v133, v133
	v_rcp_f32_e32 v134, v134
	v_rcp_f32_e32 v135, v135
	v_rcp_f32_e32 v139, v137
	v_rcp_f32_e32 v137, v151
	v_pk_mul_f32 v[132:133], v[100:101], v[132:133]
	v_pk_mul_f32 v[134:135], v[102:103], v[134:135]
	v_pk_mul_f32 v[138:139], v[90:91], v[138:139]
	v_pk_mul_f32 v[136:137], v[88:89], v[136:137]
; __device__ __forceinline__ unsigned cvtpk(float lo, float hi) { f32x2_t v = {lo, hi}; bf16x2_t b = __builtin_convertvector(v, bf16x2_t); return __builtin_bit_cast(unsigned, b); }
; __device__ __forceinline__ float silu_f(float v) { return v * __builtin_amdgcn_rcpf(1.f + __builtin_amdgcn_exp2f(-LOG2E * v)); }
;     __device__ __forceinline__ void operator()(const f32x4 (&acc)[2][2][4][2], const Unit& u, int wr, int wc, int fr, int fq) const {
;     ...
;             for (int m = 0; m < 4; ++m) { bf16_t* rowp = O + (size_t)(row0 + ai * HALF + m * 16) * ldc + col0;
; #pragma unroll
;                 for (int bj = 0; bj < 2; ++bj) { f32x4 v0 = acc[ai][bj][m][0] * scale, v1 = acc[ai][bj][m][1] * scale;
;                     if (act) {
; #pragma unroll
;                         for (int i = 0; i < 4; ++i) { v0[i] = silu_f(v0[i]); v1[i] = silu_f(v1[i]); } }
;                     u32x4 w; w.x = cvtpk(v0[0], v0[1]); w.y = cvtpk(v0[2], v0[3]); w.z = cvtpk(v1[0], v1[1]); w.w = cvtpk(v1[2], v1[3]);
;                     *(u32x4*)(rowp + bj * HALF) = w; } }
.LBB0_901:
	v_cvt_pk_bf16_f32 v132, v132, v133
	v_cvt_pk_bf16_f32 v133, v134, v135
	v_cvt_pk_bf16_f32 v134, v136, v137
	v_cvt_pk_bf16_f32 v135, v138, v139
	global_store_dwordx4 v[158:159], v[132:135], off offset:256
	v_mov_b64_e32 v[138:139], v[94:95]
	s_and_b64 vcc, exec, s[2:3]
	v_mov_b64_e32 v[134:135], v[106:107]
	v_mov_b64_e32 v[132:133], v[104:105]
	v_mov_b64_e32 v[136:137], v[92:93]
	s_cbranch_vccnz .LBB0_903
	v_mul_f32_e32 v133, 0xbfb8aa3b, v92
	v_mul_f32_e32 v134, 0xbfb8aa3b, v105
	v_exp_f32_e32 v133, v133
	v_exp_f32_e32 v134, v134
	v_mul_f32_e32 v135, 0xbfb8aa3b, v106
	v_mul_f32_e32 v137, 0xbfb8aa3b, v94
	v_add_f32_e32 v133, 1.0, v133
	v_rcp_f32_e32 v136, v133
	v_add_f32_e32 v133, 1.0, v134
	v_mul_f32_e32 v134, 0xbfb8aa3b, v93
	v_exp_f32_e32 v134, v134
	v_exp_f32_e32 v135, v135
	v_exp_f32_e32 v137, v137
	v_mul_f32_e32 v132, 0xbfb8aa3b, v104
	v_add_f32_e32 v151, 1.0, v134
	v_add_f32_e32 v134, 1.0, v135
	v_add_f32_e32 v135, 1.0, v137
	v_mul_f32_e32 v137, 0xbfb8aa3b, v107
	v_mul_f32_e32 v138, 0xbfb8aa3b, v95
	v_exp_f32_e32 v132, v132
	v_exp_f32_e32 v137, v137
	v_exp_f32_e32 v139, v138
	v_rcp_f32_e32 v138, v135
	v_add_f32_e32 v132, 1.0, v132
	v_add_f32_e32 v135, 1.0, v137
	v_add_f32_e32 v137, 1.0, v139
	v_rcp_f32_e32 v132, v132
	v_rcp_f32_e32 v133, v133
	v_rcp_f32_e32 v134, v134
	v_rcp_f32_e32 v135, v135
	v_rcp_f32_e32 v139, v137
	v_rcp_f32_e32 v137, v151
	v_pk_mul_f32 v[132:133], v[104:105], v[132:133]
	v_pk_mul_f32 v[134:135], v[106:107], v[134:135]
	v_pk_mul_f32 v[138:139], v[94:95], v[138:139]
	v_pk_mul_f32 v[136:137], v[92:93], v[136:137]
.LBB0_903:
	v_or_b32_e32 v151, 32, v96
	v_mov_b64_e32 v[158:159], s[78:79]
	v_mad_i64_i32 v[158:159], s[18:19], v151, s33, v[158:159]
	v_lshl_add_u64 v[158:159], v[98:99], 1, v[158:159]
	v_cvt_pk_bf16_f32 v132, v132, v133
	v_cvt_pk_bf16_f32 v133, v134, v135
	v_cvt_pk_bf16_f32 v134, v136, v137
	v_cvt_pk_bf16_f32 v135, v138, v139
	global_store_dwordx4 v[158:159], v[132:135], off
	v_mov_b64_e32 v[138:139], v[74:75]
	s_and_b64 vcc, exec, s[2:3]
	v_mov_b64_e32 v[134:135], v[82:83]
	v_mov_b64_e32 v[132:133], v[80:81]
	v_mov_b64_e32 v[136:137], v[72:73]
	s_cbranch_vccnz .LBB0_905
	v_mul_f32_e32 v133, 0xbfb8aa3b, v72
	v_mul_f32_e32 v134, 0xbfb8aa3b, v81
	v_exp_f32_e32 v133, v133
	v_exp_f32_e32 v134, v134
	v_mul_f32_e32 v135, 0xbfb8aa3b, v82
	v_mul_f32_e32 v137, 0xbfb8aa3b, v74
	v_add_f32_e32 v133, 1.0, v133
	v_rcp_f32_e32 v136, v133
	v_add_f32_e32 v133, 1.0, v134
	v_mul_f32_e32 v134, 0xbfb8aa3b, v73
	v_exp_f32_e32 v134, v134
	v_exp_f32_e32 v135, v135
	v_exp_f32_e32 v137, v137
	v_mul_f32_e32 v132, 0xbfb8aa3b, v80
	v_add_f32_e32 v151, 1.0, v134
	v_add_f32_e32 v134, 1.0, v135
	v_add_f32_e32 v135, 1.0, v137
	v_mul_f32_e32 v137, 0xbfb8aa3b, v83
	v_mul_f32_e32 v138, 0xbfb8aa3b, v75
	v_exp_f32_e32 v132, v132
	v_exp_f32_e32 v137, v137
	v_exp_f32_e32 v139, v138
	v_rcp_f32_e32 v138, v135
	v_add_f32_e32 v132, 1.0, v132
	v_add_f32_e32 v135, 1.0, v137
	v_add_f32_e32 v137, 1.0, v139
	v_rcp_f32_e32 v132, v132
	v_rcp_f32_e32 v133, v133
	v_rcp_f32_e32 v134, v134
	v_rcp_f32_e32 v135, v135
	v_rcp_f32_e32 v139, v137
	v_rcp_f32_e32 v137, v151
	v_pk_mul_f32 v[132:133], v[80:81], v[132:133]
	v_pk_mul_f32 v[134:135], v[82:83], v[134:135]
	v_pk_mul_f32 v[138:139], v[74:75], v[138:139]
	v_pk_mul_f32 v[136:137], v[72:73], v[136:137]
.LBB0_905:
	v_cvt_pk_bf16_f32 v132, v132, v133
	v_cvt_pk_bf16_f32 v133, v134, v135
	v_cvt_pk_bf16_f32 v134, v136, v137
	v_cvt_pk_bf16_f32 v135, v138, v139
	global_store_dwordx4 v[158:159], v[132:135], off offset:256
	v_mov_b64_e32 v[138:139], v[78:79]
	s_and_b64 vcc, exec, s[2:3]
	v_mov_b64_e32 v[134:135], v[86:87]
	v_mov_b64_e32 v[132:133], v[84:85]
	v_mov_b64_e32 v[136:137], v[76:77]
	s_cbranch_vccnz .LBB0_907
	v_mul_f32_e32 v133, 0xbfb8aa3b, v76
	v_mul_f32_e32 v134, 0xbfb8aa3b, v85
	v_exp_f32_e32 v133, v133
	v_exp_f32_e32 v134, v134
	v_mul_f32_e32 v135, 0xbfb8aa3b, v86
	v_mul_f32_e32 v137, 0xbfb8aa3b, v78
	v_add_f32_e32 v133, 1.0, v133
	v_rcp_f32_e32 v136, v133
	v_add_f32_e32 v133, 1.0, v134
	v_mul_f32_e32 v134, 0xbfb8aa3b, v77
	v_exp_f32_e32 v134, v134
	v_exp_f32_e32 v135, v135
	v_exp_f32_e32 v137, v137
	v_mul_f32_e32 v132, 0xbfb8aa3b, v84
	v_add_f32_e32 v151, 1.0, v134
	v_add_f32_e32 v134, 1.0, v135
	v_add_f32_e32 v135, 1.0, v137
	v_mul_f32_e32 v137, 0xbfb8aa3b, v87
	v_mul_f32_e32 v138, 0xbfb8aa3b, v79
	v_exp_f32_e32 v132, v132
	v_exp_f32_e32 v137, v137
	v_exp_f32_e32 v139, v138
	v_rcp_f32_e32 v138, v135
	v_add_f32_e32 v132, 1.0, v132
	v_add_f32_e32 v135, 1.0, v137
	v_add_f32_e32 v137, 1.0, v139
	v_rcp_f32_e32 v132, v132
	v_rcp_f32_e32 v133, v133
	v_rcp_f32_e32 v134, v134
	v_rcp_f32_e32 v135, v135
	v_rcp_f32_e32 v139, v137
	v_rcp_f32_e32 v137, v151
	v_pk_mul_f32 v[132:133], v[84:85], v[132:133]
	v_pk_mul_f32 v[134:135], v[86:87], v[134:135]
	v_pk_mul_f32 v[138:139], v[78:79], v[138:139]
	v_pk_mul_f32 v[136:137], v[76:77], v[136:137]
; __device__ __forceinline__ unsigned cvtpk(float lo, float hi) { f32x2_t v = {lo, hi}; bf16x2_t b = __builtin_convertvector(v, bf16x2_t); return __builtin_bit_cast(unsigned, b); }
; __device__ __forceinline__ float silu_f(float v) { return v * __builtin_amdgcn_rcpf(1.f + __builtin_amdgcn_exp2f(-LOG2E * v)); }
;     __device__ __forceinline__ void operator()(const f32x4 (&acc)[2][2][4][2], const Unit& u, int wr, int wc, int fr, int fq) const {
;     ...
;             for (int m = 0; m < 4; ++m) { bf16_t* rowp = O + (size_t)(row0 + ai * HALF + m * 16) * ldc + col0;
; #pragma unroll
;                 for (int bj = 0; bj < 2; ++bj) { f32x4 v0 = acc[ai][bj][m][0] * scale, v1 = acc[ai][bj][m][1] * scale;
;                     if (act) {
; #pragma unroll
;                         for (int i = 0; i < 4; ++i) { v0[i] = silu_f(v0[i]); v1[i] = silu_f(v1[i]); } }
;                     u32x4 w; w.x = cvtpk(v0[0], v0[1]); w.y = cvtpk(v0[2], v0[3]); w.z = cvtpk(v1[0], v1[1]); w.w = cvtpk(v1[2], v1[3]);
;                     *(u32x4*)(rowp + bj * HALF) = w; } }
.LBB0_907:
	v_or_b32_e32 v151, 48, v96
	v_mov_b64_e32 v[158:159], s[78:79]
	v_mad_i64_i32 v[158:159], s[18:19], v151, s33, v[158:159]
	v_lshl_add_u64 v[158:159], v[98:99], 1, v[158:159]
	v_cvt_pk_bf16_f32 v132, v132, v133
	v_cvt_pk_bf16_f32 v133, v134, v135
	v_cvt_pk_bf16_f32 v134, v136, v137
	v_cvt_pk_bf16_f32 v135, v138, v139
	global_store_dwordx4 v[158:159], v[132:135], off
	v_mov_b64_e32 v[138:139], v[66:67]
	s_and_b64 vcc, exec, s[2:3]
	v_mov_b64_e32 v[134:135], v[70:71]
	v_mov_b64_e32 v[132:133], v[68:69]
	v_mov_b64_e32 v[136:137], v[64:65]
	s_cbranch_vccnz .LBB0_909
	v_mul_f32_e32 v133, 0xbfb8aa3b, v64
	v_mul_f32_e32 v134, 0xbfb8aa3b, v69
	v_exp_f32_e32 v133, v133
	v_exp_f32_e32 v134, v134
	v_mul_f32_e32 v135, 0xbfb8aa3b, v70
	v_mul_f32_e32 v137, 0xbfb8aa3b, v66
	v_add_f32_e32 v133, 1.0, v133
	v_rcp_f32_e32 v136, v133
	v_add_f32_e32 v133, 1.0, v134
	v_mul_f32_e32 v134, 0xbfb8aa3b, v65
	v_exp_f32_e32 v134, v134
	v_exp_f32_e32 v135, v135
	v_exp_f32_e32 v137, v137
	v_mul_f32_e32 v132, 0xbfb8aa3b, v68
	v_add_f32_e32 v151, 1.0, v134
	v_add_f32_e32 v134, 1.0, v135
	v_add_f32_e32 v135, 1.0, v137
	v_mul_f32_e32 v137, 0xbfb8aa3b, v71
	v_mul_f32_e32 v138, 0xbfb8aa3b, v67
	v_exp_f32_e32 v132, v132
	v_exp_f32_e32 v137, v137
	v_exp_f32_e32 v139, v138
	v_rcp_f32_e32 v138, v135
	v_add_f32_e32 v132, 1.0, v132
	v_add_f32_e32 v135, 1.0, v137
	v_add_f32_e32 v137, 1.0, v139
	v_rcp_f32_e32 v132, v132
	v_rcp_f32_e32 v133, v133
	v_rcp_f32_e32 v134, v134
	v_rcp_f32_e32 v135, v135
	v_rcp_f32_e32 v139, v137
	v_rcp_f32_e32 v137, v151
	v_pk_mul_f32 v[132:133], v[68:69], v[132:133]
	v_pk_mul_f32 v[134:135], v[70:71], v[134:135]
	v_pk_mul_f32 v[138:139], v[66:67], v[138:139]
	v_pk_mul_f32 v[136:137], v[64:65], v[136:137]
.LBB0_909:
	v_cvt_pk_bf16_f32 v132, v132, v133
	v_cvt_pk_bf16_f32 v133, v134, v135
	v_cvt_pk_bf16_f32 v134, v136, v137
	v_cvt_pk_bf16_f32 v135, v138, v139
	global_store_dwordx4 v[158:159], v[132:135], off offset:256
	v_mov_b64_e32 v[138:139], v[58:59]
	s_and_b64 vcc, exec, s[2:3]
	v_mov_b64_e32 v[134:135], v[62:63]
	v_mov_b64_e32 v[132:133], v[60:61]
	v_mov_b64_e32 v[136:137], v[56:57]
	s_cbranch_vccnz .LBB0_911
	v_mul_f32_e32 v133, 0xbfb8aa3b, v56
	v_mul_f32_e32 v134, 0xbfb8aa3b, v61
	v_exp_f32_e32 v133, v133
	v_exp_f32_e32 v134, v134
	v_mul_f32_e32 v135, 0xbfb8aa3b, v62
	v_mul_f32_e32 v137, 0xbfb8aa3b, v58
	v_add_f32_e32 v133, 1.0, v133
	v_rcp_f32_e32 v136, v133
	v_add_f32_e32 v133, 1.0, v134
	v_mul_f32_e32 v134, 0xbfb8aa3b, v57
	v_exp_f32_e32 v134, v134
	v_exp_f32_e32 v135, v135
	v_exp_f32_e32 v137, v137
	v_mul_f32_e32 v132, 0xbfb8aa3b, v60
	v_add_f32_e32 v151, 1.0, v134
	v_add_f32_e32 v134, 1.0, v135
	v_add_f32_e32 v135, 1.0, v137
	v_mul_f32_e32 v137, 0xbfb8aa3b, v63
	v_mul_f32_e32 v138, 0xbfb8aa3b, v59
	v_exp_f32_e32 v132, v132
	v_exp_f32_e32 v137, v137
	v_exp_f32_e32 v139, v138
	v_rcp_f32_e32 v138, v135
	v_add_f32_e32 v132, 1.0, v132
	v_add_f32_e32 v135, 1.0, v137
	v_add_f32_e32 v137, 1.0, v139
	v_rcp_f32_e32 v132, v132
	v_rcp_f32_e32 v133, v133
	v_rcp_f32_e32 v134, v134
	v_rcp_f32_e32 v135, v135
	v_rcp_f32_e32 v139, v137
	v_rcp_f32_e32 v137, v151
	v_pk_mul_f32 v[132:133], v[60:61], v[132:133]
	v_pk_mul_f32 v[134:135], v[62:63], v[134:135]
	v_pk_mul_f32 v[138:139], v[58:59], v[138:139]
	v_pk_mul_f32 v[136:137], v[56:57], v[136:137]
.LBB0_911:
	v_add_u32_e32 v151, 0x80, v96
	v_mov_b64_e32 v[158:159], s[78:79]
	v_mad_i64_i32 v[158:159], s[18:19], v151, s33, v[158:159]
	v_lshl_add_u64 v[158:159], v[98:99], 1, v[158:159]
	v_cvt_pk_bf16_f32 v132, v132, v133
	v_cvt_pk_bf16_f32 v133, v134, v135
	v_cvt_pk_bf16_f32 v134, v136, v137
	v_cvt_pk_bf16_f32 v135, v138, v139
	global_store_dwordx4 v[158:159], v[132:135], off
	v_mov_b64_e32 v[138:139], v[42:43]
	s_and_b64 vcc, exec, s[2:3]
	v_mov_b64_e32 v[134:135], v[46:47]
	v_mov_b64_e32 v[132:133], v[44:45]
	v_mov_b64_e32 v[136:137], v[40:41]
	s_cbranch_vccnz .LBB0_913
	v_mul_f32_e32 v133, 0xbfb8aa3b, v40
	v_mul_f32_e32 v134, 0xbfb8aa3b, v45
	v_exp_f32_e32 v133, v133
	v_exp_f32_e32 v134, v134
	v_mul_f32_e32 v135, 0xbfb8aa3b, v46
	v_mul_f32_e32 v137, 0xbfb8aa3b, v42
	v_add_f32_e32 v133, 1.0, v133
	v_rcp_f32_e32 v136, v133
	v_add_f32_e32 v133, 1.0, v134
	v_mul_f32_e32 v134, 0xbfb8aa3b, v41
	v_exp_f32_e32 v134, v134
	v_exp_f32_e32 v135, v135
	v_exp_f32_e32 v137, v137
	v_mul_f32_e32 v132, 0xbfb8aa3b, v44
	v_add_f32_e32 v151, 1.0, v134
	v_add_f32_e32 v134, 1.0, v135
	v_add_f32_e32 v135, 1.0, v137
	v_mul_f32_e32 v137, 0xbfb8aa3b, v47
	v_mul_f32_e32 v138, 0xbfb8aa3b, v43
	v_exp_f32_e32 v132, v132
	v_exp_f32_e32 v137, v137
	v_exp_f32_e32 v139, v138
	v_rcp_f32_e32 v138, v135
	v_add_f32_e32 v132, 1.0, v132
	v_add_f32_e32 v135, 1.0, v137
	v_add_f32_e32 v137, 1.0, v139
	v_rcp_f32_e32 v132, v132
	v_rcp_f32_e32 v133, v133
	v_rcp_f32_e32 v134, v134
	v_rcp_f32_e32 v135, v135
	v_rcp_f32_e32 v139, v137
	v_rcp_f32_e32 v137, v151
	v_pk_mul_f32 v[132:133], v[44:45], v[132:133]
	v_pk_mul_f32 v[134:135], v[46:47], v[134:135]
	v_pk_mul_f32 v[138:139], v[42:43], v[138:139]
	v_pk_mul_f32 v[136:137], v[40:41], v[136:137]
; __device__ __forceinline__ unsigned cvtpk(float lo, float hi) { f32x2_t v = {lo, hi}; bf16x2_t b = __builtin_convertvector(v, bf16x2_t); return __builtin_bit_cast(unsigned, b); }
; __device__ __forceinline__ float silu_f(float v) { return v * __builtin_amdgcn_rcpf(1.f + __builtin_amdgcn_exp2f(-LOG2E * v)); }
;     __device__ __forceinline__ void operator()(const f32x4 (&acc)[2][2][4][2], const Unit& u, int wr, int wc, int fr, int fq) const {
;     ...
;             for (int m = 0; m < 4; ++m) { bf16_t* rowp = O + (size_t)(row0 + ai * HALF + m * 16) * ldc + col0;
; #pragma unroll
;                 for (int bj = 0; bj < 2; ++bj) { f32x4 v0 = acc[ai][bj][m][0] * scale, v1 = acc[ai][bj][m][1] * scale;
;                     if (act) {
; #pragma unroll
;                         for (int i = 0; i < 4; ++i) { v0[i] = silu_f(v0[i]); v1[i] = silu_f(v1[i]); } }
;                     u32x4 w; w.x = cvtpk(v0[0], v0[1]); w.y = cvtpk(v0[2], v0[3]); w.z = cvtpk(v1[0], v1[1]); w.w = cvtpk(v1[2], v1[3]);
;                     *(u32x4*)(rowp + bj * HALF) = w; } }
.LBB0_913:
	v_cvt_pk_bf16_f32 v132, v132, v133
	v_cvt_pk_bf16_f32 v133, v134, v135
	v_cvt_pk_bf16_f32 v134, v136, v137
	v_cvt_pk_bf16_f32 v135, v138, v139
	global_store_dwordx4 v[158:159], v[132:135], off offset:256
	v_mov_b64_e32 v[138:139], v[50:51]
	s_and_b64 vcc, exec, s[2:3]
	v_mov_b64_e32 v[134:135], v[54:55]
	v_mov_b64_e32 v[132:133], v[52:53]
	v_mov_b64_e32 v[136:137], v[48:49]
	s_cbranch_vccnz .LBB0_915
	v_mul_f32_e32 v133, 0xbfb8aa3b, v48
	v_mul_f32_e32 v134, 0xbfb8aa3b, v53
	v_exp_f32_e32 v133, v133
	v_exp_f32_e32 v134, v134
	v_mul_f32_e32 v135, 0xbfb8aa3b, v54
	v_mul_f32_e32 v137, 0xbfb8aa3b, v50
	v_add_f32_e32 v133, 1.0, v133
	v_rcp_f32_e32 v136, v133
	v_add_f32_e32 v133, 1.0, v134
	v_mul_f32_e32 v134, 0xbfb8aa3b, v49
	v_exp_f32_e32 v134, v134
	v_exp_f32_e32 v135, v135
	v_exp_f32_e32 v137, v137
	v_mul_f32_e32 v132, 0xbfb8aa3b, v52
	v_add_f32_e32 v151, 1.0, v134
	v_add_f32_e32 v134, 1.0, v135
	v_add_f32_e32 v135, 1.0, v137
	v_mul_f32_e32 v137, 0xbfb8aa3b, v55
	v_mul_f32_e32 v138, 0xbfb8aa3b, v51
	v_exp_f32_e32 v132, v132
	v_exp_f32_e32 v137, v137
	v_exp_f32_e32 v139, v138
	v_rcp_f32_e32 v138, v135
	v_add_f32_e32 v132, 1.0, v132
	v_add_f32_e32 v135, 1.0, v137
	v_add_f32_e32 v137, 1.0, v139
	v_rcp_f32_e32 v132, v132
	v_rcp_f32_e32 v133, v133
	v_rcp_f32_e32 v134, v134
	v_rcp_f32_e32 v135, v135
	v_rcp_f32_e32 v139, v137
	v_rcp_f32_e32 v137, v151
	v_pk_mul_f32 v[132:133], v[52:53], v[132:133]
	v_pk_mul_f32 v[134:135], v[54:55], v[134:135]
	v_pk_mul_f32 v[138:139], v[50:51], v[138:139]
	v_pk_mul_f32 v[136:137], v[48:49], v[136:137]
.LBB0_915:
	v_add_u32_e32 v151, 0x90, v96
	v_mov_b64_e32 v[158:159], s[78:79]
	v_mad_i64_i32 v[158:159], s[18:19], v151, s33, v[158:159]
	v_lshl_add_u64 v[158:159], v[98:99], 1, v[158:159]
	v_cvt_pk_bf16_f32 v132, v132, v133
	v_cvt_pk_bf16_f32 v133, v134, v135
	v_cvt_pk_bf16_f32 v134, v136, v137
	v_cvt_pk_bf16_f32 v135, v138, v139
	global_store_dwordx4 v[158:159], v[132:135], off
	v_mov_b64_e32 v[138:139], v[26:27]
	s_and_b64 vcc, exec, s[2:3]
	v_mov_b64_e32 v[134:135], v[30:31]
	v_mov_b64_e32 v[132:133], v[28:29]
	v_mov_b64_e32 v[136:137], v[24:25]
	s_cbranch_vccnz .LBB0_917
	v_mul_f32_e32 v133, 0xbfb8aa3b, v24
	v_mul_f32_e32 v134, 0xbfb8aa3b, v29
	v_exp_f32_e32 v133, v133
	v_exp_f32_e32 v134, v134
	v_mul_f32_e32 v135, 0xbfb8aa3b, v30
	v_mul_f32_e32 v137, 0xbfb8aa3b, v26
	v_add_f32_e32 v133, 1.0, v133
	v_rcp_f32_e32 v136, v133
	v_add_f32_e32 v133, 1.0, v134
	v_mul_f32_e32 v134, 0xbfb8aa3b, v25
	v_exp_f32_e32 v134, v134
	v_exp_f32_e32 v135, v135
	v_exp_f32_e32 v137, v137
	v_mul_f32_e32 v132, 0xbfb8aa3b, v28
	v_add_f32_e32 v151, 1.0, v134
	v_add_f32_e32 v134, 1.0, v135
	v_add_f32_e32 v135, 1.0, v137
	v_mul_f32_e32 v137, 0xbfb8aa3b, v31
	v_mul_f32_e32 v138, 0xbfb8aa3b, v27
	v_exp_f32_e32 v132, v132
	v_exp_f32_e32 v137, v137
	v_exp_f32_e32 v139, v138
	v_rcp_f32_e32 v138, v135
	v_add_f32_e32 v132, 1.0, v132
	v_add_f32_e32 v135, 1.0, v137
	v_add_f32_e32 v137, 1.0, v139
	v_rcp_f32_e32 v132, v132
	v_rcp_f32_e32 v133, v133
	v_rcp_f32_e32 v134, v134
	v_rcp_f32_e32 v135, v135
	v_rcp_f32_e32 v139, v137
	v_rcp_f32_e32 v137, v151
	v_pk_mul_f32 v[132:133], v[28:29], v[132:133]
	v_pk_mul_f32 v[134:135], v[30:31], v[134:135]
	v_pk_mul_f32 v[138:139], v[26:27], v[138:139]
	v_pk_mul_f32 v[136:137], v[24:25], v[136:137]
.LBB0_917:
	v_cvt_pk_bf16_f32 v132, v132, v133
	v_cvt_pk_bf16_f32 v133, v134, v135
	v_cvt_pk_bf16_f32 v134, v136, v137
	v_cvt_pk_bf16_f32 v135, v138, v139
	global_store_dwordx4 v[158:159], v[132:135], off offset:256
	v_mov_b64_e32 v[138:139], v[34:35]
	s_and_b64 vcc, exec, s[2:3]
	v_mov_b64_e32 v[134:135], v[38:39]
	v_mov_b64_e32 v[132:133], v[36:37]
	v_mov_b64_e32 v[136:137], v[32:33]
	s_cbranch_vccnz .LBB0_919
	v_mul_f32_e32 v133, 0xbfb8aa3b, v32
	v_mul_f32_e32 v134, 0xbfb8aa3b, v37
	v_exp_f32_e32 v133, v133
	v_exp_f32_e32 v134, v134
	v_mul_f32_e32 v135, 0xbfb8aa3b, v38
	v_mul_f32_e32 v137, 0xbfb8aa3b, v34
	v_add_f32_e32 v133, 1.0, v133
	v_rcp_f32_e32 v136, v133
	v_add_f32_e32 v133, 1.0, v134
	v_mul_f32_e32 v134, 0xbfb8aa3b, v33
	v_exp_f32_e32 v134, v134
	v_exp_f32_e32 v135, v135
	v_exp_f32_e32 v137, v137
	v_mul_f32_e32 v132, 0xbfb8aa3b, v36
	v_add_f32_e32 v151, 1.0, v134
	v_add_f32_e32 v134, 1.0, v135
	v_add_f32_e32 v135, 1.0, v137
	v_mul_f32_e32 v137, 0xbfb8aa3b, v39
	v_mul_f32_e32 v138, 0xbfb8aa3b, v35
	v_exp_f32_e32 v132, v132
	v_exp_f32_e32 v137, v137
	v_exp_f32_e32 v139, v138
	v_rcp_f32_e32 v138, v135
	v_add_f32_e32 v132, 1.0, v132
	v_add_f32_e32 v135, 1.0, v137
	v_add_f32_e32 v137, 1.0, v139
	v_rcp_f32_e32 v132, v132
	v_rcp_f32_e32 v133, v133
	v_rcp_f32_e32 v134, v134
	v_rcp_f32_e32 v135, v135
	v_rcp_f32_e32 v139, v137
	v_rcp_f32_e32 v137, v151
	v_pk_mul_f32 v[132:133], v[36:37], v[132:133]
	v_pk_mul_f32 v[134:135], v[38:39], v[134:135]
	v_pk_mul_f32 v[138:139], v[34:35], v[138:139]
	v_pk_mul_f32 v[136:137], v[32:33], v[136:137]
; __device__ __forceinline__ unsigned cvtpk(float lo, float hi) { f32x2_t v = {lo, hi}; bf16x2_t b = __builtin_convertvector(v, bf16x2_t); return __builtin_bit_cast(unsigned, b); }
; __device__ __forceinline__ float silu_f(float v) { return v * __builtin_amdgcn_rcpf(1.f + __builtin_amdgcn_exp2f(-LOG2E * v)); }
;     __device__ __forceinline__ void operator()(const f32x4 (&acc)[2][2][4][2], const Unit& u, int wr, int wc, int fr, int fq) const {
;     ...
;             for (int m = 0; m < 4; ++m) { bf16_t* rowp = O + (size_t)(row0 + ai * HALF + m * 16) * ldc + col0;
; #pragma unroll
;                 for (int bj = 0; bj < 2; ++bj) { f32x4 v0 = acc[ai][bj][m][0] * scale, v1 = acc[ai][bj][m][1] * scale;
;                     if (act) {
; #pragma unroll
;                         for (int i = 0; i < 4; ++i) { v0[i] = silu_f(v0[i]); v1[i] = silu_f(v1[i]); } }
;                     u32x4 w; w.x = cvtpk(v0[0], v0[1]); w.y = cvtpk(v0[2], v0[3]); w.z = cvtpk(v1[0], v1[1]); w.w = cvtpk(v1[2], v1[3]);
;                     *(u32x4*)(rowp + bj * HALF) = w; } }
.LBB0_919:
	v_add_u32_e32 v151, 0xa0, v96
	v_mov_b64_e32 v[158:159], s[78:79]
	v_mad_i64_i32 v[158:159], s[18:19], v151, s33, v[158:159]
	v_lshl_add_u64 v[158:159], v[98:99], 1, v[158:159]
	v_cvt_pk_bf16_f32 v132, v132, v133
	v_cvt_pk_bf16_f32 v133, v134, v135
	v_cvt_pk_bf16_f32 v134, v136, v137
	v_cvt_pk_bf16_f32 v135, v138, v139
	global_store_dwordx4 v[158:159], v[132:135], off
	v_mov_b64_e32 v[138:139], v[10:11]
	s_and_b64 vcc, exec, s[2:3]
	v_mov_b64_e32 v[134:135], v[14:15]
	v_mov_b64_e32 v[132:133], v[12:13]
	v_mov_b64_e32 v[136:137], v[8:9]
	s_cbranch_vccnz .LBB0_921
	v_mul_f32_e32 v133, 0xbfb8aa3b, v8
	v_mul_f32_e32 v134, 0xbfb8aa3b, v13
	v_exp_f32_e32 v133, v133
	v_exp_f32_e32 v134, v134
	v_mul_f32_e32 v135, 0xbfb8aa3b, v14
	v_mul_f32_e32 v137, 0xbfb8aa3b, v10
	v_add_f32_e32 v133, 1.0, v133
	v_rcp_f32_e32 v136, v133
	v_add_f32_e32 v133, 1.0, v134
	v_mul_f32_e32 v134, 0xbfb8aa3b, v9
	v_exp_f32_e32 v134, v134
	v_exp_f32_e32 v135, v135
	v_exp_f32_e32 v137, v137
	v_mul_f32_e32 v132, 0xbfb8aa3b, v12
	v_add_f32_e32 v151, 1.0, v134
	v_add_f32_e32 v134, 1.0, v135
	v_add_f32_e32 v135, 1.0, v137
	v_mul_f32_e32 v137, 0xbfb8aa3b, v15
	v_mul_f32_e32 v138, 0xbfb8aa3b, v11
	v_exp_f32_e32 v132, v132
	v_exp_f32_e32 v137, v137
	v_exp_f32_e32 v139, v138
	v_rcp_f32_e32 v138, v135
	v_add_f32_e32 v132, 1.0, v132
	v_add_f32_e32 v135, 1.0, v137
	v_add_f32_e32 v137, 1.0, v139
	v_rcp_f32_e32 v132, v132
	v_rcp_f32_e32 v133, v133
	v_rcp_f32_e32 v134, v134
	v_rcp_f32_e32 v135, v135
	v_rcp_f32_e32 v139, v137
	v_rcp_f32_e32 v137, v151
	v_pk_mul_f32 v[132:133], v[12:13], v[132:133]
	v_pk_mul_f32 v[134:135], v[14:15], v[134:135]
	v_pk_mul_f32 v[138:139], v[10:11], v[138:139]
	v_pk_mul_f32 v[136:137], v[8:9], v[136:137]
.LBB0_921:
	v_cvt_pk_bf16_f32 v132, v132, v133
	v_cvt_pk_bf16_f32 v133, v134, v135
	v_cvt_pk_bf16_f32 v134, v136, v137
	v_cvt_pk_bf16_f32 v135, v138, v139
	global_store_dwordx4 v[158:159], v[132:135], off offset:256
	v_mov_b64_e32 v[138:139], v[18:19]
	s_and_b64 vcc, exec, s[2:3]
	v_mov_b64_e32 v[134:135], v[22:23]
	v_mov_b64_e32 v[132:133], v[20:21]
	v_mov_b64_e32 v[136:137], v[16:17]
	s_cbranch_vccnz .LBB0_923
	v_mul_f32_e32 v133, 0xbfb8aa3b, v16
	v_mul_f32_e32 v134, 0xbfb8aa3b, v21
	v_exp_f32_e32 v133, v133
	v_exp_f32_e32 v134, v134
	v_mul_f32_e32 v135, 0xbfb8aa3b, v22
	v_mul_f32_e32 v137, 0xbfb8aa3b, v18
	v_add_f32_e32 v133, 1.0, v133
	v_rcp_f32_e32 v136, v133
	v_add_f32_e32 v133, 1.0, v134
	v_mul_f32_e32 v134, 0xbfb8aa3b, v17
	v_exp_f32_e32 v134, v134
	v_exp_f32_e32 v135, v135
	v_exp_f32_e32 v137, v137
	v_mul_f32_e32 v132, 0xbfb8aa3b, v20
	v_add_f32_e32 v151, 1.0, v134
	v_add_f32_e32 v134, 1.0, v135
	v_add_f32_e32 v135, 1.0, v137
	v_mul_f32_e32 v137, 0xbfb8aa3b, v23
	v_mul_f32_e32 v138, 0xbfb8aa3b, v19
	v_exp_f32_e32 v132, v132
	v_exp_f32_e32 v137, v137
	v_exp_f32_e32 v139, v138
	v_rcp_f32_e32 v138, v135
	v_add_f32_e32 v132, 1.0, v132
	v_add_f32_e32 v135, 1.0, v137
	v_add_f32_e32 v137, 1.0, v139
	v_rcp_f32_e32 v132, v132
	v_rcp_f32_e32 v133, v133
	v_rcp_f32_e32 v134, v134
	v_rcp_f32_e32 v135, v135
	v_rcp_f32_e32 v139, v137
	v_rcp_f32_e32 v137, v151
	v_pk_mul_f32 v[132:133], v[20:21], v[132:133]
	v_pk_mul_f32 v[134:135], v[22:23], v[134:135]
	v_pk_mul_f32 v[138:139], v[18:19], v[138:139]
	v_pk_mul_f32 v[136:137], v[16:17], v[136:137]
.LBB0_923:
	v_add_u32_e32 v96, 0xb0, v96
	v_mov_b64_e32 v[158:159], s[78:79]
	v_mad_i64_i32 v[158:159], s[18:19], v96, s33, v[158:159]
	v_lshl_add_u64 v[98:99], v[98:99], 1, v[158:159]
	v_cvt_pk_bf16_f32 v132, v132, v133
	v_cvt_pk_bf16_f32 v133, v134, v135
	v_cvt_pk_bf16_f32 v134, v136, v137
	v_cvt_pk_bf16_f32 v135, v138, v139
	global_store_dwordx4 v[98:99], v[132:135], off
	v_mov_b64_e32 v[138:139], v[2:3]
	s_and_b64 vcc, exec, s[2:3]
	v_mov_b64_e32 v[134:135], v[6:7]
	v_mov_b64_e32 v[136:137], v[0:1]
	v_mov_b64_e32 v[132:133], v[4:5]
	s_cbranch_vccnz .LBB0_925
	v_mul_f32_e32 v96, 0xbfb8aa3b, v4
	v_exp_f32_e32 v96, v96
	v_mul_f32_e32 v132, 0xbfb8aa3b, v0
	v_mul_f32_e32 v133, 0xbfb8aa3b, v5
	v_exp_f32_e32 v134, v132
	v_exp_f32_e32 v133, v133
	v_add_f32_e32 v96, 1.0, v96
	v_rcp_f32_e32 v132, v96
	v_add_f32_e32 v96, 1.0, v134
	v_rcp_f32_e32 v136, v96
	v_add_f32_e32 v96, 1.0, v133
	v_mul_f32_e32 v135, 0xbfb8aa3b, v2
	v_rcp_f32_e32 v133, v96
	v_mul_f32_e32 v96, 0xbfb8aa3b, v1
	v_mul_f32_e32 v134, 0xbfb8aa3b, v6
	v_exp_f32_e32 v135, v135
	v_mul_f32_e32 v137, 0xbfb8aa3b, v7
	v_mul_f32_e32 v138, 0xbfb8aa3b, v3
	v_exp_f32_e32 v96, v96
	v_exp_f32_e32 v134, v134
	v_exp_f32_e32 v137, v137
	v_exp_f32_e32 v139, v138
	v_add_f32_e32 v135, 1.0, v135
	v_add_f32_e32 v96, 1.0, v96
	v_add_f32_e32 v134, 1.0, v134
	v_rcp_f32_e32 v138, v135
	v_add_f32_e32 v135, 1.0, v137
	v_add_f32_e32 v137, 1.0, v139
	v_rcp_f32_e32 v134, v134
	v_rcp_f32_e32 v135, v135
	v_rcp_f32_e32 v139, v137
	v_rcp_f32_e32 v137, v96
	v_pk_mul_f32 v[132:133], v[4:5], v[132:133]
	v_pk_mul_f32 v[134:135], v[6:7], v[134:135]
	v_pk_mul_f32 v[138:139], v[2:3], v[138:139]
	v_pk_mul_f32 v[136:137], v[0:1], v[136:137]

; __device__ __forceinline__ unsigned cvtpk(float lo, float hi) { f32x2_t v = {lo, hi}; bf16x2_t b = __builtin_convertvector(v, bf16x2_t); return __builtin_bit_cast(unsigned, b); }
; __device__ __forceinline__ float silu_f(float v) { return v * __builtin_amdgcn_rcpf(1.f + __builtin_amdgcn_exp2f(-LOG2E * v)); }
;     __device__ __forceinline__ void operator()(const f32x4 (&acc)[2][2][4][2], const Unit& u, int wr, int wc, int fr, int fq) const {
;     ...
;             for (int m = 0; m < 4; ++m) { bf16_t* rowp = O + (size_t)(row0 + ai * HALF + m * 16) * ldc + col0;
; #pragma unroll
;                 for (int bj = 0; bj < 2; ++bj) { f32x4 v0 = acc[ai][bj][m][0] * scale, v1 = acc[ai][bj][m][1] * scale;
;                     if (act) {
; #pragma unroll
;                         for (int i = 0; i < 4; ++i) { v0[i] = silu_f(v0[i]); v1[i] = silu_f(v1[i]); } }
;                     u32x4 w; w.x = cvtpk(v0[0], v0[1]); w.y = cvtpk(v0[2], v0[3]); w.z = cvtpk(v1[0], v1[1]); w.w = cvtpk(v1[2], v1[3]);
;                     *(u32x4*)(rowp + bj * HALF) = w; } }
;     __device__ __forceinline__ void operator()(const f32x4 (&acc)[2][2][4][2], const Unit& u, int wr, int wc, int fr, int fq) const {
;         if (u.pm >= TH) { const Unit v{u.pm - TH, u.pn - pnA}; ea(acc, v, wr, wc, fr, fq); }
;         else { const Unit v{u.pm - pmB, u.pn - TH}; eb(acc, v, wr, wc, fr, fq); }
.LBB0_926:
	s_and_b64 vcc, exec, s[2:3]
	s_cbranch_vccz .LBB0_928
	s_sub_i32 s2, s51, s23
	v_lshl_or_b32 v98, s2, 8, v148
	v_lshl_add_u32 v132, s84, 8, v149
	v_ashrrev_i32_e32 v99, 31, v98
	v_ashrrev_i32_e32 v133, 31, v132
	v_readlane_b32 s2, v255, 52
	v_lshlrev_b64 v[136:137], 1, v[98:99]
	v_or_b32_e32 v98, 16, v132
	v_lshlrev_b64 v[134:135], 15, v[132:133]
	v_readlane_b32 s3, v255, 53
	v_ashrrev_i32_e32 v99, 31, v98
	v_lshlrev_b64 v[98:99], 15, v[98:99]
	v_lshl_add_u64 v[134:135], s[2:3], 0, v[134:135]
	v_lshl_add_u64 v[134:135], v[134:135], 0, v[136:137]
	v_cvt_pk_bf16_f32 v116, v116, v117
	v_cvt_pk_bf16_f32 v117, v118, v119
	v_cvt_pk_bf16_f32 v118, v108, v109
	v_cvt_pk_bf16_f32 v119, v110, v111
	v_lshl_add_u64 v[98:99], s[2:3], 0, v[98:99]
	global_store_dwordx4 v[134:135], v[116:119], off offset:256
	v_cvt_pk_bf16_f32 v80, v80, v81
	v_cvt_pk_bf16_f32 v81, v82, v83
	v_lshl_add_u64 v[116:117], v[98:99], 0, v[136:137]
	v_cvt_pk_bf16_f32 v98, v100, v101
	v_cvt_pk_bf16_f32 v100, v88, v89
	v_or_b32_e32 v88, 32, v132
	v_cvt_pk_bf16_f32 v82, v72, v73
	v_or_b32_e32 v72, 48, v132
	v_ashrrev_i32_e32 v89, 31, v88
	v_ashrrev_i32_e32 v73, 31, v72
	v_lshlrev_b64 v[88:89], 15, v[88:89]
	v_lshlrev_b64 v[72:73], 15, v[72:73]
	v_lshl_add_u64 v[88:89], s[2:3], 0, v[88:89]
	v_lshl_add_u64 v[72:73], s[2:3], 0, v[72:73]
	s_mov_b64 s[2:3], 0x400000
	v_cvt_pk_bf16_f32 v68, v68, v69
	v_cvt_pk_bf16_f32 v69, v70, v71
	v_cvt_pk_bf16_f32 v70, v64, v65
	v_lshl_add_u64 v[64:65], v[134:135], 0, s[2:3]
	s_mov_b32 s2, 0x400000
	v_cvt_pk_bf16_f32 v60, v60, v61
	v_cvt_pk_bf16_f32 v61, v62, v63
	v_cvt_pk_bf16_f32 v62, v56, v57
	v_add_co_u32_e32 v56, vcc, s2, v134
	v_cvt_pk_bf16_f32 v44, v44, v45
	v_cvt_pk_bf16_f32 v45, v46, v47
	v_cvt_pk_bf16_f32 v46, v40, v41
	v_cvt_pk_bf16_f32 v47, v42, v43
	s_mov_b64 s[2:3], 0x480000
	v_addc_co_u32_e32 v57, vcc, 0, v135, vcc
	global_store_dwordx4 v[64:65], v[44:47], off offset:256
	v_cvt_pk_bf16_f32 v28, v28, v29
	v_cvt_pk_bf16_f32 v29, v30, v31
	v_lshl_add_u64 v[44:45], v[134:135], 0, s[2:3]
	s_mov_b32 s2, 0x480000
	v_add_co_u32_e32 v46, vcc, s2, v134
	v_cvt_pk_bf16_f32 v30, v24, v25
	v_cvt_pk_bf16_f32 v31, v26, v27
	s_mov_b64 s[2:3], 0x500000
	v_addc_co_u32_e32 v47, vcc, 0, v135, vcc
	global_store_dwordx4 v[44:45], v[28:31], off offset:256
	v_cvt_pk_bf16_f32 v99, v102, v103
	v_cvt_pk_bf16_f32 v101, v90, v91
	v_lshl_add_u64 v[28:29], v[134:135], 0, s[2:3]
	s_mov_b32 s2, 0x500000
	v_add_co_u32_e32 v30, vcc, s2, v134
	v_cvt_pk_bf16_f32 v12, v12, v13
	s_nop 0
	v_addc_co_u32_e32 v31, vcc, 0, v135, vcc
	v_cvt_pk_bf16_f32 v13, v14, v15
	v_cvt_pk_bf16_f32 v14, v8, v9
	v_cvt_pk_bf16_f32 v15, v10, v11
	v_cvt_pk_bf16_f32 v128, v128, v129
	v_cvt_pk_bf16_f32 v129, v130, v131
	v_cvt_pk_bf16_f32 v130, v124, v125
	v_cvt_pk_bf16_f32 v131, v126, v127
	global_store_dwordx4 v[116:117], v[98:101], off offset:256
	v_cvt_pk_bf16_f32 v90, v92, v93
	v_cvt_pk_bf16_f32 v91, v94, v95
	v_lshl_add_u64 v[98:99], v[88:89], 0, v[136:137]
	v_cvt_pk_bf16_f32 v88, v104, v105
	v_cvt_pk_bf16_f32 v89, v106, v107
	v_cvt_pk_bf16_f32 v83, v74, v75
	global_store_dwordx4 v[28:29], v[12:15], off offset:256
	s_mov_b64 s[2:3], 0x580000
	global_store_dwordx4 v[134:135], v[128:131], off
	v_add_co_u32_e32 v12, vcc, 0x580000, v134
	global_store_dwordx4 v[98:99], v[88:91], off
	global_store_dwordx4 v[98:99], v[80:83], off offset:256
	v_lshl_add_u64 v[98:99], v[134:135], 0, s[2:3]
	v_addc_co_u32_e32 v13, vcc, 0, v135, vcc
	v_lshl_add_u64 v[80:81], v[72:73], 0, v[136:137]
	v_mov_b64_e32 v[134:135], v[6:7]
	v_mov_b64_e32 v[138:139], v[2:3]
	v_cvt_pk_bf16_f32 v108, v120, v121
	v_cvt_pk_bf16_f32 v109, v122, v123
	v_cvt_pk_bf16_f32 v110, v112, v113
	v_cvt_pk_bf16_f32 v111, v114, v115
	v_cvt_pk_bf16_f32 v72, v84, v85
	v_cvt_pk_bf16_f32 v73, v86, v87
	v_cvt_pk_bf16_f32 v74, v76, v77
	v_cvt_pk_bf16_f32 v75, v78, v79
	v_cvt_pk_bf16_f32 v71, v66, v67
	v_cvt_pk_bf16_f32 v63, v58, v59
	v_cvt_pk_bf16_f32 v40, v52, v53
	v_cvt_pk_bf16_f32 v41, v54, v55
	v_cvt_pk_bf16_f32 v42, v48, v49
	v_cvt_pk_bf16_f32 v43, v50, v51
	v_cvt_pk_bf16_f32 v24, v36, v37
	v_cvt_pk_bf16_f32 v25, v38, v39
	v_cvt_pk_bf16_f32 v26, v32, v33
	v_cvt_pk_bf16_f32 v27, v34, v35
	v_cvt_pk_bf16_f32 v8, v20, v21
	v_cvt_pk_bf16_f32 v9, v22, v23
	v_cvt_pk_bf16_f32 v10, v16, v17
	v_cvt_pk_bf16_f32 v11, v18, v19
	v_mov_b64_e32 v[132:133], v[4:5]
	v_mov_b64_e32 v[136:137], v[0:1]
	global_store_dwordx4 v[116:117], v[108:111], off
	global_store_dwordx4 v[80:81], v[72:75], off
	global_store_dwordx4 v[80:81], v[68:71], off offset:256
	global_store_dwordx4 v[56:57], v[60:63], off
	global_store_dwordx4 v[46:47], v[40:43], off
	global_store_dwordx4 v[30:31], v[24:27], off
	global_store_dwordx4 v[12:13], v[8:11], off
.LBB0_928:
	v_cvt_pk_bf16_f32 v0, v132, v133
	v_cvt_pk_bf16_f32 v1, v134, v135
	v_cvt_pk_bf16_f32 v2, v136, v137
	v_cvt_pk_bf16_f32 v3, v138, v139
	s_and_b64 vcc, exec, s[0:1]
	s_mov_b64 s[0:1], -1
	global_store_dwordx4 v[98:99], v[0:3], off offset:256
	s_cbranch_vccnz .LBB0_867
	s_andn2_b64 vcc, exec, s[94:95]
	s_cbranch_vccnz .LBB0_866
	s_barrier
	s_branch .LBB0_866

; __device__ __forceinline__ float bflo(unsigned w) { return __uint_as_float(w << 16); }
; __device__ __forceinline__ float bfhi(unsigned w) { return __uint_as_float(w & 0xffff0000u); }
; template <int HW>
; __device__ __forceinline__ void pool4(const bf16_t* zc, bf16_t* pc, int t0) {
;     ...
;     for (int i = 0; i < NR; ++i) { const int r = min(max(t0 - HW + i, 0), S - 1); v[i] = *(const u32x4*)(zc + (size_t)r * ZP); }
; #pragma unroll
;     for (int q = 0; q < 4; ++q) { const int t = t0 + q; float a[8];
; #pragma unroll
;         for (int i = 0; i < 8; ++i) a[i] = 0.f;
; #pragma unroll
;         for (int i = 0; i < 2 * HW; ++i) { const int r = t - HW + i; const bool ok = (r >= 0) && (r < S); const u32x4 w = v[q + i];
;             if (ok) { a[0] += bflo(w.x); a[1] += bfhi(w.x); a[2] += bflo(w.y); a[3] += bfhi(w.y); a[4] += bflo(w.z); a[5] += bfhi(w.z); a[6] += bflo(w.w); a[7] += bfhi(w.w); } }
; __device__ __forceinline__ void poolqk_phase(bf16_t* Z, bf16_t* P, const float* wq, const float* wk, int wid_s_) {
;     ...
;     for (int it = gt; it < (S / 4) * 128; it += NT) { const int tc = it >> 7, ch = it & 127, g = ch >> 5, t0 = tc * 4;
;         const bf16_t* zc = Z + ch * 8; bf16_t* pc = P + ((size_t)g * S) * 256 + (ch & 31) * 8;
;         if (g == 0) pool4<1>(zc, pc, t0); else if (g == 1) pool4<2>(zc, pc, t0); else if (g == 2) pool4<4>(zc, pc, t0); else pool4<8>(zc, pc, t0); }
.LBB0_987:
	s_or_b64 exec, exec, s[8:9]
	v_ashrrev_i32_e32 v79, 31, v78
	v_add_u32_e32 v150, s92, v150
	s_mov_b32 s2, 0x7ffff
	v_cvt_pk_bf16_f32 v3, v4, v5
	v_lshlrev_b64 v[4:5], 9, v[78:79]
	v_cmp_lt_i32_e32 vcc, s2, v150
	v_lshl_add_u64 v[4:5], v[76:77], 0, v[4:5]
	s_or_b64 s[86:87], vcc, s[86:87]
	v_add_u32_e32 v149, s26, v149
	global_store_dwordx4 v[4:5], v[0:3], off
	s_andn2_b64 exec, exec, s[86:87]
	s_cbranch_execz .LBB0_1209
.LBB0_988:
	v_and_b32_e32 v0, 0xf8, v149
	v_ashrrev_i32_e32 v79, 5, v150
	v_lshlrev_b32_e32 v96, 1, v0
	v_and_b32_e32 v80, -4, v79
	v_lshl_add_u64 v[76:77], v[74:75], 0, v[96:97]
	s_and_saveexec_b64 s[2:3], s[0:1]
	s_xor_b64 s[88:89], exec, s[2:3]
	s_cbranch_execz .LBB0_1166
	v_cmp_lt_i32_e32 vcc, 1, v148
	s_mov_b64 s[90:91], 0
	s_mov_b64 s[2:3], 0
	s_and_saveexec_b64 s[4:5], vcc
	s_xor_b64 s[10:11], exec, s[4:5]
	s_cbranch_execz .LBB0_1094
	v_cmp_eq_u32_e32 vcc, 2, v148
	s_mov_b64 s[2:3], -1
	s_and_saveexec_b64 s[12:13], vcc
	s_cbranch_execz .LBB0_1036
	v_add_u32_e32 v45, -3, v80
	v_max_i32_e32 v0, 0, v45
	v_add_u32_e32 v44, -2, v80
	v_mul_lo_u32 v96, v0, s33
	v_max_i32_e32 v2, 0, v44
	v_lshl_add_u64 v[0:1], v[72:73], 0, v[96:97]
	v_mul_lo_u32 v96, v2, s33
	v_add_u32_e32 v41, -1, v80
	v_lshl_add_u64 v[2:3], v[72:73], 0, v[96:97]
	global_load_dwordx4 v[36:39], v[0:1], off
	global_load_dwordx4 v[32:35], v[2:3], off
	v_max_i32_e32 v0, 0, v41
	v_mul_lo_u32 v96, v0, s33
	v_max_i32_e32 v2, 0, v80
	v_lshl_add_u64 v[0:1], v[72:73], 0, v[96:97]
	v_mul_lo_u32 v96, v2, s33
	v_or_b32_e32 v56, 1, v80
	v_lshl_add_u64 v[2:3], v[72:73], 0, v[96:97]
	global_load_dwordx4 v[28:31], v[0:1], off
	global_load_dwordx4 v[24:27], v[2:3], off
	v_max_i32_e32 v0, 0, v56
	v_or_b32_e32 v40, 2, v80
	v_mul_lo_u32 v96, v0, s33
	v_max_i32_e32 v2, 0, v40
	v_lshl_add_u64 v[0:1], v[72:73], 0, v[96:97]
	v_mul_lo_u32 v96, v2, s33
	v_lshl_add_u64 v[2:3], v[72:73], 0, v[96:97]
	global_load_dwordx4 v[20:23], v[0:1], off
	global_load_dwordx4 v[16:19], v[2:3], off
	v_or_b32_e32 v78, 3, v79
	v_max_i32_e32 v2, -4, v80
	v_max_i32_e32 v0, 0, v78
	v_add_u32_e32 v2, 4, v2
	v_mul_lo_u32 v96, v0, s33
	v_min_u32_e32 v2, 0x3fff, v2
	v_lshl_add_u64 v[0:1], v[72:73], 0, v[96:97]
	v_mul_u32_u24_e32 v96, 0x2800, v2
	v_lshl_add_u64 v[2:3], v[72:73], 0, v[96:97]
	global_load_dwordx4 v[12:15], v[0:1], off
	global_load_dwordx4 v[8:11], v[2:3], off
	v_max_i32_e32 v0, -5, v80
	v_add_u32_e32 v0, 5, v0
	v_max_i32_e32 v2, -6, v80
	v_min_u32_e32 v0, 0x3fff, v0
	v_add_u32_e32 v2, 6, v2
	v_mul_u32_u24_e32 v96, 0x2800, v0
	v_min_u32_e32 v2, 0x3fff, v2
	v_lshl_add_u64 v[0:1], v[72:73], 0, v[96:97]
	v_mul_u32_u24_e32 v96, 0x2800, v2
	v_lshl_add_u64 v[2:3], v[72:73], 0, v[96:97]
	global_load_dwordx4 v[4:7], v[0:1], off
	s_nop 0
	global_load_dwordx4 v[0:3], v[2:3], off
	v_add_u32_e32 v46, -4, v80
	v_mov_b32_e32 v42, 0
	v_cmp_gt_u32_e32 vcc, s80, v46
	v_mov_b32_e32 v43, 0
	v_mov_b32_e32 v70, 0
	v_mov_b32_e32 v71, v42
	v_mov_b32_e32 v68, v42
	v_mov_b32_e32 v69, v42
	v_mov_b32_e32 v66, v42
	v_mov_b32_e32 v67, v42
	v_mov_b32_e32 v90, v42
	v_mov_b32_e32 v91, v42
	s_and_saveexec_b64 s[2:3], vcc
	s_cbranch_execz .LBB0_993
	v_mul_lo_u32 v96, v46, s33
	v_lshl_add_u64 v[42:43], v[72:73], 0, v[96:97]
	global_load_dwordx4 v[46:49], v[42:43], off
	s_waitcnt vmcnt(0) lgkmcnt(0)
	v_lshlrev_b32_e32 v42, 16, v46
	v_and_b32_e32 v43, 0xffff0000, v46
	v_lshlrev_b32_e32 v50, 16, v48
	v_and_b32_e32 v51, 0xffff0000, v48
	v_lshlrev_b32_e32 v48, 16, v49
	v_and_b32_e32 v49, 0xffff0000, v49
	v_lshlrev_b32_e32 v46, 16, v47
	v_and_b32_e32 v47, 0xffff0000, v47
	v_pk_add_f32 v[70:71], v[42:43], 0 op_sel_hi:[1,0]
	v_pk_add_f32 v[42:43], v[48:49], 0 op_sel_hi:[1,0]
	v_pk_add_f32 v[68:69], v[46:47], 0 op_sel_hi:[1,0]
	v_pk_add_f32 v[66:67], v[50:51], 0 op_sel_hi:[1,0]
	v_mov_b32_e32 v90, v42
	v_mov_b32_e32 v91, v43
; __device__ __forceinline__ float bflo(unsigned w) { return __uint_as_float(w << 16); }
; __device__ __forceinline__ float bfhi(unsigned w) { return __uint_as_float(w & 0xffff0000u); }
; __device__ __forceinline__ unsigned cvtpk(float lo, float hi) { f32x2_t v = {lo, hi}; bf16x2_t b = __builtin_convertvector(v, bf16x2_t); return __builtin_bit_cast(unsigned, b); }
; template <int HW>
; __device__ __forceinline__ void pool4(const bf16_t* zc, bf16_t* pc, int t0) {
;     ...
;         for (int i = 0; i < 2 * HW; ++i) { const int r = t - HW + i; const bool ok = (r >= 0) && (r < S); const u32x4 w = v[q + i];
;             if (ok) { a[0] += bflo(w.x); a[1] += bfhi(w.x); a[2] += bflo(w.y); a[3] += bfhi(w.y); a[4] += bflo(w.z); a[5] += bfhi(w.z); a[6] += bflo(w.w); a[7] += bfhi(w.w); } }
;         const int lo = max(t - HW, 0), hi = min(t + HW - 1, S - 1); const float inv = 1.0f / (float)(hi - lo + 1);
;         const u32x4 sv = v[q + HW];
;         u32x4 w; w.x = cvtpk(a[0] * inv - bflo(sv.x), a[1] * inv - bfhi(sv.x)); w.y = cvtpk(a[2] * inv - bflo(sv.y), a[3] * inv - bfhi(sv.y));
;         w.z = cvtpk(a[4] * inv - bflo(sv.z), a[5] * inv - bfhi(sv.z)); w.w = cvtpk(a[6] * inv - bflo(sv.w), a[7] * inv - bfhi(sv.w));
;         *(u32x4*)(pc + (size_t)t * 256) = w; }
.LBB0_993:
	s_or_b64 exec, exec, s[2:3]
	v_cmp_gt_u32_e64 s[8:9], s80, v45
	s_waitcnt vmcnt(0) lgkmcnt(0)
	v_lshlrev_b32_e32 v88, 16, v36
	v_and_b32_e32 v89, 0xffff0000, v36
	v_lshlrev_b32_e32 v86, 16, v37
	v_and_b32_e32 v87, 0xffff0000, v37
	v_lshlrev_b32_e32 v84, 16, v38
	v_and_b32_e32 v85, 0xffff0000, v38
	v_lshlrev_b32_e32 v82, 16, v39
	v_and_b32_e32 v83, 0xffff0000, v39
	s_and_saveexec_b64 s[2:3], s[8:9]
	v_pk_add_f32 v[70:71], v[70:71], v[88:89]
	v_pk_add_f32 v[68:69], v[68:69], v[86:87]
	v_pk_add_f32 v[66:67], v[66:67], v[84:85]
	v_pk_add_f32 v[90:91], v[42:43], v[82:83]
	s_or_b64 exec, exec, s[2:3]
	v_cmp_gt_u32_e64 s[6:7], s80, v44
	v_lshlrev_b32_e32 v64, 16, v32
	v_and_b32_e32 v65, 0xffff0000, v32
	v_lshlrev_b32_e32 v62, 16, v33
	v_and_b32_e32 v63, 0xffff0000, v33
	v_lshlrev_b32_e32 v60, 16, v34
	v_and_b32_e32 v61, 0xffff0000, v34
	v_lshlrev_b32_e32 v58, 16, v35
	v_and_b32_e32 v59, 0xffff0000, v35
	s_and_saveexec_b64 s[2:3], s[6:7]
	v_pk_add_f32 v[70:71], v[70:71], v[64:65]
	v_pk_add_f32 v[68:69], v[68:69], v[62:63]
	v_pk_add_f32 v[66:67], v[66:67], v[60:61]
	v_pk_add_f32 v[90:91], v[90:91], v[58:59]
	s_or_b64 exec, exec, s[2:3]
	v_cmp_gt_u32_e64 s[4:5], s80, v41
	v_lshlrev_b32_e32 v36, 16, v28
	v_and_b32_e32 v37, 0xffff0000, v28
	v_lshlrev_b32_e32 v34, 16, v29
	v_and_b32_e32 v35, 0xffff0000, v29
	v_lshlrev_b32_e32 v32, 16, v30
	v_and_b32_e32 v33, 0xffff0000, v30
	v_lshlrev_b32_e32 v30, 16, v31
	v_and_b32_e32 v31, 0xffff0000, v31
	s_and_saveexec_b64 s[2:3], s[4:5]
	v_pk_add_f32 v[70:71], v[70:71], v[36:37]
	v_pk_add_f32 v[68:69], v[68:69], v[34:35]
	v_pk_add_f32 v[66:67], v[66:67], v[32:33]
	v_pk_add_f32 v[90:91], v[90:91], v[30:31]
	s_or_b64 exec, exec, s[2:3]
	v_cmp_gt_u32_e64 s[2:3], s80, v79
	v_lshlrev_b32_e32 v28, 16, v24
	v_and_b32_e32 v29, 0xffff0000, v24
	v_lshlrev_b32_e32 v42, 16, v25
	v_and_b32_e32 v43, 0xffff0000, v25
	v_lshlrev_b32_e32 v38, 16, v26
	v_and_b32_e32 v39, 0xffff0000, v26
	v_lshlrev_b32_e32 v24, 16, v27
	v_and_b32_e32 v25, 0xffff0000, v27
	s_and_saveexec_b64 s[14:15], s[2:3]
	v_pk_add_f32 v[70:71], v[70:71], v[28:29]
	v_pk_add_f32 v[68:69], v[68:69], v[42:43]
	v_pk_add_f32 v[66:67], v[66:67], v[38:39]
	v_pk_add_f32 v[90:91], v[90:91], v[24:25]
	s_or_b64 exec, exec, s[14:15]
	v_lshlrev_b32_e32 v26, 16, v20
	v_and_b32_e32 v27, 0xffff0000, v20
	v_lshlrev_b32_e32 v46, 16, v21
	v_and_b32_e32 v47, 0xffff0000, v21
	v_lshlrev_b32_e32 v44, 16, v22
	v_and_b32_e32 v45, 0xffff0000, v22
	v_lshlrev_b32_e32 v22, 16, v23
	v_and_b32_e32 v23, 0xffff0000, v23
	s_and_saveexec_b64 s[14:15], s[2:3]
	v_pk_add_f32 v[70:71], v[70:71], v[26:27]
	v_pk_add_f32 v[68:69], v[68:69], v[46:47]
	v_pk_add_f32 v[66:67], v[66:67], v[44:45]
	v_pk_add_f32 v[90:91], v[90:91], v[22:23]
	s_or_b64 exec, exec, s[14:15]
	v_lshlrev_b32_e32 v48, 16, v16
	v_and_b32_e32 v49, 0xffff0000, v16
	v_lshlrev_b32_e32 v54, 16, v17
	v_and_b32_e32 v55, 0xffff0000, v17
	v_lshlrev_b32_e32 v52, 16, v18
	v_and_b32_e32 v53, 0xffff0000, v18
	v_lshlrev_b32_e32 v50, 16, v19
	v_and_b32_e32 v51, 0xffff0000, v19
	s_and_saveexec_b64 s[14:15], s[2:3]
	v_pk_add_f32 v[70:71], v[70:71], v[48:49]
	v_pk_add_f32 v[68:69], v[68:69], v[54:55]
	v_pk_add_f32 v[66:67], v[66:67], v[52:53]
	v_pk_add_f32 v[90:91], v[90:91], v[50:51]
	s_or_b64 exec, exec, s[14:15]
	v_lshlrev_b32_e32 v20, 16, v12
	v_and_b32_e32 v21, 0xffff0000, v12
	v_lshlrev_b32_e32 v18, 16, v13
	v_and_b32_e32 v19, 0xffff0000, v13
	v_lshlrev_b32_e32 v16, 16, v14
	v_and_b32_e32 v17, 0xffff0000, v14
	v_lshlrev_b32_e32 v12, 16, v15
	v_and_b32_e32 v13, 0xffff0000, v15
	s_and_saveexec_b64 s[14:15], s[2:3]
	v_pk_add_f32 v[70:71], v[70:71], v[20:21]
	v_pk_add_f32 v[68:69], v[68:69], v[18:19]
	v_pk_add_f32 v[66:67], v[66:67], v[16:17]
	v_pk_add_f32 v[90:91], v[90:91], v[12:13]
	s_or_b64 exec, exec, s[14:15]
	v_max_i32_e32 v14, 4, v80
	v_sub_u32_e32 v14, v80, v14
	v_add_u32_e32 v14, 8, v14
	v_cvt_f32_i32_e32 v14, v14
	v_div_scale_f32 v15, s[14:15], v14, v14, 1.0
	v_rcp_f32_e32 v41, v15
	v_div_scale_f32 v57, vcc, 1.0, v14, 1.0
	v_fma_f32 v81, -v15, v41, 1.0
	v_fmac_f32_e32 v41, v81, v41
	v_mul_f32_e32 v81, v57, v41
	v_fma_f32 v92, -v15, v81, v57
	v_fmac_f32_e32 v81, v92, v41
	v_fma_f32 v15, -v15, v81, v57
	v_div_fmas_f32 v15, v15, v41, v81
	v_div_fixup_f32 v14, v15, v14, 1.0
	v_pk_fma_f32 v[70:71], v[14:15], v[70:71], v[28:29] op_sel_hi:[0,1,1] neg_lo:[0,0,1] neg_hi:[0,0,1]
	v_pk_fma_f32 v[92:93], v[14:15], v[68:69], v[42:43] op_sel_hi:[0,1,1] neg_lo:[0,0,1] neg_hi:[0,0,1]
	v_pk_fma_f32 v[66:67], v[14:15], v[66:67], v[38:39] op_sel_hi:[0,1,1] neg_lo:[0,0,1] neg_hi:[0,0,1]
	v_pk_fma_f32 v[14:15], v[14:15], v[90:91], v[24:25] op_sel_hi:[0,1,1] neg_lo:[0,0,1] neg_hi:[0,0,1]
	v_ashrrev_i32_e32 v81, 31, v80
	v_cvt_pk_bf16_f32 v68, v70, v71
	v_cvt_pk_bf16_f32 v71, v14, v15
	v_lshlrev_b64 v[14:15], 9, v[80:81]
	v_cvt_pk_bf16_f32 v69, v92, v93
	v_cvt_pk_bf16_f32 v70, v66, v67
	v_lshl_add_u64 v[14:15], v[76:77], 0, v[14:15]
	v_mov_b32_e32 v90, 0
	global_store_dwordx4 v[14:15], v[68:71], off
	v_mov_b32_e32 v91, 0
	v_mov_b32_e32 v66, 0
	v_mov_b32_e32 v67, 0
	v_mov_b32_e32 v14, 0
	v_mov_b32_e32 v15, v90
	v_mov_b32_e32 v68, v90
	v_mov_b32_e32 v69, v90
	v_mov_b32_e32 v70, 0
	v_mov_b32_e32 v71, 0
	s_and_saveexec_b64 s[14:15], s[8:9]
	s_cbranch_execz .LBB0_1201
	v_pk_add_f32 v[90:91], v[82:83], 0 op_sel_hi:[1,0]
	v_pk_add_f32 v[66:67], v[88:89], 0 op_sel_hi:[1,0]
	v_pk_add_f32 v[14:15], v[86:87], 0 op_sel_hi:[1,0]
	v_pk_add_f32 v[68:69], v[84:85], 0 op_sel_hi:[1,0]
	v_mov_b32_e32 v70, v90
	v_mov_b32_e32 v71, v91
	s_or_b64 exec, exec, s[14:15]
	s_and_saveexec_b64 s[8:9], s[6:7]
	s_cbranch_execnz .LBB0_1202

; __device__ __forceinline__ float bflo(unsigned w) { return __uint_as_float(w << 16); }
; __device__ __forceinline__ float bfhi(unsigned w) { return __uint_as_float(w & 0xffff0000u); }
; __device__ __forceinline__ unsigned cvtpk(float lo, float hi) { f32x2_t v = {lo, hi}; bf16x2_t b = __builtin_convertvector(v, bf16x2_t); return __builtin_bit_cast(unsigned, b); }
; template <int HW>
; __device__ __forceinline__ void pool4(const bf16_t* zc, bf16_t* pc, int t0) {
;     ...
;         for (int i = 0; i < 2 * HW; ++i) { const int r = t - HW + i; const bool ok = (r >= 0) && (r < S); const u32x4 w = v[q + i];
;             if (ok) { a[0] += bflo(w.x); a[1] += bfhi(w.x); a[2] += bflo(w.y); a[3] += bfhi(w.y); a[4] += bflo(w.z); a[5] += bfhi(w.z); a[6] += bflo(w.w); a[7] += bfhi(w.w); } }
;         const int lo = max(t - HW, 0), hi = min(t + HW - 1, S - 1); const float inv = 1.0f / (float)(hi - lo + 1);
;         const u32x4 sv = v[q + HW];
;         u32x4 w; w.x = cvtpk(a[0] * inv - bflo(sv.x), a[1] * inv - bfhi(sv.x)); w.y = cvtpk(a[2] * inv - bflo(sv.y), a[3] * inv - bfhi(sv.y));
;         w.z = cvtpk(a[4] * inv - bflo(sv.z), a[5] * inv - bfhi(sv.z)); w.w = cvtpk(a[6] * inv - bflo(sv.w), a[7] * inv - bfhi(sv.w));
;         *(u32x4*)(pc + (size_t)t * 256) = w; }
.LBB0_1015:
	s_or_b64 exec, exec, s[8:9]
	v_add_u32_e32 v14, 4, v79
	v_cmp_gt_u32_e64 s[8:9], s80, v14
	v_lshlrev_b32_e32 v68, 16, v8
	v_and_b32_e32 v69, 0xffff0000, v8
	v_lshlrev_b32_e32 v66, 16, v9
	v_and_b32_e32 v67, 0xffff0000, v9
	v_lshlrev_b32_e32 v14, 16, v10
	v_and_b32_e32 v15, 0xffff0000, v10
	v_lshlrev_b32_e32 v8, 16, v11
	v_and_b32_e32 v9, 0xffff0000, v11
	s_and_saveexec_b64 s[14:15], s[8:9]
	v_pk_add_f32 v[86:87], v[86:87], v[68:69]
	v_pk_add_f32 v[84:85], v[84:85], v[66:67]
	v_pk_add_f32 v[82:83], v[82:83], v[14:15]
	v_pk_add_f32 v[70:71], v[70:71], v[8:9]
	s_or_b64 exec, exec, s[14:15]
	v_max_i32_e32 v10, 4, v56
	v_min_i32_e32 v11, 0x3ffc, v56
	v_sub_u32_e32 v10, v11, v10
	v_add_u32_e32 v10, 8, v10
	v_cvt_f32_i32_e32 v10, v10
	v_div_scale_f32 v11, s[14:15], v10, v10, 1.0
	v_rcp_f32_e32 v41, v11
	v_div_scale_f32 v57, vcc, 1.0, v10, 1.0
	v_fma_f32 v81, -v11, v41, 1.0
	v_fmac_f32_e32 v41, v81, v41
	v_mul_f32_e32 v81, v57, v41
	v_fma_f32 v88, -v11, v81, v57
	v_fmac_f32_e32 v81, v88, v41
	v_fma_f32 v11, -v11, v81, v57
	v_div_fmas_f32 v11, v11, v41, v81
	v_div_fixup_f32 v10, v11, v10, 1.0
	v_pk_fma_f32 v[86:87], v[10:11], v[86:87], v[26:27] op_sel_hi:[0,1,1] neg_lo:[0,0,1] neg_hi:[0,0,1]
	v_pk_fma_f32 v[88:89], v[10:11], v[84:85], v[46:47] op_sel_hi:[0,1,1] neg_lo:[0,0,1] neg_hi:[0,0,1]
	v_pk_fma_f32 v[82:83], v[10:11], v[82:83], v[44:45] op_sel_hi:[0,1,1] neg_lo:[0,0,1] neg_hi:[0,0,1]
	v_pk_fma_f32 v[10:11], v[10:11], v[70:71], v[22:23] op_sel_hi:[0,1,1] neg_lo:[0,0,1] neg_hi:[0,0,1]
	v_ashrrev_i32_e32 v57, 31, v56
	v_cvt_pk_bf16_f32 v84, v86, v87
	v_cvt_pk_bf16_f32 v87, v10, v11
	v_lshlrev_b64 v[10:11], 9, v[56:57]
	v_cvt_pk_bf16_f32 v85, v88, v89
	v_cvt_pk_bf16_f32 v86, v82, v83
	v_lshl_add_u64 v[10:11], v[76:77], 0, v[10:11]
	v_mov_b32_e32 v82, 0
	global_store_dwordx4 v[10:11], v[84:87], off
	v_mov_b32_e32 v83, 0
	v_mov_b32_e32 v10, 0
	v_mov_b32_e32 v11, 0
	v_mov_b32_e32 v56, 0
	v_mov_b32_e32 v57, v82
	v_mov_b32_e32 v70, v82
	v_mov_b32_e32 v71, v82
	v_mov_b32_e32 v84, 0
	v_mov_b32_e32 v85, 0
	s_and_saveexec_b64 s[14:15], s[6:7]
	v_pk_add_f32 v[82:83], v[58:59], 0 op_sel_hi:[1,0]
	v_pk_add_f32 v[10:11], v[64:65], 0 op_sel_hi:[1,0]
	v_pk_add_f32 v[56:57], v[62:63], 0 op_sel_hi:[1,0]
	v_pk_add_f32 v[70:71], v[60:61], 0 op_sel_hi:[1,0]
	v_mov_b32_e32 v84, v82
	v_mov_b32_e32 v85, v83
	s_or_b64 exec, exec, s[14:15]
	s_and_saveexec_b64 s[6:7], s[4:5]
	v_pk_add_f32 v[10:11], v[10:11], v[36:37]
	v_pk_add_f32 v[56:57], v[56:57], v[34:35]
	v_pk_add_f32 v[70:71], v[70:71], v[32:33]
	v_pk_add_f32 v[84:85], v[82:83], v[30:31]
	s_or_b64 exec, exec, s[6:7]
	v_pk_add_f32 v[58:59], v[56:57], v[42:43]
	v_pk_add_f32 v[60:61], v[70:71], v[38:39]
	v_pk_add_f32 v[62:63], v[84:85], v[24:25]
	v_pk_add_f32 v[64:65], v[10:11], v[28:29]
	v_cndmask_b32_e64 v63, v85, v63, s[2:3]
	v_cndmask_b32_e64 v62, v84, v62, s[2:3]
	v_cndmask_b32_e64 v71, v71, v61, s[2:3]
	v_cndmask_b32_e64 v70, v70, v60, s[2:3]
	v_cndmask_b32_e64 v57, v57, v59, s[2:3]
	v_cndmask_b32_e64 v56, v56, v58, s[2:3]
	v_cndmask_b32_e64 v11, v11, v65, s[2:3]
	v_cndmask_b32_e64 v10, v10, v64, s[2:3]
	v_pk_add_f32 v[58:59], v[56:57], v[46:47]
	v_pk_add_f32 v[64:65], v[70:71], v[44:45]
	v_pk_add_f32 v[60:61], v[62:63], v[22:23]
	v_pk_add_f32 v[82:83], v[10:11], v[26:27]
	v_cndmask_b32_e64 v61, v63, v61, s[2:3]
	v_cndmask_b32_e64 v60, v62, v60, s[2:3]
	v_cndmask_b32_e64 v63, v71, v65, s[2:3]
	v_cndmask_b32_e64 v62, v70, v64, s[2:3]
	v_cndmask_b32_e64 v65, v57, v59, s[2:3]
	v_cndmask_b32_e64 v64, v56, v58, s[2:3]
	v_cndmask_b32_e64 v71, v11, v83, s[2:3]
	v_cndmask_b32_e64 v70, v10, v82, s[2:3]
	s_and_saveexec_b64 s[6:7], s[2:3]
	s_cbranch_execz .LBB0_1205
	v_pk_add_f32 v[70:71], v[70:71], v[48:49]
	v_pk_add_f32 v[64:65], v[64:65], v[54:55]
	v_pk_add_f32 v[62:63], v[62:63], v[52:53]
	v_pk_add_f32 v[60:61], v[60:61], v[50:51]
	s_or_b64 exec, exec, s[6:7]
	s_and_saveexec_b64 s[6:7], s[2:3]
	s_cbranch_execnz .LBB0_1206

; __device__ __forceinline__ float bflo(unsigned w) { return __uint_as_float(w << 16); }
; __device__ __forceinline__ float bfhi(unsigned w) { return __uint_as_float(w & 0xffff0000u); }
; __device__ __forceinline__ unsigned cvtpk(float lo, float hi) { f32x2_t v = {lo, hi}; bf16x2_t b = __builtin_convertvector(v, bf16x2_t); return __builtin_bit_cast(unsigned, b); }
; template <int HW>
; __device__ __forceinline__ void pool4(const bf16_t* zc, bf16_t* pc, int t0) {
;     ...
;         for (int i = 0; i < 2 * HW; ++i) { const int r = t - HW + i; const bool ok = (r >= 0) && (r < S); const u32x4 w = v[q + i];
;             if (ok) { a[0] += bflo(w.x); a[1] += bfhi(w.x); a[2] += bflo(w.y); a[3] += bfhi(w.y); a[4] += bflo(w.z); a[5] += bfhi(w.z); a[6] += bflo(w.w); a[7] += bfhi(w.w); } }
;         const int lo = max(t - HW, 0), hi = min(t + HW - 1, S - 1); const float inv = 1.0f / (float)(hi - lo + 1);
;         const u32x4 sv = v[q + HW];
;         u32x4 w; w.x = cvtpk(a[0] * inv - bflo(sv.x), a[1] * inv - bfhi(sv.x)); w.y = cvtpk(a[2] * inv - bflo(sv.y), a[3] * inv - bfhi(sv.y));
;         w.z = cvtpk(a[4] * inv - bflo(sv.z), a[5] * inv - bfhi(sv.z)); w.w = cvtpk(a[6] * inv - bflo(sv.w), a[7] * inv - bfhi(sv.w));
;         *(u32x4*)(pc + (size_t)t * 256) = w; }
.LBB0_1025:
	s_or_b64 exec, exec, s[6:7]
	v_add_u32_e32 v10, 5, v80
	v_cmp_gt_u32_e64 s[6:7], s80, v10
	v_lshlrev_b32_e32 v58, 16, v4
	v_and_b32_e32 v59, 0xffff0000, v4
	v_lshlrev_b32_e32 v56, 16, v5
	v_and_b32_e32 v57, 0xffff0000, v5
	v_lshlrev_b32_e32 v10, 16, v6
	v_and_b32_e32 v11, 0xffff0000, v6
	v_lshlrev_b32_e32 v4, 16, v7
	v_and_b32_e32 v5, 0xffff0000, v7
	s_and_saveexec_b64 s[14:15], s[6:7]
	v_pk_add_f32 v[70:71], v[70:71], v[58:59]
	v_pk_add_f32 v[64:65], v[64:65], v[56:57]
	v_pk_add_f32 v[62:63], v[62:63], v[10:11]
	v_pk_add_f32 v[60:61], v[60:61], v[4:5]
	s_or_b64 exec, exec, s[14:15]
	v_max_i32_e32 v6, 4, v40
	v_min_i32_e32 v7, 0x3ffc, v40
	v_sub_u32_e32 v6, v7, v6
	v_add_u32_e32 v6, 8, v6
	v_cvt_f32_i32_e32 v6, v6
	v_div_scale_f32 v7, s[14:15], v6, v6, 1.0
	v_rcp_f32_e32 v41, v7
	v_div_scale_f32 v81, vcc, 1.0, v6, 1.0
	v_fma_f32 v82, -v7, v41, 1.0
	v_fmac_f32_e32 v41, v82, v41
	v_mul_f32_e32 v82, v81, v41
	v_fma_f32 v83, -v7, v82, v81
	v_fmac_f32_e32 v82, v83, v41
	v_fma_f32 v7, -v7, v82, v81
	v_div_fmas_f32 v7, v7, v41, v82
	v_div_fixup_f32 v6, v7, v6, 1.0
	v_pk_fma_f32 v[70:71], v[6:7], v[70:71], v[48:49] op_sel_hi:[0,1,1] neg_lo:[0,0,1] neg_hi:[0,0,1]
	v_pk_fma_f32 v[64:65], v[6:7], v[64:65], v[54:55] op_sel_hi:[0,1,1] neg_lo:[0,0,1] neg_hi:[0,0,1]
	v_pk_fma_f32 v[62:63], v[6:7], v[62:63], v[52:53] op_sel_hi:[0,1,1] neg_lo:[0,0,1] neg_hi:[0,0,1]
	v_pk_fma_f32 v[6:7], v[6:7], v[60:61], v[50:51] op_sel_hi:[0,1,1] neg_lo:[0,0,1] neg_hi:[0,0,1]
	v_ashrrev_i32_e32 v41, 31, v40
	v_cvt_pk_bf16_f32 v85, v6, v7
	v_lshlrev_b64 v[6:7], 9, v[40:41]
	v_cvt_pk_bf16_f32 v82, v70, v71
	v_cvt_pk_bf16_f32 v83, v64, v65
	v_cvt_pk_bf16_f32 v84, v62, v63
	v_lshl_add_u64 v[6:7], v[76:77], 0, v[6:7]
	global_store_dwordx4 v[6:7], v[82:85], off
	v_mov_b32_e32 v6, 0
	v_mov_b32_e32 v7, 0
	v_mov_b32_e32 v40, 0
	v_mov_b32_e32 v41, 0
	v_mov_b32_e32 v60, 0
	v_mov_b32_e32 v61, 0
	v_mov_b32_e32 v62, 0
	v_mov_b32_e32 v63, 0
	s_and_saveexec_b64 s[14:15], s[4:5]
	v_pk_add_f32 v[6:7], v[36:37], 0 op_sel_hi:[1,0]
	v_pk_add_f32 v[40:41], v[34:35], 0 op_sel_hi:[1,0]
	v_pk_add_f32 v[60:61], v[32:33], 0 op_sel_hi:[1,0]
	v_pk_add_f32 v[62:63], v[30:31], 0 op_sel_hi:[1,0]
	s_or_b64 exec, exec, s[14:15]
	v_pk_add_f32 v[30:31], v[40:41], v[42:43]
	v_pk_add_f32 v[32:33], v[60:61], v[38:39]
	v_pk_add_f32 v[24:25], v[62:63], v[24:25]
	v_pk_add_f32 v[28:29], v[6:7], v[28:29]
	v_cndmask_b32_e64 v25, v63, v25, s[2:3]
	v_cndmask_b32_e64 v24, v62, v24, s[2:3]
	v_cndmask_b32_e64 v33, v61, v33, s[2:3]
	v_cndmask_b32_e64 v32, v60, v32, s[2:3]
	v_cndmask_b32_e64 v31, v41, v31, s[2:3]
	v_cndmask_b32_e64 v30, v40, v30, s[2:3]
	v_cndmask_b32_e64 v7, v7, v29, s[2:3]
	v_cndmask_b32_e64 v6, v6, v28, s[2:3]
	v_pk_add_f32 v[28:29], v[30:31], v[46:47]
	v_pk_add_f32 v[34:35], v[32:33], v[44:45]
	v_pk_add_f32 v[22:23], v[24:25], v[22:23]
	v_pk_add_f32 v[26:27], v[6:7], v[26:27]
	v_cndmask_b32_e64 v23, v25, v23, s[2:3]
	v_cndmask_b32_e64 v22, v24, v22, s[2:3]
	v_cndmask_b32_e64 v25, v33, v35, s[2:3]
	v_cndmask_b32_e64 v24, v32, v34, s[2:3]
	v_cndmask_b32_e64 v29, v31, v29, s[2:3]
	v_cndmask_b32_e64 v28, v30, v28, s[2:3]
	v_cndmask_b32_e64 v27, v7, v27, s[2:3]
	v_cndmask_b32_e64 v26, v6, v26, s[2:3]
	v_pk_add_f32 v[30:31], v[28:29], v[54:55]
	v_pk_add_f32 v[32:33], v[24:25], v[52:53]
	v_pk_add_f32 v[6:7], v[22:23], v[50:51]
	v_pk_add_f32 v[34:35], v[26:27], v[48:49]
	v_cndmask_b32_e64 v7, v23, v7, s[2:3]
	v_cndmask_b32_e64 v6, v22, v6, s[2:3]
	v_cndmask_b32_e64 v23, v25, v33, s[2:3]
	v_cndmask_b32_e64 v22, v24, v32, s[2:3]
	v_cndmask_b32_e64 v25, v29, v31, s[2:3]
	v_cndmask_b32_e64 v24, v28, v30, s[2:3]
	v_cndmask_b32_e64 v27, v27, v35, s[2:3]
	v_cndmask_b32_e64 v26, v26, v34, s[2:3]
	s_and_saveexec_b64 s[4:5], s[2:3]
	s_cbranch_execz .LBB0_1207
	v_pk_add_f32 v[26:27], v[26:27], v[20:21]
	v_pk_add_f32 v[24:25], v[24:25], v[18:19]
	v_pk_add_f32 v[22:23], v[22:23], v[16:17]
	v_pk_add_f32 v[6:7], v[6:7], v[12:13]
	s_or_b64 exec, exec, s[4:5]
	s_and_saveexec_b64 s[2:3], s[8:9]
	s_cbranch_execnz .LBB0_1208

; template <int HW>
; __device__ __forceinline__ void pool4(const bf16_t* zc, bf16_t* pc, int t0) {
;     ...
;     for (int i = 0; i < NR; ++i) { const int r = min(max(t0 - HW + i, 0), S - 1); v[i] = *(const u32x4*)(zc + (size_t)r * ZP); }
.LBB0_1038:
	v_add_u32_e32 v88, -7, v80
	v_max_i32_e32 v0, 0, v88
	v_add_u32_e32 v87, -6, v80
	v_mul_lo_u32 v96, v0, s33
	v_max_i32_e32 v2, 0, v87
	v_lshl_add_u64 v[0:1], v[72:73], 0, v[96:97]
	v_mul_lo_u32 v96, v2, s33
	v_add_u32_e32 v86, -5, v80
	v_lshl_add_u64 v[2:3], v[72:73], 0, v[96:97]
	global_load_dwordx4 v[68:71], v[0:1], off
	global_load_dwordx4 v[64:67], v[2:3], off
	v_max_i32_e32 v0, 0, v86
	v_add_u32_e32 v92, -4, v80
	v_mul_lo_u32 v96, v0, s33
	v_max_i32_e32 v2, 0, v92
	v_lshl_add_u64 v[0:1], v[72:73], 0, v[96:97]
	v_mul_lo_u32 v96, v2, s33
	v_add_u32_e32 v91, -3, v80
	v_lshl_add_u64 v[2:3], v[72:73], 0, v[96:97]
	global_load_dwordx4 v[60:63], v[0:1], off
	global_load_dwordx4 v[56:59], v[2:3], off
	v_max_i32_e32 v0, 0, v91
	v_add_u32_e32 v90, -2, v80
	v_mul_lo_u32 v96, v0, s33
	v_max_i32_e32 v2, 0, v90
	v_lshl_add_u64 v[0:1], v[72:73], 0, v[96:97]
	v_mul_lo_u32 v96, v2, s33
	v_add_u32_e32 v94, -1, v80
	v_lshl_add_u64 v[2:3], v[72:73], 0, v[96:97]
	global_load_dwordx4 v[52:55], v[0:1], off
	global_load_dwordx4 v[48:51], v[2:3], off
	v_max_i32_e32 v0, 0, v94
	v_mul_lo_u32 v96, v0, s33
	v_max_i32_e32 v2, 0, v80
	v_lshl_add_u64 v[0:1], v[72:73], 0, v[96:97]
	v_mul_lo_u32 v96, v2, s33
	v_or_b32_e32 v132, 1, v80
	v_lshl_add_u64 v[2:3], v[72:73], 0, v[96:97]
	global_load_dwordx4 v[44:47], v[0:1], off
	global_load_dwordx4 v[40:43], v[2:3], off
	v_max_i32_e32 v0, 0, v132
	v_or_b32_e32 v82, 2, v80
	v_mul_lo_u32 v96, v0, s33
	v_max_i32_e32 v2, 0, v82
	v_lshl_add_u64 v[0:1], v[72:73], 0, v[96:97]
	v_mul_lo_u32 v96, v2, s33
	v_or_b32_e32 v78, 3, v79
	v_lshl_add_u64 v[2:3], v[72:73], 0, v[96:97]
	global_load_dwordx4 v[36:39], v[0:1], off
	global_load_dwordx4 v[32:35], v[2:3], off
	v_max_i32_e32 v0, 0, v78
	v_add_u32_e32 v110, 4, v80
	v_mul_lo_u32 v96, v0, s33
	v_med3_i32 v2, v110, 0, v244
	v_lshl_add_u64 v[0:1], v[72:73], 0, v[96:97]
	v_mul_u32_u24_e32 v96, 0x2800, v2
	v_add_u32_e32 v120, 5, v80
	v_lshl_add_u64 v[2:3], v[72:73], 0, v[96:97]
	global_load_dwordx4 v[28:31], v[0:1], off
	global_load_dwordx4 v[24:27], v[2:3], off
	v_med3_i32 v0, v120, 0, v244
	v_add_u32_e32 v83, 6, v80
	v_mul_u32_u24_e32 v96, 0x2800, v0
	v_med3_i32 v2, v83, 0, v244
	v_lshl_add_u64 v[0:1], v[72:73], 0, v[96:97]
	v_mul_u32_u24_e32 v96, 0x2800, v2
	v_lshl_add_u64 v[2:3], v[72:73], 0, v[96:97]
	global_load_dwordx4 v[20:23], v[0:1], off
	global_load_dwordx4 v[16:19], v[2:3], off
	v_add_u32_e32 v81, 7, v80
	v_max_i32_e32 v2, -8, v80
	v_med3_i32 v0, v81, 0, v244
	v_add_u32_e32 v2, 8, v2
	v_mul_u32_u24_e32 v96, 0x2800, v0
	v_min_u32_e32 v2, 0x3fff, v2
	v_lshl_add_u64 v[0:1], v[72:73], 0, v[96:97]
	v_mul_u32_u24_e32 v96, 0x2800, v2
	v_lshl_add_u64 v[2:3], v[72:73], 0, v[96:97]
	global_load_dwordx4 v[12:15], v[0:1], off
	global_load_dwordx4 v[8:11], v[2:3], off
	v_max_i32_e32 v0, -9, v80
	v_add_u32_e32 v0, 9, v0
	v_max_i32_e32 v2, -10, v80
	v_min_u32_e32 v0, 0x3fff, v0
	v_add_u32_e32 v2, 10, v2
	v_mul_u32_u24_e32 v96, 0x2800, v0
	v_min_u32_e32 v2, 0x3fff, v2
	v_lshl_add_u64 v[0:1], v[72:73], 0, v[96:97]
	v_mul_u32_u24_e32 v96, 0x2800, v2
	v_lshl_add_u64 v[2:3], v[72:73], 0, v[96:97]
	global_load_dwordx4 v[4:7], v[0:1], off
	s_nop 0
	global_load_dwordx4 v[0:3], v[2:3], off
	v_add_u32_e32 v89, -8, v80
	v_mov_b32_e32 v84, 0
	v_cmp_gt_u32_e32 vcc, s80, v89
	v_mov_b32_e32 v85, 0
	v_mov_b32_e32 v152, 0
	v_mov_b32_e32 v153, v84
	v_mov_b32_e32 v144, v84
	v_mov_b32_e32 v145, v84
	v_mov_b32_e32 v142, v84
	v_mov_b32_e32 v143, v84
	v_mov_b32_e32 v162, v84
	v_mov_b32_e32 v163, v84
	s_and_saveexec_b64 s[2:3], vcc
	s_cbranch_execz .LBB0_1040
	v_mul_lo_u32 v96, v89, s33
	v_lshl_add_u64 v[84:85], v[72:73], 0, v[96:97]
	global_load_dwordx4 v[98:101], v[84:85], off
	s_waitcnt vmcnt(0) lgkmcnt(0)
	v_lshlrev_b32_e32 v84, 16, v98
	v_and_b32_e32 v85, 0xffff0000, v98
	v_lshlrev_b32_e32 v102, 16, v100
	v_and_b32_e32 v103, 0xffff0000, v100
	v_lshlrev_b32_e32 v100, 16, v101
	v_and_b32_e32 v101, 0xffff0000, v101
	v_lshlrev_b32_e32 v98, 16, v99
	v_and_b32_e32 v99, 0xffff0000, v99
	v_pk_add_f32 v[152:153], v[84:85], 0 op_sel_hi:[1,0]
	v_pk_add_f32 v[84:85], v[100:101], 0 op_sel_hi:[1,0]
	v_pk_add_f32 v[144:145], v[98:99], 0 op_sel_hi:[1,0]
	v_pk_add_f32 v[142:143], v[102:103], 0 op_sel_hi:[1,0]
	v_mov_b32_e32 v162, v84
	v_mov_b32_e32 v163, v85
; __device__ __forceinline__ float bflo(unsigned w) { return __uint_as_float(w << 16); }
; __device__ __forceinline__ float bfhi(unsigned w) { return __uint_as_float(w & 0xffff0000u); }
; template <int HW>
; __device__ __forceinline__ void pool4(const bf16_t* zc, bf16_t* pc, int t0) {
;     ...
;         for (int i = 0; i < 2 * HW; ++i) { const int r = t - HW + i; const bool ok = (r >= 0) && (r < S); const u32x4 w = v[q + i];
;             if (ok) { a[0] += bflo(w.x); a[1] += bfhi(w.x); a[2] += bflo(w.y); a[3] += bfhi(w.y); a[4] += bflo(w.z); a[5] += bfhi(w.z); a[6] += bflo(w.w); a[7] += bfhi(w.w); } }
.LBB0_1040:
	s_or_b64 exec, exec, s[2:3]
	v_cmp_gt_u32_e64 s[24:25], s80, v88
	s_waitcnt vmcnt(0) lgkmcnt(0)
	v_lshlrev_b32_e32 v160, 16, v68
	v_and_b32_e32 v161, 0xffff0000, v68
	v_lshlrev_b32_e32 v158, 16, v69
	v_and_b32_e32 v159, 0xffff0000, v69
	v_lshlrev_b32_e32 v156, 16, v70
	v_and_b32_e32 v157, 0xffff0000, v70
	v_lshlrev_b32_e32 v154, 16, v71
	v_and_b32_e32 v155, 0xffff0000, v71
	s_and_saveexec_b64 s[2:3], s[24:25]
	v_pk_add_f32 v[152:153], v[152:153], v[160:161]
	v_pk_add_f32 v[144:145], v[144:145], v[158:159]
	v_pk_add_f32 v[142:143], v[142:143], v[156:157]
	v_pk_add_f32 v[162:163], v[84:85], v[154:155]
	s_or_b64 exec, exec, s[2:3]
	v_cmp_gt_u32_e64 s[22:23], s80, v87
	v_lshlrev_b32_e32 v140, 16, v64
	v_and_b32_e32 v141, 0xffff0000, v64
	v_lshlrev_b32_e32 v138, 16, v65
	v_and_b32_e32 v139, 0xffff0000, v65
	v_lshlrev_b32_e32 v136, 16, v66
	v_and_b32_e32 v137, 0xffff0000, v66
	v_lshlrev_b32_e32 v134, 16, v67
	v_and_b32_e32 v135, 0xffff0000, v67
	s_and_saveexec_b64 s[2:3], s[22:23]
	v_pk_add_f32 v[152:153], v[152:153], v[140:141]
	v_pk_add_f32 v[144:145], v[144:145], v[138:139]
	v_pk_add_f32 v[142:143], v[142:143], v[136:137]
	v_pk_add_f32 v[162:163], v[162:163], v[134:135]
	s_or_b64 exec, exec, s[2:3]
	v_cmp_gt_u32_e64 s[8:9], s80, v86
	v_lshlrev_b32_e32 v88, 16, v60
	v_and_b32_e32 v89, 0xffff0000, v60
	v_lshlrev_b32_e32 v86, 16, v61
	v_and_b32_e32 v87, 0xffff0000, v61
	v_lshlrev_b32_e32 v84, 16, v62
	v_and_b32_e32 v85, 0xffff0000, v62
	v_lshlrev_b32_e32 v70, 16, v63
	v_and_b32_e32 v71, 0xffff0000, v63
	s_and_saveexec_b64 s[2:3], s[8:9]
	v_pk_add_f32 v[152:153], v[152:153], v[88:89]
	v_pk_add_f32 v[144:145], v[144:145], v[86:87]
	v_pk_add_f32 v[142:143], v[142:143], v[84:85]
	v_pk_add_f32 v[162:163], v[162:163], v[70:71]
	s_or_b64 exec, exec, s[2:3]
	v_cmp_gt_u32_e64 s[4:5], s80, v92
	v_lshlrev_b32_e32 v64, 16, v56
	v_and_b32_e32 v65, 0xffff0000, v56
	v_lshlrev_b32_e32 v62, 16, v57
	v_and_b32_e32 v63, 0xffff0000, v57
	v_lshlrev_b32_e32 v60, 16, v58
	v_and_b32_e32 v61, 0xffff0000, v58
	v_lshlrev_b32_e32 v56, 16, v59
	v_and_b32_e32 v57, 0xffff0000, v59
	s_and_saveexec_b64 s[2:3], s[4:5]
	v_pk_add_f32 v[152:153], v[152:153], v[64:65]
	v_pk_add_f32 v[144:145], v[144:145], v[62:63]
	v_pk_add_f32 v[142:143], v[142:143], v[60:61]
	v_pk_add_f32 v[162:163], v[162:163], v[56:57]
	s_or_b64 exec, exec, s[2:3]
	v_cmp_gt_u32_e64 s[6:7], s80, v91
	v_lshlrev_b32_e32 v68, 16, v52
	v_and_b32_e32 v69, 0xffff0000, v52
	v_lshlrev_b32_e32 v66, 16, v53
	v_and_b32_e32 v67, 0xffff0000, v53
	v_lshlrev_b32_e32 v58, 16, v54
	v_and_b32_e32 v59, 0xffff0000, v54
	v_lshlrev_b32_e32 v52, 16, v55
	v_and_b32_e32 v53, 0xffff0000, v55
	s_and_saveexec_b64 s[2:3], s[6:7]
	v_pk_add_f32 v[152:153], v[152:153], v[68:69]
	v_pk_add_f32 v[144:145], v[144:145], v[66:67]
	v_pk_add_f32 v[142:143], v[142:143], v[58:59]
	v_pk_add_f32 v[162:163], v[162:163], v[52:53]
	s_or_b64 exec, exec, s[2:3]
	v_cmp_gt_u32_e64 s[10:11], s80, v90
	v_lshlrev_b32_e32 v92, 16, v48
	v_and_b32_e32 v93, 0xffff0000, v48
	v_lshlrev_b32_e32 v90, 16, v49
	v_and_b32_e32 v91, 0xffff0000, v49
	v_lshlrev_b32_e32 v54, 16, v50
	v_and_b32_e32 v55, 0xffff0000, v50
	v_lshlrev_b32_e32 v48, 16, v51
	v_and_b32_e32 v49, 0xffff0000, v51
	s_and_saveexec_b64 s[2:3], s[10:11]
	v_pk_add_f32 v[152:153], v[152:153], v[92:93]
	v_pk_add_f32 v[144:145], v[144:145], v[90:91]
	v_pk_add_f32 v[142:143], v[142:143], v[54:55]
	v_pk_add_f32 v[162:163], v[162:163], v[48:49]
	s_or_b64 exec, exec, s[2:3]
	v_cmp_gt_u32_e64 s[12:13], s80, v94
	v_lshlrev_b32_e32 v98, 16, v44
	v_and_b32_e32 v99, 0xffff0000, v44
	v_lshlrev_b32_e32 v94, 16, v45
	v_and_b32_e32 v95, 0xffff0000, v45
	v_lshlrev_b32_e32 v50, 16, v46
	v_and_b32_e32 v51, 0xffff0000, v46
	v_lshlrev_b32_e32 v44, 16, v47
	v_and_b32_e32 v45, 0xffff0000, v47
	s_and_saveexec_b64 s[2:3], s[12:13]
	v_pk_add_f32 v[152:153], v[152:153], v[98:99]
	v_pk_add_f32 v[144:145], v[144:145], v[94:95]
	v_pk_add_f32 v[142:143], v[142:143], v[50:51]
	v_pk_add_f32 v[162:163], v[162:163], v[44:45]
	s_or_b64 exec, exec, s[2:3]
	v_cmp_gt_u32_e64 s[2:3], s80, v79
	v_lshlrev_b32_e32 v46, 16, v40
	v_and_b32_e32 v47, 0xffff0000, v40
	v_lshlrev_b32_e32 v102, 16, v41
	v_and_b32_e32 v103, 0xffff0000, v41
	v_lshlrev_b32_e32 v100, 16, v42
	v_and_b32_e32 v101, 0xffff0000, v42
	v_lshlrev_b32_e32 v40, 16, v43
	v_and_b32_e32 v41, 0xffff0000, v43
	s_and_saveexec_b64 s[14:15], s[2:3]
	v_pk_add_f32 v[152:153], v[152:153], v[46:47]
	v_pk_add_f32 v[144:145], v[144:145], v[102:103]
	v_pk_add_f32 v[142:143], v[142:143], v[100:101]
	v_pk_add_f32 v[162:163], v[162:163], v[40:41]
	s_or_b64 exec, exec, s[14:15]
	v_lshlrev_b32_e32 v42, 16, v36
	v_and_b32_e32 v43, 0xffff0000, v36
	v_lshlrev_b32_e32 v106, 16, v37
	v_and_b32_e32 v107, 0xffff0000, v37
	v_lshlrev_b32_e32 v104, 16, v38
	v_and_b32_e32 v105, 0xffff0000, v38
	v_lshlrev_b32_e32 v38, 16, v39
	v_and_b32_e32 v39, 0xffff0000, v39
	s_and_saveexec_b64 s[14:15], s[2:3]
	v_pk_add_f32 v[152:153], v[152:153], v[42:43]
	v_pk_add_f32 v[144:145], v[144:145], v[106:107]
	v_pk_add_f32 v[142:143], v[142:143], v[104:105]
	v_pk_add_f32 v[162:163], v[162:163], v[38:39]
	s_or_b64 exec, exec, s[14:15]
	v_lshlrev_b32_e32 v108, 16, v32
	v_and_b32_e32 v109, 0xffff0000, v32
; __device__ __forceinline__ float bflo(unsigned w) { return __uint_as_float(w << 16); }
; __device__ __forceinline__ float bfhi(unsigned w) { return __uint_as_float(w & 0xffff0000u); }
; __device__ __forceinline__ unsigned cvtpk(float lo, float hi) { f32x2_t v = {lo, hi}; bf16x2_t b = __builtin_convertvector(v, bf16x2_t); return __builtin_bit_cast(unsigned, b); }
; template <int HW>
; __device__ __forceinline__ void pool4(const bf16_t* zc, bf16_t* pc, int t0) {
;     ...
;         for (int i = 0; i < 2 * HW; ++i) { const int r = t - HW + i; const bool ok = (r >= 0) && (r < S); const u32x4 w = v[q + i];
;             if (ok) { a[0] += bflo(w.x); a[1] += bfhi(w.x); a[2] += bflo(w.y); a[3] += bfhi(w.y); a[4] += bflo(w.z); a[5] += bfhi(w.z); a[6] += bflo(w.w); a[7] += bfhi(w.w); } }
;         const int lo = max(t - HW, 0), hi = min(t + HW - 1, S - 1); const float inv = 1.0f / (float)(hi - lo + 1);
;         const u32x4 sv = v[q + HW];
;         u32x4 w; w.x = cvtpk(a[0] * inv - bflo(sv.x), a[1] * inv - bfhi(sv.x)); w.y = cvtpk(a[2] * inv - bflo(sv.y), a[3] * inv - bfhi(sv.y));
;         w.z = cvtpk(a[4] * inv - bflo(sv.z), a[5] * inv - bfhi(sv.z)); w.w = cvtpk(a[6] * inv - bflo(sv.w), a[7] * inv - bfhi(sv.w));
;         *(u32x4*)(pc + (size_t)t * 256) = w; }
	v_lshlrev_b32_e32 v118, 16, v33
	v_and_b32_e32 v119, 0xffff0000, v33
	v_lshlrev_b32_e32 v116, 16, v34
	v_and_b32_e32 v117, 0xffff0000, v34
	v_lshlrev_b32_e32 v114, 16, v35
	v_and_b32_e32 v115, 0xffff0000, v35
	s_and_saveexec_b64 s[14:15], s[2:3]
	v_pk_add_f32 v[152:153], v[152:153], v[108:109]
	v_pk_add_f32 v[144:145], v[144:145], v[118:119]
	v_pk_add_f32 v[142:143], v[142:143], v[116:117]
	v_pk_add_f32 v[162:163], v[162:163], v[114:115]
	s_or_b64 exec, exec, s[14:15]
	v_lshlrev_b32_e32 v36, 16, v28
	v_and_b32_e32 v37, 0xffff0000, v28
	v_lshlrev_b32_e32 v34, 16, v29
	v_and_b32_e32 v35, 0xffff0000, v29
	v_lshlrev_b32_e32 v32, 16, v30
	v_and_b32_e32 v33, 0xffff0000, v30
	v_lshlrev_b32_e32 v28, 16, v31
	v_and_b32_e32 v29, 0xffff0000, v31
	s_and_saveexec_b64 s[14:15], s[2:3]
	v_pk_add_f32 v[152:153], v[152:153], v[36:37]
	v_pk_add_f32 v[144:145], v[144:145], v[34:35]
	v_pk_add_f32 v[142:143], v[142:143], v[32:33]
	v_pk_add_f32 v[162:163], v[162:163], v[28:29]
	s_or_b64 exec, exec, s[14:15]
	v_cmp_gt_u32_e64 s[14:15], s80, v110
	v_lshlrev_b32_e32 v112, 16, v24
	v_and_b32_e32 v113, 0xffff0000, v24
	v_lshlrev_b32_e32 v110, 16, v25
	v_and_b32_e32 v111, 0xffff0000, v25
	v_lshlrev_b32_e32 v30, 16, v26
	v_and_b32_e32 v31, 0xffff0000, v26
	v_lshlrev_b32_e32 v24, 16, v27
	v_and_b32_e32 v25, 0xffff0000, v27
	s_and_saveexec_b64 s[16:17], s[14:15]
	v_pk_add_f32 v[152:153], v[152:153], v[112:113]
	v_pk_add_f32 v[144:145], v[144:145], v[110:111]
	v_pk_add_f32 v[142:143], v[142:143], v[30:31]
	v_pk_add_f32 v[162:163], v[162:163], v[24:25]
	s_or_b64 exec, exec, s[16:17]
	v_cmp_gt_u32_e64 s[16:17], s80, v120
	v_lshlrev_b32_e32 v122, 16, v20
	v_and_b32_e32 v123, 0xffff0000, v20
	v_lshlrev_b32_e32 v120, 16, v21
	v_and_b32_e32 v121, 0xffff0000, v21
	v_lshlrev_b32_e32 v26, 16, v22
	v_and_b32_e32 v27, 0xffff0000, v22
	v_lshlrev_b32_e32 v20, 16, v23
	v_and_b32_e32 v21, 0xffff0000, v23
	s_and_saveexec_b64 s[18:19], s[16:17]
	v_pk_add_f32 v[152:153], v[152:153], v[122:123]
	v_pk_add_f32 v[144:145], v[144:145], v[120:121]
	v_pk_add_f32 v[142:143], v[142:143], v[26:27]
	v_pk_add_f32 v[162:163], v[162:163], v[20:21]
	s_or_b64 exec, exec, s[18:19]
	v_cmp_gt_u32_e64 s[18:19], s80, v83
	v_lshlrev_b32_e32 v126, 16, v16
	v_and_b32_e32 v127, 0xffff0000, v16
	v_lshlrev_b32_e32 v124, 16, v17
	v_and_b32_e32 v125, 0xffff0000, v17
	v_lshlrev_b32_e32 v22, 16, v18
	v_and_b32_e32 v23, 0xffff0000, v18
	v_lshlrev_b32_e32 v16, 16, v19
	v_and_b32_e32 v17, 0xffff0000, v19
	s_and_saveexec_b64 s[20:21], s[18:19]
	v_pk_add_f32 v[152:153], v[152:153], v[126:127]
	v_pk_add_f32 v[144:145], v[144:145], v[124:125]
	v_pk_add_f32 v[142:143], v[142:143], v[22:23]
	v_pk_add_f32 v[162:163], v[162:163], v[16:17]
	s_or_b64 exec, exec, s[20:21]
	v_cmp_gt_u32_e64 s[20:21], s80, v81
	v_lshlrev_b32_e32 v130, 16, v12
	v_and_b32_e32 v131, 0xffff0000, v12
	v_lshlrev_b32_e32 v128, 16, v13
	v_and_b32_e32 v129, 0xffff0000, v13
	v_lshlrev_b32_e32 v18, 16, v14
	v_and_b32_e32 v19, 0xffff0000, v14
	v_lshlrev_b32_e32 v12, 16, v15
	v_and_b32_e32 v13, 0xffff0000, v15
	s_and_saveexec_b64 vcc, s[20:21]
	v_pk_add_f32 v[152:153], v[152:153], v[130:131]
	v_pk_add_f32 v[144:145], v[144:145], v[128:129]
	v_pk_add_f32 v[142:143], v[142:143], v[18:19]
	v_pk_add_f32 v[162:163], v[162:163], v[12:13]
	s_or_b64 exec, exec, vcc
	v_max_i32_e32 v14, 8, v80
	v_min_i32_e32 v15, 0x3ff8, v80
	v_sub_u32_e32 v14, v15, v14
	v_add_u32_e32 v14, 16, v14
	v_cvt_f32_i32_e32 v14, v14
	v_div_scale_f32 v15, s[40:41], v14, v14, 1.0
	v_rcp_f32_e32 v81, v15
	v_div_scale_f32 v83, vcc, 1.0, v14, 1.0
	v_fma_f32 v96, -v15, v81, 1.0
	v_fmac_f32_e32 v81, v96, v81
	v_mul_f32_e32 v96, v83, v81
	v_fma_f32 v133, -v15, v96, v83
	v_fmac_f32_e32 v96, v133, v81
	v_fma_f32 v15, -v15, v96, v83
	v_div_fmas_f32 v15, v15, v81, v96
	v_div_fixup_f32 v14, v15, v14, 1.0
	v_pk_fma_f32 v[152:153], v[14:15], v[152:153], v[46:47] op_sel_hi:[0,1,1] neg_lo:[0,0,1] neg_hi:[0,0,1]
	v_pk_fma_f32 v[144:145], v[14:15], v[144:145], v[102:103] op_sel_hi:[0,1,1] neg_lo:[0,0,1] neg_hi:[0,0,1]
	v_pk_fma_f32 v[142:143], v[14:15], v[142:143], v[100:101] op_sel_hi:[0,1,1] neg_lo:[0,0,1] neg_hi:[0,0,1]
	v_pk_fma_f32 v[14:15], v[14:15], v[162:163], v[40:41] op_sel_hi:[0,1,1] neg_lo:[0,0,1] neg_hi:[0,0,1]
	v_ashrrev_i32_e32 v81, 31, v80
	v_cvt_pk_bf16_f32 v167, v14, v15
	v_lshlrev_b64 v[14:15], 9, v[80:81]
	v_cvt_pk_bf16_f32 v164, v152, v153
	v_cvt_pk_bf16_f32 v165, v144, v145
	v_cvt_pk_bf16_f32 v166, v142, v143
	v_lshl_add_u64 v[14:15], v[76:77], 0, v[14:15]
	v_mov_b32_e32 v162, 0
	global_store_dwordx4 v[14:15], v[164:167], off
	v_mov_b32_e32 v163, 0
	v_mov_b32_e32 v142, 0
	v_mov_b32_e32 v143, 0
	v_mov_b32_e32 v14, 0
	v_mov_b32_e32 v15, v162
	v_mov_b32_e32 v144, v162
	v_mov_b32_e32 v145, v162
	v_mov_b32_e32 v152, 0
	v_mov_b32_e32 v153, 0
	s_and_saveexec_b64 vcc, s[24:25]
	s_cbranch_execz .LBB0_1097
	v_pk_add_f32 v[162:163], v[154:155], 0 op_sel_hi:[1,0]
	v_pk_add_f32 v[142:143], v[160:161], 0 op_sel_hi:[1,0]
	v_pk_add_f32 v[14:15], v[158:159], 0 op_sel_hi:[1,0]
	v_pk_add_f32 v[144:145], v[156:157], 0 op_sel_hi:[1,0]
	v_mov_b32_e32 v152, v162
	v_mov_b32_e32 v153, v163
	s_or_b64 exec, exec, vcc
	s_and_saveexec_b64 s[24:25], s[22:23]
	s_cbranch_execnz .LBB0_1098

; __device__ __forceinline__ float bflo(unsigned w) { return __uint_as_float(w << 16); }
; __device__ __forceinline__ float bfhi(unsigned w) { return __uint_as_float(w & 0xffff0000u); }
; __device__ __forceinline__ unsigned cvtpk(float lo, float hi) { f32x2_t v = {lo, hi}; bf16x2_t b = __builtin_convertvector(v, bf16x2_t); return __builtin_bit_cast(unsigned, b); }
; template <int HW>
; __device__ __forceinline__ void pool4(const bf16_t* zc, bf16_t* pc, int t0) {
;     ...
;         for (int i = 0; i < 2 * HW; ++i) { const int r = t - HW + i; const bool ok = (r >= 0) && (r < S); const u32x4 w = v[q + i];
;             if (ok) { a[0] += bflo(w.x); a[1] += bfhi(w.x); a[2] += bflo(w.y); a[3] += bfhi(w.y); a[4] += bflo(w.z); a[5] += bfhi(w.z); a[6] += bflo(w.w); a[7] += bfhi(w.w); } }
;         const int lo = max(t - HW, 0), hi = min(t + HW - 1, S - 1); const float inv = 1.0f / (float)(hi - lo + 1);
;         const u32x4 sv = v[q + HW];
;         u32x4 w; w.x = cvtpk(a[0] * inv - bflo(sv.x), a[1] * inv - bfhi(sv.x)); w.y = cvtpk(a[2] * inv - bflo(sv.y), a[3] * inv - bfhi(sv.y));
;         w.z = cvtpk(a[4] * inv - bflo(sv.z), a[5] * inv - bfhi(sv.z)); w.w = cvtpk(a[6] * inv - bflo(sv.w), a[7] * inv - bfhi(sv.w));
;         *(u32x4*)(pc + (size_t)t * 256) = w; }
.LBB0_1086:
	s_or_b64 exec, exec, s[24:25]
	v_add_u32_e32 v14, 8, v79
	v_cmp_gt_u32_e64 s[24:25], s80, v14
	v_lshlrev_b32_e32 v144, 16, v8
	v_and_b32_e32 v145, 0xffff0000, v8
	v_lshlrev_b32_e32 v142, 16, v9
	v_and_b32_e32 v143, 0xffff0000, v9
	v_lshlrev_b32_e32 v14, 16, v10
	v_and_b32_e32 v15, 0xffff0000, v10
	v_lshlrev_b32_e32 v8, 16, v11
	v_and_b32_e32 v9, 0xffff0000, v11
	s_and_saveexec_b64 vcc, s[24:25]
	v_pk_add_f32 v[158:159], v[158:159], v[144:145]
	v_pk_add_f32 v[156:157], v[156:157], v[142:143]
	v_pk_add_f32 v[154:155], v[154:155], v[14:15]
	v_pk_add_f32 v[152:153], v[152:153], v[8:9]
	s_or_b64 exec, exec, vcc
	v_max_i32_e32 v10, 8, v132
	v_min_i32_e32 v11, 0x3ff8, v132
	v_sub_u32_e32 v10, v11, v10
	v_add_u32_e32 v10, 16, v10
	v_cvt_f32_i32_e32 v10, v10
	v_div_scale_f32 v11, s[40:41], v10, v10, 1.0
	v_rcp_f32_e32 v81, v11
	v_div_scale_f32 v83, vcc, 1.0, v10, 1.0
	v_fma_f32 v96, -v11, v81, 1.0
	v_fmac_f32_e32 v81, v96, v81
	v_mul_f32_e32 v96, v83, v81
	v_fma_f32 v133, -v11, v96, v83
	v_fmac_f32_e32 v96, v133, v81
	v_fma_f32 v11, -v11, v96, v83
	v_div_fmas_f32 v11, v11, v81, v96
	v_div_fixup_f32 v10, v11, v10, 1.0
	v_pk_fma_f32 v[158:159], v[10:11], v[158:159], v[42:43] op_sel_hi:[0,1,1] neg_lo:[0,0,1] neg_hi:[0,0,1]
	v_pk_fma_f32 v[160:161], v[10:11], v[156:157], v[106:107] op_sel_hi:[0,1,1] neg_lo:[0,0,1] neg_hi:[0,0,1]
	v_pk_fma_f32 v[154:155], v[10:11], v[154:155], v[104:105] op_sel_hi:[0,1,1] neg_lo:[0,0,1] neg_hi:[0,0,1]
	v_pk_fma_f32 v[10:11], v[10:11], v[152:153], v[38:39] op_sel_hi:[0,1,1] neg_lo:[0,0,1] neg_hi:[0,0,1]
	v_ashrrev_i32_e32 v133, 31, v132
	v_cvt_pk_bf16_f32 v156, v158, v159
	v_cvt_pk_bf16_f32 v159, v10, v11
	v_lshlrev_b64 v[10:11], 9, v[132:133]
	v_cvt_pk_bf16_f32 v157, v160, v161
	v_cvt_pk_bf16_f32 v158, v154, v155
	v_lshl_add_u64 v[10:11], v[76:77], 0, v[10:11]
	global_store_dwordx4 v[10:11], v[156:159], off
	v_mov_b32_e32 v10, 0
	v_mov_b32_e32 v11, 0
	v_mov_b32_e32 v156, 0
	v_mov_b32_e32 v157, 0
	v_mov_b32_e32 v132, 0
	v_mov_b32_e32 v133, v156
	v_mov_b32_e32 v152, v156
	v_mov_b32_e32 v153, v156
	v_mov_b32_e32 v154, 0
	v_mov_b32_e32 v155, 0
	s_and_saveexec_b64 vcc, s[22:23]
	s_cbranch_execz .LBB0_1109
	v_pk_add_f32 v[156:157], v[134:135], 0 op_sel_hi:[1,0]
	v_pk_add_f32 v[10:11], v[140:141], 0 op_sel_hi:[1,0]
	v_pk_add_f32 v[132:133], v[138:139], 0 op_sel_hi:[1,0]
	v_pk_add_f32 v[152:153], v[136:137], 0 op_sel_hi:[1,0]
	v_mov_b32_e32 v154, v156
	v_mov_b32_e32 v155, v157
	s_or_b64 exec, exec, vcc
	s_and_saveexec_b64 s[22:23], s[8:9]
	s_cbranch_execnz .LBB0_1110

; __device__ __forceinline__ float bflo(unsigned w) { return __uint_as_float(w << 16); }
; __device__ __forceinline__ float bfhi(unsigned w) { return __uint_as_float(w & 0xffff0000u); }
; __device__ __forceinline__ unsigned cvtpk(float lo, float hi) { f32x2_t v = {lo, hi}; bf16x2_t b = __builtin_convertvector(v, bf16x2_t); return __builtin_bit_cast(unsigned, b); }
; template <int HW>
; __device__ __forceinline__ void pool4(const bf16_t* zc, bf16_t* pc, int t0) {
;     ...
;         for (int i = 0; i < 2 * HW; ++i) { const int r = t - HW + i; const bool ok = (r >= 0) && (r < S); const u32x4 w = v[q + i];
;             if (ok) { a[0] += bflo(w.x); a[1] += bfhi(w.x); a[2] += bflo(w.y); a[3] += bfhi(w.y); a[4] += bflo(w.z); a[5] += bfhi(w.z); a[6] += bflo(w.w); a[7] += bfhi(w.w); } }
;         const int lo = max(t - HW, 0), hi = min(t + HW - 1, S - 1); const float inv = 1.0f / (float)(hi - lo + 1);
;         const u32x4 sv = v[q + HW];
;         u32x4 w; w.x = cvtpk(a[0] * inv - bflo(sv.x), a[1] * inv - bfhi(sv.x)); w.y = cvtpk(a[2] * inv - bflo(sv.y), a[3] * inv - bfhi(sv.y));
;         w.z = cvtpk(a[4] * inv - bflo(sv.z), a[5] * inv - bfhi(sv.z)); w.w = cvtpk(a[6] * inv - bflo(sv.w), a[7] * inv - bfhi(sv.w));
;         *(u32x4*)(pc + (size_t)t * 256) = w; }
.LBB0_1123:
	s_or_b64 exec, exec, s[22:23]
	v_add_u32_e32 v10, 9, v80
	v_cmp_gt_u32_e64 s[22:23], s80, v10
	v_lshlrev_b32_e32 v134, 16, v4
	v_and_b32_e32 v135, 0xffff0000, v4
	v_lshlrev_b32_e32 v132, 16, v5
	v_and_b32_e32 v133, 0xffff0000, v5
	v_lshlrev_b32_e32 v10, 16, v6
	v_and_b32_e32 v11, 0xffff0000, v6
	v_lshlrev_b32_e32 v4, 16, v7
	v_and_b32_e32 v5, 0xffff0000, v7
	s_and_saveexec_b64 vcc, s[22:23]
	v_pk_add_f32 v[152:153], v[152:153], v[134:135]
	v_pk_add_f32 v[140:141], v[140:141], v[132:133]
	v_pk_add_f32 v[138:139], v[138:139], v[10:11]
	v_pk_add_f32 v[136:137], v[136:137], v[4:5]
	s_or_b64 exec, exec, vcc
	v_max_i32_e32 v6, 8, v82
	v_min_i32_e32 v7, 0x3ff8, v82
	v_sub_u32_e32 v6, v7, v6
	v_add_u32_e32 v6, 16, v6
	v_cvt_f32_i32_e32 v6, v6
	v_div_scale_f32 v7, s[40:41], v6, v6, 1.0
	v_rcp_f32_e32 v81, v7
	v_div_scale_f32 v83, vcc, 1.0, v6, 1.0
	v_fma_f32 v96, -v7, v81, 1.0
	v_fmac_f32_e32 v81, v96, v81
	v_mul_f32_e32 v96, v83, v81
	v_fma_f32 v151, -v7, v96, v83
	v_fmac_f32_e32 v96, v151, v81
	v_fma_f32 v7, -v7, v96, v83
	v_div_fmas_f32 v7, v7, v81, v96
	v_div_fixup_f32 v6, v7, v6, 1.0
	v_pk_fma_f32 v[152:153], v[6:7], v[152:153], v[108:109] op_sel_hi:[0,1,1] neg_lo:[0,0,1] neg_hi:[0,0,1]
	v_pk_fma_f32 v[140:141], v[6:7], v[140:141], v[118:119] op_sel_hi:[0,1,1] neg_lo:[0,0,1] neg_hi:[0,0,1]
	v_pk_fma_f32 v[138:139], v[6:7], v[138:139], v[116:117] op_sel_hi:[0,1,1] neg_lo:[0,0,1] neg_hi:[0,0,1]
	v_pk_fma_f32 v[6:7], v[6:7], v[136:137], v[114:115] op_sel_hi:[0,1,1] neg_lo:[0,0,1] neg_hi:[0,0,1]
	v_ashrrev_i32_e32 v83, 31, v82
	v_cvt_pk_bf16_f32 v155, v6, v7
	v_lshlrev_b64 v[6:7], 9, v[82:83]
	v_cvt_pk_bf16_f32 v152, v152, v153
	v_cvt_pk_bf16_f32 v153, v140, v141
	v_cvt_pk_bf16_f32 v154, v138, v139
	v_lshl_add_u64 v[6:7], v[76:77], 0, v[6:7]
	v_mov_b32_e32 v140, 0
	global_store_dwordx4 v[6:7], v[152:155], off
	v_mov_b32_e32 v141, 0
	v_mov_b32_e32 v6, 0
	v_mov_b32_e32 v7, 0
	v_mov_b32_e32 v82, 0
	v_mov_b32_e32 v83, v140
	v_mov_b32_e32 v136, v140
	v_mov_b32_e32 v137, v140
	v_mov_b32_e32 v138, 0
	v_mov_b32_e32 v139, 0
	s_and_saveexec_b64 vcc, s[8:9]
	s_cbranch_execz .LBB0_1191
	v_pk_add_f32 v[140:141], v[70:71], 0 op_sel_hi:[1,0]
	v_pk_add_f32 v[6:7], v[88:89], 0 op_sel_hi:[1,0]
	v_pk_add_f32 v[82:83], v[86:87], 0 op_sel_hi:[1,0]
	v_pk_add_f32 v[136:137], v[84:85], 0 op_sel_hi:[1,0]
	v_mov_b32_e32 v138, v140
	v_mov_b32_e32 v139, v141
	s_or_b64 exec, exec, vcc
	s_and_saveexec_b64 s[8:9], s[4:5]
	s_cbranch_execnz .LBB0_1192

; __device__ __forceinline__ float bflo(unsigned w) { return __uint_as_float(w << 16); }
; __device__ __forceinline__ float bfhi(unsigned w) { return __uint_as_float(w & 0xffff0000u); }
; __device__ __forceinline__ unsigned cvtpk(float lo, float hi) { f32x2_t v = {lo, hi}; bf16x2_t b = __builtin_convertvector(v, bf16x2_t); return __builtin_bit_cast(unsigned, b); }
; template <int HW>
; __device__ __forceinline__ void pool4(const bf16_t* zc, bf16_t* pc, int t0) {
;     ...
;     for (int i = 0; i < NR; ++i) { const int r = min(max(t0 - HW + i, 0), S - 1); v[i] = *(const u32x4*)(zc + (size_t)r * ZP); }
; #pragma unroll
;     for (int q = 0; q < 4; ++q) { const int t = t0 + q; float a[8];
; #pragma unroll
;         for (int i = 0; i < 8; ++i) a[i] = 0.f;
; #pragma unroll
;         for (int i = 0; i < 2 * HW; ++i) { const int r = t - HW + i; const bool ok = (r >= 0) && (r < S); const u32x4 w = v[q + i];
;             if (ok) { a[0] += bflo(w.x); a[1] += bfhi(w.x); a[2] += bflo(w.y); a[3] += bfhi(w.y); a[4] += bflo(w.z); a[5] += bfhi(w.z); a[6] += bflo(w.w); a[7] += bfhi(w.w); } }
;         const int lo = max(t - HW, 0), hi = min(t + HW - 1, S - 1); const float inv = 1.0f / (float)(hi - lo + 1);
;         const u32x4 sv = v[q + HW];
;         u32x4 w; w.x = cvtpk(a[0] * inv - bflo(sv.x), a[1] * inv - bfhi(sv.x)); w.y = cvtpk(a[2] * inv - bflo(sv.y), a[3] * inv - bfhi(sv.y));
;         w.z = cvtpk(a[4] * inv - bflo(sv.z), a[5] * inv - bfhi(sv.z)); w.w = cvtpk(a[6] * inv - bflo(sv.w), a[7] * inv - bfhi(sv.w));
;         *(u32x4*)(pc + (size_t)t * 256) = w; }
.LBB0_1142:
	v_add_u32_e32 v25, -1, v80
	v_max_i32_e32 v0, 0, v25
	v_mul_lo_u32 v96, v0, s33
	v_max_i32_e32 v2, 0, v80
	v_lshl_add_u64 v[0:1], v[72:73], 0, v[96:97]
	v_mul_lo_u32 v96, v2, s33
	v_or_b32_e32 v26, 1, v80
	v_lshl_add_u64 v[2:3], v[72:73], 0, v[96:97]
	global_load_dwordx4 v[20:23], v[0:1], off
	global_load_dwordx4 v[16:19], v[2:3], off
	v_max_i32_e32 v0, 0, v26
	v_or_b32_e32 v24, 2, v80
	v_mul_lo_u32 v96, v0, s33
	v_max_i32_e32 v2, 0, v24
	v_lshl_add_u64 v[0:1], v[72:73], 0, v[96:97]
	v_mul_lo_u32 v96, v2, s33
	v_lshl_add_u64 v[2:3], v[72:73], 0, v[96:97]
	global_load_dwordx4 v[12:15], v[0:1], off
	global_load_dwordx4 v[8:11], v[2:3], off
	v_or_b32_e32 v78, 3, v79
	v_max_i32_e32 v2, -4, v80
	v_max_i32_e32 v0, 0, v78
	v_add_u32_e32 v2, 4, v2
	v_mul_lo_u32 v96, v0, s33
	v_min_u32_e32 v2, 0x3fff, v2
	v_lshl_add_u64 v[0:1], v[72:73], 0, v[96:97]
	v_mul_u32_u24_e32 v96, 0x2800, v2
	v_lshl_add_u64 v[2:3], v[72:73], 0, v[96:97]
	global_load_dwordx4 v[4:7], v[0:1], off
	s_nop 0
	global_load_dwordx4 v[0:3], v[2:3], off
	v_add_u32_e32 v27, -2, v80
	v_mov_b32_e32 v28, 0
	v_cmp_gt_u32_e32 vcc, s80, v27
	v_mov_b32_e32 v29, 0
	v_mov_b32_e32 v38, 0
	v_mov_b32_e32 v39, v28
	v_mov_b32_e32 v36, v28
	v_mov_b32_e32 v37, v28
	v_mov_b32_e32 v34, v28
	v_mov_b32_e32 v35, v28
	v_mov_b32_e32 v48, v28
	v_mov_b32_e32 v49, v28
	s_and_saveexec_b64 s[2:3], vcc
	s_cbranch_execz .LBB0_1144
	v_mul_lo_u32 v96, v27, s33
	v_lshl_add_u64 v[28:29], v[72:73], 0, v[96:97]
	global_load_dwordx4 v[28:31], v[28:29], off
	s_waitcnt vmcnt(0) lgkmcnt(0)
	v_lshlrev_b32_e32 v32, 16, v28
	v_and_b32_e32 v33, 0xffff0000, v28
	v_lshlrev_b32_e32 v28, 16, v29
	v_and_b32_e32 v29, 0xffff0000, v29
	v_lshlrev_b32_e32 v34, 16, v30
	v_and_b32_e32 v35, 0xffff0000, v30
	v_lshlrev_b32_e32 v30, 16, v31
	v_and_b32_e32 v31, 0xffff0000, v31
	v_pk_add_f32 v[36:37], v[28:29], 0 op_sel_hi:[1,0]
	v_pk_add_f32 v[28:29], v[30:31], 0 op_sel_hi:[1,0]
	v_pk_add_f32 v[38:39], v[32:33], 0 op_sel_hi:[1,0]
	v_pk_add_f32 v[34:35], v[34:35], 0 op_sel_hi:[1,0]
	v_mov_b32_e32 v48, v28
	v_mov_b32_e32 v49, v29
.LBB0_1144:
	s_or_b64 exec, exec, s[2:3]
	v_cmp_gt_u32_e64 s[4:5], s80, v25
	s_waitcnt vmcnt(0) lgkmcnt(0)
	v_lshlrev_b32_e32 v46, 16, v20
	v_and_b32_e32 v47, 0xffff0000, v20
	v_lshlrev_b32_e32 v44, 16, v21
	v_and_b32_e32 v45, 0xffff0000, v21
	v_lshlrev_b32_e32 v42, 16, v22
	v_and_b32_e32 v43, 0xffff0000, v22
	v_lshlrev_b32_e32 v40, 16, v23
	v_and_b32_e32 v41, 0xffff0000, v23
	s_and_saveexec_b64 s[2:3], s[4:5]
	v_pk_add_f32 v[38:39], v[38:39], v[46:47]
	v_pk_add_f32 v[36:37], v[36:37], v[44:45]
	v_pk_add_f32 v[34:35], v[34:35], v[42:43]
	v_pk_add_f32 v[48:49], v[28:29], v[40:41]
	s_or_b64 exec, exec, s[2:3]
	v_cmp_gt_u32_e64 s[2:3], s80, v79
	v_lshlrev_b32_e32 v22, 16, v16
	v_and_b32_e32 v23, 0xffff0000, v16
	v_lshlrev_b32_e32 v32, 16, v17
	v_and_b32_e32 v33, 0xffff0000, v17
	v_lshlrev_b32_e32 v30, 16, v18
	v_and_b32_e32 v31, 0xffff0000, v18
	v_lshlrev_b32_e32 v28, 16, v19
	v_and_b32_e32 v29, 0xffff0000, v19
	s_and_saveexec_b64 s[8:9], s[2:3]
	v_pk_add_f32 v[38:39], v[38:39], v[22:23]
	v_pk_add_f32 v[36:37], v[36:37], v[32:33]
	v_pk_add_f32 v[34:35], v[34:35], v[30:31]
	v_pk_add_f32 v[48:49], v[48:49], v[28:29]
	s_or_b64 exec, exec, s[8:9]
	v_lshlrev_b32_e32 v16, 16, v12
	v_and_b32_e32 v17, 0xffff0000, v12
	v_lshlrev_b32_e32 v20, 16, v13
	v_and_b32_e32 v21, 0xffff0000, v13
	v_lshlrev_b32_e32 v18, 16, v14
	v_and_b32_e32 v19, 0xffff0000, v14
	v_lshlrev_b32_e32 v12, 16, v15
	v_and_b32_e32 v13, 0xffff0000, v15
	s_and_saveexec_b64 s[8:9], s[2:3]
	v_pk_add_f32 v[38:39], v[38:39], v[16:17]
	v_pk_add_f32 v[36:37], v[36:37], v[20:21]
	v_pk_add_f32 v[34:35], v[34:35], v[18:19]
	v_pk_add_f32 v[48:49], v[48:49], v[12:13]
	s_or_b64 exec, exec, s[8:9]
	v_max_i32_e32 v14, 2, v80
	v_sub_u32_e32 v14, v80, v14
	v_add_u32_e32 v14, 4, v14
	v_cvt_f32_i32_e32 v14, v14
	v_ashrrev_i32_e32 v81, 31, v80
	v_div_scale_f32 v15, s[8:9], v14, v14, 1.0
	v_rcp_f32_e32 v25, v15
	v_div_scale_f32 v27, vcc, 1.0, v14, 1.0
	v_fma_f32 v50, -v15, v25, 1.0
	v_fmac_f32_e32 v25, v50, v25
	v_mul_f32_e32 v50, v27, v25
	v_fma_f32 v51, -v15, v50, v27
	v_fmac_f32_e32 v50, v51, v25
	v_fma_f32 v15, -v15, v50, v27
	v_div_fmas_f32 v15, v15, v25, v50
	v_div_fixup_f32 v14, v15, v14, 1.0
	v_pk_fma_f32 v[38:39], v[14:15], v[38:39], v[22:23] op_sel_hi:[0,1,1] neg_lo:[0,0,1] neg_hi:[0,0,1]
	v_pk_fma_f32 v[50:51], v[14:15], v[36:37], v[32:33] op_sel_hi:[0,1,1] neg_lo:[0,0,1] neg_hi:[0,0,1]
	v_pk_fma_f32 v[34:35], v[14:15], v[34:35], v[30:31] op_sel_hi:[0,1,1] neg_lo:[0,0,1] neg_hi:[0,0,1]
	v_pk_fma_f32 v[14:15], v[14:15], v[48:49], v[28:29] op_sel_hi:[0,1,1] neg_lo:[0,0,1] neg_hi:[0,0,1]
	v_cvt_pk_bf16_f32 v36, v38, v39
	v_cvt_pk_bf16_f32 v39, v14, v15
	v_lshlrev_b64 v[14:15], 9, v[80:81]
	v_cvt_pk_bf16_f32 v37, v50, v51
	v_cvt_pk_bf16_f32 v38, v34, v35
	v_lshl_add_u64 v[14:15], v[76:77], 0, v[14:15]
	global_store_dwordx4 v[14:15], v[36:39], off
	v_mov_b32_e32 v14, 0
	v_mov_b32_e32 v15, 0
	v_mov_b32_e32 v34, 0
	v_mov_b32_e32 v35, 0
	v_mov_b32_e32 v36, 0
	v_mov_b32_e32 v37, 0
	v_mov_b32_e32 v38, 0
	v_mov_b32_e32 v39, 0
	s_and_saveexec_b64 s[8:9], s[4:5]
	v_pk_add_f32 v[14:15], v[46:47], 0 op_sel_hi:[1,0]
	v_pk_add_f32 v[34:35], v[44:45], 0 op_sel_hi:[1,0]
	v_pk_add_f32 v[36:37], v[42:43], 0 op_sel_hi:[1,0]
	v_pk_add_f32 v[38:39], v[40:41], 0 op_sel_hi:[1,0]
	s_or_b64 exec, exec, s[8:9]
	v_pk_add_f32 v[44:45], v[14:15], v[22:23]
	v_pk_add_f32 v[42:43], v[34:35], v[32:33]
	v_pk_add_f32 v[40:41], v[36:37], v[30:31]
	v_pk_add_f32 v[46:47], v[38:39], v[28:29]
	v_cndmask_b32_e64 v41, v37, v41, s[2:3]
	v_cndmask_b32_e64 v39, v39, v47, s[2:3]
	v_cndmask_b32_e64 v38, v38, v46, s[2:3]
; __device__ __forceinline__ float bflo(unsigned w) { return __uint_as_float(w << 16); }
; __device__ __forceinline__ float bfhi(unsigned w) { return __uint_as_float(w & 0xffff0000u); }
; __device__ __forceinline__ unsigned cvtpk(float lo, float hi) { f32x2_t v = {lo, hi}; bf16x2_t b = __builtin_convertvector(v, bf16x2_t); return __builtin_bit_cast(unsigned, b); }
; template <int HW>
; __device__ __forceinline__ void pool4(const bf16_t* zc, bf16_t* pc, int t0) {
;     ...
;         for (int i = 0; i < 2 * HW; ++i) { const int r = t - HW + i; const bool ok = (r >= 0) && (r < S); const u32x4 w = v[q + i];
;             if (ok) { a[0] += bflo(w.x); a[1] += bfhi(w.x); a[2] += bflo(w.y); a[3] += bfhi(w.y); a[4] += bflo(w.z); a[5] += bfhi(w.z); a[6] += bflo(w.w); a[7] += bfhi(w.w); } }
;         const int lo = max(t - HW, 0), hi = min(t + HW - 1, S - 1); const float inv = 1.0f / (float)(hi - lo + 1);
;         const u32x4 sv = v[q + HW];
;         u32x4 w; w.x = cvtpk(a[0] * inv - bflo(sv.x), a[1] * inv - bfhi(sv.x)); w.y = cvtpk(a[2] * inv - bflo(sv.y), a[3] * inv - bfhi(sv.y));
;         w.z = cvtpk(a[4] * inv - bflo(sv.z), a[5] * inv - bfhi(sv.z)); w.w = cvtpk(a[6] * inv - bflo(sv.w), a[7] * inv - bfhi(sv.w));
;         *(u32x4*)(pc + (size_t)t * 256) = w; }
	v_cndmask_b32_e64 v40, v36, v40, s[2:3]
	v_cndmask_b32_e64 v43, v35, v43, s[2:3]
	v_cndmask_b32_e64 v42, v34, v42, s[2:3]
	v_cndmask_b32_e64 v45, v15, v45, s[2:3]
	v_cndmask_b32_e64 v44, v14, v44, s[2:3]
	s_and_saveexec_b64 s[4:5], s[2:3]
	v_pk_add_f32 v[44:45], v[44:45], v[16:17]
	v_pk_add_f32 v[42:43], v[42:43], v[20:21]
	v_pk_add_f32 v[40:41], v[40:41], v[18:19]
	v_pk_add_f32 v[38:39], v[38:39], v[12:13]
	s_or_b64 exec, exec, s[4:5]
	v_lshlrev_b32_e32 v36, 16, v8
	v_and_b32_e32 v37, 0xffff0000, v8
	v_lshlrev_b32_e32 v34, 16, v9
	v_and_b32_e32 v35, 0xffff0000, v9
	v_lshlrev_b32_e32 v14, 16, v10
	v_and_b32_e32 v15, 0xffff0000, v10
	v_lshlrev_b32_e32 v8, 16, v11
	v_and_b32_e32 v9, 0xffff0000, v11
	s_and_saveexec_b64 s[4:5], s[2:3]
	v_pk_add_f32 v[44:45], v[44:45], v[36:37]
	v_pk_add_f32 v[42:43], v[42:43], v[34:35]
	v_pk_add_f32 v[40:41], v[40:41], v[14:15]
	v_pk_add_f32 v[38:39], v[38:39], v[8:9]
	s_or_b64 exec, exec, s[4:5]
	v_max_i32_e32 v10, 2, v26
	v_sub_u32_e32 v10, v80, v10
	v_add_u32_e32 v10, 5, v10
	v_cvt_f32_i32_e32 v10, v10
	v_pk_add_f32 v[28:29], v[28:29], 0 op_sel_hi:[1,0]
	v_pk_add_f32 v[22:23], v[22:23], 0 op_sel_hi:[1,0]
	v_cndmask_b32_e64 v29, 0, v29, s[2:3]
	v_div_scale_f32 v11, s[4:5], v10, v10, 1.0
	v_rcp_f32_e32 v25, v11
	v_div_scale_f32 v27, vcc, 1.0, v10, 1.0
	v_cndmask_b32_e64 v23, 0, v23, s[2:3]
	v_fma_f32 v46, -v11, v25, 1.0
	v_fmac_f32_e32 v25, v46, v25
	v_mul_f32_e32 v46, v27, v25
	v_fma_f32 v47, -v11, v46, v27
	v_fmac_f32_e32 v46, v47, v25
	v_fma_f32 v11, -v11, v46, v27
	v_div_fmas_f32 v11, v11, v25, v46
	v_div_fixup_f32 v10, v11, v10, 1.0
	v_pk_fma_f32 v[44:45], v[10:11], v[44:45], v[16:17] op_sel_hi:[0,1,1] neg_lo:[0,0,1] neg_hi:[0,0,1]
	v_pk_fma_f32 v[46:47], v[10:11], v[42:43], v[20:21] op_sel_hi:[0,1,1] neg_lo:[0,0,1] neg_hi:[0,0,1]
	v_pk_fma_f32 v[40:41], v[10:11], v[40:41], v[18:19] op_sel_hi:[0,1,1] neg_lo:[0,0,1] neg_hi:[0,0,1]
	v_pk_fma_f32 v[10:11], v[10:11], v[38:39], v[12:13] op_sel_hi:[0,1,1] neg_lo:[0,0,1] neg_hi:[0,0,1]
	v_ashrrev_i32_e32 v27, 31, v26
	v_cvt_pk_bf16_f32 v42, v44, v45
	v_cvt_pk_bf16_f32 v45, v10, v11
	v_lshlrev_b64 v[10:11], 9, v[26:27]
	v_cvt_pk_bf16_f32 v43, v46, v47
	v_cvt_pk_bf16_f32 v44, v40, v41
	v_lshl_add_u64 v[10:11], v[76:77], 0, v[10:11]
	global_store_dwordx4 v[10:11], v[42:45], off
	v_pk_add_f32 v[10:11], v[32:33], 0 op_sel_hi:[1,0]
	v_pk_add_f32 v[26:27], v[30:31], 0 op_sel_hi:[1,0]
	v_cndmask_b32_e64 v22, 0, v22, s[2:3]
	v_cndmask_b32_e64 v28, 0, v28, s[2:3]
	v_cndmask_b32_e64 v27, 0, v27, s[2:3]
	v_cndmask_b32_e64 v26, 0, v26, s[2:3]
	v_cndmask_b32_e64 v11, 0, v11, s[2:3]
	v_cndmask_b32_e64 v10, 0, v10, s[2:3]
	v_pk_add_f32 v[38:39], v[22:23], v[16:17]
	v_pk_add_f32 v[32:33], v[10:11], v[20:21]
	v_pk_add_f32 v[30:31], v[26:27], v[18:19]
	v_pk_add_f32 v[40:41], v[28:29], v[12:13]
	v_cndmask_b32_e64 v31, v27, v31, s[2:3]
	v_cndmask_b32_e64 v29, v29, v41, s[2:3]
	v_cndmask_b32_e64 v28, v28, v40, s[2:3]
	v_cndmask_b32_e64 v30, v26, v30, s[2:3]
	v_cndmask_b32_e64 v33, v11, v33, s[2:3]
	v_cndmask_b32_e64 v32, v10, v32, s[2:3]
	v_cndmask_b32_e64 v39, v23, v39, s[2:3]
	v_cndmask_b32_e64 v38, v22, v38, s[2:3]
	s_and_saveexec_b64 s[4:5], s[2:3]
	v_pk_add_f32 v[38:39], v[38:39], v[36:37]
	v_pk_add_f32 v[32:33], v[32:33], v[34:35]
	v_pk_add_f32 v[30:31], v[30:31], v[14:15]
	v_pk_add_f32 v[28:29], v[28:29], v[8:9]
	s_or_b64 exec, exec, s[4:5]
	v_lshlrev_b32_e32 v26, 16, v4
	v_and_b32_e32 v27, 0xffff0000, v4
	v_lshlrev_b32_e32 v22, 16, v5
	v_and_b32_e32 v23, 0xffff0000, v5
	v_lshlrev_b32_e32 v10, 16, v6
	v_and_b32_e32 v11, 0xffff0000, v6
	v_lshlrev_b32_e32 v4, 16, v7
	v_and_b32_e32 v5, 0xffff0000, v7
	s_and_saveexec_b64 s[4:5], s[2:3]
	v_pk_add_f32 v[38:39], v[38:39], v[26:27]
	v_pk_add_f32 v[32:33], v[32:33], v[22:23]
	v_pk_add_f32 v[30:31], v[30:31], v[10:11]
	v_pk_add_f32 v[28:29], v[28:29], v[4:5]
	s_or_b64 exec, exec, s[4:5]
	v_max_i32_e32 v6, 2, v24
	v_sub_u32_e32 v6, v80, v6
	v_add_u32_e32 v6, 6, v6
	v_cvt_f32_i32_e32 v6, v6
	v_pk_add_f32 v[18:19], v[18:19], 0 op_sel_hi:[1,0]
	v_pk_add_f32 v[12:13], v[12:13], 0 op_sel_hi:[1,0]
	v_pk_add_f32 v[16:17], v[16:17], 0 op_sel_hi:[1,0]
	v_div_scale_f32 v7, s[4:5], v6, v6, 1.0
	v_rcp_f32_e32 v25, v7
	v_div_scale_f32 v40, vcc, 1.0, v6, 1.0
	v_cndmask_b32_e64 v17, 0, v17, s[2:3]
	v_fma_f32 v41, -v7, v25, 1.0
	v_fmac_f32_e32 v25, v41, v25
	v_mul_f32_e32 v41, v40, v25
	v_fma_f32 v42, -v7, v41, v40
	v_fmac_f32_e32 v41, v42, v25
	v_fma_f32 v7, -v7, v41, v40
	v_div_fmas_f32 v7, v7, v25, v41
	v_div_fixup_f32 v6, v7, v6, 1.0
	v_pk_fma_f32 v[38:39], v[6:7], v[38:39], v[36:37] op_sel_hi:[0,1,1] neg_lo:[0,0,1] neg_hi:[0,0,1]
	v_pk_fma_f32 v[32:33], v[6:7], v[32:33], v[34:35] op_sel_hi:[0,1,1] neg_lo:[0,0,1] neg_hi:[0,0,1]
	v_pk_fma_f32 v[30:31], v[6:7], v[30:31], v[14:15] op_sel_hi:[0,1,1] neg_lo:[0,0,1] neg_hi:[0,0,1]
	v_pk_fma_f32 v[6:7], v[6:7], v[28:29], v[8:9] op_sel_hi:[0,1,1] neg_lo:[0,0,1] neg_hi:[0,0,1]
	v_ashrrev_i32_e32 v25, 31, v24
	v_cvt_pk_bf16_f32 v41, v6, v7
	v_lshlrev_b64 v[6:7], 9, v[24:25]
	v_cvt_pk_bf16_f32 v38, v38, v39
	v_cvt_pk_bf16_f32 v39, v32, v33
	v_cvt_pk_bf16_f32 v40, v30, v31
	v_lshl_add_u64 v[6:7], v[76:77], 0, v[6:7]
	global_store_dwordx4 v[6:7], v[38:41], off
	v_pk_add_f32 v[6:7], v[20:21], 0 op_sel_hi:[1,0]
	v_cndmask_b32_e64 v16, 0, v16, s[2:3]
	v_cndmask_b32_e64 v13, 0, v13, s[2:3]
	v_cndmask_b32_e64 v12, 0, v12, s[2:3]
	v_cndmask_b32_e64 v19, 0, v19, s[2:3]
	v_cndmask_b32_e64 v18, 0, v18, s[2:3]
	v_cndmask_b32_e64 v21, 0, v7, s[2:3]
	v_cndmask_b32_e64 v20, 0, v6, s[2:3]
	v_pk_add_f32 v[24:25], v[16:17], v[36:37]
	v_pk_add_f32 v[28:29], v[20:21], v[34:35]
	v_pk_add_f32 v[14:15], v[18:19], v[14:15]
	v_pk_add_f32 v[6:7], v[12:13], v[8:9]
	v_cndmask_b32_e64 v9, v19, v15, s[2:3]
	v_cndmask_b32_e64 v7, v13, v7, s[2:3]
	v_cndmask_b32_e64 v6, v12, v6, s[2:3]
	v_cndmask_b32_e64 v8, v18, v14, s[2:3]
	v_cndmask_b32_e64 v13, v21, v29, s[2:3]
	v_cndmask_b32_e64 v12, v20, v28, s[2:3]
	v_cndmask_b32_e64 v15, v17, v25, s[2:3]
	v_cndmask_b32_e64 v14, v16, v24, s[2:3]
	s_and_saveexec_b64 s[4:5], s[2:3]
	v_pk_add_f32 v[14:15], v[14:15], v[26:27]
	v_pk_add_f32 v[12:13], v[12:13], v[22:23]
	v_pk_add_f32 v[8:9], v[8:9], v[10:11]
	v_pk_add_f32 v[6:7], v[6:7], v[4:5]
	s_or_b64 exec, exec, s[4:5]
	v_add_u32_e32 v16, 4, v79
	v_cmp_gt_u32_e32 vcc, s80, v16
	s_and_saveexec_b64 s[2:3], vcc
	s_cbranch_execz .LBB0_1164
	v_lshlrev_b32_e32 v16, 16, v0
	v_and_b32_e32 v17, 0xffff0000, v0
	v_lshlrev_b32_e32 v0, 16, v1
	v_and_b32_e32 v1, 0xffff0000, v1
	v_pk_add_f32 v[12:13], v[12:13], v[0:1]
	v_lshlrev_b32_e32 v0, 16, v2
	v_and_b32_e32 v1, 0xffff0000, v2
	v_pk_add_f32 v[8:9], v[8:9], v[0:1]
	v_lshlrev_b32_e32 v0, 16, v3
	v_and_b32_e32 v1, 0xffff0000, v3
	v_pk_add_f32 v[14:15], v[14:15], v[16:17]
	v_pk_add_f32 v[6:7], v[6:7], v[0:1]

; __device__ __forceinline__ float bflo(unsigned w) { return __uint_as_float(w << 16); }
; __device__ __forceinline__ float bfhi(unsigned w) { return __uint_as_float(w & 0xffff0000u); }
; template <int HW>
; __device__ __forceinline__ void pool4(const bf16_t* zc, bf16_t* pc, int t0) {
;     ...
;     for (int i = 0; i < NR; ++i) { const int r = min(max(t0 - HW + i, 0), S - 1); v[i] = *(const u32x4*)(zc + (size_t)r * ZP); }
; #pragma unroll
;     for (int q = 0; q < 4; ++q) { const int t = t0 + q; float a[8];
; #pragma unroll
;         for (int i = 0; i < 8; ++i) a[i] = 0.f;
; #pragma unroll
;         for (int i = 0; i < 2 * HW; ++i) { const int r = t - HW + i; const bool ok = (r >= 0) && (r < S); const u32x4 w = v[q + i];
;             if (ok) { a[0] += bflo(w.x); a[1] += bfhi(w.x); a[2] += bflo(w.y); a[3] += bfhi(w.y); a[4] += bflo(w.z); a[5] += bfhi(w.z); a[6] += bflo(w.w); a[7] += bfhi(w.w); } }
.LBB0_1166:
	s_andn2_saveexec_b64 s[8:9], s[88:89]
	s_cbranch_execz .LBB0_987
	v_max_i32_e32 v0, 0, v80
	v_or_b32_e32 v26, 1, v80
	v_mul_lo_u32 v96, v0, s33
	v_max_i32_e32 v2, 0, v26
	v_lshl_add_u64 v[0:1], v[72:73], 0, v[96:97]
	v_mul_lo_u32 v96, v2, s33
	v_or_b32_e32 v24, 2, v80
	v_lshl_add_u64 v[2:3], v[72:73], 0, v[96:97]
	global_load_dwordx4 v[20:23], v[0:1], off
	global_load_dwordx4 v[16:19], v[2:3], off
	v_max_i32_e32 v0, 0, v24
	v_or_b32_e32 v78, 3, v79
	v_mul_lo_u32 v96, v0, s33
	v_max_i32_e32 v2, 0, v78
	v_lshl_add_u64 v[0:1], v[72:73], 0, v[96:97]
	v_mul_lo_u32 v96, v2, s33
	v_lshl_add_u64 v[2:3], v[72:73], 0, v[96:97]
	global_load_dwordx4 v[12:15], v[0:1], off
	global_load_dwordx4 v[8:11], v[2:3], off
	v_mov_b32_e32 v96, v97
	v_mov_b32_e32 v98, v97
	v_mov_b32_e32 v99, v97
	v_mov_b32_e32 v100, v97
	v_mov_b32_e32 v101, v97
	v_mov_b32_e32 v102, v97
	v_mov_b32_e32 v103, v97
	v_mov_b64_e32 v[0:1], v[96:97]
	v_cmp_lt_i32_e32 vcc, 3, v79
	v_mov_b64_e32 v[2:3], v[98:99]
	v_mov_b64_e32 v[4:5], v[100:101]
	v_mov_b64_e32 v[6:7], v[102:103]
	s_and_saveexec_b64 s[2:3], vcc
	s_cbranch_execz .LBB0_1169
	v_mul_lo_u32 v0, v80, s33
	v_add_u32_e32 v96, 0xffffd800, v0
	v_lshl_add_u64 v[0:1], v[72:73], 0, v[96:97]
	global_load_dwordx4 v[4:7], v[0:1], off
	s_waitcnt vmcnt(0) lgkmcnt(0)
	v_lshlrev_b32_e32 v0, 16, v4
	v_and_b32_e32 v1, 0xffff0000, v4
	v_lshlrev_b32_e32 v2, 16, v5
	v_and_b32_e32 v3, 0xffff0000, v5
	v_lshlrev_b32_e32 v4, 16, v6
	v_and_b32_e32 v5, 0xffff0000, v6
	v_lshlrev_b32_e32 v6, 16, v7
	v_and_b32_e32 v7, 0xffff0000, v7
	v_pk_add_f32 v[0:1], v[0:1], 0 op_sel_hi:[1,0]
	v_pk_add_f32 v[2:3], v[2:3], 0 op_sel_hi:[1,0]
	v_pk_add_f32 v[4:5], v[4:5], 0 op_sel_hi:[1,0]
	v_pk_add_f32 v[6:7], v[6:7], 0 op_sel_hi:[1,0]

; __device__ __forceinline__ float bflo(unsigned w) { return __uint_as_float(w << 16); }
; __device__ __forceinline__ float bfhi(unsigned w) { return __uint_as_float(w & 0xffff0000u); }
; __device__ __forceinline__ unsigned cvtpk(float lo, float hi) { f32x2_t v = {lo, hi}; bf16x2_t b = __builtin_convertvector(v, bf16x2_t); return __builtin_bit_cast(unsigned, b); }
; template <int HW>
; __device__ __forceinline__ void pool4(const bf16_t* zc, bf16_t* pc, int t0) {
;     ...
;         for (int i = 0; i < 2 * HW; ++i) { const int r = t - HW + i; const bool ok = (r >= 0) && (r < S); const u32x4 w = v[q + i];
;             if (ok) { a[0] += bflo(w.x); a[1] += bfhi(w.x); a[2] += bflo(w.y); a[3] += bfhi(w.y); a[4] += bflo(w.z); a[5] += bfhi(w.z); a[6] += bflo(w.w); a[7] += bfhi(w.w); } }
;         const int lo = max(t - HW, 0), hi = min(t + HW - 1, S - 1); const float inv = 1.0f / (float)(hi - lo + 1);
;         const u32x4 sv = v[q + HW];
;         u32x4 w; w.x = cvtpk(a[0] * inv - bflo(sv.x), a[1] * inv - bfhi(sv.x)); w.y = cvtpk(a[2] * inv - bflo(sv.y), a[3] * inv - bfhi(sv.y));
;         w.z = cvtpk(a[4] * inv - bflo(sv.z), a[5] * inv - bfhi(sv.z)); w.w = cvtpk(a[6] * inv - bflo(sv.w), a[7] * inv - bfhi(sv.w));
;         *(u32x4*)(pc + (size_t)t * 256) = w; }
.LBB0_1173:
	s_or_b64 exec, exec, s[4:5]
	v_max_i32_e32 v20, 1, v80
	v_sub_u32_e32 v20, v24, v20
	v_cvt_f32_i32_e32 v20, v20
	v_ashrrev_i32_e32 v81, 31, v80
	v_div_scale_f32 v21, s[4:5], v20, v20, 1.0
	v_rcp_f32_e32 v22, v21
	v_cmp_lt_i32_e64 s[4:5], -2, v80
	v_fma_f32 v23, -v21, v22, 1.0
	v_fmac_f32_e32 v22, v23, v22
	v_div_scale_f32 v23, vcc, 1.0, v20, 1.0
	v_mul_f32_e32 v25, v23, v22
	v_fma_f32 v27, -v21, v25, v23
	v_fmac_f32_e32 v25, v27, v22
	v_fma_f32 v21, -v21, v25, v23
	v_div_fmas_f32 v21, v21, v22, v25
	v_div_fixup_f32 v20, v21, v20, 1.0
	v_pk_fma_f32 v[0:1], v[20:21], v[0:1], v[28:29] op_sel_hi:[0,1,1] neg_lo:[0,0,1] neg_hi:[0,0,1]
	v_pk_fma_f32 v[2:3], v[20:21], v[2:3], v[30:31] op_sel_hi:[0,1,1] neg_lo:[0,0,1] neg_hi:[0,0,1]
	v_cvt_pk_bf16_f32 v0, v0, v1
	v_cvt_pk_bf16_f32 v1, v2, v3
	v_pk_fma_f32 v[2:3], v[20:21], v[4:5], v[32:33] op_sel_hi:[0,1,1] neg_lo:[0,0,1] neg_hi:[0,0,1]
	v_pk_fma_f32 v[4:5], v[20:21], v[6:7], v[34:35] op_sel_hi:[0,1,1] neg_lo:[0,0,1] neg_hi:[0,0,1]
	v_cvt_pk_bf16_f32 v2, v2, v3
	v_cvt_pk_bf16_f32 v3, v4, v5
	v_lshlrev_b64 v[4:5], 9, v[80:81]
	v_lshl_add_u64 v[4:5], v[76:77], 0, v[4:5]
	global_store_dwordx4 v[4:5], v[0:3], off
	v_cmp_gt_i32_e32 vcc, -1, v80
	s_nop 0
	v_lshlrev_b32_e32 v0, 16, v16
	s_and_saveexec_b64 s[10:11], vcc
	s_xor_b64 s[10:11], exec, s[10:11]
	v_and_b32_e32 v1, 0xffff0000, v16
	v_lshlrev_b32_e32 v2, 16, v17
	v_and_b32_e32 v3, 0xffff0000, v17
	v_lshlrev_b32_e32 v4, 16, v18
	v_and_b32_e32 v5, 0xffff0000, v18
	v_lshlrev_b32_e32 v6, 16, v19
	v_and_b32_e32 v7, 0xffff0000, v19
	s_or_saveexec_b64 s[10:11], s[10:11]
	v_pk_add_f32 v[36:37], v[28:29], 0 op_sel_hi:[1,0]
	v_pk_add_f32 v[28:29], v[30:31], 0 op_sel_hi:[1,0]
	v_pk_add_f32 v[22:23], v[32:33], 0 op_sel_hi:[1,0]
	v_pk_add_f32 v[20:21], v[34:35], 0 op_sel_hi:[1,0]
	v_cndmask_b32_e64 v23, 0, v23, s[6:7]
	v_cndmask_b32_e64 v21, 0, v21, s[6:7]
	v_cndmask_b32_e64 v20, 0, v20, s[6:7]
	v_cndmask_b32_e64 v22, 0, v22, s[6:7]
	v_cndmask_b32_e64 v29, 0, v29, s[6:7]
	v_cndmask_b32_e64 v28, 0, v28, s[6:7]
	v_cndmask_b32_e64 v31, 0, v37, s[6:7]
	v_cndmask_b32_e64 v30, 0, v36, s[6:7]
	s_xor_b64 exec, exec, s[10:11]
	s_cbranch_execz .LBB0_1177
	v_and_b32_e32 v1, 0xffff0000, v16
	v_lshlrev_b32_e32 v2, 16, v17
	v_and_b32_e32 v3, 0xffff0000, v17
	v_lshlrev_b32_e32 v4, 16, v18
	v_and_b32_e32 v5, 0xffff0000, v18
	v_lshlrev_b32_e32 v6, 16, v19
	v_and_b32_e32 v7, 0xffff0000, v19
	v_pk_add_f32 v[20:21], v[20:21], v[6:7]
	v_pk_add_f32 v[28:29], v[28:29], v[2:3]
	v_pk_add_f32 v[22:23], v[22:23], v[4:5]
	v_pk_add_f32 v[30:31], v[30:31], v[0:1]
.LBB0_1177:
	s_or_b64 exec, exec, s[10:11]
	v_max_i32_e32 v16, 1, v26
	v_sub_u32_e32 v16, v26, v16
	v_or_b32_e32 v16, 2, v16
	v_cvt_f32_i32_e32 v16, v16
	v_div_scale_f32 v17, s[6:7], v16, v16, 1.0
	v_rcp_f32_e32 v18, v17
	v_div_scale_f32 v19, vcc, 1.0, v16, 1.0
	v_cmp_lt_i32_e64 s[6:7], -3, v80
	v_fma_f32 v25, -v17, v18, 1.0
	v_fmac_f32_e32 v18, v25, v18
	v_mul_f32_e32 v25, v19, v18
	v_fma_f32 v27, -v17, v25, v19
	v_fmac_f32_e32 v25, v27, v18
	v_fma_f32 v17, -v17, v25, v19
	v_div_fmas_f32 v17, v17, v18, v25
	v_div_fixup_f32 v32, v17, v16, 1.0
	v_pk_fma_f32 v[16:17], v[32:33], v[30:31], v[0:1] op_sel_hi:[0,1,1] neg_lo:[0,0,1] neg_hi:[0,0,1]
	v_pk_fma_f32 v[18:19], v[32:33], v[28:29], v[2:3] op_sel_hi:[0,1,1] neg_lo:[0,0,1] neg_hi:[0,0,1]
	v_cvt_pk_bf16_f32 v16, v16, v17
	v_cvt_pk_bf16_f32 v17, v18, v19
	v_pk_fma_f32 v[18:19], v[32:33], v[22:23], v[4:5] op_sel_hi:[0,1,1] neg_lo:[0,0,1] neg_hi:[0,0,1]
	v_pk_fma_f32 v[20:21], v[32:33], v[20:21], v[6:7] op_sel_hi:[0,1,1] neg_lo:[0,0,1] neg_hi:[0,0,1]
	v_ashrrev_i32_e32 v27, 31, v26
	v_cvt_pk_bf16_f32 v18, v18, v19
	v_cvt_pk_bf16_f32 v19, v20, v21
	v_lshlrev_b64 v[20:21], 9, v[26:27]
	v_lshl_add_u64 v[20:21], v[76:77], 0, v[20:21]
	global_store_dwordx4 v[20:21], v[16:19], off
	v_cmp_gt_i32_e32 vcc, -2, v80
	s_nop 0
	v_lshlrev_b32_e32 v16, 16, v12
	s_and_saveexec_b64 s[10:11], vcc
	s_xor_b64 s[10:11], exec, s[10:11]
	v_and_b32_e32 v17, 0xffff0000, v12
	v_lshlrev_b32_e32 v18, 16, v13
	v_and_b32_e32 v19, 0xffff0000, v13
	v_lshlrev_b32_e32 v20, 16, v14
	v_and_b32_e32 v21, 0xffff0000, v14
	v_lshlrev_b32_e32 v22, 16, v15
	v_and_b32_e32 v23, 0xffff0000, v15
	s_or_saveexec_b64 s[10:11], s[10:11]
	v_pk_add_f32 v[26:27], v[0:1], 0 op_sel_hi:[1,0]
	v_pk_add_f32 v[28:29], v[2:3], 0 op_sel_hi:[1,0]
	v_pk_add_f32 v[2:3], v[4:5], 0 op_sel_hi:[1,0]
	v_pk_add_f32 v[0:1], v[6:7], 0 op_sel_hi:[1,0]
	v_cndmask_b32_e64 v3, 0, v3, s[4:5]
	v_cndmask_b32_e64 v1, 0, v1, s[4:5]
	v_cndmask_b32_e64 v0, 0, v0, s[4:5]
	v_cndmask_b32_e64 v2, 0, v2, s[4:5]
	v_cndmask_b32_e64 v5, 0, v29, s[4:5]
	v_cndmask_b32_e64 v4, 0, v28, s[4:5]
	v_cndmask_b32_e64 v7, 0, v27, s[4:5]
	v_cndmask_b32_e64 v6, 0, v26, s[4:5]
	s_xor_b64 exec, exec, s[10:11]
	s_cbranch_execz .LBB0_1181
	v_and_b32_e32 v17, 0xffff0000, v12
	v_lshlrev_b32_e32 v18, 16, v13
	v_and_b32_e32 v19, 0xffff0000, v13
	v_lshlrev_b32_e32 v20, 16, v14
	v_and_b32_e32 v21, 0xffff0000, v14
	v_lshlrev_b32_e32 v22, 16, v15
	v_and_b32_e32 v23, 0xffff0000, v15
	v_pk_add_f32 v[0:1], v[0:1], v[22:23]
	v_pk_add_f32 v[4:5], v[4:5], v[18:19]
	v_pk_add_f32 v[2:3], v[2:3], v[20:21]
	v_pk_add_f32 v[6:7], v[6:7], v[16:17]
; __device__ __forceinline__ float bflo(unsigned w) { return __uint_as_float(w << 16); }
; __device__ __forceinline__ float bfhi(unsigned w) { return __uint_as_float(w & 0xffff0000u); }
; __device__ __forceinline__ unsigned cvtpk(float lo, float hi) { f32x2_t v = {lo, hi}; bf16x2_t b = __builtin_convertvector(v, bf16x2_t); return __builtin_bit_cast(unsigned, b); }
; template <int HW>
; __device__ __forceinline__ void pool4(const bf16_t* zc, bf16_t* pc, int t0) {
;     ...
;         for (int i = 0; i < 2 * HW; ++i) { const int r = t - HW + i; const bool ok = (r >= 0) && (r < S); const u32x4 w = v[q + i];
;             if (ok) { a[0] += bflo(w.x); a[1] += bfhi(w.x); a[2] += bflo(w.y); a[3] += bfhi(w.y); a[4] += bflo(w.z); a[5] += bfhi(w.z); a[6] += bflo(w.w); a[7] += bfhi(w.w); } }
;         const int lo = max(t - HW, 0), hi = min(t + HW - 1, S - 1); const float inv = 1.0f / (float)(hi - lo + 1);
;         const u32x4 sv = v[q + HW];
;         u32x4 w; w.x = cvtpk(a[0] * inv - bflo(sv.x), a[1] * inv - bfhi(sv.x)); w.y = cvtpk(a[2] * inv - bflo(sv.y), a[3] * inv - bfhi(sv.y));
;         w.z = cvtpk(a[4] * inv - bflo(sv.z), a[5] * inv - bfhi(sv.z)); w.w = cvtpk(a[6] * inv - bflo(sv.w), a[7] * inv - bfhi(sv.w));
;         *(u32x4*)(pc + (size_t)t * 256) = w; }
.LBB0_1181:
	s_or_b64 exec, exec, s[10:11]
	v_max_i32_e32 v12, 1, v24
	v_sub_u32_e32 v12, v80, v12
	v_add_u32_e32 v12, 4, v12
	v_cvt_f32_i32_e32 v12, v12
	v_div_scale_f32 v13, s[4:5], v12, v12, 1.0
	v_rcp_f32_e32 v14, v13
	v_div_scale_f32 v15, vcc, 1.0, v12, 1.0
	v_fma_f32 v25, -v13, v14, 1.0
	v_fmac_f32_e32 v14, v25, v14
	v_mul_f32_e32 v25, v15, v14
	v_fma_f32 v26, -v13, v25, v15
	v_fmac_f32_e32 v25, v26, v14
	v_fma_f32 v13, -v13, v25, v15
	v_div_fmas_f32 v13, v13, v14, v25
	v_div_fixup_f32 v12, v13, v12, 1.0
	v_pk_fma_f32 v[6:7], v[12:13], v[6:7], v[16:17] op_sel_hi:[0,1,1] neg_lo:[0,0,1] neg_hi:[0,0,1]
	v_pk_fma_f32 v[0:1], v[12:13], v[0:1], v[22:23] op_sel_hi:[0,1,1] neg_lo:[0,0,1] neg_hi:[0,0,1]
	v_ashrrev_i32_e32 v25, 31, v24
	v_pk_fma_f32 v[14:15], v[12:13], v[4:5], v[18:19] op_sel_hi:[0,1,1] neg_lo:[0,0,1] neg_hi:[0,0,1]
	v_cvt_pk_bf16_f32 v4, v6, v7
	v_pk_fma_f32 v[2:3], v[12:13], v[2:3], v[20:21] op_sel_hi:[0,1,1] neg_lo:[0,0,1] neg_hi:[0,0,1]
	v_cvt_pk_bf16_f32 v7, v0, v1
	v_lshlrev_b64 v[0:1], 9, v[24:25]
	v_cvt_pk_bf16_f32 v5, v14, v15
	v_cvt_pk_bf16_f32 v6, v2, v3
	v_lshl_add_u64 v[0:1], v[76:77], 0, v[0:1]
	global_store_dwordx4 v[0:1], v[4:7], off
	v_pk_add_f32 v[0:1], v[18:19], 0 op_sel_hi:[1,0]
	v_pk_add_f32 v[2:3], v[20:21], 0 op_sel_hi:[1,0]
	v_pk_add_f32 v[6:7], v[16:17], 0 op_sel_hi:[1,0]
	v_pk_add_f32 v[4:5], v[22:23], 0 op_sel_hi:[1,0]
	v_cndmask_b32_e64 v3, 0, v3, s[6:7]
	v_cndmask_b32_e64 v5, 0, v5, s[6:7]
	v_cndmask_b32_e64 v4, 0, v4, s[6:7]
	v_cndmask_b32_e64 v2, 0, v2, s[6:7]
	v_cndmask_b32_e64 v1, 0, v1, s[6:7]
	v_cndmask_b32_e64 v0, 0, v0, s[6:7]
	v_cndmask_b32_e64 v7, 0, v7, s[6:7]
	v_cndmask_b32_e64 v6, 0, v6, s[6:7]
	v_lshlrev_b32_e32 v12, 16, v8
	s_and_saveexec_b64 s[4:5], s[2:3]
	s_xor_b64 s[2:3], exec, s[4:5]
	v_and_b32_e32 v13, 0xffff0000, v8
	v_and_b32_e32 v19, 0xffff0000, v9
	v_lshlrev_b32_e32 v18, 16, v9
	v_and_b32_e32 v17, 0xffff0000, v10
	v_lshlrev_b32_e32 v16, 16, v10
	v_lshlrev_b32_e32 v14, 16, v11
	v_and_b32_e32 v15, 0xffff0000, v11
	s_andn2_saveexec_b64 s[2:3], s[2:3]
	s_cbranch_execz .LBB0_986
	v_and_b32_e32 v13, 0xffff0000, v8
	v_and_b32_e32 v8, 0xffff0000, v9
	v_lshlrev_b32_e32 v9, 16, v9
	v_and_b32_e32 v18, 0xffff0000, v10
	v_lshlrev_b32_e32 v19, 16, v10
	v_lshlrev_b32_e32 v14, 16, v11
	v_and_b32_e32 v15, 0xffff0000, v11
	v_pk_add_f32 v[6:7], v[6:7], v[12:13]
	v_pk_add_f32 v[0:1], v[0:1], v[8:9] op_sel:[0,1] op_sel_hi:[1,0]
	v_pk_add_f32 v[2:3], v[2:3], v[18:19] op_sel:[0,1] op_sel_hi:[1,0]
	v_pk_add_f32 v[4:5], v[4:5], v[14:15]
	v_mov_b32_e32 v16, v19
	v_mov_b32_e32 v17, v18
	v_mov_b32_e32 v18, v9
	v_mov_b32_e32 v19, v8
	s_branch .LBB0_986

; __device__ __forceinline__ float bflo(unsigned w) { return __uint_as_float(w << 16); }
; __device__ __forceinline__ float bfhi(unsigned w) { return __uint_as_float(w & 0xffff0000u); }
; __device__ __forceinline__ unsigned cvtpk(float lo, float hi) { f32x2_t v = {lo, hi}; bf16x2_t b = __builtin_convertvector(v, bf16x2_t); return __builtin_bit_cast(unsigned, b); }
; __device__ __forceinline__ void poolqk_phase(bf16_t* Z, bf16_t* P, const float* wq, const float* wk, int wid_s_) {
;     ...
;     for (int it = gt; it < S * 256; it += 4 * NT) {
;         bf16_t* ptr[4]; u32x4 v[4];
; #pragma unroll
;         for (int q = 0; q < 4; ++q) { const int iq = it + q * NT, t = iq >> 8, ch = iq & 255; ptr[q] = Z + (size_t)t * ZP + 1024 + ch * 8; v[q] = *(const u32x4*)ptr[q]; }
;         const int ch = it & 255;
;         const bool isq = ch < 128; const float* wv = (isq ? wq : wk) + (ch & 7) * 8; const float sc = isq ? 0.125f * LOG2E : 1.0f;
; #pragma unroll
;         for (int q = 0; q < 4; ++q) { float f[8] = {bflo(v[q].x), bfhi(v[q].x), bflo(v[q].y), bfhi(v[q].y), bflo(v[q].z), bfhi(v[q].z), bflo(v[q].w), bfhi(v[q].w)};
;             float ss = 0.f;
; #pragma unroll
;             for (int i = 0; i < 8; ++i) ss += f[i] * f[i];
;             ss += __shfl_xor(ss, 1); ss += __shfl_xor(ss, 2); ss += __shfl_xor(ss, 4);
;             const float r = (1.0f / sqrtf(ss * (1.f / 64.f) + NORM_EPS)) * sc;
; #pragma unroll
;             for (int i = 0; i < 8; ++i) f[i] = f[i] * r * wv[i];
;             u32x4 w; w.x = cvtpk(f[0], f[1]); w.y = cvtpk(f[2], f[3]); w.z = cvtpk(f[4], f[5]); w.w = cvtpk(f[6], f[7]);
;             *(u32x4*)ptr[q] = w; } }
.LBB0_1211:
	v_lshrrev_b32_e32 v0, 8, v146
	v_and_b32_e32 v2, 0x7f8, v17
	v_mul_hi_i32_i24_e32 v1, 0x2800, v0
	v_mul_i32_i24_e32 v0, 0x2800, v0
	v_lshl_add_u64 v[0:1], s[78:79], 0, v[0:1]
	v_lshlrev_b32_e32 v96, 1, v2
	v_lshl_add_u64 v[36:37], v[0:1], 0, v[96:97]
	global_load_dwordx4 v[20:23], v[36:37], off offset:2048
	v_add_u32_e32 v2, s92, v146
	v_lshrrev_b32_e32 v0, 8, v2
	v_mul_hi_i32_i24_e32 v1, 0x2800, v0
	v_mul_i32_i24_e32 v0, 0x2800, v0
	v_lshl_add_u64 v[0:1], s[78:79], 0, v[0:1]
	v_add_u32_e32 v2, s92, v2
	v_lshl_add_u64 v[12:13], v[0:1], 0, v[96:97]
	v_lshrrev_b32_e32 v0, 8, v2
	v_mul_hi_i32_i24_e32 v1, 0x2800, v0
	v_mul_i32_i24_e32 v0, 0x2800, v0
	v_lshl_add_u64 v[0:1], s[78:79], 0, v[0:1]
	v_add_u32_e32 v18, s92, v2
	v_and_b32_e32 v19, 0x80, v146
	v_lshl_add_u64 v[10:11], v[0:1], 0, v[96:97]
	v_lshrrev_b32_e32 v0, 8, v18
	v_cmp_eq_u32_e32 vcc, 0, v19
	v_mov_b32_e32 v19, s9
	v_mov_b32_e32 v28, s7
	v_mul_hi_i32_i24_e32 v1, 0x2800, v0
	v_mul_i32_i24_e32 v0, 0x2800, v0
	v_cndmask_b32_e32 v29, v19, v28, vcc
	v_mov_b32_e32 v19, s8
	v_mov_b32_e32 v28, s6
	v_lshl_add_u64 v[0:1], s[78:79], 0, v[0:1]
	v_cndmask_b32_e32 v28, v19, v28, vcc
	v_and_b32_e32 v19, 56, v17
	v_lshl_add_u64 v[8:9], v[0:1], 0, v[96:97]
	v_lshlrev_b32_e32 v96, 2, v19
	v_lshl_add_u64 v[38:39], v[28:29], 0, v[96:97]
	global_load_dwordx4 v[24:27], v[12:13], off offset:2048
	global_load_dwordx4 v[4:7], v[10:11], off offset:2048
	global_load_dwordx4 v[0:3], v[8:9], off offset:2048
	global_load_dwordx4 v[28:31], v[38:39], off offset:16
	global_load_dwordx4 v[32:35], v[38:39], off
	v_mov_b32_e32 v19, 0x3e38aa3b
	v_cndmask_b32_e32 v19, 1.0, v19, vcc
	v_add_u32_e32 v146, s92, v18
	v_add_u32_e32 v17, s37, v17
	s_waitcnt vmcnt(0) lgkmcnt(0)
	v_lshlrev_b32_e32 v50, 16, v20
	v_and_b32_e32 v51, 0xffff0000, v20
	v_lshlrev_b32_e32 v46, 16, v21
	v_and_b32_e32 v47, 0xffff0000, v21
	v_pk_mul_f32 v[20:21], v[50:51], v[50:51]
	v_pk_mul_f32 v[48:49], v[46:47], v[46:47]
	v_add_f32_e32 v20, v20, v21
	v_lshlrev_b32_e32 v44, 16, v22
	v_and_b32_e32 v45, 0xffff0000, v22
	v_add_f32_e32 v20, v48, v20
	v_lshlrev_b32_e32 v40, 16, v23
	v_and_b32_e32 v41, 0xffff0000, v23
	v_pk_mul_f32 v[22:23], v[44:45], v[44:45]
	v_add_f32_e32 v20, v49, v20
	v_add_f32_e32 v20, v22, v20
	v_pk_mul_f32 v[42:43], v[40:41], v[40:41]
	v_add_f32_e32 v20, v23, v20
	v_add_f32_e32 v20, v42, v20
	v_add_f32_e32 v20, v43, v20
	ds_bpermute_b32 v21, v14, v20
	s_waitcnt lgkmcnt(0)
	v_add_f32_e32 v20, v20, v21
	ds_bpermute_b32 v21, v15, v20
	s_waitcnt lgkmcnt(0)
	v_add_f32_e32 v20, v20, v21
	ds_bpermute_b32 v21, v16, v20
	s_waitcnt lgkmcnt(0)
	v_add_f32_e32 v20, v20, v21
	v_fmamk_f32 v20, v20, 0x3c800000, v185
	v_cmp_gt_f32_e32 vcc, s36, v20
	v_mul_f32_e32 v21, 0x4f800000, v20
	s_nop 0
	v_cndmask_b32_e32 v20, v20, v21, vcc
	v_sqrt_f32_e32 v21, v20
	s_nop 0
	v_add_u32_e32 v22, -1, v21
	v_fma_f32 v23, -v22, v21, v20
	v_cmp_ge_f32_e64 s[0:1], 0, v23
	v_add_u32_e32 v23, 1, v21
	s_nop 0
	v_cndmask_b32_e64 v22, v21, v22, s[0:1]
	v_fma_f32 v21, -v23, v21, v20
	v_cmp_lt_f32_e64 s[0:1], 0, v21
	s_nop 1
	v_cndmask_b32_e64 v21, v22, v23, s[0:1]
	v_mul_f32_e32 v22, 0x37800000, v21
	v_cndmask_b32_e32 v21, v21, v22, vcc
	v_cmp_class_f32_e32 vcc, v20, v186
	s_nop 1
	v_cndmask_b32_e32 v20, v21, v20, vcc
	v_div_scale_f32 v21, s[0:1], v20, v20, 1.0
	v_rcp_f32_e32 v22, v21
	s_nop 0
	v_fma_f32 v23, -v21, v22, 1.0
	v_fmac_f32_e32 v22, v23, v22
	v_div_scale_f32 v23, vcc, 1.0, v20, 1.0
	v_mul_f32_e32 v42, v23, v22
	v_fma_f32 v43, -v21, v42, v23
	v_fmac_f32_e32 v42, v43, v22
	v_fma_f32 v21, -v21, v42, v23
	v_div_fmas_f32 v21, v21, v22, v42
	v_div_fixup_f32 v20, v21, v20, 1.0
	v_mul_f32_e32 v20, v19, v20
	v_pk_mul_f32 v[22:23], v[20:21], v[50:51] op_sel_hi:[0,1]
	v_pk_mul_f32 v[22:23], v[32:33], v[22:23]
	v_pk_mul_f32 v[32:33], v[20:21], v[46:47] op_sel_hi:[0,1]
	v_pk_mul_f32 v[32:33], v[34:35], v[32:33]
	v_pk_mul_f32 v[34:35], v[20:21], v[44:45] op_sel_hi:[0,1]
	v_pk_mul_f32 v[20:21], v[20:21], v[40:41] op_sel_hi:[0,1]
	v_pk_mul_f32 v[28:29], v[28:29], v[34:35]
	v_pk_mul_f32 v[30:31], v[30:31], v[20:21]
	v_cvt_pk_bf16_f32 v20, v22, v23
	v_cvt_pk_bf16_f32 v21, v32, v33
	v_cvt_pk_bf16_f32 v22, v28, v29
	v_cvt_pk_bf16_f32 v23, v30, v31
	global_store_dwordx4 v[36:37], v[20:23], off offset:2048
	v_lshlrev_b32_e32 v30, 16, v27
	v_and_b32_e32 v31, 0xffff0000, v27
	v_lshlrev_b32_e32 v34, 16, v26
	v_and_b32_e32 v35, 0xffff0000, v26
	global_load_dwordx4 v[20:23], v[38:39], off offset:16
	global_load_dwordx4 v[26:29], v[38:39], off
	v_lshlrev_b32_e32 v44, 16, v24
	v_and_b32_e32 v45, 0xffff0000, v24
	v_lshlrev_b32_e32 v40, 16, v25
	v_and_b32_e32 v41, 0xffff0000, v25
	v_pk_mul_f32 v[24:25], v[44:45], v[44:45]
	v_pk_mul_f32 v[42:43], v[40:41], v[40:41]
	v_add_f32_e32 v24, v24, v25
	v_add_f32_e32 v24, v42, v24
	v_pk_mul_f32 v[36:37], v[34:35], v[34:35]
	v_add_f32_e32 v24, v43, v24
	v_add_f32_e32 v24, v36, v24
	v_pk_mul_f32 v[32:33], v[30:31], v[30:31]
	v_add_f32_e32 v24, v37, v24
	v_add_f32_e32 v24, v32, v24
	v_add_f32_e32 v24, v33, v24
	ds_bpermute_b32 v25, v14, v24
	s_waitcnt lgkmcnt(0)
	v_add_f32_e32 v24, v24, v25
	ds_bpermute_b32 v25, v15, v24
	s_waitcnt lgkmcnt(0)
	v_add_f32_e32 v24, v24, v25
	ds_bpermute_b32 v25, v16, v24
	s_waitcnt lgkmcnt(0)
; __device__ __forceinline__ float bflo(unsigned w) { return __uint_as_float(w << 16); }
; __device__ __forceinline__ float bfhi(unsigned w) { return __uint_as_float(w & 0xffff0000u); }
; __device__ __forceinline__ unsigned cvtpk(float lo, float hi) { f32x2_t v = {lo, hi}; bf16x2_t b = __builtin_convertvector(v, bf16x2_t); return __builtin_bit_cast(unsigned, b); }
; __device__ __forceinline__ void poolqk_phase(bf16_t* Z, bf16_t* P, const float* wq, const float* wk, int wid_s_) {
;     ...
;         for (int q = 0; q < 4; ++q) { float f[8] = {bflo(v[q].x), bfhi(v[q].x), bflo(v[q].y), bfhi(v[q].y), bflo(v[q].z), bfhi(v[q].z), bflo(v[q].w), bfhi(v[q].w)};
;             float ss = 0.f;
; #pragma unroll
;             for (int i = 0; i < 8; ++i) ss += f[i] * f[i];
;             ss += __shfl_xor(ss, 1); ss += __shfl_xor(ss, 2); ss += __shfl_xor(ss, 4);
;             const float r = (1.0f / sqrtf(ss * (1.f / 64.f) + NORM_EPS)) * sc;
; #pragma unroll
;             for (int i = 0; i < 8; ++i) f[i] = f[i] * r * wv[i];
;             u32x4 w; w.x = cvtpk(f[0], f[1]); w.y = cvtpk(f[2], f[3]); w.z = cvtpk(f[4], f[5]); w.w = cvtpk(f[6], f[7]);
;             *(u32x4*)ptr[q] = w; } }
	v_add_f32_e32 v24, v24, v25
	v_fmamk_f32 v24, v24, 0x3c800000, v185
	v_cmp_gt_f32_e32 vcc, s36, v24
	v_mul_f32_e32 v25, 0x4f800000, v24
	s_nop 0
	v_cndmask_b32_e32 v24, v24, v25, vcc
	v_sqrt_f32_e32 v25, v24
	s_nop 0
	v_add_u32_e32 v32, -1, v25
	v_fma_f32 v33, -v32, v25, v24
	v_cmp_ge_f32_e64 s[0:1], 0, v33
	v_add_u32_e32 v33, 1, v25
	s_nop 0
	v_cndmask_b32_e64 v32, v25, v32, s[0:1]
	v_fma_f32 v25, -v33, v25, v24
	v_cmp_lt_f32_e64 s[0:1], 0, v25
	s_nop 1
	v_cndmask_b32_e64 v25, v32, v33, s[0:1]
	v_mul_f32_e32 v32, 0x37800000, v25
	v_cndmask_b32_e32 v25, v25, v32, vcc
	v_cmp_class_f32_e32 vcc, v24, v186
	s_nop 1
	v_cndmask_b32_e32 v24, v25, v24, vcc
	v_div_scale_f32 v25, s[0:1], v24, v24, 1.0
	v_rcp_f32_e32 v32, v25
	s_nop 0
	v_fma_f32 v33, -v25, v32, 1.0
	v_fmac_f32_e32 v32, v33, v32
	v_div_scale_f32 v33, vcc, 1.0, v24, 1.0
	v_mul_f32_e32 v36, v33, v32
	v_fma_f32 v37, -v25, v36, v33
	v_fmac_f32_e32 v36, v37, v32
	v_fma_f32 v25, -v25, v36, v33
	v_div_fmas_f32 v25, v25, v32, v36
	v_div_fixup_f32 v24, v25, v24, 1.0
	v_mul_f32_e32 v24, v19, v24
	v_pk_mul_f32 v[32:33], v[24:25], v[44:45] op_sel_hi:[0,1]
	v_lshlrev_b32_e32 v36, 16, v4
	v_and_b32_e32 v37, 0xffff0000, v4
	s_waitcnt vmcnt(0)
	v_pk_mul_f32 v[26:27], v[26:27], v[32:33]
	v_pk_mul_f32 v[32:33], v[24:25], v[40:41] op_sel_hi:[0,1]
	v_pk_mul_f32 v[28:29], v[28:29], v[32:33]
	v_pk_mul_f32 v[32:33], v[24:25], v[34:35] op_sel_hi:[0,1]
	v_pk_mul_f32 v[32:33], v[20:21], v[32:33]
	v_pk_mul_f32 v[20:21], v[24:25], v[30:31] op_sel_hi:[0,1]
	v_pk_mul_f32 v[24:25], v[22:23], v[20:21]
	v_cvt_pk_bf16_f32 v20, v26, v27
	v_cvt_pk_bf16_f32 v21, v28, v29
	v_cvt_pk_bf16_f32 v22, v32, v33
	v_cvt_pk_bf16_f32 v23, v24, v25
	global_store_dwordx4 v[12:13], v[20:23], off offset:2048
	global_load_dwordx4 v[20:23], v[38:39], off offset:16
	s_nop 0
	global_load_dwordx4 v[24:27], v[38:39], off
	v_lshlrev_b32_e32 v32, 16, v5
	v_and_b32_e32 v33, 0xffff0000, v5
	v_pk_mul_f32 v[4:5], v[36:37], v[36:37]
	v_pk_mul_f32 v[34:35], v[32:33], v[32:33]
	v_add_f32_e32 v4, v4, v5
	v_lshlrev_b32_e32 v30, 16, v6
	v_and_b32_e32 v31, 0xffff0000, v6
	v_add_f32_e32 v4, v34, v4
	v_lshlrev_b32_e32 v12, 16, v7
	v_and_b32_e32 v13, 0xffff0000, v7
	v_pk_mul_f32 v[6:7], v[30:31], v[30:31]
	v_add_f32_e32 v4, v35, v4
	v_add_f32_e32 v4, v6, v4
	v_pk_mul_f32 v[28:29], v[12:13], v[12:13]
	v_add_f32_e32 v4, v7, v4
	v_add_f32_e32 v4, v28, v4
	v_add_f32_e32 v4, v29, v4
	ds_bpermute_b32 v5, v14, v4
	s_waitcnt lgkmcnt(0)
	v_add_f32_e32 v4, v4, v5
	ds_bpermute_b32 v5, v15, v4
	s_waitcnt lgkmcnt(0)
	v_add_f32_e32 v4, v4, v5
	ds_bpermute_b32 v5, v16, v4
	s_waitcnt lgkmcnt(0)
	v_add_f32_e32 v4, v4, v5
	v_fmamk_f32 v4, v4, 0x3c800000, v185
	v_cmp_gt_f32_e32 vcc, s36, v4
	v_mul_f32_e32 v5, 0x4f800000, v4
	s_nop 0
	v_cndmask_b32_e32 v4, v4, v5, vcc
	v_sqrt_f32_e32 v5, v4
	s_nop 0
	v_add_u32_e32 v6, -1, v5
	v_fma_f32 v7, -v6, v5, v4
	v_cmp_ge_f32_e64 s[0:1], 0, v7
	v_add_u32_e32 v7, 1, v5
	s_nop 0
	v_cndmask_b32_e64 v6, v5, v6, s[0:1]
	v_fma_f32 v5, -v7, v5, v4
	v_cmp_lt_f32_e64 s[0:1], 0, v5
	s_nop 1
	v_cndmask_b32_e64 v5, v6, v7, s[0:1]
	v_mul_f32_e32 v6, 0x37800000, v5
	v_cndmask_b32_e32 v5, v5, v6, vcc
	v_cmp_class_f32_e32 vcc, v4, v186
	s_nop 1
	v_cndmask_b32_e32 v4, v5, v4, vcc
	v_div_scale_f32 v5, s[0:1], v4, v4, 1.0
	v_rcp_f32_e32 v6, v5
	s_nop 0
	v_fma_f32 v7, -v5, v6, 1.0
	v_fmac_f32_e32 v6, v7, v6
	v_div_scale_f32 v7, vcc, 1.0, v4, 1.0
	v_mul_f32_e32 v28, v7, v6
	v_fma_f32 v29, -v5, v28, v7
	v_fmac_f32_e32 v28, v29, v6
	v_fma_f32 v5, -v5, v28, v7
	v_div_fmas_f32 v5, v5, v6, v28
	v_div_fixup_f32 v4, v5, v4, 1.0
	v_mul_f32_e32 v4, v19, v4
	v_pk_mul_f32 v[6:7], v[4:5], v[36:37] op_sel_hi:[0,1]
	s_waitcnt vmcnt(0)
	v_pk_mul_f32 v[6:7], v[24:25], v[6:7]
	v_pk_mul_f32 v[24:25], v[4:5], v[32:33] op_sel_hi:[0,1]
	v_pk_mul_f32 v[24:25], v[26:27], v[24:25]
	v_pk_mul_f32 v[26:27], v[4:5], v[30:31] op_sel_hi:[0,1]
	v_pk_mul_f32 v[4:5], v[4:5], v[12:13] op_sel_hi:[0,1]
	v_pk_mul_f32 v[20:21], v[20:21], v[26:27]
	v_pk_mul_f32 v[12:13], v[22:23], v[4:5]
	v_cvt_pk_bf16_f32 v4, v6, v7
	v_cvt_pk_bf16_f32 v5, v24, v25
	v_cvt_pk_bf16_f32 v6, v20, v21
	v_cvt_pk_bf16_f32 v7, v12, v13
	global_store_dwordx4 v[10:11], v[4:7], off offset:2048
	v_lshlrev_b32_e32 v22, 16, v2
	v_and_b32_e32 v23, 0xffff0000, v2
	v_lshlrev_b32_e32 v6, 16, v3
	v_and_b32_e32 v7, 0xffff0000, v3
	global_load_dwordx4 v[2:5], v[38:39], off offset:16
	global_load_dwordx4 v[10:13], v[38:39], off
	v_lshlrev_b32_e32 v30, 16, v0
	v_and_b32_e32 v31, 0xffff0000, v0
	v_lshlrev_b32_e32 v26, 16, v1
	v_and_b32_e32 v27, 0xffff0000, v1
	v_pk_mul_f32 v[0:1], v[30:31], v[30:31]
	v_pk_mul_f32 v[28:29], v[26:27], v[26:27]
	v_add_f32_e32 v0, v0, v1
	v_add_f32_e32 v0, v28, v0
	v_pk_mul_f32 v[24:25], v[22:23], v[22:23]
	v_add_f32_e32 v0, v29, v0
	v_add_f32_e32 v0, v24, v0
	v_pk_mul_f32 v[20:21], v[6:7], v[6:7]
	v_add_f32_e32 v0, v25, v0
	v_add_f32_e32 v0, v20, v0
	v_add_f32_e32 v0, v21, v0
	ds_bpermute_b32 v1, v14, v0
	s_waitcnt lgkmcnt(0)
	v_add_f32_e32 v0, v0, v1
	ds_bpermute_b32 v1, v15, v0
	s_waitcnt lgkmcnt(0)
	v_add_f32_e32 v0, v0, v1
	ds_bpermute_b32 v1, v16, v0
	s_waitcnt lgkmcnt(0)
	v_add_f32_e32 v0, v0, v1
	v_fmamk_f32 v0, v0, 0x3c800000, v185
	v_cmp_gt_f32_e32 vcc, s36, v0
	v_mul_f32_e32 v1, 0x4f800000, v0
	s_nop 0
	v_cndmask_b32_e32 v0, v0, v1, vcc
	v_sqrt_f32_e32 v1, v0
	s_nop 0
	v_add_u32_e32 v20, -1, v1
	v_fma_f32 v21, -v20, v1, v0
	v_cmp_ge_f32_e64 s[0:1], 0, v21
	v_add_u32_e32 v21, 1, v1
	s_nop 0
	v_cndmask_b32_e64 v20, v1, v20, s[0:1]
	v_fma_f32 v1, -v21, v1, v0
	v_cmp_lt_f32_e64 s[0:1], 0, v1
	s_nop 1
	v_cndmask_b32_e64 v1, v20, v21, s[0:1]
	v_mul_f32_e32 v20, 0x37800000, v1
	v_cndmask_b32_e32 v1, v1, v20, vcc
	v_cmp_class_f32_e32 vcc, v0, v186
	s_nop 1
	v_cndmask_b32_e32 v0, v1, v0, vcc
	v_div_scale_f32 v1, s[0:1], v0, v0, 1.0
	v_rcp_f32_e32 v20, v1
	s_mov_b32 s0, 0x3fffff
	v_fma_f32 v21, -v1, v20, 1.0
	v_fmac_f32_e32 v20, v21, v20
	v_div_scale_f32 v21, vcc, 1.0, v0, 1.0
	v_mul_f32_e32 v24, v21, v20
	v_fma_f32 v25, -v1, v24, v21
	v_fmac_f32_e32 v24, v25, v20
	v_fma_f32 v1, -v1, v24, v21
	v_div_fmas_f32 v1, v1, v20, v24
	v_div_fixup_f32 v0, v1, v0, 1.0
	v_mul_f32_e32 v0, v19, v0
	v_pk_mul_f32 v[20:21], v[0:1], v[30:31] op_sel_hi:[0,1]
	v_cmp_lt_i32_e32 vcc, s0, v146
	s_or_b64 s[4:5], vcc, s[4:5]
	s_waitcnt vmcnt(0)
	v_pk_mul_f32 v[10:11], v[10:11], v[20:21]
	v_pk_mul_f32 v[20:21], v[0:1], v[26:27] op_sel_hi:[0,1]
	v_pk_mul_f32 v[12:13], v[12:13], v[20:21]
	v_pk_mul_f32 v[20:21], v[0:1], v[22:23] op_sel_hi:[0,1]
	v_pk_mul_f32 v[0:1], v[0:1], v[6:7] op_sel_hi:[0,1]
	v_pk_mul_f32 v[2:3], v[2:3], v[20:21]
	v_pk_mul_f32 v[4:5], v[4:5], v[0:1]
	v_cvt_pk_bf16_f32 v0, v10, v11
	v_cvt_pk_bf16_f32 v1, v12, v13
	v_cvt_pk_bf16_f32 v2, v2, v3
	v_cvt_pk_bf16_f32 v3, v4, v5
	global_store_dwordx4 v[8:9], v[0:3], off offset:2048
	s_andn2_b64 exec, exec, s[4:5]
	s_cbranch_execnz .LBB0_1211

; __device__ __forceinline__ float bflo(unsigned w) { return __uint_as_float(w << 16); }
; __device__ __forceinline__ float bfhi(unsigned w) { return __uint_as_float(w & 0xffff0000u); }
; __device__ __forceinline__ unsigned cvtpk(float lo, float hi) { f32x2_t v = {lo, hi}; bf16x2_t b = __builtin_convertvector(v, bf16x2_t); return __builtin_bit_cast(unsigned, b); }
;     __device__ __forceinline__ void operator()(const f32x4 (&acc)[2][2][4][2], const Unit& u, int wr, int wc, int fr, int fq) const {
;         const int g = u.pn, row0 = (u.pm & 63) * BM + wr * 64 + fr, col0 = g * 256 + wc * 32 + 8 * fq;
; #pragma unroll
;         for (int bj = 0; bj < 2; ++bj) { const int col = col0 + bj * HALF;
;             const f32x4 p0 = *(const f32x4*)(pscale + col), p1 = *(const f32x4*)(pscale + col + 4);
; #pragma unroll
;             for (int ai = 0; ai < 2; ++ai)
; #pragma unroll
;                 for (int m = 0; m < 4; ++m) { const size_t row = (size_t)(row0 + ai * HALF + m * 16);
;                     const u32x4 sg = *(const u32x4*)(Z + row * ZP + 3072 + col);
;                     f32x4 v0 = acc[ai][bj][m][0] * p0, v1 = acc[ai][bj][m][1] * p1;
;                     v0[0] *= bflo(sg.x); v0[1] *= bfhi(sg.x); v0[2] *= bflo(sg.y); v0[3] *= bfhi(sg.y);
;                     v1[0] *= bflo(sg.z); v1[1] *= bfhi(sg.z); v1[2] *= bflo(sg.w); v1[3] *= bfhi(sg.w);
;                     u32x4 w; w.x = cvtpk(v0[0], v0[1]); w.y = cvtpk(v0[2], v0[3]); w.z = cvtpk(v1[0], v1[1]); w.w = cvtpk(v1[2], v1[3]);
;                     *(u32x4*)(Y + row * D + col) = w; } }
.LBB0_1280:
	s_lshl_b32 s8, s91, 8
	s_and_b32 s8, s8, 0x3f00
	v_add_u32_e32 v160, s8, v146
	v_lshl_or_b32 v154, s90, 8, v148
	v_mov_b64_e32 v[164:165], s[78:79]
	v_ashrrev_i32_e32 v155, 31, v154
	v_mad_i64_i32 v[150:151], s[20:21], v160, s33, v[164:165]
	v_lshl_add_u64 v[156:157], v[150:151], 0, s[80:81]
	v_lshlrev_b64 v[162:163], 1, v[154:155]
	v_lshl_add_u64 v[158:159], v[154:155], 2, s[10:11]
	v_lshl_add_u64 v[150:151], v[156:157], 0, v[162:163]
	global_load_dwordx4 v[130:133], v[158:159], off offset:16
	global_load_dwordx4 v[134:137], v[158:159], off
	global_load_dwordx4 v[168:171], v[150:151], off
	v_ashrrev_i32_e32 v161, 31, v160
	v_add_u32_e32 v166, 0x80, v160
	v_ashrrev_i32_e32 v167, 31, v166
	s_and_b64 vcc, exec, s[0:1]
	s_waitcnt vmcnt(0)
	v_pk_mul_f32 v[126:127], v[126:127], v[130:131]
	v_pk_mul_f32 v[122:123], v[122:123], v[134:135]
	s_waitcnt lgkmcnt(0)
	v_lshlrev_b32_e32 v150, 16, v168
	v_and_b32_e32 v151, 0xffff0000, v168
	v_pk_mul_f32 v[124:125], v[124:125], v[136:137]
	v_pk_mul_f32 v[122:123], v[122:123], v[150:151]
	v_lshlrev_b32_e32 v150, 16, v169
	v_and_b32_e32 v151, 0xffff0000, v169
	v_pk_mul_f32 v[124:125], v[124:125], v[150:151]
	v_lshlrev_b32_e32 v150, 16, v170
	v_and_b32_e32 v151, 0xffff0000, v170
	v_pk_mul_f32 v[128:129], v[128:129], v[132:133]
	v_pk_mul_f32 v[150:151], v[126:127], v[150:151]
	v_lshlrev_b32_e32 v126, 16, v171
	v_and_b32_e32 v127, 0xffff0000, v171
	v_pk_mul_f32 v[168:169], v[128:129], v[126:127]
	v_cvt_pk_bf16_f32 v126, v122, v123
	v_lshlrev_b64 v[122:123], 12, v[160:161]
	v_cvt_pk_bf16_f32 v128, v150, v151
	v_lshl_add_u64 v[122:123], s[4:5], 0, v[122:123]
	v_or_b32_e32 v150, 16, v160
	v_cvt_pk_bf16_f32 v127, v124, v125
	v_lshl_add_u64 v[124:125], v[122:123], 0, v[162:163]
	v_mad_i64_i32 v[122:123], s[20:21], v150, s33, v[164:165]
	v_cvt_pk_bf16_f32 v129, v168, v169
	v_lshl_add_u64 v[122:123], v[122:123], 0, s[80:81]
	global_store_dwordx4 v[124:125], v[126:129], off
	v_pk_mul_f32 v[120:121], v[120:121], v[136:137]
	v_pk_mul_f32 v[118:119], v[118:119], v[134:135]
	v_lshl_add_u64 v[126:127], v[122:123], 0, v[162:163]
	global_load_dwordx4 v[126:129], v[126:127], off
	v_pk_mul_f32 v[114:115], v[114:115], v[130:131]
	v_ashrrev_i32_e32 v151, 31, v150
	v_pk_mul_f32 v[116:117], v[116:117], v[132:133]
	v_pk_mul_f32 v[112:113], v[112:113], v[136:137]
	v_pk_mul_f32 v[110:111], v[110:111], v[134:135]
	v_pk_mul_f32 v[106:107], v[106:107], v[130:131]
	v_pk_mul_f32 v[108:109], v[108:109], v[132:133]
	v_pk_mul_f32 v[104:105], v[104:105], v[136:137]
	v_pk_mul_f32 v[102:103], v[102:103], v[134:135]
	v_pk_mul_f32 v[98:99], v[98:99], v[130:131]
	v_pk_mul_f32 v[100:101], v[100:101], v[132:133]
	v_pk_mul_f32 v[94:95], v[94:95], v[136:137]
	v_pk_mul_f32 v[92:93], v[92:93], v[134:135]
	v_pk_mul_f32 v[88:89], v[88:89], v[130:131]
	v_pk_mul_f32 v[90:91], v[90:91], v[132:133]
	v_pk_mul_f32 v[86:87], v[86:87], v[136:137]
	v_pk_mul_f32 v[84:85], v[84:85], v[134:135]
	v_pk_mul_f32 v[80:81], v[80:81], v[130:131]
	v_pk_mul_f32 v[82:83], v[82:83], v[132:133]
	v_pk_mul_f32 v[78:79], v[78:79], v[136:137]
	v_pk_mul_f32 v[76:77], v[76:77], v[134:135]
	v_pk_mul_f32 v[72:73], v[72:73], v[130:131]
	v_pk_mul_f32 v[74:75], v[74:75], v[132:133]
	v_pk_mul_f32 v[68:69], v[68:69], v[134:135]
	v_pk_mul_f32 v[70:71], v[70:71], v[136:137]
	v_pk_mul_f32 v[64:65], v[64:65], v[130:131]
	v_pk_mul_f32 v[66:67], v[66:67], v[132:133]
	s_waitcnt vmcnt(0) lgkmcnt(0)
	v_lshlrev_b32_e32 v168, 16, v126
	v_and_b32_e32 v169, 0xffff0000, v126
	v_lshlrev_b32_e32 v126, 16, v127
	v_and_b32_e32 v127, 0xffff0000, v127
	v_pk_mul_f32 v[120:121], v[120:121], v[126:127]
	v_lshlrev_b32_e32 v126, 16, v128
	v_and_b32_e32 v127, 0xffff0000, v128
	v_pk_mul_f32 v[118:119], v[118:119], v[168:169]
	v_pk_mul_f32 v[114:115], v[114:115], v[126:127]
	v_lshlrev_b32_e32 v126, 16, v129
	v_and_b32_e32 v127, 0xffff0000, v129
	v_cvt_pk_bf16_f32 v118, v118, v119
	v_cvt_pk_bf16_f32 v119, v120, v121
	v_cvt_pk_bf16_f32 v120, v114, v115
	v_lshlrev_b64 v[114:115], 12, v[150:151]
	v_pk_mul_f32 v[116:117], v[116:117], v[126:127]
	v_lshl_add_u64 v[114:115], s[4:5], 0, v[114:115]
	v_or_b32_e32 v126, 32, v160
	v_cvt_pk_bf16_f32 v121, v116, v117
	v_lshl_add_u64 v[116:117], v[114:115], 0, v[162:163]
	v_mad_i64_i32 v[114:115], s[20:21], v126, s33, v[164:165]
	v_lshl_add_u64 v[114:115], v[114:115], 0, s[80:81]
	global_store_dwordx4 v[116:117], v[118:121], off
	v_ashrrev_i32_e32 v127, 31, v126
	s_nop 0
	v_lshl_add_u64 v[118:119], v[114:115], 0, v[162:163]
	global_load_dwordx4 v[118:121], v[118:119], off
	s_waitcnt vmcnt(0) lgkmcnt(0)
	v_lshlrev_b32_e32 v128, 16, v118
	v_and_b32_e32 v129, 0xffff0000, v118
	v_lshlrev_b32_e32 v118, 16, v119
	v_and_b32_e32 v119, 0xffff0000, v119
	v_pk_mul_f32 v[112:113], v[112:113], v[118:119]
	v_lshlrev_b32_e32 v118, 16, v120
	v_and_b32_e32 v119, 0xffff0000, v120
	v_pk_mul_f32 v[110:111], v[110:111], v[128:129]
	v_pk_mul_f32 v[106:107], v[106:107], v[118:119]
	v_lshlrev_b32_e32 v118, 16, v121
	v_and_b32_e32 v119, 0xffff0000, v121
	v_cvt_pk_bf16_f32 v110, v110, v111
	v_cvt_pk_bf16_f32 v111, v112, v113
	v_cvt_pk_bf16_f32 v112, v106, v107
	v_lshlrev_b64 v[106:107], 12, v[126:127]
	v_pk_mul_f32 v[108:109], v[108:109], v[118:119]
	v_lshl_add_u64 v[106:107], s[4:5], 0, v[106:107]
	v_or_b32_e32 v118, 48, v160
	v_cvt_pk_bf16_f32 v113, v108, v109
	v_lshl_add_u64 v[108:109], v[106:107], 0, v[162:163]
	v_mad_i64_i32 v[106:107], s[20:21], v118, s33, v[164:165]
	v_lshl_add_u64 v[106:107], v[106:107], 0, s[80:81]
	global_store_dwordx4 v[108:109], v[110:113], off
	v_ashrrev_i32_e32 v119, 31, v118
	s_nop 0
	v_lshl_add_u64 v[110:111], v[106:107], 0, v[162:163]
	global_load_dwordx4 v[110:113], v[110:111], off
	s_waitcnt vmcnt(0) lgkmcnt(0)
; __device__ __forceinline__ float bflo(unsigned w) { return __uint_as_float(w << 16); }
; __device__ __forceinline__ float bfhi(unsigned w) { return __uint_as_float(w & 0xffff0000u); }
; __device__ __forceinline__ unsigned cvtpk(float lo, float hi) { f32x2_t v = {lo, hi}; bf16x2_t b = __builtin_convertvector(v, bf16x2_t); return __builtin_bit_cast(unsigned, b); }
;     __device__ __forceinline__ void operator()(const f32x4 (&acc)[2][2][4][2], const Unit& u, int wr, int wc, int fr, int fq) const {
;         const int g = u.pn, row0 = (u.pm & 63) * BM + wr * 64 + fr, col0 = g * 256 + wc * 32 + 8 * fq;
; #pragma unroll
;         for (int bj = 0; bj < 2; ++bj) { const int col = col0 + bj * HALF;
;             const f32x4 p0 = *(const f32x4*)(pscale + col), p1 = *(const f32x4*)(pscale + col + 4);
; #pragma unroll
;             for (int ai = 0; ai < 2; ++ai)
; #pragma unroll
;                 for (int m = 0; m < 4; ++m) { const size_t row = (size_t)(row0 + ai * HALF + m * 16);
;                     const u32x4 sg = *(const u32x4*)(Z + row * ZP + 3072 + col);
;                     f32x4 v0 = acc[ai][bj][m][0] * p0, v1 = acc[ai][bj][m][1] * p1;
;                     v0[0] *= bflo(sg.x); v0[1] *= bfhi(sg.x); v0[2] *= bflo(sg.y); v0[3] *= bfhi(sg.y);
;                     v1[0] *= bflo(sg.z); v1[1] *= bfhi(sg.z); v1[2] *= bflo(sg.w); v1[3] *= bfhi(sg.w);
;                     u32x4 w; w.x = cvtpk(v0[0], v0[1]); w.y = cvtpk(v0[2], v0[3]); w.z = cvtpk(v1[0], v1[1]); w.w = cvtpk(v1[2], v1[3]);
;                     *(u32x4*)(Y + row * D + col) = w; } }
	v_lshlrev_b32_e32 v120, 16, v110
	v_and_b32_e32 v121, 0xffff0000, v110
	v_lshlrev_b32_e32 v110, 16, v111
	v_and_b32_e32 v111, 0xffff0000, v111
	v_pk_mul_f32 v[104:105], v[104:105], v[110:111]
	v_lshlrev_b32_e32 v110, 16, v112
	v_and_b32_e32 v111, 0xffff0000, v112
	v_pk_mul_f32 v[102:103], v[102:103], v[120:121]
	v_pk_mul_f32 v[98:99], v[98:99], v[110:111]
	v_lshlrev_b32_e32 v110, 16, v113
	v_and_b32_e32 v111, 0xffff0000, v113
	v_cvt_pk_bf16_f32 v102, v102, v103
	v_cvt_pk_bf16_f32 v103, v104, v105
	v_cvt_pk_bf16_f32 v104, v98, v99
	v_lshlrev_b64 v[98:99], 12, v[118:119]
	v_pk_mul_f32 v[100:101], v[100:101], v[110:111]
	v_lshl_add_u64 v[98:99], s[4:5], 0, v[98:99]
	v_cvt_pk_bf16_f32 v105, v100, v101
	v_lshl_add_u64 v[100:101], v[98:99], 0, v[162:163]
	v_mad_i64_i32 v[98:99], s[20:21], v166, s33, v[164:165]
	v_lshl_add_u64 v[98:99], v[98:99], 0, s[80:81]
	global_store_dwordx4 v[100:101], v[102:105], off
	s_nop 1
	v_lshl_add_u64 v[102:103], v[98:99], 0, v[162:163]
	global_load_dwordx4 v[102:105], v[102:103], off
	s_waitcnt vmcnt(0) lgkmcnt(0)
	v_lshlrev_b32_e32 v110, 16, v102
	v_and_b32_e32 v111, 0xffff0000, v102
	v_lshlrev_b32_e32 v102, 16, v103
	v_and_b32_e32 v103, 0xffff0000, v103
	v_pk_mul_f32 v[94:95], v[94:95], v[102:103]
	v_lshlrev_b32_e32 v102, 16, v104
	v_and_b32_e32 v103, 0xffff0000, v104
	v_pk_mul_f32 v[92:93], v[92:93], v[110:111]
	v_pk_mul_f32 v[88:89], v[88:89], v[102:103]
	v_lshlrev_b32_e32 v102, 16, v105
	v_and_b32_e32 v103, 0xffff0000, v105
	v_cvt_pk_bf16_f32 v92, v92, v93
	v_cvt_pk_bf16_f32 v93, v94, v95
	v_cvt_pk_bf16_f32 v94, v88, v89
	v_lshlrev_b64 v[88:89], 12, v[166:167]
	v_pk_mul_f32 v[90:91], v[90:91], v[102:103]
	v_lshl_add_u64 v[88:89], s[4:5], 0, v[88:89]
	v_add_u32_e32 v102, 0x90, v160
	v_cvt_pk_bf16_f32 v95, v90, v91
	v_lshl_add_u64 v[90:91], v[88:89], 0, v[162:163]
	v_mad_i64_i32 v[88:89], s[20:21], v102, s33, v[164:165]
	v_lshl_add_u64 v[88:89], v[88:89], 0, s[80:81]
	global_store_dwordx4 v[90:91], v[92:95], off
	v_ashrrev_i32_e32 v103, 31, v102
	s_nop 0
	v_lshl_add_u64 v[92:93], v[88:89], 0, v[162:163]
	global_load_dwordx4 v[92:95], v[92:93], off
	s_waitcnt vmcnt(0) lgkmcnt(0)
	v_lshlrev_b32_e32 v104, 16, v92
	v_and_b32_e32 v105, 0xffff0000, v92
	v_lshlrev_b32_e32 v92, 16, v93
	v_and_b32_e32 v93, 0xffff0000, v93
	v_pk_mul_f32 v[86:87], v[86:87], v[92:93]
	v_lshlrev_b32_e32 v92, 16, v94
	v_and_b32_e32 v93, 0xffff0000, v94
	v_pk_mul_f32 v[84:85], v[84:85], v[104:105]
	v_pk_mul_f32 v[80:81], v[80:81], v[92:93]
	v_lshlrev_b32_e32 v92, 16, v95
	v_and_b32_e32 v93, 0xffff0000, v95
	v_cvt_pk_bf16_f32 v84, v84, v85
	v_cvt_pk_bf16_f32 v85, v86, v87
	v_cvt_pk_bf16_f32 v86, v80, v81
	v_lshlrev_b64 v[80:81], 12, v[102:103]
	v_pk_mul_f32 v[82:83], v[82:83], v[92:93]
	v_lshl_add_u64 v[80:81], s[4:5], 0, v[80:81]
	v_add_u32_e32 v92, 0xa0, v160
	v_cvt_pk_bf16_f32 v87, v82, v83
	v_lshl_add_u64 v[82:83], v[80:81], 0, v[162:163]
	v_mad_i64_i32 v[80:81], s[20:21], v92, s33, v[164:165]
	v_lshl_add_u64 v[80:81], v[80:81], 0, s[80:81]
	global_store_dwordx4 v[82:83], v[84:87], off
	v_ashrrev_i32_e32 v93, 31, v92
	s_nop 0
	v_lshl_add_u64 v[84:85], v[80:81], 0, v[162:163]
	global_load_dwordx4 v[84:87], v[84:85], off
	s_waitcnt vmcnt(0) lgkmcnt(0)
	v_lshlrev_b32_e32 v94, 16, v84
	v_and_b32_e32 v95, 0xffff0000, v84
	v_lshlrev_b32_e32 v84, 16, v85
	v_and_b32_e32 v85, 0xffff0000, v85
	v_pk_mul_f32 v[78:79], v[78:79], v[84:85]
	v_lshlrev_b32_e32 v84, 16, v86
	v_and_b32_e32 v85, 0xffff0000, v86
	v_pk_mul_f32 v[76:77], v[76:77], v[94:95]
	v_pk_mul_f32 v[84:85], v[72:73], v[84:85]
	v_lshlrev_b32_e32 v72, 16, v87
	v_and_b32_e32 v73, 0xffff0000, v87
	v_pk_mul_f32 v[86:87], v[74:75], v[72:73]
	v_cvt_pk_bf16_f32 v72, v76, v77
	v_lshlrev_b64 v[76:77], 12, v[92:93]
	v_lshl_add_u64 v[76:77], s[4:5], 0, v[76:77]
	v_cvt_pk_bf16_f32 v73, v78, v79
	v_cvt_pk_bf16_f32 v74, v84, v85
	v_cvt_pk_bf16_f32 v75, v86, v87
	v_lshl_add_u64 v[76:77], v[76:77], 0, v[162:163]
	global_store_dwordx4 v[76:77], v[72:75], off
	s_nop 1
	v_add_u32_e32 v72, 0xb0, v160
	v_mad_i64_i32 v[74:75], s[20:21], v72, s33, v[164:165]
	v_lshl_add_u64 v[74:75], v[74:75], 0, s[80:81]
	v_lshl_add_u64 v[78:79], v[74:75], 0, v[162:163]
	global_load_dwordx4 v[84:87], v[78:79], off
	v_ashrrev_i32_e32 v73, 31, v72
	s_mov_b64 s[20:21], -1
	s_waitcnt vmcnt(0) lgkmcnt(0)
	v_lshlrev_b32_e32 v78, 16, v84
	v_and_b32_e32 v79, 0xffff0000, v84
	v_pk_mul_f32 v[68:69], v[68:69], v[78:79]
	v_lshlrev_b32_e32 v78, 16, v85
	v_and_b32_e32 v79, 0xffff0000, v85
	v_pk_mul_f32 v[70:71], v[70:71], v[78:79]
	v_lshlrev_b32_e32 v78, 16, v86
	v_and_b32_e32 v79, 0xffff0000, v86
	v_pk_mul_f32 v[78:79], v[64:65], v[78:79]
	v_lshlrev_b32_e32 v64, 16, v87
	v_and_b32_e32 v65, 0xffff0000, v87
	v_pk_mul_f32 v[84:85], v[66:67], v[64:65]
	v_cvt_pk_bf16_f32 v64, v68, v69
	v_cvt_pk_bf16_f32 v66, v78, v79
	v_lshlrev_b64 v[68:69], 12, v[72:73]
	v_or_b32_e32 v78, 0x80, v154
	v_lshl_add_u64 v[68:69], s[4:5], 0, v[68:69]
	v_ashrrev_i32_e32 v79, 31, v78
	v_cvt_pk_bf16_f32 v65, v70, v71
	v_cvt_pk_bf16_f32 v67, v84, v85
	v_lshl_add_u64 v[72:73], v[68:69], 0, v[162:163]
	v_lshlrev_b64 v[78:79], 1, v[78:79]
	global_store_dwordx4 v[72:73], v[64:67], off
	v_lshl_add_u64 v[84:85], v[156:157], 0, v[78:79]
	global_load_dwordx4 v[64:67], v[158:159], off offset:528
	global_load_dwordx4 v[68:71], v[158:159], off offset:512
	s_waitcnt vmcnt(0)
; __device__ __forceinline__ float bflo(unsigned w) { return __uint_as_float(w << 16); }
; __device__ __forceinline__ float bfhi(unsigned w) { return __uint_as_float(w & 0xffff0000u); }
; __device__ __forceinline__ unsigned cvtpk(float lo, float hi) { f32x2_t v = {lo, hi}; bf16x2_t b = __builtin_convertvector(v, bf16x2_t); return __builtin_bit_cast(unsigned, b); }
;     __device__ __forceinline__ void operator()(const f32x4 (&acc)[2][2][4][2], const Unit& u, int wr, int wc, int fr, int fq) const {
;         const int g = u.pn, row0 = (u.pm & 63) * BM + wr * 64 + fr, col0 = g * 256 + wc * 32 + 8 * fq;
; #pragma unroll
;         for (int bj = 0; bj < 2; ++bj) { const int col = col0 + bj * HALF;
;             const f32x4 p0 = *(const f32x4*)(pscale + col), p1 = *(const f32x4*)(pscale + col + 4);
; #pragma unroll
;             for (int ai = 0; ai < 2; ++ai)
; #pragma unroll
;                 for (int m = 0; m < 4; ++m) { const size_t row = (size_t)(row0 + ai * HALF + m * 16);
;                     const u32x4 sg = *(const u32x4*)(Z + row * ZP + 3072 + col);
;                     f32x4 v0 = acc[ai][bj][m][0] * p0, v1 = acc[ai][bj][m][1] * p1;
;                     v0[0] *= bflo(sg.x); v0[1] *= bfhi(sg.x); v0[2] *= bflo(sg.y); v0[3] *= bfhi(sg.y);
;                     v1[0] *= bflo(sg.z); v1[1] *= bfhi(sg.z); v1[2] *= bflo(sg.w); v1[3] *= bfhi(sg.w);
;                     u32x4 w; w.x = cvtpk(v0[0], v0[1]); w.y = cvtpk(v0[2], v0[3]); w.z = cvtpk(v1[0], v1[1]); w.w = cvtpk(v1[2], v1[3]);
;                     *(u32x4*)(Y + row * D + col) = w; } }
	v_pk_mul_f32 v[56:57], v[56:57], v[64:65]
	global_load_dwordx4 v[84:87], v[84:85], off
	v_pk_mul_f32 v[62:63], v[62:63], v[70:71]
	v_pk_mul_f32 v[60:61], v[60:61], v[68:69]
	v_pk_mul_f32 v[58:59], v[58:59], v[66:67]
	v_pk_mul_f32 v[54:55], v[54:55], v[70:71]
	v_pk_mul_f32 v[48:49], v[48:49], v[64:65]
	v_pk_mul_f32 v[52:53], v[52:53], v[68:69]
	v_pk_mul_f32 v[50:51], v[50:51], v[66:67]
	v_pk_mul_f32 v[46:47], v[46:47], v[70:71]
	v_pk_mul_f32 v[40:41], v[40:41], v[64:65]
	v_pk_mul_f32 v[44:45], v[44:45], v[68:69]
	v_pk_mul_f32 v[42:43], v[42:43], v[66:67]
	v_pk_mul_f32 v[38:39], v[38:39], v[70:71]
	v_pk_mul_f32 v[32:33], v[32:33], v[64:65]
	v_pk_mul_f32 v[36:37], v[36:37], v[68:69]
	v_pk_mul_f32 v[34:35], v[34:35], v[66:67]
	v_pk_mul_f32 v[30:31], v[30:31], v[70:71]
	v_pk_mul_f32 v[24:25], v[24:25], v[64:65]
	v_pk_mul_f32 v[28:29], v[28:29], v[68:69]
	v_pk_mul_f32 v[26:27], v[26:27], v[66:67]
	v_pk_mul_f32 v[22:23], v[22:23], v[70:71]
	v_pk_mul_f32 v[16:17], v[16:17], v[64:65]
	v_pk_mul_f32 v[20:21], v[20:21], v[68:69]
	v_pk_mul_f32 v[18:19], v[18:19], v[66:67]
	v_pk_mul_f32 v[14:15], v[14:15], v[70:71]
	v_pk_mul_f32 v[8:9], v[8:9], v[64:65]
	v_pk_mul_f32 v[12:13], v[12:13], v[68:69]
	v_pk_mul_f32 v[10:11], v[10:11], v[66:67]
	v_pk_mul_f32 v[6:7], v[6:7], v[70:71]
	v_pk_mul_f32 v[0:1], v[0:1], v[64:65]
	v_pk_mul_f32 v[4:5], v[4:5], v[68:69]
	v_pk_mul_f32 v[2:3], v[2:3], v[66:67]
	s_waitcnt vmcnt(0) lgkmcnt(0)
	v_lshlrev_b32_e32 v92, 16, v84
	v_and_b32_e32 v93, 0xffff0000, v84
	v_lshlrev_b32_e32 v84, 16, v85
	v_and_b32_e32 v85, 0xffff0000, v85
	v_pk_mul_f32 v[62:63], v[62:63], v[84:85]
	v_lshlrev_b32_e32 v84, 16, v86
	v_and_b32_e32 v85, 0xffff0000, v86
	v_pk_mul_f32 v[84:85], v[56:57], v[84:85]
	v_lshlrev_b32_e32 v56, 16, v87
	v_and_b32_e32 v57, 0xffff0000, v87
	v_pk_mul_f32 v[60:61], v[60:61], v[92:93]
	v_pk_mul_f32 v[86:87], v[58:59], v[56:57]
	v_cvt_pk_bf16_f32 v56, v60, v61
	v_cvt_pk_bf16_f32 v57, v62, v63
	v_cvt_pk_bf16_f32 v58, v84, v85
	v_cvt_pk_bf16_f32 v59, v86, v87
	global_store_dwordx4 v[124:125], v[56:59], off offset:256
	s_nop 1
	v_lshl_add_u64 v[56:57], v[122:123], 0, v[78:79]
	global_load_dwordx4 v[56:59], v[56:57], off
	s_waitcnt vmcnt(0) lgkmcnt(0)
	v_lshlrev_b32_e32 v60, 16, v56
	v_and_b32_e32 v61, 0xffff0000, v56
	v_lshlrev_b32_e32 v56, 16, v57
	v_and_b32_e32 v57, 0xffff0000, v57
	v_pk_mul_f32 v[54:55], v[54:55], v[56:57]
	v_lshlrev_b32_e32 v56, 16, v58
	v_and_b32_e32 v57, 0xffff0000, v58
	v_pk_mul_f32 v[56:57], v[48:49], v[56:57]
	v_lshlrev_b32_e32 v48, 16, v59
	v_and_b32_e32 v49, 0xffff0000, v59
	v_pk_mul_f32 v[52:53], v[52:53], v[60:61]
	v_pk_mul_f32 v[58:59], v[50:51], v[48:49]
	v_cvt_pk_bf16_f32 v48, v52, v53
	v_cvt_pk_bf16_f32 v49, v54, v55
	v_cvt_pk_bf16_f32 v50, v56, v57
	v_cvt_pk_bf16_f32 v51, v58, v59
	global_store_dwordx4 v[116:117], v[48:51], off offset:256
	s_nop 1
	v_lshl_add_u64 v[48:49], v[114:115], 0, v[78:79]
	global_load_dwordx4 v[48:51], v[48:49], off
	s_waitcnt vmcnt(0) lgkmcnt(0)
	v_lshlrev_b32_e32 v52, 16, v48
	v_and_b32_e32 v53, 0xffff0000, v48
	v_lshlrev_b32_e32 v48, 16, v49
	v_and_b32_e32 v49, 0xffff0000, v49
	v_pk_mul_f32 v[46:47], v[46:47], v[48:49]
	v_lshlrev_b32_e32 v48, 16, v50
	v_and_b32_e32 v49, 0xffff0000, v50
	v_pk_mul_f32 v[48:49], v[40:41], v[48:49]
	v_lshlrev_b32_e32 v40, 16, v51
	v_and_b32_e32 v41, 0xffff0000, v51
	v_pk_mul_f32 v[44:45], v[44:45], v[52:53]
	v_pk_mul_f32 v[50:51], v[42:43], v[40:41]
	v_cvt_pk_bf16_f32 v40, v44, v45
	v_cvt_pk_bf16_f32 v41, v46, v47
	v_cvt_pk_bf16_f32 v42, v48, v49
	v_cvt_pk_bf16_f32 v43, v50, v51
	global_store_dwordx4 v[108:109], v[40:43], off offset:256
	s_nop 1
	v_lshl_add_u64 v[40:41], v[106:107], 0, v[78:79]
	global_load_dwordx4 v[40:43], v[40:41], off
	s_waitcnt vmcnt(0) lgkmcnt(0)
; #define PG8_BAR __builtin_amdgcn_s_barrier()
; __device__ __forceinline__ float bflo(unsigned w) { return __uint_as_float(w << 16); }
; __device__ __forceinline__ float bfhi(unsigned w) { return __uint_as_float(w & 0xffff0000u); }
; __device__ __forceinline__ unsigned cvtpk(float lo, float hi) { f32x2_t v = {lo, hi}; bf16x2_t b = __builtin_convertvector(v, bf16x2_t); return __builtin_bit_cast(unsigned, b); }
; template <class Epi, class Sched, bool ALIGN_EPI = false, bool SP2 = false>
; __device__ __forceinline__ void gemm_phase(PG8_LAS unsigned char* lds, const Gemm g, const Sched& S, const Epi& E, int wid_s_) {
;     ...
;         if constexpr (ALIGN_EPI) { if (wr == 0) PG8_BAR; }
;         if constexpr (!Epi::AFTER_DRAIN) { E(acc, cur, wr, wc, fr, fq); S.done(cur); }
;         if (!has_next) break;
;     __device__ __forceinline__ void operator()(const f32x4 (&acc)[2][2][4][2], const Unit& u, int wr, int wc, int fr, int fq) const {
;         const int g = u.pn, row0 = (u.pm & 63) * BM + wr * 64 + fr, col0 = g * 256 + wc * 32 + 8 * fq;
; #pragma unroll
;         for (int bj = 0; bj < 2; ++bj) { const int col = col0 + bj * HALF;
;             const f32x4 p0 = *(const f32x4*)(pscale + col), p1 = *(const f32x4*)(pscale + col + 4);
; #pragma unroll
;             for (int ai = 0; ai < 2; ++ai)
; #pragma unroll
;                 for (int m = 0; m < 4; ++m) { const size_t row = (size_t)(row0 + ai * HALF + m * 16);
;                     const u32x4 sg = *(const u32x4*)(Z + row * ZP + 3072 + col);
;                     f32x4 v0 = acc[ai][bj][m][0] * p0, v1 = acc[ai][bj][m][1] * p1;
;                     v0[0] *= bflo(sg.x); v0[1] *= bfhi(sg.x); v0[2] *= bflo(sg.y); v0[3] *= bfhi(sg.y);
;                     v1[0] *= bflo(sg.z); v1[1] *= bfhi(sg.z); v1[2] *= bflo(sg.w); v1[3] *= bfhi(sg.w);
;                     u32x4 w; w.x = cvtpk(v0[0], v0[1]); w.y = cvtpk(v0[2], v0[3]); w.z = cvtpk(v1[0], v1[1]); w.w = cvtpk(v1[2], v1[3]);
;                     *(u32x4*)(Y + row * D + col) = w; } }
	v_lshlrev_b32_e32 v44, 16, v40
	v_and_b32_e32 v45, 0xffff0000, v40
	v_lshlrev_b32_e32 v40, 16, v41
	v_and_b32_e32 v41, 0xffff0000, v41
	v_pk_mul_f32 v[38:39], v[38:39], v[40:41]
	v_lshlrev_b32_e32 v40, 16, v42
	v_and_b32_e32 v41, 0xffff0000, v42
	v_pk_mul_f32 v[40:41], v[32:33], v[40:41]
	v_lshlrev_b32_e32 v32, 16, v43
	v_and_b32_e32 v33, 0xffff0000, v43
	v_pk_mul_f32 v[36:37], v[36:37], v[44:45]
	v_pk_mul_f32 v[42:43], v[34:35], v[32:33]
	v_cvt_pk_bf16_f32 v32, v36, v37
	v_cvt_pk_bf16_f32 v33, v38, v39
	v_cvt_pk_bf16_f32 v34, v40, v41
	v_cvt_pk_bf16_f32 v35, v42, v43
	global_store_dwordx4 v[100:101], v[32:35], off offset:256
	s_nop 1
	v_lshl_add_u64 v[32:33], v[98:99], 0, v[78:79]
	global_load_dwordx4 v[32:35], v[32:33], off
	s_waitcnt vmcnt(0) lgkmcnt(0)
	v_lshlrev_b32_e32 v36, 16, v32
	v_and_b32_e32 v37, 0xffff0000, v32
	v_lshlrev_b32_e32 v32, 16, v33
	v_and_b32_e32 v33, 0xffff0000, v33
	v_pk_mul_f32 v[30:31], v[30:31], v[32:33]
	v_lshlrev_b32_e32 v32, 16, v34
	v_and_b32_e32 v33, 0xffff0000, v34
	v_pk_mul_f32 v[32:33], v[24:25], v[32:33]
	v_lshlrev_b32_e32 v24, 16, v35
	v_and_b32_e32 v25, 0xffff0000, v35
	v_pk_mul_f32 v[28:29], v[28:29], v[36:37]
	v_pk_mul_f32 v[34:35], v[26:27], v[24:25]
	v_cvt_pk_bf16_f32 v24, v28, v29
	v_cvt_pk_bf16_f32 v25, v30, v31
	v_cvt_pk_bf16_f32 v26, v32, v33
	v_cvt_pk_bf16_f32 v27, v34, v35
	global_store_dwordx4 v[90:91], v[24:27], off offset:256
	s_nop 1
	v_lshl_add_u64 v[24:25], v[88:89], 0, v[78:79]
	global_load_dwordx4 v[24:27], v[24:25], off
	s_waitcnt vmcnt(0) lgkmcnt(0)
	v_lshlrev_b32_e32 v28, 16, v24
	v_and_b32_e32 v29, 0xffff0000, v24
	v_lshlrev_b32_e32 v24, 16, v25
	v_and_b32_e32 v25, 0xffff0000, v25
	v_pk_mul_f32 v[22:23], v[22:23], v[24:25]
	v_lshlrev_b32_e32 v24, 16, v26
	v_and_b32_e32 v25, 0xffff0000, v26
	v_pk_mul_f32 v[24:25], v[16:17], v[24:25]
	v_lshlrev_b32_e32 v16, 16, v27
	v_and_b32_e32 v17, 0xffff0000, v27
	v_pk_mul_f32 v[20:21], v[20:21], v[28:29]
	v_pk_mul_f32 v[26:27], v[18:19], v[16:17]
	v_cvt_pk_bf16_f32 v16, v20, v21
	v_cvt_pk_bf16_f32 v17, v22, v23
	v_cvt_pk_bf16_f32 v18, v24, v25
	v_cvt_pk_bf16_f32 v19, v26, v27
	global_store_dwordx4 v[82:83], v[16:19], off offset:256
	s_nop 1
	v_lshl_add_u64 v[16:17], v[80:81], 0, v[78:79]
	global_load_dwordx4 v[16:19], v[16:17], off
	s_waitcnt vmcnt(0) lgkmcnt(0)
	v_lshlrev_b32_e32 v20, 16, v16
	v_and_b32_e32 v21, 0xffff0000, v16
	v_lshlrev_b32_e32 v16, 16, v17
	v_and_b32_e32 v17, 0xffff0000, v17
	v_pk_mul_f32 v[14:15], v[14:15], v[16:17]
	v_lshlrev_b32_e32 v16, 16, v18
	v_and_b32_e32 v17, 0xffff0000, v18
	v_pk_mul_f32 v[16:17], v[8:9], v[16:17]
	v_lshlrev_b32_e32 v8, 16, v19
	v_and_b32_e32 v9, 0xffff0000, v19
	v_pk_mul_f32 v[12:13], v[12:13], v[20:21]
	v_pk_mul_f32 v[18:19], v[10:11], v[8:9]
	v_cvt_pk_bf16_f32 v8, v12, v13
	v_cvt_pk_bf16_f32 v9, v14, v15
	v_cvt_pk_bf16_f32 v10, v16, v17
	v_cvt_pk_bf16_f32 v11, v18, v19
	global_store_dwordx4 v[76:77], v[8:11], off offset:256
	s_nop 1
	v_lshl_add_u64 v[8:9], v[74:75], 0, v[78:79]
	global_load_dwordx4 v[8:11], v[8:9], off
	s_waitcnt vmcnt(0) lgkmcnt(0)
	v_lshlrev_b32_e32 v12, 16, v8
	v_and_b32_e32 v13, 0xffff0000, v8
	v_lshlrev_b32_e32 v8, 16, v9
	v_and_b32_e32 v9, 0xffff0000, v9
	v_pk_mul_f32 v[6:7], v[6:7], v[8:9]
	v_lshlrev_b32_e32 v8, 16, v10
	v_and_b32_e32 v9, 0xffff0000, v10
	v_pk_mul_f32 v[8:9], v[0:1], v[8:9]
	v_lshlrev_b32_e32 v0, 16, v11
	v_and_b32_e32 v1, 0xffff0000, v11
	v_pk_mul_f32 v[4:5], v[4:5], v[12:13]
	v_pk_mul_f32 v[10:11], v[2:3], v[0:1]
	v_cvt_pk_bf16_f32 v0, v4, v5
	v_cvt_pk_bf16_f32 v1, v6, v7
	v_cvt_pk_bf16_f32 v2, v8, v9
	v_cvt_pk_bf16_f32 v3, v10, v11
	global_store_dwordx4 v[72:73], v[0:3], off offset:256
	s_cbranch_vccnz .LBB0_1269
	v_readlane_b32 s0, v255, 58
	v_readlane_b32 s1, v255, 59
	s_andn2_b64 vcc, exec, s[0:1]
	s_cbranch_vccnz .LBB0_1268
	s_barrier
	s_branch .LBB0_1268

; #define ATT_DMA(t, b) do { \
;         _Pragma("unroll") for (int i_ = 0; i_ < 2; ++i_) glds16(Kg + (size_t)(t) * 64 * ZP + offK[i_], lds + (b) * BUF + (i_ * 8 + wid) * 1024); \
;         _Pragma("unroll") for (int i_ = 0; i_ < 2; ++i_) glds16(Vg + (size_t)(t) * 64 + offV[i_], lds + (b) * BUF + KBYTES + (i_ * 8 + wid) * 1024); } while (0)
; __device__ __forceinline__ void attn_phase(LAS unsigned char* lds, const bf16_t* Z, const bf16_t* VT, bf16_t* Y, const float* subln, float lam, float lam_init, float M0, unsigned* ctr, LAS int* s_unit, int wid_s_) {
;     ...
;         __syncthreads();
;         if (tid == 0) *s_unit = (int)atomicAdd(ctr, 1u);
;         __syncthreads();
;         const int U = *s_unit;
;         if (U >= 1024) break;
;         const int h = 7 - (U >> 7), qb = U & 127, q0 = qb * 128, qw = q0 + rg * 32;
;         const float m2 = exp2f(-(float)(h + 1)) * LOG2E;
;         const int W = (int)(150.f / m2) + 1;
;         const int tlo = max(0, q0 - W) >> 6, thi = min(S - 1, q0 + 127 + W) >> 6;
;         const int wlo = max(0, qw - W) >> 6, whi = min(S - 1, qw + 31 + W) >> 6;
;         const bf16_t* Kg = Z + 2048 + h * 128; const bf16_t* Vg = VT + (size_t)h * 128 * S;
;         bf16x8 qf[4];
;         { const bf16_t* qp = Z + (size_t)(qw + rr) * ZP + 1024 + h * 128 + jm * 64 + hh * 8;
; #pragma unroll
;           for (int t4 = 0; t4 < 4; ++t4) qf[t4] = *(const bf16x8*)(qp + t4 * 16); }
;         f32x16 O[4];
; #pragma unroll
;         for (int cb = 0; cb < 4; ++cb)
; #pragma unroll
;             for (int r = 0; r < 16; ++r) O[cb][r] = 0.f;
;         float ls = 0.f;
;     ...
;         const int Tlo = tlo >> 1, Thi = thi >> 1;
;         ATT_DMA(2 * Tlo, 0); ATT_DMA(2 * Tlo + 1, 1);
.LBB0_1294:
	s_or_b64 exec, exec, s[2:3]
	s_waitcnt lgkmcnt(0)
	s_barrier
	ds_read_b32 v0, v97 offset:8
	s_movk_i32 s2, 0x3ff
	s_waitcnt lgkmcnt(0)
	v_cmp_lt_i32_e32 vcc, s2, v0
	v_readfirstlane_b32 s15, v0
	s_mov_b64 s[2:3], -1
	s_cbranch_vccnz .LBB0_1291
	s_ashr_i32 s2, s15, 7
	s_sub_i32 s3, 8, s2
	v_cvt_f32_u32_e32 v0, s3
	s_sub_i32 s26, 7, s2
	s_lshl_b32 s2, s15, 7
	s_and_b32 s16, s2, 0x3f80
	s_mov_b32 s2, 0x42fc0000
	v_cmp_lt_f32_e32 vcc, s2, v0
	v_mov_b32_e32 v1, 0x42800000
	s_add_i32 s40, s16, s25
	v_cndmask_b32_e32 v1, 0, v1, vcc
	v_sub_f32_e32 v0, v1, v0
	v_exp_f32_e32 v0, v0
	s_and_b64 s[2:3], vcc, exec
	s_cselect_b32 s2, 0xffffffc0, 0
	s_mov_b32 s15, 0x42fc0000
	v_ldexp_f32 v0, v0, s2
	v_mul_f32_e32 v171, 0x3fb8aa3b, v0
	v_div_scale_f32 v0, s[2:3], v171, v171, s15
	v_rcp_f32_e32 v1, v0
	s_lshl_b32 s41, s26, 7
	s_mov_b32 m0, s37
	v_mov_b32_e32 v15, 0
	v_fma_f32 v2, -v0, v1, 1.0
	v_fmac_f32_e32 v1, v2, v1
	v_div_scale_f32 v2, vcc, s15, v171, s15
	v_mul_f32_e32 v3, v2, v1
	v_fma_f32 v4, -v0, v3, v2
	v_fmac_f32_e32 v3, v4, v1
	v_fma_f32 v0, -v0, v3, v2
	v_div_fmas_f32 v0, v0, v1, v3
	v_div_fixup_f32 v0, v0, v171, s15
	v_cvt_i32_f32_e32 v0, v0
	v_or_b32_e32 v2, s40, v203
	s_mov_b32 s15, s27
	v_mov_b32_e32 v14, 0
	v_readfirstlane_b32 s17, v0
	s_add_i32 s17, s17, 1
	s_add_i32 s2, s17, s16
	v_mov_b64_e32 v[0:1], s[78:79]
	s_add_i32 s51, s2, 0x7f
	s_lshl_b64 s[2:3], s[26:27], 22
	v_mad_i64_i32 v[0:1], s[48:49], v2, s33, v[0:1]
	s_lshl_b32 s26, s26, 8
	s_sub_i32 s50, s16, s17
	v_lshl_add_u64 v[0:1], v[0:1], 0, s[26:27]
	v_lshl_add_u64 v[0:1], v[0:1], 0, s[14:15]
	s_max_i32 s15, s50, 0
	s_add_u32 s50, s22, s26
	s_addc_u32 s78, s23, 0
	s_lshr_b32 s15, s15, 7
	s_lshl_b32 s26, s15, 1
	s_mul_i32 s86, s15, 0x140000
	s_mul_hi_u32 s49, s26, 0xa0000
	s_add_u32 s48, s50, s86
	v_lshl_add_u64 v[0:1], v[0:1], 0, v[96:97]
	s_addc_u32 s49, s78, s49
	global_load_dwordx4 v[98:101], v[0:1], off offset:2048
	global_load_dwordx4 v[102:105], v[0:1], off offset:2080
	global_load_dwordx4 v[106:109], v[0:1], off offset:2112
	global_load_dwordx4 v[110:113], v[0:1], off offset:2144
	v_lshl_add_u64 v[0:1], s[48:49], 0, v[168:169]
	global_load_lds_dwordx4 v[0:1], off
	v_lshl_add_u64 v[0:1], s[48:49], 0, v[166:167]
	s_add_i32 m0, s37, 0x2000
	v_readlane_b32 s48, v255, 52
	v_readlane_b32 s49, v255, 53
	s_add_u32 s48, s48, s2
	s_addc_u32 s49, s49, s3
	s_lshl_b32 s87, s15, 8
	s_add_u32 s48, s48, s87
	s_addc_u32 s49, s49, 0
	global_load_lds_dwordx4 v[0:1], off
	v_lshl_add_u64 v[0:1], v[156:157], 1, s[48:49]
	s_add_i32 m0, s37, 0x4000
	v_lshl_add_u64 v[2:3], v[158:159], 1, s[48:49]
	s_or_b32 s48, s26, 1
	global_load_lds_dwordx4 v[0:1], off
	s_add_i32 m0, s37, 0x6000
	s_min_i32 s51, s51, 0x3fff
	s_mul_hi_u32 s49, s48, 0xa0000
	s_mul_i32 s48, s48, 0xa0000
	s_add_u32 s48, s50, s48
	s_addc_u32 s49, s78, s49
	global_load_lds_dwordx4 v[2:3], off
	v_lshl_add_u64 v[4:5], s[48:49], 0, v[168:169]
	s_add_i32 m0, s37, 0x8000
	v_lshl_add_u64 v[0:1], v[0:1], 0, s[42:43]
	global_load_lds_dwordx4 v[4:5], off
	v_lshl_add_u64 v[4:5], s[48:49], 0, v[166:167]
	s_add_i32 m0, s37, 0xa000
	s_ashr_i32 s48, s51, 7
	global_load_lds_dwordx4 v[4:5], off
	s_add_i32 m0, s37, 0xc000
	v_mov_b32_e32 v13, 0
	global_load_lds_dwordx4 v[0:1], off
	v_lshl_add_u64 v[0:1], v[2:3], 0, s[42:43]
	s_add_i32 m0, s37, 0xe000
	s_cmp_gt_i32 s15, s48
	global_load_lds_dwordx4 v[0:1], off
	v_mov_b32_e32 v12, 0
	v_mov_b32_e32 v11, 0
	v_mov_b32_e32 v10, 0
	v_mov_b32_e32 v9, 0
	v_mov_b32_e32 v8, 0
	v_mov_b32_e32 v7, 0
	v_mov_b32_e32 v6, 0
	v_mov_b32_e32 v5, 0
	v_mov_b32_e32 v4, 0
	v_mov_b32_e32 v3, 0
	v_mov_b32_e32 v2, 0
	v_mov_b32_e32 v1, 0
	v_mov_b32_e32 v0, 0
	v_mov_b32_e32 v31, 0
	v_mov_b32_e32 v30, 0
	v_mov_b32_e32 v29, 0
	v_mov_b32_e32 v28, 0
	v_mov_b32_e32 v27, 0
	v_mov_b32_e32 v26, 0
	v_mov_b32_e32 v25, 0
	v_mov_b32_e32 v24, 0
	v_mov_b32_e32 v23, 0
	v_mov_b32_e32 v22, 0
	v_mov_b32_e32 v21, 0
	v_mov_b32_e32 v20, 0
	v_mov_b32_e32 v19, 0
	v_mov_b32_e32 v18, 0
	v_mov_b32_e32 v17, 0
	v_mov_b32_e32 v16, 0
	v_mov_b32_e32 v63, 0
	v_mov_b32_e32 v62, 0
	v_mov_b32_e32 v61, 0
	v_mov_b32_e32 v60, 0
	v_mov_b32_e32 v59, 0
	v_mov_b32_e32 v58, 0
	v_mov_b32_e32 v57, 0
	v_mov_b32_e32 v56, 0
	v_mov_b32_e32 v55, 0
	v_mov_b32_e32 v54, 0
	v_mov_b32_e32 v53, 0
	v_mov_b32_e32 v52, 0
	v_mov_b32_e32 v51, 0
	v_mov_b32_e32 v50, 0
	v_mov_b32_e32 v49, 0
	v_mov_b32_e32 v48, 0
	v_mov_b32_e32 v47, 0
	v_mov_b32_e32 v46, 0
	v_mov_b32_e32 v45, 0
	v_mov_b32_e32 v44, 0
	v_mov_b32_e32 v43, 0
	v_mov_b32_e32 v42, 0
	v_mov_b32_e32 v41, 0
	v_mov_b32_e32 v40, 0
	v_mov_b32_e32 v39, 0
	v_mov_b32_e32 v38, 0
	v_mov_b32_e32 v37, 0
	v_mov_b32_e32 v36, 0
	v_mov_b32_e32 v35, 0
	v_mov_b32_e32 v34, 0
	v_mov_b32_e32 v33, 0
	v_mov_b32_e32 v32, 0
	v_mov_b32_e32 v197, 0
	s_cbranch_scc1 .LBB0_1315
; #define LAS __attribute__((address_space(3)))
; #define ATT_DMA(t, b) do { \
;         _Pragma("unroll") for (int i_ = 0; i_ < 2; ++i_) glds16(Kg + (size_t)(t) * 64 * ZP + offK[i_], lds + (b) * BUF + (i_ * 8 + wid) * 1024); \
;         _Pragma("unroll") for (int i_ = 0; i_ < 2; ++i_) glds16(Vg + (size_t)(t) * 64 + offV[i_], lds + (b) * BUF + KBYTES + (i_ * 8 + wid) * 1024); } while (0)
; __device__ __forceinline__ void attn_phase(LAS unsigned char* lds, const bf16_t* Z, const bf16_t* VT, bf16_t* Y, const float* subln, float lam, float lam_init, float M0, unsigned* ctr, LAS int* s_unit, int wid_s_) {
;     ...
;         const int tlo = max(0, q0 - W) >> 6, thi = min(S - 1, q0 + 127 + W) >> 6;
;         const int wlo = max(0, qw - W) >> 6, whi = min(S - 1, qw + 31 + W) >> 6;
;         const bf16_t* Kg = Z + 2048 + h * 128; const bf16_t* Vg = VT + (size_t)h * 128 * S;
;         bf16x8 qf[4];
;         { const bf16_t* qp = Z + (size_t)(qw + rr) * ZP + 1024 + h * 128 + jm * 64 + hh * 8;
; #pragma unroll
;           for (int t4 = 0; t4 < 4; ++t4) qf[t4] = *(const bf16x8*)(qp + t4 * 16); }
;         f32x16 O[4];
; #pragma unroll
;         for (int cb = 0; cb < 4; ++cb)
; #pragma unroll
;             for (int r = 0; r < 16; ++r) O[cb][r] = 0.f;
;         float ls = 0.f;
;     ...
;         const int Tlo = tlo >> 1, Thi = thi >> 1;
;         ATT_DMA(2 * Tlo, 0); ATT_DMA(2 * Tlo + 1, 1);
;         for (int T = Tlo; T <= Thi; ++T) {
;             const int b = (T - Tlo) & 1;
;             asm volatile("s_waitcnt vmcnt(0)" ::: "memory");
;             __syncthreads();
;             if (T + 1 <= Thi) { ATT_DMA(2 * T + 2, 2 * (b ^ 1)); ATT_DMA(2 * T + 3, 2 * (b ^ 1) + 1); }
; #pragma unroll
;             for (int half = 0; half < 2; ++half) { const int t = 2 * T + half;
;                 if (t >= wlo && t <= whi) {
;                     const LAS unsigned char* kb = lds + (2 * b + half) * BUF; const LAS unsigned char* vb = kb + KBYTES;
;                     const int k0 = t * 64;
;                     const float d00 = (float)(qw + rr - (k0 + 8 * hh));
;                     const bool left = (k0 + 63 <= qw), right = (k0 >= qw + 31);
;                     tile_body(!(left || right), kb, vb, krow, jm, hh, rr, d00, m2, right ? -m2 : m2, M0, qf, O, ls);
	s_sub_i32 s50, s40, s17
	s_max_i32 s51, s50, 0
	s_or_b32 s50, s40, 31
	s_add_i32 s17, s17, s50
	s_min_i32 s17, s17, 0x3fff
	s_lshr_b32 s51, s51, 6
	s_ashr_i32 s84, s17, 6
	s_lshl_b32 s85, s15, 7
	s_add_u32 s2, s87, s2
	s_addc_u32 s3, 0, s3
	s_add_u32 s70, s2, s28
	s_addc_u32 s71, s3, s29
	s_add_u32 s76, s70, 0x1a400180
	s_addc_u32 s77, s71, 0
	s_add_u32 s70, s70, 0x1a400100
	s_addc_u32 s71, s71, 0
	s_lshl_b32 s2, s41, 1
	v_add_u32_e32 v0, s16, v240
	s_mul_hi_u32 s3, s15, 0x140000
	s_add_u32 s2, s2, s86
	v_mov_b32_e32 v32, v97
	v_mov_b32_e32 v33, v97
	v_mov_b32_e32 v46, v97
	v_mov_b32_e32 v47, v97
	v_xor_b32_e32 v172, 0x80000000, v171
	v_subrev_u32_e32 v193, s85, v0
	s_addc_u32 s3, 0, s3
	v_mov_b32_e32 v34, v97
	v_mov_b32_e32 v35, v97
	v_mov_b32_e32 v36, v97
	v_mov_b32_e32 v37, v97
	v_mov_b32_e32 v38, v97
	v_mov_b32_e32 v39, v97
	v_mov_b32_e32 v40, v97
	v_mov_b32_e32 v41, v97
	v_mov_b32_e32 v42, v97
	v_mov_b32_e32 v43, v97
	v_mov_b32_e32 v44, v97
	v_mov_b32_e32 v45, v97
	v_mov_b64_e32 v[62:63], v[46:47]
	v_mov_b64_e32 v[16:17], v[32:33]
	v_mov_b64_e32 v[0:1], v[32:33]
	s_mov_b32 s49, 0
	v_mov_b32_e32 v174, v172
	v_mov_b32_e32 v175, v172
	s_add_u32 s68, s2, s28
	s_addc_u32 s69, s3, s29
	s_add_u32 s72, s68, 0x105e1000
	s_addc_u32 s73, s69, 0
	s_add_u32 s68, s68, 0x10541000
	s_addc_u32 s69, s69, 0
	v_mov_b32_e32 v197, 0
	v_mov_b64_e32 v[60:61], v[44:45]
	v_mov_b64_e32 v[58:59], v[42:43]
	v_mov_b64_e32 v[56:57], v[40:41]
	v_mov_b64_e32 v[54:55], v[38:39]
	v_mov_b64_e32 v[52:53], v[36:37]
	v_mov_b64_e32 v[50:51], v[34:35]
	v_mov_b64_e32 v[48:49], v[32:33]
	v_mov_b64_e32 v[18:19], v[34:35]
	v_mov_b64_e32 v[20:21], v[36:37]
	v_mov_b64_e32 v[22:23], v[38:39]
	v_mov_b64_e32 v[24:25], v[40:41]
	v_mov_b64_e32 v[26:27], v[42:43]
	v_mov_b64_e32 v[28:29], v[44:45]
	v_mov_b64_e32 v[30:31], v[46:47]
	v_mov_b64_e32 v[2:3], v[34:35]
	v_mov_b64_e32 v[4:5], v[36:37]
	v_mov_b64_e32 v[6:7], v[38:39]
	v_mov_b64_e32 v[8:9], v[40:41]
	v_mov_b64_e32 v[10:11], v[42:43]
	v_mov_b64_e32 v[12:13], v[44:45]
	v_mov_b64_e32 v[14:15], v[46:47]
	v_add3_u32 v176, v210, v211, 16
	v_add3_u32 v177, v210, v212, 16
	v_add3_u32 v178, v210, v213, 16
	v_add3_u32 v179, v210, v214, 16
	v_add3_u32 v180, v205, v206, 16
	v_add3_u32 v181, v205, v207, 16
	v_add3_u32 v182, v205, v208, 16
	v_add3_u32 v183, v205, v209, 16
	s_waitcnt vmcnt(0)
	s_branch .LBB0_1299

; #define LAS __attribute__((address_space(3)))
; __device__ __forceinline__ unsigned cvtpk(float lo, float hi) { f32x2_t v = {lo, hi}; bf16x2_t b = __builtin_convertvector(v, bf16x2_t); return __builtin_bit_cast(unsigned, b); }
; __device__ __forceinline__ void attn_phase(LAS unsigned char* lds, const bf16_t* Z, const bf16_t* VT, bf16_t* Y, const float* subln, float lam, float lam_init, float M0, unsigned* ctr, LAS int* s_unit, int wid_s_) {
;     ...
;         const float lt = ls + __shfl_xor(ls, 32);
;         const float inv = (jm == 0 ? 1.0f : lam) / lt;
;         if (jm == 1) {
; #pragma unroll
;             for (int r = 0; r < 16; ++r) { const int qrow = (r & 3) + 8 * (r >> 2) + 4 * hh; const float a = __shfl(inv, qrow);
; #pragma unroll
;                 for (int cb = 0; cb < 4; ++cb) xch[(cb * 16 + r) * 64] = O[cb][r] * a; }
;         }
;         __syncthreads();
;         if (jm == 0) {
;             float sw[4];
; #pragma unroll
;             for (int cb = 0; cb < 4; ++cb) sw[cb] = subln[32 * cb + rr] * (1.0f - lam_init);
; #pragma unroll
;             for (int r = 0; r < 16; ++r) { const int qrow = (r & 3) + 8 * (r >> 2) + 4 * hh; const float a = __shfl(inv, qrow);
;                 float o[4]; float ss = 0.f;
; #pragma unroll
;                 for (int cb = 0; cb < 4; ++cb) { o[cb] = O[cb][r] * a - xch[(cb * 16 + r) * 64]; ss += o[cb] * o[cb]; }
;                 ss += __shfl_xor(ss, 1); ss += __shfl_xor(ss, 2); ss += __shfl_xor(ss, 4); ss += __shfl_xor(ss, 8); ss += __shfl_xor(ss, 16);
;                 const float rn = 1.0f / sqrtf(ss * (1.f / 128.f) + NORM_EPS);
;                 LAS bf16_t* st = (LAS bf16_t*)(lds + rg * 8192) + qrow * 128 + rr;
; #pragma unroll
;                 for (int cb = 0; cb < 4; ++cb) st[32 * cb] = (bf16_t)(cvtpk(o[cb] * rn * sw[cb], 0.f) & 0xffffu);
;             }
.LBB0_1317:
	s_andn2_b64 vcc, exec, s[10:11]
	s_waitcnt lgkmcnt(0)
	s_barrier
	s_cbranch_vccnz .LBB0_1290
	global_load_dword v65, v[160:161], off
	global_load_dword v66, v[160:161], off offset:128
	global_load_dword v67, v[160:161], off offset:256
	global_load_dword v68, v[160:161], off offset:384
	v_or_b32_e32 v74, v191, v216
	v_lshlrev_b32_e32 v74, 2, v74
	ds_bpermute_b32 v82, v74, v64
	ds_read2st64_b32 v[74:75], v204 offset1:1
	ds_read2st64_b32 v[76:77], v204 offset0:16 offset1:17
	ds_read2st64_b32 v[78:79], v204 offset0:32 offset1:33
	ds_read2st64_b32 v[80:81], v204 offset0:48 offset1:49
	v_xor_b32_e32 v69, 1, v190
	s_waitcnt lgkmcnt(3)
	v_fma_f32 v32, v32, v82, -v74
	s_waitcnt lgkmcnt(2)
	v_fma_f32 v48, v48, v82, -v76
	v_mul_f32_e32 v74, v48, v48
	v_cmp_lt_i32_e32 vcc, v69, v192
	v_fmac_f32_e32 v74, v32, v32
	s_waitcnt lgkmcnt(1)
	v_fma_f32 v16, v16, v82, -v78
	v_cndmask_b32_e32 v69, v190, v69, vcc
	v_fmac_f32_e32 v74, v16, v16
	s_waitcnt lgkmcnt(0)
	v_fma_f32 v0, v0, v82, -v80
	v_lshlrev_b32_e32 v73, 2, v69
	v_fmac_f32_e32 v74, v0, v0
	s_nop 1
	v_mov_b32_dpp v76, v74 quad_perm:[1,0,3,2] row_mask:0xf bank_mask:0xf
	v_xor_b32_e32 v69, 2, v190
	v_cmp_lt_i32_e32 vcc, v69, v192
	s_lshl_b32 s26, s41, 1
	v_mov_b32_e32 v171, v97
	v_cndmask_b32_e32 v69, v190, v69, vcc
	v_lshlrev_b32_e32 v72, 2, v69
	s_waitcnt lgkmcnt(0)
	v_add_f32_e32 v74, v74, v76
	s_nop 1
	v_mov_b32_dpp v76, v74 quad_perm:[2,3,0,1] row_mask:0xf bank_mask:0xf
	v_xor_b32_e32 v69, 4, v190
	v_cmp_lt_i32_e32 vcc, v69, v192
	s_movk_i32 s15, 0x2000
	s_waitcnt lgkmcnt(0)
	v_add_f32_e32 v74, v74, v76
	v_cndmask_b32_e32 v69, v190, v69, vcc
	v_lshlrev_b32_e32 v71, 2, v69
	s_nop 1
	v_mov_b32_dpp v76, v74 row_half_mirror row_mask:0xf bank_mask:0xf
	v_xor_b32_e32 v69, 8, v190
	v_cmp_lt_i32_e32 vcc, v69, v192
	s_waitcnt lgkmcnt(0)
	v_add_f32_e32 v74, v74, v76
	v_cndmask_b32_e32 v69, v190, v69, vcc
	v_lshlrev_b32_e32 v70, 2, v69
	s_nop 1
	v_mov_b32_dpp v76, v74 row_mirror row_mask:0xf bank_mask:0xf
	v_xor_b32_e32 v69, 16, v190
	v_cmp_lt_i32_e32 vcc, v69, v192
	s_waitcnt lgkmcnt(0)
	v_add_f32_e32 v74, v74, v76
	v_cndmask_b32_e32 v69, v190, v69, vcc
	v_lshlrev_b32_e32 v69, 2, v69
	ds_bpermute_b32 v76, v69, v74
	s_waitcnt lgkmcnt(0)
	v_add_f32_e32 v74, v74, v76
	v_fmamk_f32 v74, v74, 0x3c000000, v185
	v_cmp_gt_f32_e32 vcc, s36, v74
	v_mul_f32_e32 v76, 0x4f800000, v74
	s_waitcnt vmcnt(3)
	v_mul_f32_e32 v65, v202, v65
	v_cndmask_b32_e32 v74, v74, v76, vcc
	v_sqrt_f32_e32 v76, v74
	s_waitcnt vmcnt(0)
	v_mul_f32_e32 v68, v202, v68
	v_mul_f32_e32 v66, v202, v66
	v_mul_f32_e32 v67, v202, v67
	v_add_u32_e32 v78, -1, v76
	v_fma_f32 v80, -v78, v76, v74
	v_cmp_ge_f32_e64 s[2:3], 0, v80
	v_add_u32_e32 v80, 1, v76
	s_nop 0
	v_cndmask_b32_e64 v78, v76, v78, s[2:3]
	v_fma_f32 v76, -v80, v76, v74
	v_cmp_lt_f32_e64 s[2:3], 0, v76
	s_nop 1
	v_cndmask_b32_e64 v76, v78, v80, s[2:3]
	v_mul_f32_e32 v78, 0x37800000, v76
	v_cndmask_b32_e32 v76, v76, v78, vcc
	v_cmp_class_f32_e32 vcc, v74, v186
	s_nop 1
	v_cndmask_b32_e32 v74, v76, v74, vcc
	v_div_scale_f32 v76, s[2:3], v74, v74, 1.0
	v_rcp_f32_e32 v78, v76
	s_nop 0
	v_fma_f32 v80, -v76, v78, 1.0
	v_fmac_f32_e32 v78, v80, v78
	v_div_scale_f32 v80, vcc, 1.0, v74, 1.0
	v_mul_f32_e32 v82, v80, v78
	v_fma_f32 v83, -v76, v82, v80
	v_fmac_f32_e32 v82, v83, v78
	v_fma_f32 v76, -v76, v82, v80
	v_div_fmas_f32 v76, v76, v78, v82
	v_div_fixup_f32 v74, v76, v74, 1.0
	v_mul_f32_e32 v0, v0, v74
	v_mul_f32_e32 v0, v68, v0
	v_cvt_pk_bf16_f32 v0, v0, s0
	ds_write_b16 v241, v0 offset:192
	v_or_b32_e32 v0, 1, v216
	v_or_b32_e32 v0, v191, v0
	v_mul_f32_e32 v32, v32, v74
	v_lshlrev_b32_e32 v0, 2, v0
	v_mul_f32_e32 v32, v65, v32
	ds_bpermute_b32 v0, v0, v64
	v_cvt_pk_bf16_f32 v32, v32, s0
	ds_write_b16 v241, v32
	v_mul_f32_e32 v32, v48, v74
	v_mul_f32_e32 v32, v66, v32
	v_mul_f32_e32 v16, v16, v74
	v_cvt_pk_bf16_f32 v32, v32, s0
	v_mul_f32_e32 v16, v67, v16
	ds_write_b16 v241, v32 offset:64
	v_cvt_pk_bf16_f32 v16, v16, s0
	s_waitcnt lgkmcnt(2)
	v_fma_f32 v32, v49, v0, -v77
	ds_write_b16 v241, v16 offset:128
	v_fma_f32 v16, v33, v0, -v75
	v_mul_f32_e32 v33, v32, v32
	v_fmac_f32_e32 v33, v16, v16
	v_fma_f32 v17, v17, v0, -v79
	v_fmac_f32_e32 v33, v17, v17
	v_fma_f32 v0, v1, v0, -v81
	v_fmac_f32_e32 v33, v0, v0
	s_nop 1
	v_mov_b32_dpp v1, v33 quad_perm:[1,0,3,2] row_mask:0xf bank_mask:0xf
	s_waitcnt lgkmcnt(0)
	v_add_f32_e32 v1, v33, v1
	s_nop 1
	v_mov_b32_dpp v33, v1 quad_perm:[2,3,0,1] row_mask:0xf bank_mask:0xf
	s_waitcnt lgkmcnt(0)
	v_add_f32_e32 v1, v1, v33
	s_nop 1
	v_mov_b32_dpp v33, v1 row_half_mirror row_mask:0xf bank_mask:0xf
	s_waitcnt lgkmcnt(0)
	v_add_f32_e32 v1, v1, v33
	s_nop 1
	v_mov_b32_dpp v33, v1 row_mirror row_mask:0xf bank_mask:0xf
	s_waitcnt lgkmcnt(0)
	v_add_f32_e32 v1, v1, v33
	ds_bpermute_b32 v33, v69, v1
	s_waitcnt lgkmcnt(0)
; #define LAS __attribute__((address_space(3)))
; __device__ __forceinline__ unsigned cvtpk(float lo, float hi) { f32x2_t v = {lo, hi}; bf16x2_t b = __builtin_convertvector(v, bf16x2_t); return __builtin_bit_cast(unsigned, b); }
; __device__ __forceinline__ void attn_phase(LAS unsigned char* lds, const bf16_t* Z, const bf16_t* VT, bf16_t* Y, const float* subln, float lam, float lam_init, float M0, unsigned* ctr, LAS int* s_unit, int wid_s_) {
;     ...
;             for (int cb = 0; cb < 4; ++cb) sw[cb] = subln[32 * cb + rr] * (1.0f - lam_init);
; #pragma unroll
;             for (int r = 0; r < 16; ++r) { const int qrow = (r & 3) + 8 * (r >> 2) + 4 * hh; const float a = __shfl(inv, qrow);
;                 float o[4]; float ss = 0.f;
; #pragma unroll
;                 for (int cb = 0; cb < 4; ++cb) { o[cb] = O[cb][r] * a - xch[(cb * 16 + r) * 64]; ss += o[cb] * o[cb]; }
;                 ss += __shfl_xor(ss, 1); ss += __shfl_xor(ss, 2); ss += __shfl_xor(ss, 4); ss += __shfl_xor(ss, 8); ss += __shfl_xor(ss, 16);
;                 const float rn = 1.0f / sqrtf(ss * (1.f / 128.f) + NORM_EPS);
;                 LAS bf16_t* st = (LAS bf16_t*)(lds + rg * 8192) + qrow * 128 + rr;
; #pragma unroll
;                 for (int cb = 0; cb < 4; ++cb) st[32 * cb] = (bf16_t)(cvtpk(o[cb] * rn * sw[cb], 0.f) & 0xffffu);
;             }
	v_add_f32_e32 v1, v1, v33
	v_fmamk_f32 v1, v1, 0x3c000000, v185
	v_cmp_gt_f32_e32 vcc, s36, v1
	v_mul_f32_e32 v33, 0x4f800000, v1
	s_nop 0
	v_cndmask_b32_e32 v1, v1, v33, vcc
	v_sqrt_f32_e32 v33, v1
	s_nop 0
	v_add_u32_e32 v48, -1, v33
	v_fma_f32 v49, -v48, v33, v1
	v_cmp_ge_f32_e64 s[2:3], 0, v49
	v_add_u32_e32 v49, 1, v33
	s_nop 0
	v_cndmask_b32_e64 v48, v33, v48, s[2:3]
	v_fma_f32 v33, -v49, v33, v1
	v_cmp_lt_f32_e64 s[2:3], 0, v33
	s_nop 1
	v_cndmask_b32_e64 v33, v48, v49, s[2:3]
	v_mul_f32_e32 v48, 0x37800000, v33
	v_cndmask_b32_e32 v33, v33, v48, vcc
	v_cmp_class_f32_e32 vcc, v1, v186
	s_nop 1
	v_cndmask_b32_e32 v1, v33, v1, vcc
	v_div_scale_f32 v33, s[2:3], v1, v1, 1.0
	v_rcp_f32_e32 v48, v33
	s_nop 0
	v_fma_f32 v49, -v33, v48, 1.0
	v_fmac_f32_e32 v48, v49, v48
	v_div_scale_f32 v49, vcc, 1.0, v1, 1.0
	v_mul_f32_e32 v74, v49, v48
	v_fma_f32 v75, -v33, v74, v49
	v_fmac_f32_e32 v74, v75, v48
	v_fma_f32 v33, -v33, v74, v49
	v_div_fmas_f32 v33, v33, v48, v74
	v_div_fixup_f32 v1, v33, v1, 1.0
	v_mul_f32_e32 v16, v16, v1
	v_mul_f32_e32 v16, v65, v16
	v_cvt_pk_bf16_f32 v16, v16, s0
	ds_write_b16 v242, v16
	v_mul_f32_e32 v16, v32, v1
	v_mul_f32_e32 v0, v0, v1
	v_mul_f32_e32 v16, v66, v16
	v_mul_f32_e32 v0, v68, v0
	v_cvt_pk_bf16_f32 v16, v16, s0
	v_cvt_pk_bf16_f32 v0, v0, s0
	ds_write_b16 v242, v16 offset:64
	v_mul_f32_e32 v16, v17, v1
	ds_write_b16 v242, v0 offset:192
	v_or_b32_e32 v0, 2, v216
	v_mul_f32_e32 v16, v67, v16
	v_or_b32_e32 v0, v191, v0
	v_cvt_pk_bf16_f32 v16, v16, s0
	v_lshlrev_b32_e32 v0, 2, v0
	ds_write_b16 v242, v16 offset:128
	ds_bpermute_b32 v0, v0, v64
	ds_read2st64_b32 v[16:17], v204 offset0:2 offset1:3
	ds_read2st64_b32 v[32:33], v204 offset0:18 offset1:19
	ds_read2st64_b32 v[48:49], v204 offset0:34 offset1:35
	ds_read2st64_b32 v[74:75], v204 offset0:50 offset1:51
	s_waitcnt lgkmcnt(3)
	v_fma_f32 v1, v34, v0, -v16
	s_waitcnt lgkmcnt(2)
	v_fma_f32 v16, v50, v0, -v32
	v_mul_f32_e32 v32, v16, v16
	v_fmac_f32_e32 v32, v1, v1
	s_waitcnt lgkmcnt(1)
	v_fma_f32 v18, v18, v0, -v48
	v_fmac_f32_e32 v32, v18, v18
	s_waitcnt lgkmcnt(0)
	v_fma_f32 v0, v2, v0, -v74
	v_fmac_f32_e32 v32, v0, v0
	s_nop 1
	v_mov_b32_dpp v2, v32 quad_perm:[1,0,3,2] row_mask:0xf bank_mask:0xf
	s_waitcnt lgkmcnt(0)
	v_add_f32_e32 v2, v32, v2
	s_nop 1
	v_mov_b32_dpp v32, v2 quad_perm:[2,3,0,1] row_mask:0xf bank_mask:0xf
	s_waitcnt lgkmcnt(0)
	v_add_f32_e32 v2, v2, v32
	s_nop 1
	v_mov_b32_dpp v32, v2 row_half_mirror row_mask:0xf bank_mask:0xf
	s_waitcnt lgkmcnt(0)
	v_add_f32_e32 v2, v2, v32
	s_nop 1
	v_mov_b32_dpp v32, v2 row_mirror row_mask:0xf bank_mask:0xf
	s_waitcnt lgkmcnt(0)
	v_add_f32_e32 v2, v2, v32
	ds_bpermute_b32 v32, v69, v2
	s_waitcnt lgkmcnt(0)
	v_add_f32_e32 v2, v2, v32
	v_fmamk_f32 v2, v2, 0x3c000000, v185
	v_cmp_gt_f32_e32 vcc, s36, v2
	v_mul_f32_e32 v32, 0x4f800000, v2
	s_nop 0
	v_cndmask_b32_e32 v2, v2, v32, vcc
	v_sqrt_f32_e32 v32, v2
	s_nop 0
	v_add_u32_e32 v34, -1, v32
	v_fma_f32 v48, -v34, v32, v2
	v_cmp_ge_f32_e64 s[2:3], 0, v48
	v_add_u32_e32 v48, 1, v32
	s_nop 0
	v_cndmask_b32_e64 v34, v32, v34, s[2:3]
	v_fma_f32 v32, -v48, v32, v2
	v_cmp_lt_f32_e64 s[2:3], 0, v32
	s_nop 1
	v_cndmask_b32_e64 v32, v34, v48, s[2:3]
	v_mul_f32_e32 v34, 0x37800000, v32
	v_cndmask_b32_e32 v32, v32, v34, vcc
	v_cmp_class_f32_e32 vcc, v2, v186
	s_nop 1
	v_cndmask_b32_e32 v2, v32, v2, vcc
	v_div_scale_f32 v32, s[2:3], v2, v2, 1.0
	v_rcp_f32_e32 v34, v32
	s_nop 0
	v_fma_f32 v48, -v32, v34, 1.0
	v_fmac_f32_e32 v34, v48, v34
	v_div_scale_f32 v48, vcc, 1.0, v2, 1.0
	v_mul_f32_e32 v50, v48, v34
	v_fma_f32 v74, -v32, v50, v48
	v_fmac_f32_e32 v50, v74, v34
	v_fma_f32 v32, -v32, v50, v48
	v_div_fmas_f32 v32, v32, v34, v50
	v_div_fixup_f32 v2, v32, v2, 1.0
	v_mul_f32_e32 v0, v0, v2
	v_mul_f32_e32 v0, v68, v0
	v_cvt_pk_bf16_f32 v0, v0, s0
	v_mul_f32_e32 v1, v1, v2
	ds_write_b16 v243, v0 offset:192
	v_or_b32_e32 v0, 3, v216
	v_mul_f32_e32 v1, v65, v1
	v_or_b32_e32 v0, v191, v0
	v_cvt_pk_bf16_f32 v1, v1, s0
	v_lshlrev_b32_e32 v0, 2, v0
	ds_write_b16 v243, v1
	v_mul_f32_e32 v1, v16, v2
	ds_bpermute_b32 v0, v0, v64
	v_mul_f32_e32 v1, v66, v1
	v_cvt_pk_bf16_f32 v1, v1, s0
	ds_write_b16 v243, v1 offset:64
	v_mul_f32_e32 v1, v18, v2
	v_mul_f32_e32 v1, v67, v1
	v_cvt_pk_bf16_f32 v1, v1, s0
	s_waitcnt lgkmcnt(1)
	v_fma_f32 v2, v51, v0, -v33
	ds_write_b16 v243, v1 offset:128
	v_fma_f32 v1, v35, v0, -v17
	v_mul_f32_e32 v16, v2, v2
	v_fmac_f32_e32 v16, v1, v1
	v_fma_f32 v17, v19, v0, -v49
	v_fmac_f32_e32 v16, v17, v17
	v_fma_f32 v0, v3, v0, -v75
	v_fmac_f32_e32 v16, v0, v0
	s_nop 1
	v_mov_b32_dpp v3, v16 quad_perm:[1,0,3,2] row_mask:0xf bank_mask:0xf
	s_waitcnt lgkmcnt(0)
	v_add_f32_e32 v3, v16, v3
	s_nop 1
	v_mov_b32_dpp v16, v3 quad_perm:[2,3,0,1] row_mask:0xf bank_mask:0xf
	s_waitcnt lgkmcnt(0)
	v_add_f32_e32 v3, v3, v16
	s_nop 1
	v_mov_b32_dpp v16, v3 row_half_mirror row_mask:0xf bank_mask:0xf
	s_waitcnt lgkmcnt(0)
	v_add_f32_e32 v3, v3, v16
	s_nop 1
	v_mov_b32_dpp v16, v3 row_mirror row_mask:0xf bank_mask:0xf
	s_waitcnt lgkmcnt(0)
	v_add_f32_e32 v3, v3, v16
	ds_bpermute_b32 v16, v69, v3
	s_waitcnt lgkmcnt(0)
; #define LAS __attribute__((address_space(3)))
; __device__ __forceinline__ unsigned cvtpk(float lo, float hi) { f32x2_t v = {lo, hi}; bf16x2_t b = __builtin_convertvector(v, bf16x2_t); return __builtin_bit_cast(unsigned, b); }
; __device__ __forceinline__ void attn_phase(LAS unsigned char* lds, const bf16_t* Z, const bf16_t* VT, bf16_t* Y, const float* subln, float lam, float lam_init, float M0, unsigned* ctr, LAS int* s_unit, int wid_s_) {
;     ...
;             for (int cb = 0; cb < 4; ++cb) sw[cb] = subln[32 * cb + rr] * (1.0f - lam_init);
; #pragma unroll
;             for (int r = 0; r < 16; ++r) { const int qrow = (r & 3) + 8 * (r >> 2) + 4 * hh; const float a = __shfl(inv, qrow);
;                 float o[4]; float ss = 0.f;
; #pragma unroll
;                 for (int cb = 0; cb < 4; ++cb) { o[cb] = O[cb][r] * a - xch[(cb * 16 + r) * 64]; ss += o[cb] * o[cb]; }
;                 ss += __shfl_xor(ss, 1); ss += __shfl_xor(ss, 2); ss += __shfl_xor(ss, 4); ss += __shfl_xor(ss, 8); ss += __shfl_xor(ss, 16);
;                 const float rn = 1.0f / sqrtf(ss * (1.f / 128.f) + NORM_EPS);
;                 LAS bf16_t* st = (LAS bf16_t*)(lds + rg * 8192) + qrow * 128 + rr;
; #pragma unroll
;                 for (int cb = 0; cb < 4; ++cb) st[32 * cb] = (bf16_t)(cvtpk(o[cb] * rn * sw[cb], 0.f) & 0xffffu);
;             }
	v_add_f32_e32 v3, v3, v16
	v_fmamk_f32 v3, v3, 0x3c000000, v185
	v_cmp_gt_f32_e32 vcc, s36, v3
	v_mul_f32_e32 v16, 0x4f800000, v3
	s_nop 0
	v_cndmask_b32_e32 v3, v3, v16, vcc
	v_sqrt_f32_e32 v16, v3
	s_nop 0
	v_add_u32_e32 v18, -1, v16
	v_fma_f32 v19, -v18, v16, v3
	v_cmp_ge_f32_e64 s[2:3], 0, v19
	v_add_u32_e32 v19, 1, v16
	s_nop 0
	v_cndmask_b32_e64 v18, v16, v18, s[2:3]
	v_fma_f32 v16, -v19, v16, v3
	v_cmp_lt_f32_e64 s[2:3], 0, v16
	s_nop 1
	v_cndmask_b32_e64 v16, v18, v19, s[2:3]
	v_mul_f32_e32 v18, 0x37800000, v16
	v_cndmask_b32_e32 v16, v16, v18, vcc
	v_cmp_class_f32_e32 vcc, v3, v186
	s_nop 1
	v_cndmask_b32_e32 v3, v16, v3, vcc
	v_div_scale_f32 v16, s[2:3], v3, v3, 1.0
	v_rcp_f32_e32 v18, v16
	s_nop 0
	v_fma_f32 v19, -v16, v18, 1.0
	v_fmac_f32_e32 v18, v19, v18
	v_div_scale_f32 v19, vcc, 1.0, v3, 1.0
	v_mul_f32_e32 v32, v19, v18
	v_fma_f32 v33, -v16, v32, v19
	v_fmac_f32_e32 v32, v33, v18
	v_fma_f32 v16, -v16, v32, v19
	v_div_fmas_f32 v16, v16, v18, v32
	v_div_fixup_f32 v3, v16, v3, 1.0
	v_mul_f32_e32 v1, v1, v3
	v_mul_f32_e32 v0, v0, v3
	v_mul_f32_e32 v1, v65, v1
	v_mul_f32_e32 v0, v68, v0
	v_cvt_pk_bf16_f32 v1, v1, s0
	v_cvt_pk_bf16_f32 v0, v0, s0
	ds_write_b16 v244, v1
	v_mul_f32_e32 v1, v2, v3
	ds_write_b16 v244, v0 offset:192
	v_or_b32_e32 v0, 8, v216
	v_mul_f32_e32 v1, v66, v1
	v_or_b32_e32 v0, v191, v0
	v_cvt_pk_bf16_f32 v1, v1, s0
	v_lshlrev_b32_e32 v0, 2, v0
	ds_write_b16 v244, v1 offset:64
	v_mul_f32_e32 v1, v17, v3
	ds_bpermute_b32 v0, v0, v64
	ds_read2st64_b32 v[2:3], v204 offset0:4 offset1:5
	ds_read2st64_b32 v[16:17], v204 offset0:20 offset1:21
	ds_read2st64_b32 v[18:19], v204 offset0:36 offset1:37
	ds_read2st64_b32 v[32:33], v204 offset0:52 offset1:53
	v_mul_f32_e32 v1, v67, v1
	v_cvt_pk_bf16_f32 v1, v1, s0
	ds_write_b16 v244, v1 offset:128
	s_waitcnt lgkmcnt(4)
	v_fma_f32 v1, v36, v0, -v2
	s_waitcnt lgkmcnt(3)
	v_fma_f32 v2, v52, v0, -v16
	v_mul_f32_e32 v16, v2, v2
	v_fmac_f32_e32 v16, v1, v1
	s_waitcnt lgkmcnt(2)
	v_fma_f32 v18, v20, v0, -v18
	v_fmac_f32_e32 v16, v18, v18
	s_waitcnt lgkmcnt(1)
	v_fma_f32 v0, v4, v0, -v32
	v_fmac_f32_e32 v16, v0, v0
	s_nop 1
	v_mov_b32_dpp v4, v16 quad_perm:[1,0,3,2] row_mask:0xf bank_mask:0xf
	s_waitcnt lgkmcnt(0)
	v_add_f32_e32 v4, v16, v4
	s_nop 1
	v_mov_b32_dpp v16, v4 quad_perm:[2,3,0,1] row_mask:0xf bank_mask:0xf
	s_waitcnt lgkmcnt(0)
	v_add_f32_e32 v4, v4, v16
	s_nop 1
	v_mov_b32_dpp v16, v4 row_half_mirror row_mask:0xf bank_mask:0xf
	s_waitcnt lgkmcnt(0)
	v_add_f32_e32 v4, v4, v16
	s_nop 1
	v_mov_b32_dpp v16, v4 row_mirror row_mask:0xf bank_mask:0xf
	s_waitcnt lgkmcnt(0)
	v_add_f32_e32 v4, v4, v16
	ds_bpermute_b32 v16, v69, v4
	s_waitcnt lgkmcnt(0)
	v_add_f32_e32 v4, v4, v16
	v_fmamk_f32 v4, v4, 0x3c000000, v185
	v_cmp_gt_f32_e32 vcc, s36, v4
	v_mul_f32_e32 v16, 0x4f800000, v4
	s_nop 0
	v_cndmask_b32_e32 v4, v4, v16, vcc
	v_sqrt_f32_e32 v16, v4
	s_nop 0
	v_add_u32_e32 v20, -1, v16
	v_fma_f32 v32, -v20, v16, v4
	v_cmp_ge_f32_e64 s[2:3], 0, v32
	v_add_u32_e32 v32, 1, v16
	s_nop 0
	v_cndmask_b32_e64 v20, v16, v20, s[2:3]
	v_fma_f32 v16, -v32, v16, v4
	v_cmp_lt_f32_e64 s[2:3], 0, v16
	s_nop 1
	v_cndmask_b32_e64 v16, v20, v32, s[2:3]
	v_mul_f32_e32 v20, 0x37800000, v16
	v_cndmask_b32_e32 v16, v16, v20, vcc
	v_cmp_class_f32_e32 vcc, v4, v186
	s_nop 1
	v_cndmask_b32_e32 v4, v16, v4, vcc
	v_div_scale_f32 v16, s[2:3], v4, v4, 1.0
	v_rcp_f32_e32 v20, v16
	s_nop 0
	v_fma_f32 v32, -v16, v20, 1.0
	v_fmac_f32_e32 v20, v32, v20
	v_div_scale_f32 v32, vcc, 1.0, v4, 1.0
	v_mul_f32_e32 v34, v32, v20
	v_fma_f32 v35, -v16, v34, v32
	v_fmac_f32_e32 v34, v35, v20
	v_fma_f32 v16, -v16, v34, v32
	v_div_fmas_f32 v16, v16, v20, v34
	v_div_fixup_f32 v4, v16, v4, 1.0
	v_mul_f32_e32 v0, v0, v4
	v_mul_f32_e32 v0, v68, v0
	v_cvt_pk_bf16_f32 v0, v0, s0
	v_mul_f32_e32 v1, v1, v4
	ds_write_b16 v245, v0 offset:192
	v_or_b32_e32 v0, 9, v216
	v_mul_f32_e32 v1, v65, v1
	v_or_b32_e32 v0, v191, v0
	v_cvt_pk_bf16_f32 v1, v1, s0
	v_lshlrev_b32_e32 v0, 2, v0
	ds_write_b16 v245, v1
	v_mul_f32_e32 v1, v2, v4
	ds_bpermute_b32 v0, v0, v64
	v_mul_f32_e32 v1, v66, v1
	v_cvt_pk_bf16_f32 v1, v1, s0
	ds_write_b16 v245, v1 offset:64
	v_mul_f32_e32 v1, v18, v4
	v_mul_f32_e32 v1, v67, v1
	v_cvt_pk_bf16_f32 v1, v1, s0
	s_waitcnt lgkmcnt(1)
	v_fma_f32 v2, v53, v0, -v17
	ds_write_b16 v245, v1 offset:128
	v_fma_f32 v1, v37, v0, -v3
	v_mul_f32_e32 v3, v2, v2
	v_fmac_f32_e32 v3, v1, v1
	v_fma_f32 v4, v21, v0, -v19
	v_fmac_f32_e32 v3, v4, v4
	v_fma_f32 v0, v5, v0, -v33
	v_fmac_f32_e32 v3, v0, v0
	s_nop 1
	v_mov_b32_dpp v5, v3 quad_perm:[1,0,3,2] row_mask:0xf bank_mask:0xf
	s_waitcnt lgkmcnt(0)
	v_add_f32_e32 v3, v3, v5
	s_nop 1
	v_mov_b32_dpp v5, v3 quad_perm:[2,3,0,1] row_mask:0xf bank_mask:0xf
	s_waitcnt lgkmcnt(0)
	v_add_f32_e32 v3, v3, v5
	s_nop 1
	v_mov_b32_dpp v5, v3 row_half_mirror row_mask:0xf bank_mask:0xf
	s_waitcnt lgkmcnt(0)
	v_add_f32_e32 v3, v3, v5
	s_nop 1
	v_mov_b32_dpp v5, v3 row_mirror row_mask:0xf bank_mask:0xf
	s_waitcnt lgkmcnt(0)
	v_add_f32_e32 v3, v3, v5
	ds_bpermute_b32 v5, v69, v3
	s_waitcnt lgkmcnt(0)
; #define LAS __attribute__((address_space(3)))
; __device__ __forceinline__ unsigned cvtpk(float lo, float hi) { f32x2_t v = {lo, hi}; bf16x2_t b = __builtin_convertvector(v, bf16x2_t); return __builtin_bit_cast(unsigned, b); }
; __device__ __forceinline__ void attn_phase(LAS unsigned char* lds, const bf16_t* Z, const bf16_t* VT, bf16_t* Y, const float* subln, float lam, float lam_init, float M0, unsigned* ctr, LAS int* s_unit, int wid_s_) {
;     ...
;             for (int cb = 0; cb < 4; ++cb) sw[cb] = subln[32 * cb + rr] * (1.0f - lam_init);
; #pragma unroll
;             for (int r = 0; r < 16; ++r) { const int qrow = (r & 3) + 8 * (r >> 2) + 4 * hh; const float a = __shfl(inv, qrow);
;                 float o[4]; float ss = 0.f;
; #pragma unroll
;                 for (int cb = 0; cb < 4; ++cb) { o[cb] = O[cb][r] * a - xch[(cb * 16 + r) * 64]; ss += o[cb] * o[cb]; }
;                 ss += __shfl_xor(ss, 1); ss += __shfl_xor(ss, 2); ss += __shfl_xor(ss, 4); ss += __shfl_xor(ss, 8); ss += __shfl_xor(ss, 16);
;                 const float rn = 1.0f / sqrtf(ss * (1.f / 128.f) + NORM_EPS);
;                 LAS bf16_t* st = (LAS bf16_t*)(lds + rg * 8192) + qrow * 128 + rr;
; #pragma unroll
;                 for (int cb = 0; cb < 4; ++cb) st[32 * cb] = (bf16_t)(cvtpk(o[cb] * rn * sw[cb], 0.f) & 0xffffu);
;             }
	v_add_f32_e32 v3, v3, v5
	v_fmamk_f32 v3, v3, 0x3c000000, v185
	v_cmp_gt_f32_e32 vcc, s36, v3
	v_mul_f32_e32 v5, 0x4f800000, v3
	s_nop 0
	v_cndmask_b32_e32 v3, v3, v5, vcc
	v_sqrt_f32_e32 v5, v3
	s_nop 0
	v_add_u32_e32 v16, -1, v5
	v_fma_f32 v17, -v16, v5, v3
	v_cmp_ge_f32_e64 s[2:3], 0, v17
	v_add_u32_e32 v17, 1, v5
	s_nop 0
	v_cndmask_b32_e64 v16, v5, v16, s[2:3]
	v_fma_f32 v5, -v17, v5, v3
	v_cmp_lt_f32_e64 s[2:3], 0, v5
	s_nop 1
	v_cndmask_b32_e64 v5, v16, v17, s[2:3]
	v_mul_f32_e32 v16, 0x37800000, v5
	v_cndmask_b32_e32 v5, v5, v16, vcc
	v_cmp_class_f32_e32 vcc, v3, v186
	s_nop 1
	v_cndmask_b32_e32 v3, v5, v3, vcc
	v_div_scale_f32 v5, s[2:3], v3, v3, 1.0
	v_rcp_f32_e32 v16, v5
	s_nop 0
	v_fma_f32 v17, -v5, v16, 1.0
	v_fmac_f32_e32 v16, v17, v16
	v_div_scale_f32 v17, vcc, 1.0, v3, 1.0
	v_mul_f32_e32 v18, v17, v16
	v_fma_f32 v19, -v5, v18, v17
	v_fmac_f32_e32 v18, v19, v16
	v_fma_f32 v5, -v5, v18, v17
	v_div_fmas_f32 v5, v5, v16, v18
	v_div_fixup_f32 v3, v5, v3, 1.0
	v_mul_f32_e32 v1, v1, v3
	v_mul_f32_e32 v1, v65, v1
	v_cvt_pk_bf16_f32 v1, v1, s0
	ds_write_b16 v246, v1
	v_mul_f32_e32 v1, v2, v3
	v_mul_f32_e32 v0, v0, v3
	v_mul_f32_e32 v1, v66, v1
	v_mul_f32_e32 v0, v68, v0
	v_cvt_pk_bf16_f32 v1, v1, s0
	v_cvt_pk_bf16_f32 v0, v0, s0
	ds_write_b16 v246, v1 offset:64
	v_mul_f32_e32 v1, v4, v3
	ds_write_b16 v246, v0 offset:192
	v_or_b32_e32 v0, 10, v216
	v_mul_f32_e32 v1, v67, v1
	v_or_b32_e32 v0, v191, v0
	v_cvt_pk_bf16_f32 v1, v1, s0
	v_lshlrev_b32_e32 v0, 2, v0
	ds_write_b16 v246, v1 offset:128
	ds_bpermute_b32 v18, v0, v64
	ds_read2st64_b32 v[0:1], v204 offset0:6 offset1:7
	ds_read2st64_b32 v[2:3], v204 offset0:22 offset1:23
	ds_read2st64_b32 v[4:5], v204 offset0:38 offset1:39
	ds_read2st64_b32 v[16:17], v204 offset0:54 offset1:55
	s_waitcnt lgkmcnt(3)
	v_fma_f32 v0, v38, v18, -v0
	s_waitcnt lgkmcnt(2)
	v_fma_f32 v2, v54, v18, -v2
	v_mul_f32_e32 v19, v2, v2
	v_fmac_f32_e32 v19, v0, v0
	s_waitcnt lgkmcnt(1)
	v_fma_f32 v4, v22, v18, -v4
	v_fmac_f32_e32 v19, v4, v4
	s_waitcnt lgkmcnt(0)
	v_fma_f32 v6, v6, v18, -v16
	v_fmac_f32_e32 v19, v6, v6
	s_nop 1
	v_mov_b32_dpp v16, v19 quad_perm:[1,0,3,2] row_mask:0xf bank_mask:0xf
	s_waitcnt lgkmcnt(0)
	v_add_f32_e32 v16, v19, v16
	s_nop 1
	v_mov_b32_dpp v18, v16 quad_perm:[2,3,0,1] row_mask:0xf bank_mask:0xf
	s_waitcnt lgkmcnt(0)
	v_add_f32_e32 v16, v16, v18
	s_nop 1
	v_mov_b32_dpp v18, v16 row_half_mirror row_mask:0xf bank_mask:0xf
	s_waitcnt lgkmcnt(0)
	v_add_f32_e32 v16, v16, v18
	s_nop 1
	v_mov_b32_dpp v18, v16 row_mirror row_mask:0xf bank_mask:0xf
	s_waitcnt lgkmcnt(0)
	v_add_f32_e32 v16, v16, v18
	ds_bpermute_b32 v18, v69, v16
	s_waitcnt lgkmcnt(0)
	v_add_f32_e32 v16, v16, v18
	v_fmamk_f32 v16, v16, 0x3c000000, v185
	v_cmp_gt_f32_e32 vcc, s36, v16
	v_mul_f32_e32 v18, 0x4f800000, v16
	s_nop 0
	v_cndmask_b32_e32 v16, v16, v18, vcc
	v_sqrt_f32_e32 v18, v16
	s_nop 0
	v_add_u32_e32 v19, -1, v18
	v_fma_f32 v20, -v19, v18, v16
	v_cmp_ge_f32_e64 s[2:3], 0, v20
	v_add_u32_e32 v20, 1, v18
	s_nop 0
	v_cndmask_b32_e64 v19, v18, v19, s[2:3]
	v_fma_f32 v18, -v20, v18, v16
	v_cmp_lt_f32_e64 s[2:3], 0, v18
	s_nop 1
	v_cndmask_b32_e64 v18, v19, v20, s[2:3]
	v_mul_f32_e32 v19, 0x37800000, v18
	v_cndmask_b32_e32 v18, v18, v19, vcc
	v_cmp_class_f32_e32 vcc, v16, v186
	s_nop 1
	v_cndmask_b32_e32 v16, v18, v16, vcc
	v_div_scale_f32 v18, s[2:3], v16, v16, 1.0
	v_rcp_f32_e32 v19, v18
	s_nop 0
	v_fma_f32 v20, -v18, v19, 1.0
	v_fmac_f32_e32 v19, v20, v19
	v_div_scale_f32 v20, vcc, 1.0, v16, 1.0
	v_mul_f32_e32 v21, v20, v19
	v_fma_f32 v22, -v18, v21, v20
	v_fmac_f32_e32 v21, v22, v19
	v_fma_f32 v18, -v18, v21, v20
	v_div_fmas_f32 v18, v18, v19, v21
	v_div_fixup_f32 v16, v18, v16, 1.0
	v_mul_f32_e32 v0, v0, v16
	v_mul_f32_e32 v0, v65, v0
	v_cvt_pk_bf16_f32 v0, v0, s0
	ds_write_b16 v247, v0
	v_mul_f32_e32 v0, v2, v16
	v_mul_f32_e32 v0, v66, v0
	v_cvt_pk_bf16_f32 v0, v0, s0
	ds_write_b16 v247, v0 offset:64
	v_mul_f32_e32 v0, v4, v16
	v_mul_f32_e32 v0, v67, v0
	v_cvt_pk_bf16_f32 v0, v0, s0
	ds_write_b16 v247, v0 offset:128
	v_mul_f32_e32 v0, v6, v16
	v_mul_f32_e32 v0, v68, v0
	v_cvt_pk_bf16_f32 v0, v0, s0
	ds_write_b16 v247, v0 offset:192
	v_or_b32_e32 v0, 11, v216
	v_or_b32_e32 v0, v191, v0
	v_lshlrev_b32_e32 v0, 2, v0
	ds_bpermute_b32 v0, v0, v64
	s_waitcnt lgkmcnt(0)
	v_fma_f32 v2, v55, v0, -v3
	v_fma_f32 v1, v39, v0, -v1
	v_mul_f32_e32 v3, v2, v2
	v_fmac_f32_e32 v3, v1, v1
	v_fma_f32 v4, v23, v0, -v5
	v_fmac_f32_e32 v3, v4, v4
	v_fma_f32 v0, v7, v0, -v17
	v_fmac_f32_e32 v3, v0, v0
	s_nop 1
	v_mov_b32_dpp v5, v3 quad_perm:[1,0,3,2] row_mask:0xf bank_mask:0xf
	s_waitcnt lgkmcnt(0)
	v_add_f32_e32 v3, v3, v5
	s_nop 1
	v_mov_b32_dpp v5, v3 quad_perm:[2,3,0,1] row_mask:0xf bank_mask:0xf
	s_waitcnt lgkmcnt(0)
	v_add_f32_e32 v3, v3, v5
	s_nop 1
	v_mov_b32_dpp v5, v3 row_half_mirror row_mask:0xf bank_mask:0xf
	s_waitcnt lgkmcnt(0)
	v_add_f32_e32 v3, v3, v5
	s_nop 1
	v_mov_b32_dpp v5, v3 row_mirror row_mask:0xf bank_mask:0xf
	s_waitcnt lgkmcnt(0)
	v_add_f32_e32 v3, v3, v5
	ds_bpermute_b32 v5, v69, v3
	s_waitcnt lgkmcnt(0)
; #define LAS __attribute__((address_space(3)))
; __device__ __forceinline__ unsigned cvtpk(float lo, float hi) { f32x2_t v = {lo, hi}; bf16x2_t b = __builtin_convertvector(v, bf16x2_t); return __builtin_bit_cast(unsigned, b); }
; __device__ __forceinline__ void attn_phase(LAS unsigned char* lds, const bf16_t* Z, const bf16_t* VT, bf16_t* Y, const float* subln, float lam, float lam_init, float M0, unsigned* ctr, LAS int* s_unit, int wid_s_) {
;     ...
;             for (int cb = 0; cb < 4; ++cb) sw[cb] = subln[32 * cb + rr] * (1.0f - lam_init);
; #pragma unroll
;             for (int r = 0; r < 16; ++r) { const int qrow = (r & 3) + 8 * (r >> 2) + 4 * hh; const float a = __shfl(inv, qrow);
;                 float o[4]; float ss = 0.f;
; #pragma unroll
;                 for (int cb = 0; cb < 4; ++cb) { o[cb] = O[cb][r] * a - xch[(cb * 16 + r) * 64]; ss += o[cb] * o[cb]; }
;                 ss += __shfl_xor(ss, 1); ss += __shfl_xor(ss, 2); ss += __shfl_xor(ss, 4); ss += __shfl_xor(ss, 8); ss += __shfl_xor(ss, 16);
;                 const float rn = 1.0f / sqrtf(ss * (1.f / 128.f) + NORM_EPS);
;                 LAS bf16_t* st = (LAS bf16_t*)(lds + rg * 8192) + qrow * 128 + rr;
; #pragma unroll
;                 for (int cb = 0; cb < 4; ++cb) st[32 * cb] = (bf16_t)(cvtpk(o[cb] * rn * sw[cb], 0.f) & 0xffffu);
;             }
	v_add_f32_e32 v3, v3, v5
	v_fmamk_f32 v3, v3, 0x3c000000, v185
	v_cmp_gt_f32_e32 vcc, s36, v3
	v_mul_f32_e32 v5, 0x4f800000, v3
	s_nop 0
	v_cndmask_b32_e32 v3, v3, v5, vcc
	v_sqrt_f32_e32 v5, v3
	s_nop 0
	v_add_u32_e32 v6, -1, v5
	v_fma_f32 v7, -v6, v5, v3
	v_cmp_ge_f32_e64 s[2:3], 0, v7
	v_add_u32_e32 v7, 1, v5
	s_nop 0
	v_cndmask_b32_e64 v6, v5, v6, s[2:3]
	v_fma_f32 v5, -v7, v5, v3
	v_cmp_lt_f32_e64 s[2:3], 0, v5
	s_nop 1
	v_cndmask_b32_e64 v5, v6, v7, s[2:3]
	v_mul_f32_e32 v6, 0x37800000, v5
	v_cndmask_b32_e32 v5, v5, v6, vcc
	v_cmp_class_f32_e32 vcc, v3, v186
	s_nop 1
	v_cndmask_b32_e32 v3, v5, v3, vcc
	v_div_scale_f32 v5, s[2:3], v3, v3, 1.0
	v_rcp_f32_e32 v6, v5
	s_nop 0
	v_fma_f32 v7, -v5, v6, 1.0
	v_fmac_f32_e32 v6, v7, v6
	v_div_scale_f32 v7, vcc, 1.0, v3, 1.0
	v_mul_f32_e32 v16, v7, v6
	v_fma_f32 v17, -v5, v16, v7
	v_fmac_f32_e32 v16, v17, v6
	v_fma_f32 v5, -v5, v16, v7
	v_div_fmas_f32 v5, v5, v6, v16
	v_div_fixup_f32 v3, v5, v3, 1.0
	v_mul_f32_e32 v1, v1, v3
	v_mul_f32_e32 v1, v65, v1
	v_cvt_pk_bf16_f32 v1, v1, s0
	ds_write_b16 v248, v1
	v_mul_f32_e32 v1, v2, v3
	v_mul_f32_e32 v0, v0, v3
	v_mul_f32_e32 v1, v66, v1
	v_mul_f32_e32 v0, v68, v0
	v_cvt_pk_bf16_f32 v1, v1, s0
	v_cvt_pk_bf16_f32 v0, v0, s0
	ds_write_b16 v248, v1 offset:64
	v_mul_f32_e32 v1, v4, v3
	ds_write_b16 v248, v0 offset:192
	v_or_b32_e32 v0, 16, v216
	v_mul_f32_e32 v1, v67, v1
	v_or_b32_e32 v0, v191, v0
	v_cvt_pk_bf16_f32 v1, v1, s0
	v_lshlrev_b32_e32 v0, 2, v0
	ds_write_b16 v248, v1 offset:128
	ds_bpermute_b32 v16, v0, v64
	ds_read2st64_b32 v[0:1], v204 offset0:8 offset1:9
	ds_read2st64_b32 v[2:3], v204 offset0:24 offset1:25
	ds_read2st64_b32 v[4:5], v204 offset0:40 offset1:41
	ds_read2st64_b32 v[6:7], v204 offset0:56 offset1:57
	s_waitcnt lgkmcnt(3)
	v_fma_f32 v0, v40, v16, -v0
	s_waitcnt lgkmcnt(2)
	v_fma_f32 v2, v56, v16, -v2
	v_mul_f32_e32 v17, v2, v2
	v_fmac_f32_e32 v17, v0, v0
	s_waitcnt lgkmcnt(1)
	v_fma_f32 v4, v24, v16, -v4
	v_fmac_f32_e32 v17, v4, v4
	s_waitcnt lgkmcnt(0)
	v_fma_f32 v6, v8, v16, -v6
	v_fmac_f32_e32 v17, v6, v6
	s_nop 1
	v_mov_b32_dpp v8, v17 quad_perm:[1,0,3,2] row_mask:0xf bank_mask:0xf
	s_waitcnt lgkmcnt(0)
	v_add_f32_e32 v8, v17, v8
	s_nop 1
	v_mov_b32_dpp v16, v8 quad_perm:[2,3,0,1] row_mask:0xf bank_mask:0xf
	s_waitcnt lgkmcnt(0)
	v_add_f32_e32 v8, v8, v16
	s_nop 1
	v_mov_b32_dpp v16, v8 row_half_mirror row_mask:0xf bank_mask:0xf
	s_waitcnt lgkmcnt(0)
	v_add_f32_e32 v8, v8, v16
	s_nop 1
	v_mov_b32_dpp v16, v8 row_mirror row_mask:0xf bank_mask:0xf
	s_waitcnt lgkmcnt(0)
	v_add_f32_e32 v8, v8, v16
	ds_bpermute_b32 v16, v69, v8
	s_waitcnt lgkmcnt(0)
	v_add_f32_e32 v8, v8, v16
	v_fmamk_f32 v8, v8, 0x3c000000, v185
	v_cmp_gt_f32_e32 vcc, s36, v8
	v_mul_f32_e32 v16, 0x4f800000, v8
	s_nop 0
	v_cndmask_b32_e32 v8, v8, v16, vcc
	v_sqrt_f32_e32 v16, v8
	s_nop 0
	v_add_u32_e32 v17, -1, v16
	v_fma_f32 v18, -v17, v16, v8
	v_cmp_ge_f32_e64 s[2:3], 0, v18
	v_add_u32_e32 v18, 1, v16
	s_nop 0
	v_cndmask_b32_e64 v17, v16, v17, s[2:3]
	v_fma_f32 v16, -v18, v16, v8
	v_cmp_lt_f32_e64 s[2:3], 0, v16
	s_nop 1
	v_cndmask_b32_e64 v16, v17, v18, s[2:3]
	v_mul_f32_e32 v17, 0x37800000, v16
	v_cndmask_b32_e32 v16, v16, v17, vcc
	v_cmp_class_f32_e32 vcc, v8, v186
	s_nop 1
	v_cndmask_b32_e32 v8, v16, v8, vcc
	v_div_scale_f32 v16, s[2:3], v8, v8, 1.0
	v_rcp_f32_e32 v17, v16
	s_nop 0
	v_fma_f32 v18, -v16, v17, 1.0
	v_fmac_f32_e32 v17, v18, v17
	v_div_scale_f32 v18, vcc, 1.0, v8, 1.0
	v_mul_f32_e32 v19, v18, v17
	v_fma_f32 v20, -v16, v19, v18
	v_fmac_f32_e32 v19, v20, v17
	v_fma_f32 v16, -v16, v19, v18
	v_div_fmas_f32 v16, v16, v17, v19
	v_div_fixup_f32 v8, v16, v8, 1.0
	v_mul_f32_e32 v0, v0, v8
	v_mul_f32_e32 v0, v65, v0
	v_cvt_pk_bf16_f32 v0, v0, s0
	ds_write_b16 v249, v0
	v_mul_f32_e32 v0, v2, v8
	v_mul_f32_e32 v0, v66, v0
	v_cvt_pk_bf16_f32 v0, v0, s0
	ds_write_b16 v249, v0 offset:64
	v_mul_f32_e32 v0, v4, v8
	v_mul_f32_e32 v0, v67, v0
	v_cvt_pk_bf16_f32 v0, v0, s0
	ds_write_b16 v249, v0 offset:128
	v_mul_f32_e32 v0, v6, v8
	v_mul_f32_e32 v0, v68, v0
	v_cvt_pk_bf16_f32 v0, v0, s0
	ds_write_b16 v249, v0 offset:192
	v_or_b32_e32 v0, 17, v216
	v_or_b32_e32 v0, v191, v0
	v_lshlrev_b32_e32 v0, 2, v0
	ds_bpermute_b32 v0, v0, v64
	s_waitcnt lgkmcnt(0)
	v_fma_f32 v2, v57, v0, -v3
	v_fma_f32 v1, v41, v0, -v1
	v_mul_f32_e32 v3, v2, v2
	v_fmac_f32_e32 v3, v1, v1
	v_fma_f32 v4, v25, v0, -v5
	v_fmac_f32_e32 v3, v4, v4
	v_fma_f32 v0, v9, v0, -v7
	v_fmac_f32_e32 v3, v0, v0
	s_nop 1
	v_mov_b32_dpp v5, v3 quad_perm:[1,0,3,2] row_mask:0xf bank_mask:0xf
	s_waitcnt lgkmcnt(0)
	v_add_f32_e32 v3, v3, v5
	s_nop 1
	v_mov_b32_dpp v5, v3 quad_perm:[2,3,0,1] row_mask:0xf bank_mask:0xf
	s_waitcnt lgkmcnt(0)
	v_add_f32_e32 v3, v3, v5
	s_nop 1
	v_mov_b32_dpp v5, v3 row_half_mirror row_mask:0xf bank_mask:0xf
	s_waitcnt lgkmcnt(0)
	v_add_f32_e32 v3, v3, v5
	s_nop 1
	v_mov_b32_dpp v5, v3 row_mirror row_mask:0xf bank_mask:0xf
	s_waitcnt lgkmcnt(0)
	v_add_f32_e32 v3, v3, v5
	ds_bpermute_b32 v5, v69, v3
	s_waitcnt lgkmcnt(0)
; #define LAS __attribute__((address_space(3)))
; __device__ __forceinline__ unsigned cvtpk(float lo, float hi) { f32x2_t v = {lo, hi}; bf16x2_t b = __builtin_convertvector(v, bf16x2_t); return __builtin_bit_cast(unsigned, b); }
; __device__ __forceinline__ void attn_phase(LAS unsigned char* lds, const bf16_t* Z, const bf16_t* VT, bf16_t* Y, const float* subln, float lam, float lam_init, float M0, unsigned* ctr, LAS int* s_unit, int wid_s_) {
;     ...
;             for (int cb = 0; cb < 4; ++cb) sw[cb] = subln[32 * cb + rr] * (1.0f - lam_init);
; #pragma unroll
;             for (int r = 0; r < 16; ++r) { const int qrow = (r & 3) + 8 * (r >> 2) + 4 * hh; const float a = __shfl(inv, qrow);
;                 float o[4]; float ss = 0.f;
; #pragma unroll
;                 for (int cb = 0; cb < 4; ++cb) { o[cb] = O[cb][r] * a - xch[(cb * 16 + r) * 64]; ss += o[cb] * o[cb]; }
;                 ss += __shfl_xor(ss, 1); ss += __shfl_xor(ss, 2); ss += __shfl_xor(ss, 4); ss += __shfl_xor(ss, 8); ss += __shfl_xor(ss, 16);
;                 const float rn = 1.0f / sqrtf(ss * (1.f / 128.f) + NORM_EPS);
;                 LAS bf16_t* st = (LAS bf16_t*)(lds + rg * 8192) + qrow * 128 + rr;
; #pragma unroll
;                 for (int cb = 0; cb < 4; ++cb) st[32 * cb] = (bf16_t)(cvtpk(o[cb] * rn * sw[cb], 0.f) & 0xffffu);
;             }
	v_add_f32_e32 v3, v3, v5
	v_fmamk_f32 v3, v3, 0x3c000000, v185
	v_cmp_gt_f32_e32 vcc, s36, v3
	v_mul_f32_e32 v5, 0x4f800000, v3
	s_nop 0
	v_cndmask_b32_e32 v3, v3, v5, vcc
	v_sqrt_f32_e32 v5, v3
	s_nop 0
	v_add_u32_e32 v6, -1, v5
	v_fma_f32 v7, -v6, v5, v3
	v_cmp_ge_f32_e64 s[2:3], 0, v7
	v_add_u32_e32 v7, 1, v5
	s_nop 0
	v_cndmask_b32_e64 v6, v5, v6, s[2:3]
	v_fma_f32 v5, -v7, v5, v3
	v_cmp_lt_f32_e64 s[2:3], 0, v5
	s_nop 1
	v_cndmask_b32_e64 v5, v6, v7, s[2:3]
	v_mul_f32_e32 v6, 0x37800000, v5
	v_cndmask_b32_e32 v5, v5, v6, vcc
	v_cmp_class_f32_e32 vcc, v3, v186
	s_nop 1
	v_cndmask_b32_e32 v3, v5, v3, vcc
	v_div_scale_f32 v5, s[2:3], v3, v3, 1.0
	v_rcp_f32_e32 v6, v5
	s_nop 0
	v_fma_f32 v7, -v5, v6, 1.0
	v_fmac_f32_e32 v6, v7, v6
	v_div_scale_f32 v7, vcc, 1.0, v3, 1.0
	v_mul_f32_e32 v8, v7, v6
	v_fma_f32 v9, -v5, v8, v7
	v_fmac_f32_e32 v8, v9, v6
	v_fma_f32 v5, -v5, v8, v7
	v_div_fmas_f32 v5, v5, v6, v8
	v_div_fixup_f32 v3, v5, v3, 1.0
	v_mul_f32_e32 v1, v1, v3
	v_mul_f32_e32 v0, v0, v3
	v_mul_f32_e32 v1, v65, v1
	v_mul_f32_e32 v0, v68, v0
	v_cvt_pk_bf16_f32 v1, v1, s0
	v_cvt_pk_bf16_f32 v0, v0, s0
	ds_write_b16 v250, v1
	v_mul_f32_e32 v1, v2, v3
	ds_write_b16 v250, v0 offset:192
	v_or_b32_e32 v0, 18, v216
	v_mul_f32_e32 v1, v66, v1
	v_or_b32_e32 v0, v191, v0
	v_cvt_pk_bf16_f32 v1, v1, s0
	v_lshlrev_b32_e32 v0, 2, v0
	ds_write_b16 v250, v1 offset:64
	v_mul_f32_e32 v1, v4, v3
	ds_bpermute_b32 v0, v0, v64
	ds_read2st64_b32 v[2:3], v204 offset0:10 offset1:11
	ds_read2st64_b32 v[4:5], v204 offset0:26 offset1:27
	ds_read2st64_b32 v[6:7], v204 offset0:42 offset1:43
	ds_read2st64_b32 v[8:9], v204 offset0:58 offset1:59
	v_mul_f32_e32 v1, v67, v1
	v_cvt_pk_bf16_f32 v1, v1, s0
	ds_write_b16 v250, v1 offset:128
	s_waitcnt lgkmcnt(4)
	v_fma_f32 v1, v42, v0, -v2
	s_waitcnt lgkmcnt(3)
	v_fma_f32 v2, v58, v0, -v4
	v_mul_f32_e32 v4, v2, v2
	v_fmac_f32_e32 v4, v1, v1
	s_waitcnt lgkmcnt(2)
	v_fma_f32 v6, v26, v0, -v6
	v_fmac_f32_e32 v4, v6, v6
	s_waitcnt lgkmcnt(1)
	v_fma_f32 v0, v10, v0, -v8
	v_fmac_f32_e32 v4, v0, v0
	s_nop 1
	v_mov_b32_dpp v8, v4 quad_perm:[1,0,3,2] row_mask:0xf bank_mask:0xf
	s_waitcnt lgkmcnt(0)
	v_add_f32_e32 v4, v4, v8
	s_nop 1
	v_mov_b32_dpp v8, v4 quad_perm:[2,3,0,1] row_mask:0xf bank_mask:0xf
	s_waitcnt lgkmcnt(0)
	v_add_f32_e32 v4, v4, v8
	s_nop 1
	v_mov_b32_dpp v8, v4 row_half_mirror row_mask:0xf bank_mask:0xf
	s_waitcnt lgkmcnt(0)
	v_add_f32_e32 v4, v4, v8
	s_nop 1
	v_mov_b32_dpp v8, v4 row_mirror row_mask:0xf bank_mask:0xf
	s_waitcnt lgkmcnt(0)
	v_add_f32_e32 v4, v4, v8
	ds_bpermute_b32 v8, v69, v4
	s_waitcnt lgkmcnt(0)
	v_add_f32_e32 v4, v4, v8
	v_fmamk_f32 v4, v4, 0x3c000000, v185
	v_cmp_gt_f32_e32 vcc, s36, v4
	v_mul_f32_e32 v8, 0x4f800000, v4
	s_nop 0
	v_cndmask_b32_e32 v4, v4, v8, vcc
	v_sqrt_f32_e32 v8, v4
	s_nop 0
	v_add_u32_e32 v10, -1, v8
	v_fma_f32 v16, -v10, v8, v4
	v_cmp_ge_f32_e64 s[2:3], 0, v16
	v_add_u32_e32 v16, 1, v8
	s_nop 0
	v_cndmask_b32_e64 v10, v8, v10, s[2:3]
	v_fma_f32 v8, -v16, v8, v4
	v_cmp_lt_f32_e64 s[2:3], 0, v8
	s_nop 1
	v_cndmask_b32_e64 v8, v10, v16, s[2:3]
	v_mul_f32_e32 v10, 0x37800000, v8
	v_cndmask_b32_e32 v8, v8, v10, vcc
	v_cmp_class_f32_e32 vcc, v4, v186
	s_nop 1
	v_cndmask_b32_e32 v4, v8, v4, vcc
	v_div_scale_f32 v8, s[2:3], v4, v4, 1.0
	v_rcp_f32_e32 v10, v8
	s_nop 0
	v_fma_f32 v16, -v8, v10, 1.0
	v_fmac_f32_e32 v10, v16, v10
	v_div_scale_f32 v16, vcc, 1.0, v4, 1.0
	v_mul_f32_e32 v17, v16, v10
	v_fma_f32 v18, -v8, v17, v16
	v_fmac_f32_e32 v17, v18, v10
	v_fma_f32 v8, -v8, v17, v16
	v_div_fmas_f32 v8, v8, v10, v17
	v_div_fixup_f32 v4, v8, v4, 1.0
	v_mul_f32_e32 v0, v0, v4
	v_mul_f32_e32 v0, v68, v0
	v_cvt_pk_bf16_f32 v0, v0, s0
	v_mul_f32_e32 v1, v1, v4
	ds_write_b16 v251, v0 offset:192
	v_or_b32_e32 v0, 19, v216
	v_mul_f32_e32 v1, v65, v1
	v_or_b32_e32 v0, v191, v0
	v_cvt_pk_bf16_f32 v1, v1, s0
	v_lshlrev_b32_e32 v0, 2, v0
	ds_write_b16 v251, v1
	v_mul_f32_e32 v1, v2, v4
	ds_bpermute_b32 v0, v0, v64
	v_mul_f32_e32 v1, v66, v1
	v_cvt_pk_bf16_f32 v1, v1, s0
	ds_write_b16 v251, v1 offset:64
	v_mul_f32_e32 v1, v6, v4
	v_mul_f32_e32 v1, v67, v1
	v_cvt_pk_bf16_f32 v1, v1, s0
	s_waitcnt lgkmcnt(1)
	v_fma_f32 v2, v59, v0, -v5
	ds_write_b16 v251, v1 offset:128
	v_fma_f32 v1, v43, v0, -v3
	v_mul_f32_e32 v3, v2, v2
	v_fmac_f32_e32 v3, v1, v1
	v_fma_f32 v4, v27, v0, -v7
	v_fmac_f32_e32 v3, v4, v4
	v_fma_f32 v0, v11, v0, -v9
	v_fmac_f32_e32 v3, v0, v0
	s_nop 1
	v_mov_b32_dpp v5, v3 quad_perm:[1,0,3,2] row_mask:0xf bank_mask:0xf
	s_waitcnt lgkmcnt(0)
	v_add_f32_e32 v3, v3, v5
	s_nop 1
	v_mov_b32_dpp v5, v3 quad_perm:[2,3,0,1] row_mask:0xf bank_mask:0xf
	s_waitcnt lgkmcnt(0)
	v_add_f32_e32 v3, v3, v5
	s_nop 1
	v_mov_b32_dpp v5, v3 row_half_mirror row_mask:0xf bank_mask:0xf
	s_waitcnt lgkmcnt(0)
	v_add_f32_e32 v3, v3, v5
	s_nop 1
	v_mov_b32_dpp v5, v3 row_mirror row_mask:0xf bank_mask:0xf
	s_waitcnt lgkmcnt(0)
	v_add_f32_e32 v3, v3, v5
	ds_bpermute_b32 v5, v69, v3
	s_waitcnt lgkmcnt(0)
; #define LAS __attribute__((address_space(3)))
; __device__ __forceinline__ unsigned cvtpk(float lo, float hi) { f32x2_t v = {lo, hi}; bf16x2_t b = __builtin_convertvector(v, bf16x2_t); return __builtin_bit_cast(unsigned, b); }
; __device__ __forceinline__ void attn_phase(LAS unsigned char* lds, const bf16_t* Z, const bf16_t* VT, bf16_t* Y, const float* subln, float lam, float lam_init, float M0, unsigned* ctr, LAS int* s_unit, int wid_s_) {
;     ...
;             for (int cb = 0; cb < 4; ++cb) sw[cb] = subln[32 * cb + rr] * (1.0f - lam_init);
; #pragma unroll
;             for (int r = 0; r < 16; ++r) { const int qrow = (r & 3) + 8 * (r >> 2) + 4 * hh; const float a = __shfl(inv, qrow);
;                 float o[4]; float ss = 0.f;
; #pragma unroll
;                 for (int cb = 0; cb < 4; ++cb) { o[cb] = O[cb][r] * a - xch[(cb * 16 + r) * 64]; ss += o[cb] * o[cb]; }
;                 ss += __shfl_xor(ss, 1); ss += __shfl_xor(ss, 2); ss += __shfl_xor(ss, 4); ss += __shfl_xor(ss, 8); ss += __shfl_xor(ss, 16);
;                 const float rn = 1.0f / sqrtf(ss * (1.f / 128.f) + NORM_EPS);
;                 LAS bf16_t* st = (LAS bf16_t*)(lds + rg * 8192) + qrow * 128 + rr;
; #pragma unroll
;                 for (int cb = 0; cb < 4; ++cb) st[32 * cb] = (bf16_t)(cvtpk(o[cb] * rn * sw[cb], 0.f) & 0xffffu);
;             }
	v_add_f32_e32 v3, v3, v5
	v_fmamk_f32 v3, v3, 0x3c000000, v185
	v_cmp_gt_f32_e32 vcc, s36, v3
	v_mul_f32_e32 v5, 0x4f800000, v3
	s_nop 0
	v_cndmask_b32_e32 v3, v3, v5, vcc
	v_sqrt_f32_e32 v5, v3
	s_nop 0
	v_add_u32_e32 v6, -1, v5
	v_fma_f32 v7, -v6, v5, v3
	v_cmp_ge_f32_e64 s[2:3], 0, v7
	v_add_u32_e32 v7, 1, v5
	s_nop 0
	v_cndmask_b32_e64 v6, v5, v6, s[2:3]
	v_fma_f32 v5, -v7, v5, v3
	v_cmp_lt_f32_e64 s[2:3], 0, v5
	s_nop 1
	v_cndmask_b32_e64 v5, v6, v7, s[2:3]
	v_mul_f32_e32 v6, 0x37800000, v5
	v_cndmask_b32_e32 v5, v5, v6, vcc
	v_cmp_class_f32_e32 vcc, v3, v186
	s_nop 1
	v_cndmask_b32_e32 v3, v5, v3, vcc
	v_div_scale_f32 v5, s[2:3], v3, v3, 1.0
	v_rcp_f32_e32 v6, v5
	s_nop 0
	v_fma_f32 v7, -v5, v6, 1.0
	v_fmac_f32_e32 v6, v7, v6
	v_div_scale_f32 v7, vcc, 1.0, v3, 1.0
	v_mul_f32_e32 v8, v7, v6
	v_fma_f32 v9, -v5, v8, v7
	v_fmac_f32_e32 v8, v9, v6
	v_fma_f32 v5, -v5, v8, v7
	v_div_fmas_f32 v5, v5, v6, v8
	v_div_fixup_f32 v3, v5, v3, 1.0
	v_mul_f32_e32 v1, v1, v3
	v_mul_f32_e32 v0, v0, v3
	v_mul_f32_e32 v1, v65, v1
	v_mul_f32_e32 v0, v68, v0
	v_cvt_pk_bf16_f32 v1, v1, s0
	v_cvt_pk_bf16_f32 v0, v0, s0
	ds_write_b16 v252, v1
	v_mul_f32_e32 v1, v2, v3
	ds_write_b16 v252, v0 offset:192
	v_or_b32_e32 v0, 24, v216
	v_mul_f32_e32 v1, v66, v1
	v_or_b32_e32 v0, v191, v0
	v_cvt_pk_bf16_f32 v1, v1, s0
	v_lshlrev_b32_e32 v0, 2, v0
	ds_write_b16 v252, v1 offset:64
	v_mul_f32_e32 v1, v4, v3
	ds_bpermute_b32 v0, v0, v64
	ds_read2st64_b32 v[2:3], v204 offset0:12 offset1:13
	ds_read2st64_b32 v[4:5], v204 offset0:28 offset1:29
	ds_read2st64_b32 v[6:7], v204 offset0:44 offset1:45
	ds_read2st64_b32 v[8:9], v204 offset0:60 offset1:61
	v_mul_f32_e32 v1, v67, v1
	v_cvt_pk_bf16_f32 v1, v1, s0
	ds_write_b16 v252, v1 offset:128
	s_waitcnt lgkmcnt(4)
	v_fma_f32 v1, v44, v0, -v2
	s_waitcnt lgkmcnt(3)
	v_fma_f32 v2, v60, v0, -v4
	v_mul_f32_e32 v4, v2, v2
	v_fmac_f32_e32 v4, v1, v1
	s_waitcnt lgkmcnt(2)
	v_fma_f32 v6, v28, v0, -v6
	v_fmac_f32_e32 v4, v6, v6
	s_waitcnt lgkmcnt(1)
	v_fma_f32 v0, v12, v0, -v8
	v_fmac_f32_e32 v4, v0, v0
	s_nop 1
	v_mov_b32_dpp v8, v4 quad_perm:[1,0,3,2] row_mask:0xf bank_mask:0xf
	s_waitcnt lgkmcnt(0)
	v_add_f32_e32 v4, v4, v8
	s_nop 1
	v_mov_b32_dpp v8, v4 quad_perm:[2,3,0,1] row_mask:0xf bank_mask:0xf
	s_waitcnt lgkmcnt(0)
	v_add_f32_e32 v4, v4, v8
	s_nop 1
	v_mov_b32_dpp v8, v4 row_half_mirror row_mask:0xf bank_mask:0xf
	s_waitcnt lgkmcnt(0)
	v_add_f32_e32 v4, v4, v8
	s_nop 1
	v_mov_b32_dpp v8, v4 row_mirror row_mask:0xf bank_mask:0xf
	s_waitcnt lgkmcnt(0)
	v_add_f32_e32 v4, v4, v8
	ds_bpermute_b32 v8, v69, v4
	s_waitcnt lgkmcnt(0)
	v_add_f32_e32 v4, v4, v8
	v_fmamk_f32 v4, v4, 0x3c000000, v185
	v_cmp_gt_f32_e32 vcc, s36, v4
	v_mul_f32_e32 v8, 0x4f800000, v4
	s_nop 0
	v_cndmask_b32_e32 v4, v4, v8, vcc
	v_sqrt_f32_e32 v8, v4
	s_nop 0
	v_add_u32_e32 v10, -1, v8
	v_fma_f32 v11, -v10, v8, v4
	v_cmp_ge_f32_e64 s[2:3], 0, v11
	v_add_u32_e32 v11, 1, v8
	s_nop 0
	v_cndmask_b32_e64 v10, v8, v10, s[2:3]
	v_fma_f32 v8, -v11, v8, v4
	v_cmp_lt_f32_e64 s[2:3], 0, v8
	s_nop 1
	v_cndmask_b32_e64 v8, v10, v11, s[2:3]
	v_mul_f32_e32 v10, 0x37800000, v8
	v_cndmask_b32_e32 v8, v8, v10, vcc
	v_cmp_class_f32_e32 vcc, v4, v186
	s_nop 1
	v_cndmask_b32_e32 v4, v8, v4, vcc
	v_div_scale_f32 v8, s[2:3], v4, v4, 1.0
	v_rcp_f32_e32 v10, v8
	s_nop 0
	v_fma_f32 v11, -v8, v10, 1.0
	v_fmac_f32_e32 v10, v11, v10
	v_div_scale_f32 v11, vcc, 1.0, v4, 1.0
	v_mul_f32_e32 v12, v11, v10
	v_fma_f32 v16, -v8, v12, v11
	v_fmac_f32_e32 v12, v16, v10
	v_fma_f32 v8, -v8, v12, v11
	v_div_fmas_f32 v8, v8, v10, v12
	v_div_fixup_f32 v4, v8, v4, 1.0
	v_mul_f32_e32 v0, v0, v4
	v_mul_f32_e32 v0, v68, v0
	v_cvt_pk_bf16_f32 v0, v0, s0
	v_mul_f32_e32 v1, v1, v4
	ds_write_b16 v253, v0 offset:192
	v_or_b32_e32 v0, 25, v216
	v_mul_f32_e32 v1, v65, v1
	v_or_b32_e32 v0, v191, v0
	v_cvt_pk_bf16_f32 v1, v1, s0
	v_lshlrev_b32_e32 v0, 2, v0
	ds_write_b16 v253, v1
	v_mul_f32_e32 v1, v2, v4
	ds_bpermute_b32 v0, v0, v64
	v_mul_f32_e32 v1, v66, v1
	v_cvt_pk_bf16_f32 v1, v1, s0
	ds_write_b16 v253, v1 offset:64
	v_mul_f32_e32 v1, v6, v4
	v_mul_f32_e32 v1, v67, v1
	v_cvt_pk_bf16_f32 v1, v1, s0
	s_waitcnt lgkmcnt(1)
	v_fma_f32 v2, v61, v0, -v5
	ds_write_b16 v253, v1 offset:128
	v_fma_f32 v1, v45, v0, -v3
	v_mul_f32_e32 v3, v2, v2
	v_fmac_f32_e32 v3, v1, v1
	v_fma_f32 v4, v29, v0, -v7
	v_fmac_f32_e32 v3, v4, v4
	v_fma_f32 v0, v13, v0, -v9
	v_fmac_f32_e32 v3, v0, v0
	s_nop 1
	v_mov_b32_dpp v5, v3 quad_perm:[1,0,3,2] row_mask:0xf bank_mask:0xf
	s_waitcnt lgkmcnt(0)
	v_add_f32_e32 v3, v3, v5
	s_nop 1
	v_mov_b32_dpp v5, v3 quad_perm:[2,3,0,1] row_mask:0xf bank_mask:0xf
	s_waitcnt lgkmcnt(0)
	v_add_f32_e32 v3, v3, v5
	s_nop 1
	v_mov_b32_dpp v5, v3 row_half_mirror row_mask:0xf bank_mask:0xf
	s_waitcnt lgkmcnt(0)
	v_add_f32_e32 v3, v3, v5
	s_nop 1
	v_mov_b32_dpp v5, v3 row_mirror row_mask:0xf bank_mask:0xf
	s_waitcnt lgkmcnt(0)
	v_add_f32_e32 v3, v3, v5
	ds_bpermute_b32 v5, v69, v3
	s_waitcnt lgkmcnt(0)
; #define LAS __attribute__((address_space(3)))
; __device__ __forceinline__ unsigned cvtpk(float lo, float hi) { f32x2_t v = {lo, hi}; bf16x2_t b = __builtin_convertvector(v, bf16x2_t); return __builtin_bit_cast(unsigned, b); }
; __device__ __forceinline__ void attn_phase(LAS unsigned char* lds, const bf16_t* Z, const bf16_t* VT, bf16_t* Y, const float* subln, float lam, float lam_init, float M0, unsigned* ctr, LAS int* s_unit, int wid_s_) {
;     ...
;             for (int cb = 0; cb < 4; ++cb) sw[cb] = subln[32 * cb + rr] * (1.0f - lam_init);
; #pragma unroll
;             for (int r = 0; r < 16; ++r) { const int qrow = (r & 3) + 8 * (r >> 2) + 4 * hh; const float a = __shfl(inv, qrow);
;                 float o[4]; float ss = 0.f;
; #pragma unroll
;                 for (int cb = 0; cb < 4; ++cb) { o[cb] = O[cb][r] * a - xch[(cb * 16 + r) * 64]; ss += o[cb] * o[cb]; }
;                 ss += __shfl_xor(ss, 1); ss += __shfl_xor(ss, 2); ss += __shfl_xor(ss, 4); ss += __shfl_xor(ss, 8); ss += __shfl_xor(ss, 16);
;                 const float rn = 1.0f / sqrtf(ss * (1.f / 128.f) + NORM_EPS);
;                 LAS bf16_t* st = (LAS bf16_t*)(lds + rg * 8192) + qrow * 128 + rr;
; #pragma unroll
;                 for (int cb = 0; cb < 4; ++cb) st[32 * cb] = (bf16_t)(cvtpk(o[cb] * rn * sw[cb], 0.f) & 0xffffu);
;             }
	v_add_f32_e32 v3, v3, v5
	v_fmamk_f32 v3, v3, 0x3c000000, v185
	v_cmp_gt_f32_e32 vcc, s36, v3
	v_mul_f32_e32 v5, 0x4f800000, v3
	s_nop 0
	v_cndmask_b32_e32 v3, v3, v5, vcc
	v_sqrt_f32_e32 v5, v3
	s_nop 0
	v_add_u32_e32 v6, -1, v5
	v_fma_f32 v7, -v6, v5, v3
	v_cmp_ge_f32_e64 s[2:3], 0, v7
	v_add_u32_e32 v7, 1, v5
	s_nop 0
	v_cndmask_b32_e64 v6, v5, v6, s[2:3]
	v_fma_f32 v5, -v7, v5, v3
	v_cmp_lt_f32_e64 s[2:3], 0, v5
	s_nop 1
	v_cndmask_b32_e64 v5, v6, v7, s[2:3]
	v_mul_f32_e32 v6, 0x37800000, v5
	v_cndmask_b32_e32 v5, v5, v6, vcc
	v_cmp_class_f32_e32 vcc, v3, v186
	s_nop 1
	v_cndmask_b32_e32 v3, v5, v3, vcc
	v_div_scale_f32 v5, s[2:3], v3, v3, 1.0
	v_rcp_f32_e32 v6, v5
	s_nop 0
	v_fma_f32 v7, -v5, v6, 1.0
	v_fmac_f32_e32 v6, v7, v6
	v_div_scale_f32 v7, vcc, 1.0, v3, 1.0
	v_mul_f32_e32 v8, v7, v6
	v_fma_f32 v9, -v5, v8, v7
	v_fmac_f32_e32 v8, v9, v6
	v_fma_f32 v5, -v5, v8, v7
	v_div_fmas_f32 v5, v5, v6, v8
	v_div_fixup_f32 v3, v5, v3, 1.0
	v_mul_f32_e32 v1, v1, v3
	v_mul_f32_e32 v1, v65, v1
	v_cvt_pk_bf16_f32 v1, v1, s0
	ds_write_b16 v187, v1
	v_mul_f32_e32 v1, v2, v3
	v_mul_f32_e32 v1, v66, v1
	v_mul_f32_e32 v0, v0, v3
	v_cvt_pk_bf16_f32 v1, v1, s0
	v_mul_f32_e32 v0, v68, v0
	ds_write_b16 v187, v1 offset:64
	v_mul_f32_e32 v1, v4, v3
	v_cvt_pk_bf16_f32 v0, v0, s0
	v_mul_f32_e32 v1, v67, v1
	ds_write_b16 v187, v0 offset:192
	v_or_b32_e32 v0, v191, v230
	v_cvt_pk_bf16_f32 v1, v1, s0
	v_lshlrev_b32_e32 v0, 2, v0
	ds_write_b16 v187, v1 offset:128
	ds_bpermute_b32 v8, v0, v64
	ds_read2st64_b32 v[0:1], v204 offset0:14 offset1:15
	ds_read2st64_b32 v[2:3], v204 offset0:30 offset1:31
	ds_read2st64_b32 v[4:5], v204 offset0:46 offset1:47
	ds_read2st64_b32 v[6:7], v204 offset0:62 offset1:63
	s_waitcnt lgkmcnt(3)
	v_fma_f32 v0, v46, v8, -v0
	s_waitcnt lgkmcnt(2)
	v_fma_f32 v2, v62, v8, -v2
	v_mul_f32_e32 v9, v2, v2
	v_fmac_f32_e32 v9, v0, v0
	s_waitcnt lgkmcnt(1)
	v_fma_f32 v4, v30, v8, -v4
	v_fmac_f32_e32 v9, v4, v4
	s_waitcnt lgkmcnt(0)
	v_fma_f32 v6, v14, v8, -v6
	v_fmac_f32_e32 v9, v6, v6
	s_nop 1
	v_mov_b32_dpp v8, v9 quad_perm:[1,0,3,2] row_mask:0xf bank_mask:0xf
	s_waitcnt lgkmcnt(0)
	v_add_f32_e32 v8, v9, v8
	s_nop 1
	v_mov_b32_dpp v9, v8 quad_perm:[2,3,0,1] row_mask:0xf bank_mask:0xf
	s_waitcnt lgkmcnt(0)
	v_add_f32_e32 v8, v8, v9
	s_nop 1
	v_mov_b32_dpp v9, v8 row_half_mirror row_mask:0xf bank_mask:0xf
	s_waitcnt lgkmcnt(0)
	v_add_f32_e32 v8, v8, v9
	s_nop 1
	v_mov_b32_dpp v9, v8 row_mirror row_mask:0xf bank_mask:0xf
	s_waitcnt lgkmcnt(0)
	v_add_f32_e32 v8, v8, v9
	ds_bpermute_b32 v9, v69, v8
	s_waitcnt lgkmcnt(0)
	v_add_f32_e32 v8, v8, v9
	v_fmamk_f32 v8, v8, 0x3c000000, v185
	v_cmp_gt_f32_e32 vcc, s36, v8
	v_mul_f32_e32 v9, 0x4f800000, v8
	s_nop 0
	v_cndmask_b32_e32 v8, v8, v9, vcc
	v_sqrt_f32_e32 v9, v8
	s_nop 0
	v_add_u32_e32 v10, -1, v9
	v_fma_f32 v11, -v10, v9, v8
	v_cmp_ge_f32_e64 s[2:3], 0, v11
	v_add_u32_e32 v11, 1, v9
	s_nop 0
	v_cndmask_b32_e64 v10, v9, v10, s[2:3]
	v_fma_f32 v9, -v11, v9, v8
	v_cmp_lt_f32_e64 s[2:3], 0, v9
	s_nop 1
	v_cndmask_b32_e64 v9, v10, v11, s[2:3]
	v_mul_f32_e32 v10, 0x37800000, v9
	v_cndmask_b32_e32 v9, v9, v10, vcc
	v_cmp_class_f32_e32 vcc, v8, v186
	s_nop 1
	v_cndmask_b32_e32 v8, v9, v8, vcc
	v_div_scale_f32 v9, s[2:3], v8, v8, 1.0
	v_rcp_f32_e32 v10, v9
	s_nop 0
	v_fma_f32 v11, -v9, v10, 1.0
	v_fmac_f32_e32 v10, v11, v10
	v_div_scale_f32 v11, vcc, 1.0, v8, 1.0
	v_mul_f32_e32 v12, v11, v10
	v_fma_f32 v13, -v9, v12, v11
	v_fmac_f32_e32 v12, v13, v10
	v_fma_f32 v9, -v9, v12, v11
	v_div_fmas_f32 v9, v9, v10, v12
	v_div_fixup_f32 v8, v9, v8, 1.0
	v_mul_f32_e32 v0, v0, v8
	v_mul_f32_e32 v0, v65, v0
	v_cvt_pk_bf16_f32 v0, v0, s0
	ds_write_b16 v200, v0
	v_mul_f32_e32 v0, v2, v8
	v_mul_f32_e32 v0, v66, v0
	v_cvt_pk_bf16_f32 v0, v0, s0
	ds_write_b16 v200, v0 offset:64
	v_mul_f32_e32 v0, v4, v8
	v_mul_f32_e32 v0, v67, v0
	v_cvt_pk_bf16_f32 v0, v0, s0
	ds_write_b16 v200, v0 offset:128
	v_mul_f32_e32 v0, v6, v8
	v_mul_f32_e32 v0, v68, v0
	v_cvt_pk_bf16_f32 v0, v0, s0
	ds_write_b16 v200, v0 offset:192
	v_or_b32_e32 v0, v191, v231
	v_lshlrev_b32_e32 v0, 2, v0
	ds_bpermute_b32 v0, v0, v64
	v_or_b32_e32 v10, s40, v232
	v_ashrrev_i32_e32 v11, 31, v10
	s_waitcnt lgkmcnt(0)
	v_fma_f32 v2, v63, v0, -v3
	v_fma_f32 v1, v47, v0, -v1
	v_mul_f32_e32 v3, v2, v2
	v_fmac_f32_e32 v3, v1, v1
	v_fma_f32 v4, v31, v0, -v5
	v_fmac_f32_e32 v3, v4, v4
	v_fma_f32 v0, v15, v0, -v7
	v_fmac_f32_e32 v3, v0, v0
	s_nop 1
	v_mov_b32_dpp v5, v3 quad_perm:[1,0,3,2] row_mask:0xf bank_mask:0xf
	s_waitcnt lgkmcnt(0)
	v_add_f32_e32 v3, v3, v5
	s_nop 1
	v_mov_b32_dpp v5, v3 quad_perm:[2,3,0,1] row_mask:0xf bank_mask:0xf
	s_waitcnt lgkmcnt(0)
	v_add_f32_e32 v3, v3, v5
	s_nop 1
	v_mov_b32_dpp v5, v3 row_half_mirror row_mask:0xf bank_mask:0xf
	s_waitcnt lgkmcnt(0)
	v_add_f32_e32 v3, v3, v5
	s_nop 1
	v_mov_b32_dpp v5, v3 row_mirror row_mask:0xf bank_mask:0xf
	s_waitcnt lgkmcnt(0)
	v_add_f32_e32 v3, v3, v5
	ds_bpermute_b32 v5, v69, v3
	s_waitcnt lgkmcnt(0)
; #define LAS __attribute__((address_space(3)))
; __device__ __forceinline__ float bflo(unsigned w) { return __uint_as_float(w << 16); }
; __device__ __forceinline__ float bfhi(unsigned w) { return __uint_as_float(w & 0xffff0000u); }
; __device__ __forceinline__ unsigned cvtpk(float lo, float hi) { f32x2_t v = {lo, hi}; bf16x2_t b = __builtin_convertvector(v, bf16x2_t); return __builtin_bit_cast(unsigned, b); }
; __device__ __forceinline__ void attn_phase(LAS unsigned char* lds, const bf16_t* Z, const bf16_t* VT, bf16_t* Y, const float* subln, float lam, float lam_init, float M0, unsigned* ctr, LAS int* s_unit, int wid_s_) {
;     ...
;             for (int r = 0; r < 16; ++r) { const int qrow = (r & 3) + 8 * (r >> 2) + 4 * hh; const float a = __shfl(inv, qrow);
;                 float o[4]; float ss = 0.f;
; #pragma unroll
;                 for (int cb = 0; cb < 4; ++cb) { o[cb] = O[cb][r] * a - xch[(cb * 16 + r) * 64]; ss += o[cb] * o[cb]; }
;                 ss += __shfl_xor(ss, 1); ss += __shfl_xor(ss, 2); ss += __shfl_xor(ss, 4); ss += __shfl_xor(ss, 8); ss += __shfl_xor(ss, 16);
;                 const float rn = 1.0f / sqrtf(ss * (1.f / 128.f) + NORM_EPS);
;                 LAS bf16_t* st = (LAS bf16_t*)(lds + rg * 8192) + qrow * 128 + rr;
; #pragma unroll
;                 for (int cb = 0; cb < 4; ++cb) st[32 * cb] = (bf16_t)(cvtpk(o[cb] * rn * sw[cb], 0.f) & 0xffffu);
;             }
;             asm volatile("s_waitcnt lgkmcnt(0)" ::: "memory");
; #pragma unroll
;             for (int i = 0; i < 8; ++i) { const int c = i * 64 + lane, row = c >> 4, ch = c & 15; const size_t tok = (size_t)(qw + row);
;                 const u32x4 v = *(const LAS u32x4*)(lds + rg * 8192 + row * 256 + ch * 16);
;                 const u32x4 sg = *(const u32x4*)(Z + tok * ZP + 4096 + h * 128 + ch * 8);
;                 u32x4 w; w.x = cvtpk(bflo(v.x) * bflo(sg.x), bfhi(v.x) * bfhi(sg.x)); w.y = cvtpk(bflo(v.y) * bflo(sg.y), bfhi(v.y) * bfhi(sg.y));
;                 w.z = cvtpk(bflo(v.z) * bflo(sg.z), bfhi(v.z) * bfhi(sg.z)); w.w = cvtpk(bflo(v.w) * bflo(sg.w), bfhi(v.w) * bfhi(sg.w));
;                 *(u32x4*)(Y + tok * D + 1024 + h * 128 + ch * 8) = w; }
	v_add_f32_e32 v3, v3, v5
	v_fmamk_f32 v3, v3, 0x3c000000, v185
	v_cmp_gt_f32_e32 vcc, s36, v3
	v_mul_f32_e32 v5, 0x4f800000, v3
	s_nop 0
	v_cndmask_b32_e32 v3, v3, v5, vcc
	v_sqrt_f32_e32 v5, v3
	s_nop 0
	v_add_u32_e32 v6, -1, v5
	v_fma_f32 v7, -v6, v5, v3
	v_cmp_ge_f32_e64 s[2:3], 0, v7
	v_add_u32_e32 v7, 1, v5
	s_nop 0
	v_cndmask_b32_e64 v6, v5, v6, s[2:3]
	v_fma_f32 v5, -v7, v5, v3
	v_cmp_lt_f32_e64 s[2:3], 0, v5
	s_nop 1
	v_cndmask_b32_e64 v5, v6, v7, s[2:3]
	v_mul_f32_e32 v6, 0x37800000, v5
	v_cndmask_b32_e32 v5, v5, v6, vcc
	v_cmp_class_f32_e32 vcc, v3, v186
	s_nop 1
	v_cndmask_b32_e32 v3, v5, v3, vcc
	v_div_scale_f32 v5, s[2:3], v3, v3, 1.0
	v_rcp_f32_e32 v6, v5
	s_nop 0
	v_fma_f32 v7, -v5, v6, 1.0
	v_fmac_f32_e32 v6, v7, v6
	v_div_scale_f32 v7, vcc, 1.0, v3, 1.0
	v_mul_f32_e32 v8, v7, v6
	v_fma_f32 v9, -v5, v8, v7
	v_fmac_f32_e32 v8, v9, v6
	v_fma_f32 v5, -v5, v8, v7
	v_div_fmas_f32 v5, v5, v6, v8
	v_div_fixup_f32 v3, v5, v3, 1.0
	v_mul_f32_e32 v1, v1, v3
	v_mul_f32_e32 v1, v65, v1
	v_cvt_pk_bf16_f32 v1, v1, s0
	ds_write_b16 v188, v1
	v_mul_f32_e32 v1, v2, v3
	v_mul_f32_e32 v1, v66, v1
	v_cvt_pk_bf16_f32 v1, v1, s0
	ds_write_b16 v188, v1 offset:64
	v_mul_f32_e32 v1, v4, v3
	v_mul_f32_e32 v0, v0, v3
	v_mul_f32_e32 v1, v67, v1
	v_mul_f32_e32 v0, v68, v0
	v_cvt_pk_bf16_f32 v1, v1, s0
	v_cvt_pk_bf16_f32 v0, v0, s0
	ds_write_b16 v188, v1 offset:128
	ds_write_b16 v188, v0 offset:192
	v_mov_b64_e32 v[0:1], s[78:79]
	v_mad_i64_i32 v[6:7], s[2:3], v10, s33, v[0:1]
	v_lshl_add_u64 v[6:7], v[6:7], 0, s[26:27]
	v_lshl_add_u64 v[6:7], v[6:7], 0, v[170:171]
	v_add_co_u32_e32 v6, vcc, s15, v6
	s_waitcnt lgkmcnt(0)
	ds_read_b128 v[2:5], v150
	s_nop 0
	v_addc_co_u32_e32 v7, vcc, 0, v7, vcc
	global_load_dwordx4 v[6:9], v[6:7], off
	s_waitcnt lgkmcnt(0)
	v_lshlrev_b32_e32 v12, 16, v2
	v_and_b32_e32 v13, 0xffff0000, v2
	s_waitcnt vmcnt(0)
	v_lshlrev_b32_e32 v14, 16, v6
	v_and_b32_e32 v15, 0xffff0000, v6
	v_pk_mul_f32 v[12:13], v[12:13], v[14:15]
	v_lshlrev_b32_e32 v6, 16, v7
	v_cvt_pk_bf16_f32 v2, v12, v13
	v_lshlrev_b32_e32 v12, 16, v3
	v_and_b32_e32 v13, 0xffff0000, v3
	v_and_b32_e32 v7, 0xffff0000, v7
	v_pk_mul_f32 v[6:7], v[12:13], v[6:7]
	v_lshlrev_b32_e32 v12, 16, v8
	v_cvt_pk_bf16_f32 v3, v6, v7
	v_lshlrev_b32_e32 v6, 16, v4
	v_and_b32_e32 v7, 0xffff0000, v4
	v_and_b32_e32 v13, 0xffff0000, v8
	v_pk_mul_f32 v[6:7], v[6:7], v[12:13]
	v_lshlrev_b32_e32 v8, 16, v9
	v_cvt_pk_bf16_f32 v4, v6, v7
	v_lshlrev_b32_e32 v6, 16, v5
	v_and_b32_e32 v7, 0xffff0000, v5
	v_and_b32_e32 v9, 0xffff0000, v9
	v_pk_mul_f32 v[6:7], v[6:7], v[8:9]
	s_nop 0
	v_cvt_pk_bf16_f32 v5, v6, v7
	v_lshlrev_b64 v[6:7], 12, v[10:11]
	v_lshl_add_u64 v[6:7], s[4:5], 0, v[6:7]
	v_lshl_add_u64 v[6:7], v[6:7], 0, s[26:27]
	v_lshl_add_u64 v[6:7], v[6:7], 0, v[170:171]
	v_or_b32_e32 v10, s40, v233
	global_store_dwordx4 v[6:7], v[2:5], off offset:2048
	v_mad_i64_i32 v[6:7], s[2:3], v10, s33, v[0:1]
	v_lshl_add_u64 v[6:7], v[6:7], 0, s[26:27]
	v_lshl_add_u64 v[6:7], v[6:7], 0, v[170:171]
	v_add_co_u32_e32 v6, vcc, s15, v6
	ds_read_b128 v[2:5], v151
	s_nop 0
	v_addc_co_u32_e32 v7, vcc, 0, v7, vcc
	global_load_dwordx4 v[6:9], v[6:7], off
	v_ashrrev_i32_e32 v11, 31, v10
	s_waitcnt lgkmcnt(0)
	v_lshlrev_b32_e32 v12, 16, v2
	v_and_b32_e32 v13, 0xffff0000, v2
	s_waitcnt vmcnt(0)
	v_lshlrev_b32_e32 v14, 16, v6
	v_and_b32_e32 v15, 0xffff0000, v6
	v_pk_mul_f32 v[12:13], v[12:13], v[14:15]
	v_lshlrev_b32_e32 v6, 16, v7
	v_cvt_pk_bf16_f32 v2, v12, v13
	v_lshlrev_b32_e32 v12, 16, v3
	v_and_b32_e32 v13, 0xffff0000, v3
	v_and_b32_e32 v7, 0xffff0000, v7
	v_pk_mul_f32 v[6:7], v[12:13], v[6:7]
	v_lshlrev_b32_e32 v12, 16, v8
	v_cvt_pk_bf16_f32 v3, v6, v7
	v_lshlrev_b32_e32 v6, 16, v4
	v_and_b32_e32 v7, 0xffff0000, v4
	v_and_b32_e32 v13, 0xffff0000, v8
	v_pk_mul_f32 v[6:7], v[6:7], v[12:13]
	v_lshlrev_b32_e32 v8, 16, v9
	v_cvt_pk_bf16_f32 v4, v6, v7
	v_lshlrev_b32_e32 v6, 16, v5
	v_and_b32_e32 v7, 0xffff0000, v5
	v_and_b32_e32 v9, 0xffff0000, v9
	v_pk_mul_f32 v[6:7], v[6:7], v[8:9]
	s_nop 0
	v_cvt_pk_bf16_f32 v5, v6, v7
	v_lshlrev_b64 v[6:7], 12, v[10:11]
	v_lshl_add_u64 v[6:7], s[4:5], 0, v[6:7]
	v_lshl_add_u64 v[6:7], v[6:7], 0, s[26:27]
	v_lshl_add_u64 v[6:7], v[6:7], 0, v[170:171]
	v_or_b32_e32 v10, s40, v234
	global_store_dwordx4 v[6:7], v[2:5], off offset:2048
	v_mad_i64_i32 v[6:7], s[2:3], v10, s33, v[0:1]
	v_lshl_add_u64 v[6:7], v[6:7], 0, s[26:27]
	v_lshl_add_u64 v[6:7], v[6:7], 0, v[170:171]
	v_add_co_u32_e32 v6, vcc, s15, v6
	ds_read_b128 v[2:5], v199
	s_nop 0
	v_addc_co_u32_e32 v7, vcc, 0, v7, vcc
	global_load_dwordx4 v[6:9], v[6:7], off
	v_ashrrev_i32_e32 v11, 31, v10
	s_waitcnt lgkmcnt(0)
	v_lshlrev_b32_e32 v12, 16, v2
	v_and_b32_e32 v13, 0xffff0000, v2
	s_waitcnt vmcnt(0)
	v_lshlrev_b32_e32 v14, 16, v6
	v_and_b32_e32 v15, 0xffff0000, v6
	v_pk_mul_f32 v[12:13], v[12:13], v[14:15]
	v_lshlrev_b32_e32 v6, 16, v7
	v_cvt_pk_bf16_f32 v2, v12, v13
	v_lshlrev_b32_e32 v12, 16, v3
	v_and_b32_e32 v13, 0xffff0000, v3
	v_and_b32_e32 v7, 0xffff0000, v7
	v_pk_mul_f32 v[6:7], v[12:13], v[6:7]
	v_lshlrev_b32_e32 v12, 16, v8
	v_cvt_pk_bf16_f32 v3, v6, v7
	v_lshlrev_b32_e32 v6, 16, v4
	v_and_b32_e32 v7, 0xffff0000, v4
	v_and_b32_e32 v13, 0xffff0000, v8
	v_pk_mul_f32 v[6:7], v[6:7], v[12:13]
	v_lshlrev_b32_e32 v8, 16, v9
	v_cvt_pk_bf16_f32 v4, v6, v7
	v_lshlrev_b32_e32 v6, 16, v5
	v_and_b32_e32 v7, 0xffff0000, v5
	v_and_b32_e32 v9, 0xffff0000, v9
	v_pk_mul_f32 v[6:7], v[6:7], v[8:9]
	s_nop 0
	v_cvt_pk_bf16_f32 v5, v6, v7
	v_lshlrev_b64 v[6:7], 12, v[10:11]
	v_lshl_add_u64 v[6:7], s[4:5], 0, v[6:7]
	v_lshl_add_u64 v[6:7], v[6:7], 0, s[26:27]
	v_lshl_add_u64 v[6:7], v[6:7], 0, v[170:171]
	v_or_b32_e32 v10, s40, v235
	global_store_dwordx4 v[6:7], v[2:5], off offset:2048
	v_mad_i64_i32 v[6:7], s[2:3], v10, s33, v[0:1]
	v_lshl_add_u64 v[6:7], v[6:7], 0, s[26:27]
	v_lshl_add_u64 v[6:7], v[6:7], 0, v[170:171]
	v_add_co_u32_e32 v6, vcc, s15, v6
	ds_read_b128 v[2:5], v148
	s_nop 0
	v_addc_co_u32_e32 v7, vcc, 0, v7, vcc
	global_load_dwordx4 v[6:9], v[6:7], off
	v_ashrrev_i32_e32 v11, 31, v10
	s_waitcnt lgkmcnt(0)
; #define LAS __attribute__((address_space(3)))
; __device__ __forceinline__ float bflo(unsigned w) { return __uint_as_float(w << 16); }
; __device__ __forceinline__ float bfhi(unsigned w) { return __uint_as_float(w & 0xffff0000u); }
; __device__ __forceinline__ unsigned cvtpk(float lo, float hi) { f32x2_t v = {lo, hi}; bf16x2_t b = __builtin_convertvector(v, bf16x2_t); return __builtin_bit_cast(unsigned, b); }
; __device__ __forceinline__ void attn_phase(LAS unsigned char* lds, const bf16_t* Z, const bf16_t* VT, bf16_t* Y, const float* subln, float lam, float lam_init, float M0, unsigned* ctr, LAS int* s_unit, int wid_s_) {
;     ...
;             asm volatile("s_waitcnt lgkmcnt(0)" ::: "memory");
; #pragma unroll
;             for (int i = 0; i < 8; ++i) { const int c = i * 64 + lane, row = c >> 4, ch = c & 15; const size_t tok = (size_t)(qw + row);
;                 const u32x4 v = *(const LAS u32x4*)(lds + rg * 8192 + row * 256 + ch * 16);
;                 const u32x4 sg = *(const u32x4*)(Z + tok * ZP + 4096 + h * 128 + ch * 8);
;                 u32x4 w; w.x = cvtpk(bflo(v.x) * bflo(sg.x), bfhi(v.x) * bfhi(sg.x)); w.y = cvtpk(bflo(v.y) * bflo(sg.y), bfhi(v.y) * bfhi(sg.y));
;                 w.z = cvtpk(bflo(v.z) * bflo(sg.z), bfhi(v.z) * bfhi(sg.z)); w.w = cvtpk(bflo(v.w) * bflo(sg.w), bfhi(v.w) * bfhi(sg.w));
;                 *(u32x4*)(Y + tok * D + 1024 + h * 128 + ch * 8) = w; }
	v_lshlrev_b32_e32 v12, 16, v2
	v_and_b32_e32 v13, 0xffff0000, v2
	s_waitcnt vmcnt(0)
	v_lshlrev_b32_e32 v14, 16, v6
	v_and_b32_e32 v15, 0xffff0000, v6
	v_pk_mul_f32 v[12:13], v[12:13], v[14:15]
	v_lshlrev_b32_e32 v6, 16, v7
	v_cvt_pk_bf16_f32 v2, v12, v13
	v_lshlrev_b32_e32 v12, 16, v3
	v_and_b32_e32 v13, 0xffff0000, v3
	v_and_b32_e32 v7, 0xffff0000, v7
	v_pk_mul_f32 v[6:7], v[12:13], v[6:7]
	v_lshlrev_b32_e32 v12, 16, v8
	v_cvt_pk_bf16_f32 v3, v6, v7
	v_lshlrev_b32_e32 v6, 16, v4
	v_and_b32_e32 v7, 0xffff0000, v4
	v_and_b32_e32 v13, 0xffff0000, v8
	v_pk_mul_f32 v[6:7], v[6:7], v[12:13]
	v_lshlrev_b32_e32 v8, 16, v9
	v_cvt_pk_bf16_f32 v4, v6, v7
	v_lshlrev_b32_e32 v6, 16, v5
	v_and_b32_e32 v7, 0xffff0000, v5
	v_and_b32_e32 v9, 0xffff0000, v9
	v_pk_mul_f32 v[6:7], v[6:7], v[8:9]
	s_nop 0
	v_cvt_pk_bf16_f32 v5, v6, v7
	v_lshlrev_b64 v[6:7], 12, v[10:11]
	v_lshl_add_u64 v[6:7], s[4:5], 0, v[6:7]
	v_lshl_add_u64 v[6:7], v[6:7], 0, s[26:27]
	v_lshl_add_u64 v[6:7], v[6:7], 0, v[170:171]
	v_or_b32_e32 v10, s40, v236
	global_store_dwordx4 v[6:7], v[2:5], off offset:2048
	v_mad_i64_i32 v[6:7], s[2:3], v10, s33, v[0:1]
	v_lshl_add_u64 v[6:7], v[6:7], 0, s[26:27]
	v_lshl_add_u64 v[6:7], v[6:7], 0, v[170:171]
	v_add_co_u32_e32 v6, vcc, s15, v6
	ds_read_b128 v[2:5], v149
	s_nop 0
	v_addc_co_u32_e32 v7, vcc, 0, v7, vcc
	global_load_dwordx4 v[6:9], v[6:7], off
	v_ashrrev_i32_e32 v11, 31, v10
	s_waitcnt lgkmcnt(0)
	v_lshlrev_b32_e32 v12, 16, v2
	v_and_b32_e32 v13, 0xffff0000, v2
	s_waitcnt vmcnt(0)
	v_lshlrev_b32_e32 v14, 16, v6
	v_and_b32_e32 v15, 0xffff0000, v6
	v_pk_mul_f32 v[12:13], v[12:13], v[14:15]
	v_lshlrev_b32_e32 v6, 16, v7
	v_cvt_pk_bf16_f32 v2, v12, v13
	v_lshlrev_b32_e32 v12, 16, v3
	v_and_b32_e32 v13, 0xffff0000, v3
	v_and_b32_e32 v7, 0xffff0000, v7
	v_pk_mul_f32 v[6:7], v[12:13], v[6:7]
	v_lshlrev_b32_e32 v12, 16, v8
	v_cvt_pk_bf16_f32 v3, v6, v7
	v_lshlrev_b32_e32 v6, 16, v4
	v_and_b32_e32 v7, 0xffff0000, v4
	v_and_b32_e32 v13, 0xffff0000, v8
	v_pk_mul_f32 v[6:7], v[6:7], v[12:13]
	v_lshlrev_b32_e32 v8, 16, v9
	v_cvt_pk_bf16_f32 v4, v6, v7
	v_lshlrev_b32_e32 v6, 16, v5
	v_and_b32_e32 v7, 0xffff0000, v5
	v_and_b32_e32 v9, 0xffff0000, v9
	v_pk_mul_f32 v[6:7], v[6:7], v[8:9]
	s_nop 0
	v_cvt_pk_bf16_f32 v5, v6, v7
	v_lshlrev_b64 v[6:7], 12, v[10:11]
	v_lshl_add_u64 v[6:7], s[4:5], 0, v[6:7]
	v_lshl_add_u64 v[6:7], v[6:7], 0, s[26:27]
	v_lshl_add_u64 v[6:7], v[6:7], 0, v[170:171]
	v_or_b32_e32 v10, s40, v237
	global_store_dwordx4 v[6:7], v[2:5], off offset:2048
	v_mad_i64_i32 v[6:7], s[2:3], v10, s33, v[0:1]
	v_lshl_add_u64 v[6:7], v[6:7], 0, s[26:27]
	v_lshl_add_u64 v[6:7], v[6:7], 0, v[170:171]
	v_add_co_u32_e32 v6, vcc, s15, v6
	ds_read_b128 v[2:5], v146
	s_nop 0
	v_addc_co_u32_e32 v7, vcc, 0, v7, vcc
	global_load_dwordx4 v[6:9], v[6:7], off
	v_ashrrev_i32_e32 v11, 31, v10
	s_waitcnt lgkmcnt(0)
	v_lshlrev_b32_e32 v12, 16, v2
	v_and_b32_e32 v13, 0xffff0000, v2
	s_waitcnt vmcnt(0)
	v_lshlrev_b32_e32 v14, 16, v6
	v_and_b32_e32 v15, 0xffff0000, v6
	v_pk_mul_f32 v[12:13], v[12:13], v[14:15]
	v_lshlrev_b32_e32 v6, 16, v7
	v_cvt_pk_bf16_f32 v2, v12, v13
	v_lshlrev_b32_e32 v12, 16, v3
	v_and_b32_e32 v13, 0xffff0000, v3
	v_and_b32_e32 v7, 0xffff0000, v7
	v_pk_mul_f32 v[6:7], v[12:13], v[6:7]
	v_lshlrev_b32_e32 v12, 16, v8
	v_cvt_pk_bf16_f32 v3, v6, v7
	v_lshlrev_b32_e32 v6, 16, v4
	v_and_b32_e32 v7, 0xffff0000, v4
	v_and_b32_e32 v13, 0xffff0000, v8
	v_pk_mul_f32 v[6:7], v[6:7], v[12:13]
	v_lshlrev_b32_e32 v8, 16, v9
	v_cvt_pk_bf16_f32 v4, v6, v7
	v_lshlrev_b32_e32 v6, 16, v5
	v_and_b32_e32 v7, 0xffff0000, v5
	v_and_b32_e32 v9, 0xffff0000, v9
	v_pk_mul_f32 v[6:7], v[6:7], v[8:9]
	s_nop 0
	v_cvt_pk_bf16_f32 v5, v6, v7
	v_lshlrev_b64 v[6:7], 12, v[10:11]
	v_lshl_add_u64 v[6:7], s[4:5], 0, v[6:7]
	v_lshl_add_u64 v[6:7], v[6:7], 0, s[26:27]
	v_lshl_add_u64 v[6:7], v[6:7], 0, v[170:171]
	v_or_b32_e32 v10, s40, v238
	global_store_dwordx4 v[6:7], v[2:5], off offset:2048
	v_mad_i64_i32 v[6:7], s[2:3], v10, s33, v[0:1]
	v_lshl_add_u64 v[6:7], v[6:7], 0, s[26:27]
	v_lshl_add_u64 v[6:7], v[6:7], 0, v[170:171]
	v_add_co_u32_e32 v6, vcc, s15, v6
	ds_read_b128 v[2:5], v147
	s_nop 0
	v_addc_co_u32_e32 v7, vcc, 0, v7, vcc
	global_load_dwordx4 v[6:9], v[6:7], off
	v_ashrrev_i32_e32 v11, 31, v10
	s_waitcnt lgkmcnt(0)
	v_lshlrev_b32_e32 v12, 16, v2
	v_and_b32_e32 v13, 0xffff0000, v2
	s_waitcnt vmcnt(0)
	v_lshlrev_b32_e32 v14, 16, v6
	v_and_b32_e32 v15, 0xffff0000, v6
	v_pk_mul_f32 v[12:13], v[12:13], v[14:15]
	v_lshlrev_b32_e32 v6, 16, v7
	v_cvt_pk_bf16_f32 v2, v12, v13
	v_lshlrev_b32_e32 v12, 16, v3
	v_and_b32_e32 v13, 0xffff0000, v3
	v_and_b32_e32 v7, 0xffff0000, v7
	v_pk_mul_f32 v[6:7], v[12:13], v[6:7]
	v_lshlrev_b32_e32 v12, 16, v8
	v_cvt_pk_bf16_f32 v3, v6, v7
	v_lshlrev_b32_e32 v6, 16, v4
	v_and_b32_e32 v7, 0xffff0000, v4
	v_and_b32_e32 v13, 0xffff0000, v8
	v_pk_mul_f32 v[6:7], v[6:7], v[12:13]
	v_lshlrev_b32_e32 v8, 16, v9
	v_cvt_pk_bf16_f32 v4, v6, v7
	v_lshlrev_b32_e32 v6, 16, v5
	v_and_b32_e32 v7, 0xffff0000, v5
	v_and_b32_e32 v9, 0xffff0000, v9
	v_pk_mul_f32 v[6:7], v[6:7], v[8:9]
	s_nop 0
	v_cvt_pk_bf16_f32 v5, v6, v7
	v_lshlrev_b64 v[6:7], 12, v[10:11]
	v_or_b32_e32 v10, s40, v239
	v_mad_i64_i32 v[0:1], s[2:3], v10, s33, v[0:1]
	v_lshl_add_u64 v[6:7], s[4:5], 0, v[6:7]
	v_lshl_add_u64 v[0:1], v[0:1], 0, s[26:27]
	v_lshl_add_u64 v[6:7], v[6:7], 0, s[26:27]
	v_lshl_add_u64 v[0:1], v[0:1], 0, v[170:171]
	v_lshl_add_u64 v[6:7], v[6:7], 0, v[170:171]
	v_add_co_u32_e32 v0, vcc, s15, v0
	global_store_dwordx4 v[6:7], v[2:5], off offset:2048
	s_nop 0
	v_addc_co_u32_e32 v1, vcc, 0, v1, vcc
	global_load_dwordx4 v[6:9], v[0:1], off
	ds_read_b128 v[2:5], v196
	v_ashrrev_i32_e32 v11, 31, v10
	s_waitcnt lgkmcnt(0)
	v_lshlrev_b32_e32 v0, 16, v2
	v_and_b32_e32 v1, 0xffff0000, v2
	v_lshlrev_b32_e32 v2, 16, v3
	v_and_b32_e32 v3, 0xffff0000, v3
	s_waitcnt vmcnt(0)
	v_lshlrev_b32_e32 v12, 16, v6
	v_and_b32_e32 v13, 0xffff0000, v6
	v_lshlrev_b32_e32 v6, 16, v7
	v_and_b32_e32 v7, 0xffff0000, v7
	v_pk_mul_f32 v[0:1], v[0:1], v[12:13]
	v_pk_mul_f32 v[2:3], v[2:3], v[6:7]
	v_cvt_pk_bf16_f32 v0, v0, v1
	v_cvt_pk_bf16_f32 v1, v2, v3
	v_lshlrev_b32_e32 v2, 16, v4
	v_and_b32_e32 v3, 0xffff0000, v4
	v_lshlrev_b32_e32 v6, 16, v8
	v_and_b32_e32 v7, 0xffff0000, v8
	v_pk_mul_f32 v[2:3], v[2:3], v[6:7]
	v_lshlrev_b32_e32 v4, 16, v5
	v_and_b32_e32 v5, 0xffff0000, v5
	v_lshlrev_b32_e32 v6, 16, v9
	v_and_b32_e32 v7, 0xffff0000, v9
	v_pk_mul_f32 v[4:5], v[4:5], v[6:7]
	v_cvt_pk_bf16_f32 v2, v2, v3
	v_cvt_pk_bf16_f32 v3, v4, v5
	v_lshlrev_b64 v[4:5], 12, v[10:11]
	v_lshl_add_u64 v[4:5], s[4:5], 0, v[4:5]
	v_lshl_add_u64 v[4:5], v[4:5], 0, s[26:27]
	v_lshl_add_u64 v[4:5], v[4:5], 0, v[170:171]
	global_store_dwordx4 v[4:5], v[0:3], off offset:2048
	s_branch .LBB0_1290

; __device__ __forceinline__ float bflo(unsigned w) { return __uint_as_float(w << 16); }
; __device__ __forceinline__ float bfhi(unsigned w) { return __uint_as_float(w & 0xffff0000u); }
; __device__ __forceinline__ unsigned cvtpk(float lo, float hi) { f32x2_t v = {lo, hi}; bf16x2_t b = __builtin_convertvector(v, bf16x2_t); return __builtin_bit_cast(unsigned, b); }
;     __device__ __forceinline__ void operator()(const f32x4 (&acc)[2][2][4][2], const Unit& u, int wr, int wc, int fr, int fq) const {
;         const int row0 = u.pm * BM + wr * 64 + fr, col0 = u.pn * BM + wc * 32 + 8 * fq;
; #pragma unroll
;         for (int bj = 0; bj < 2; ++bj) { const int col = col0 + bj * HALF;
;             const f32x4 g0 = *(const f32x4*)(gm + col), g1 = *(const f32x4*)(gm + col + 4);
; #pragma unroll
;             for (int ai = 0; ai < 2; ++ai)
; #pragma unroll
;                 for (int m = 0; m < 4; ++m) { const size_t off = (size_t)(row0 + ai * HALF + m * 16) * D + col;
;                     const u32x4 w = *(const u32x4*)(xr + off);
;                     const f32x4 y0 = (f32x4){bflo(w.x), bfhi(w.x), bflo(w.y), bfhi(w.y)} + g0 * acc[ai][bj][m][0], y1 = (f32x4){bflo(w.z), bfhi(w.z), bflo(w.w), bfhi(w.w)} + g1 * acc[ai][bj][m][1];
;                     if (xout_f) { *(f32x4*)(xout_f + off) = y0; *(f32x4*)(xout_f + off + 4) = y1; }
;                     else { u32x4 o; o.x = cvtpk(y0[0], y0[1]); o.y = cvtpk(y0[2], y0[3]); o.z = cvtpk(y1[0], y1[1]); o.w = cvtpk(y1[2], y1[3]); *(u32x4*)(xr + off) = o; } } }
.LBB0_1396:
	v_lshl_add_u32 v158, s88, 8, v146
	v_lshl_or_b32 v156, s89, 8, v148
	v_ashrrev_i32_e32 v159, 31, v158
	v_readlane_b32 s10, v255, 50
	v_ashrrev_i32_e32 v157, 31, v156
	v_lshlrev_b64 v[150:151], 12, v[158:159]
	v_readlane_b32 s11, v255, 51
	v_lshlrev_b64 v[160:161], 1, v[156:157]
	v_lshl_add_u64 v[130:131], v[156:157], 2, s[12:13]
	v_lshl_add_u64 v[150:151], s[10:11], 0, v[150:151]
	v_lshl_add_u64 v[154:155], v[150:151], 0, v[160:161]
	global_load_dwordx4 v[134:137], v[130:131], off
	s_nop 0
	global_load_dwordx4 v[130:133], v[130:131], off offset:16
	s_mov_b64 s[20:21], -1
	global_load_dwordx4 v[162:165], v[154:155], off
	s_waitcnt vmcnt(0) lgkmcnt(0)
	v_lshlrev_b32_e32 v150, 16, v162
	v_and_b32_e32 v151, 0xffff0000, v162
	v_lshlrev_b32_e32 v162, 16, v163
	v_and_b32_e32 v163, 0xffff0000, v163
	v_pk_fma_f32 v[128:129], v[128:129], v[136:137], v[162:163]
	v_pk_fma_f32 v[126:127], v[126:127], v[134:135], v[150:151]
	v_lshlrev_b32_e32 v150, 16, v164
	v_and_b32_e32 v151, 0xffff0000, v164
	v_lshlrev_b32_e32 v162, 16, v165
	v_and_b32_e32 v163, 0xffff0000, v165
	v_pk_fma_f32 v[162:163], v[124:125], v[132:133], v[162:163]
	v_pk_fma_f32 v[124:125], v[122:123], v[130:131], v[150:151]
	v_cvt_pk_bf16_f32 v122, v126, v127
	v_cvt_pk_bf16_f32 v123, v128, v129
	v_cvt_pk_bf16_f32 v124, v124, v125
	v_cvt_pk_bf16_f32 v125, v162, v163
	global_store_dwordx4 v[154:155], v[122:125], off
	s_nop 1
	v_or_b32_e32 v122, 16, v158
	v_ashrrev_i32_e32 v123, 31, v122
	v_lshlrev_b64 v[122:123], 12, v[122:123]
	v_lshl_add_u64 v[122:123], s[10:11], 0, v[122:123]
	v_lshl_add_u64 v[122:123], v[122:123], 0, v[160:161]
	global_load_dwordx4 v[124:127], v[122:123], off
	s_waitcnt vmcnt(0) lgkmcnt(0)
	v_lshlrev_b32_e32 v128, 16, v124
	v_and_b32_e32 v129, 0xffff0000, v124
	v_lshlrev_b32_e32 v124, 16, v125
	v_and_b32_e32 v125, 0xffff0000, v125
	v_pk_fma_f32 v[120:121], v[120:121], v[136:137], v[124:125]
	v_lshlrev_b32_e32 v124, 16, v126
	v_and_b32_e32 v125, 0xffff0000, v126
	v_lshlrev_b32_e32 v126, 16, v127
	v_and_b32_e32 v127, 0xffff0000, v127
	v_pk_fma_f32 v[118:119], v[118:119], v[134:135], v[128:129]
	v_pk_fma_f32 v[126:127], v[116:117], v[132:133], v[126:127]
	v_pk_fma_f32 v[116:117], v[114:115], v[130:131], v[124:125]
	v_cvt_pk_bf16_f32 v114, v118, v119
	v_cvt_pk_bf16_f32 v115, v120, v121
	v_cvt_pk_bf16_f32 v116, v116, v117
	v_cvt_pk_bf16_f32 v117, v126, v127
	global_store_dwordx4 v[122:123], v[114:117], off
	s_nop 1
	v_or_b32_e32 v114, 32, v158
	v_ashrrev_i32_e32 v115, 31, v114
	v_lshlrev_b64 v[114:115], 12, v[114:115]
	v_lshl_add_u64 v[114:115], s[10:11], 0, v[114:115]
	v_lshl_add_u64 v[114:115], v[114:115], 0, v[160:161]
	global_load_dwordx4 v[116:119], v[114:115], off
	s_waitcnt vmcnt(0) lgkmcnt(0)
	v_lshlrev_b32_e32 v120, 16, v116
	v_and_b32_e32 v121, 0xffff0000, v116
	v_lshlrev_b32_e32 v116, 16, v117
	v_and_b32_e32 v117, 0xffff0000, v117
	v_pk_fma_f32 v[112:113], v[112:113], v[136:137], v[116:117]
	v_lshlrev_b32_e32 v116, 16, v118
	v_and_b32_e32 v117, 0xffff0000, v118
	v_lshlrev_b32_e32 v118, 16, v119
	v_and_b32_e32 v119, 0xffff0000, v119
	v_pk_fma_f32 v[110:111], v[110:111], v[134:135], v[120:121]
	v_pk_fma_f32 v[118:119], v[108:109], v[132:133], v[118:119]
	v_pk_fma_f32 v[108:109], v[106:107], v[130:131], v[116:117]
	v_cvt_pk_bf16_f32 v106, v110, v111
	v_cvt_pk_bf16_f32 v107, v112, v113
	v_cvt_pk_bf16_f32 v108, v108, v109
	v_cvt_pk_bf16_f32 v109, v118, v119
	global_store_dwordx4 v[114:115], v[106:109], off
	s_nop 1
	v_or_b32_e32 v106, 48, v158
	v_ashrrev_i32_e32 v107, 31, v106
	v_lshlrev_b64 v[106:107], 12, v[106:107]
	v_lshl_add_u64 v[106:107], s[10:11], 0, v[106:107]
	v_lshl_add_u64 v[106:107], v[106:107], 0, v[160:161]
	global_load_dwordx4 v[108:111], v[106:107], off
	s_mov_b64 s[10:11], 0x80000
	s_waitcnt vmcnt(0) lgkmcnt(0)
	v_lshlrev_b32_e32 v112, 16, v108
	v_and_b32_e32 v113, 0xffff0000, v108
	v_lshlrev_b32_e32 v108, 16, v109
	v_and_b32_e32 v109, 0xffff0000, v109
	v_pk_fma_f32 v[104:105], v[104:105], v[136:137], v[108:109]
	v_lshlrev_b32_e32 v108, 16, v110
	v_and_b32_e32 v109, 0xffff0000, v110
	v_lshlrev_b32_e32 v110, 16, v111
	v_and_b32_e32 v111, 0xffff0000, v111
	v_pk_fma_f32 v[102:103], v[102:103], v[134:135], v[112:113]
	v_pk_fma_f32 v[110:111], v[100:101], v[132:133], v[110:111]
	v_pk_fma_f32 v[100:101], v[98:99], v[130:131], v[108:109]
	v_cvt_pk_bf16_f32 v98, v102, v103
	v_cvt_pk_bf16_f32 v99, v104, v105
	v_cvt_pk_bf16_f32 v100, v100, v101
	v_cvt_pk_bf16_f32 v101, v110, v111
	global_store_dwordx4 v[106:107], v[98:101], off
	s_nop 1
	v_lshl_add_u64 v[98:99], v[154:155], 0, s[10:11]
	s_mov_b32 s10, 0x80000
	v_add_co_u32_e32 v104, vcc, s10, v154
	s_mov_b64 s[10:11], 0x90000
	s_nop 0
	v_addc_co_u32_e32 v105, vcc, 0, v155, vcc
	global_load_dwordx4 v[100:103], v[104:105], off
	s_waitcnt vmcnt(0) lgkmcnt(0)
	v_lshlrev_b32_e32 v108, 16, v100
	v_and_b32_e32 v109, 0xffff0000, v100
	v_lshlrev_b32_e32 v100, 16, v101
	v_and_b32_e32 v101, 0xffff0000, v101
	v_pk_fma_f32 v[94:95], v[94:95], v[136:137], v[100:101]
	v_lshlrev_b32_e32 v100, 16, v102
	v_and_b32_e32 v101, 0xffff0000, v102
	v_lshlrev_b32_e32 v102, 16, v103
	v_and_b32_e32 v103, 0xffff0000, v103
	v_pk_fma_f32 v[92:93], v[92:93], v[134:135], v[108:109]
	v_pk_fma_f32 v[102:103], v[90:91], v[132:133], v[102:103]
	v_pk_fma_f32 v[90:91], v[88:89], v[130:131], v[100:101]
	v_cvt_pk_bf16_f32 v88, v92, v93
	v_cvt_pk_bf16_f32 v89, v94, v95
	v_cvt_pk_bf16_f32 v90, v90, v91
	v_cvt_pk_bf16_f32 v91, v102, v103
	global_store_dwordx4 v[104:105], v[88:91], off
	s_nop 1
	v_lshl_add_u64 v[88:89], v[154:155], 0, s[10:11]
	s_mov_b32 s10, 0x90000
	v_add_co_u32_e32 v94, vcc, s10, v154
	s_mov_b64 s[10:11], 0xa0000
	s_nop 0
	v_addc_co_u32_e32 v95, vcc, 0, v155, vcc
	global_load_dwordx4 v[90:93], v[94:95], off
	s_waitcnt vmcnt(0) lgkmcnt(0)
; __device__ __forceinline__ float bflo(unsigned w) { return __uint_as_float(w << 16); }
; __device__ __forceinline__ float bfhi(unsigned w) { return __uint_as_float(w & 0xffff0000u); }
; __device__ __forceinline__ unsigned cvtpk(float lo, float hi) { f32x2_t v = {lo, hi}; bf16x2_t b = __builtin_convertvector(v, bf16x2_t); return __builtin_bit_cast(unsigned, b); }
;     __device__ __forceinline__ void operator()(const f32x4 (&acc)[2][2][4][2], const Unit& u, int wr, int wc, int fr, int fq) const {
;         const int row0 = u.pm * BM + wr * 64 + fr, col0 = u.pn * BM + wc * 32 + 8 * fq;
; #pragma unroll
;         for (int bj = 0; bj < 2; ++bj) { const int col = col0 + bj * HALF;
;             const f32x4 g0 = *(const f32x4*)(gm + col), g1 = *(const f32x4*)(gm + col + 4);
; #pragma unroll
;             for (int ai = 0; ai < 2; ++ai)
; #pragma unroll
;                 for (int m = 0; m < 4; ++m) { const size_t off = (size_t)(row0 + ai * HALF + m * 16) * D + col;
;                     const u32x4 w = *(const u32x4*)(xr + off);
;                     const f32x4 y0 = (f32x4){bflo(w.x), bfhi(w.x), bflo(w.y), bfhi(w.y)} + g0 * acc[ai][bj][m][0], y1 = (f32x4){bflo(w.z), bfhi(w.z), bflo(w.w), bfhi(w.w)} + g1 * acc[ai][bj][m][1];
;                     if (xout_f) { *(f32x4*)(xout_f + off) = y0; *(f32x4*)(xout_f + off + 4) = y1; }
;                     else { u32x4 o; o.x = cvtpk(y0[0], y0[1]); o.y = cvtpk(y0[2], y0[3]); o.z = cvtpk(y1[0], y1[1]); o.w = cvtpk(y1[2], y1[3]); *(u32x4*)(xr + off) = o; } } }
	v_lshlrev_b32_e32 v100, 16, v90
	v_and_b32_e32 v101, 0xffff0000, v90
	v_lshlrev_b32_e32 v90, 16, v91
	v_and_b32_e32 v91, 0xffff0000, v91
	v_pk_fma_f32 v[86:87], v[86:87], v[136:137], v[90:91]
	v_lshlrev_b32_e32 v90, 16, v92
	v_and_b32_e32 v91, 0xffff0000, v92
	v_lshlrev_b32_e32 v92, 16, v93
	v_and_b32_e32 v93, 0xffff0000, v93
	v_pk_fma_f32 v[84:85], v[84:85], v[134:135], v[100:101]
	v_pk_fma_f32 v[92:93], v[82:83], v[132:133], v[92:93]
	v_pk_fma_f32 v[82:83], v[80:81], v[130:131], v[90:91]
	v_cvt_pk_bf16_f32 v80, v84, v85
	v_cvt_pk_bf16_f32 v81, v86, v87
	v_cvt_pk_bf16_f32 v82, v82, v83
	v_cvt_pk_bf16_f32 v83, v92, v93
	global_store_dwordx4 v[94:95], v[80:83], off
	s_nop 1
	v_lshl_add_u64 v[80:81], v[154:155], 0, s[10:11]
	s_mov_b32 s10, 0xa0000
	v_add_co_u32_e32 v86, vcc, s10, v154
	s_mov_b64 s[10:11], 0xb0000
	s_nop 0
	v_addc_co_u32_e32 v87, vcc, 0, v155, vcc
	global_load_dwordx4 v[82:85], v[86:87], off
	s_waitcnt vmcnt(0) lgkmcnt(0)
	v_lshlrev_b32_e32 v90, 16, v82
	v_and_b32_e32 v91, 0xffff0000, v82
	v_lshlrev_b32_e32 v82, 16, v83
	v_and_b32_e32 v83, 0xffff0000, v83
	v_pk_fma_f32 v[78:79], v[78:79], v[136:137], v[82:83]
	v_lshlrev_b32_e32 v82, 16, v84
	v_and_b32_e32 v83, 0xffff0000, v84
	v_lshlrev_b32_e32 v84, 16, v85
	v_and_b32_e32 v85, 0xffff0000, v85
	v_pk_fma_f32 v[76:77], v[76:77], v[134:135], v[90:91]
	v_pk_fma_f32 v[84:85], v[74:75], v[132:133], v[84:85]
	v_pk_fma_f32 v[74:75], v[72:73], v[130:131], v[82:83]
	v_cvt_pk_bf16_f32 v72, v76, v77
	v_cvt_pk_bf16_f32 v73, v78, v79
	v_cvt_pk_bf16_f32 v74, v74, v75
	v_cvt_pk_bf16_f32 v75, v84, v85
	global_store_dwordx4 v[86:87], v[72:75], off
	s_nop 1
	v_lshl_add_u64 v[72:73], v[154:155], 0, s[10:11]
	s_mov_b32 s10, 0xb0000
	v_add_co_u32_e32 v78, vcc, s10, v154
	s_nop 1
	v_addc_co_u32_e32 v79, vcc, 0, v155, vcc
	global_load_dwordx4 v[74:77], v[78:79], off
	s_and_b64 vcc, exec, s[0:1]
	s_waitcnt vmcnt(0) lgkmcnt(0)
	v_lshlrev_b32_e32 v82, 16, v74
	v_and_b32_e32 v83, 0xffff0000, v74
	v_lshlrev_b32_e32 v74, 16, v75
	v_and_b32_e32 v75, 0xffff0000, v75
	v_pk_fma_f32 v[70:71], v[70:71], v[136:137], v[74:75]
	v_lshlrev_b32_e32 v74, 16, v76
	v_and_b32_e32 v75, 0xffff0000, v76
	v_lshlrev_b32_e32 v76, 16, v77
	v_and_b32_e32 v77, 0xffff0000, v77
	v_pk_fma_f32 v[68:69], v[68:69], v[134:135], v[82:83]
	v_pk_fma_f32 v[76:77], v[66:67], v[132:133], v[76:77]
	v_pk_fma_f32 v[66:67], v[64:65], v[130:131], v[74:75]
	v_cvt_pk_bf16_f32 v64, v68, v69
	v_cvt_pk_bf16_f32 v65, v70, v71
	v_cvt_pk_bf16_f32 v66, v66, v67
	v_cvt_pk_bf16_f32 v67, v76, v77
	global_store_dwordx4 v[78:79], v[64:67], off
	s_nop 1
	v_or_b32_e32 v64, 0x80, v156
	v_ashrrev_i32_e32 v65, 31, v64
	v_lshl_add_u64 v[64:65], v[64:65], 2, s[12:13]
	global_load_dwordx4 v[68:71], v[64:65], off
	s_nop 0
	global_load_dwordx4 v[64:67], v[64:65], off offset:16
	s_nop 0
	global_load_dwordx4 v[74:77], v[154:155], off offset:256
	s_waitcnt vmcnt(0) lgkmcnt(0)
	v_lshlrev_b32_e32 v78, 16, v74
	v_and_b32_e32 v79, 0xffff0000, v74
	v_lshlrev_b32_e32 v74, 16, v75
	v_and_b32_e32 v75, 0xffff0000, v75
	v_pk_fma_f32 v[62:63], v[62:63], v[70:71], v[74:75]
	v_lshlrev_b32_e32 v74, 16, v76
	v_and_b32_e32 v75, 0xffff0000, v76
	v_lshlrev_b32_e32 v76, 16, v77
	v_and_b32_e32 v77, 0xffff0000, v77
	v_pk_fma_f32 v[60:61], v[60:61], v[68:69], v[78:79]
	v_pk_fma_f32 v[76:77], v[58:59], v[66:67], v[76:77]
	v_pk_fma_f32 v[58:59], v[56:57], v[64:65], v[74:75]
	v_cvt_pk_bf16_f32 v56, v60, v61
	v_cvt_pk_bf16_f32 v57, v62, v63
	v_cvt_pk_bf16_f32 v58, v58, v59
	v_cvt_pk_bf16_f32 v59, v76, v77
	global_store_dwordx4 v[154:155], v[56:59], off offset:256
	global_load_dwordx4 v[56:59], v[122:123], off offset:256
	s_waitcnt vmcnt(0) lgkmcnt(0)
	v_lshlrev_b32_e32 v60, 16, v56
	v_and_b32_e32 v61, 0xffff0000, v56
	v_lshlrev_b32_e32 v56, 16, v57
	v_and_b32_e32 v57, 0xffff0000, v57
	v_pk_fma_f32 v[54:55], v[54:55], v[70:71], v[56:57]
	v_lshlrev_b32_e32 v56, 16, v58
	v_and_b32_e32 v57, 0xffff0000, v58
	v_lshlrev_b32_e32 v58, 16, v59
	v_and_b32_e32 v59, 0xffff0000, v59
	v_pk_fma_f32 v[52:53], v[52:53], v[68:69], v[60:61]
	v_pk_fma_f32 v[58:59], v[50:51], v[66:67], v[58:59]
	v_pk_fma_f32 v[50:51], v[48:49], v[64:65], v[56:57]
	v_cvt_pk_bf16_f32 v48, v52, v53
	v_cvt_pk_bf16_f32 v49, v54, v55
	v_cvt_pk_bf16_f32 v50, v50, v51
	v_cvt_pk_bf16_f32 v51, v58, v59
	global_store_dwordx4 v[122:123], v[48:51], off offset:256
	global_load_dwordx4 v[48:51], v[114:115], off offset:256
	s_waitcnt vmcnt(0) lgkmcnt(0)
; #define PG8_BAR __builtin_amdgcn_s_barrier()
; __device__ __forceinline__ float bflo(unsigned w) { return __uint_as_float(w << 16); }
; __device__ __forceinline__ float bfhi(unsigned w) { return __uint_as_float(w & 0xffff0000u); }
; __device__ __forceinline__ unsigned cvtpk(float lo, float hi) { f32x2_t v = {lo, hi}; bf16x2_t b = __builtin_convertvector(v, bf16x2_t); return __builtin_bit_cast(unsigned, b); }
; template <class Epi, class Sched, bool ALIGN_EPI = false, bool SP2 = false>
; __device__ __forceinline__ void gemm_phase(PG8_LAS unsigned char* lds, const Gemm g, const Sched& S, const Epi& E, int wid_s_) {
;     ...
;         if constexpr (ALIGN_EPI) { if (wr == 0) PG8_BAR; }
;         if constexpr (!Epi::AFTER_DRAIN) { E(acc, cur, wr, wc, fr, fq); S.done(cur); }
;         if (!has_next) break;
;     __device__ __forceinline__ void operator()(const f32x4 (&acc)[2][2][4][2], const Unit& u, int wr, int wc, int fr, int fq) const {
;         const int row0 = u.pm * BM + wr * 64 + fr, col0 = u.pn * BM + wc * 32 + 8 * fq;
; #pragma unroll
;         for (int bj = 0; bj < 2; ++bj) { const int col = col0 + bj * HALF;
;             const f32x4 g0 = *(const f32x4*)(gm + col), g1 = *(const f32x4*)(gm + col + 4);
; #pragma unroll
;             for (int ai = 0; ai < 2; ++ai)
; #pragma unroll
;                 for (int m = 0; m < 4; ++m) { const size_t off = (size_t)(row0 + ai * HALF + m * 16) * D + col;
;                     const u32x4 w = *(const u32x4*)(xr + off);
;                     const f32x4 y0 = (f32x4){bflo(w.x), bfhi(w.x), bflo(w.y), bfhi(w.y)} + g0 * acc[ai][bj][m][0], y1 = (f32x4){bflo(w.z), bfhi(w.z), bflo(w.w), bfhi(w.w)} + g1 * acc[ai][bj][m][1];
;                     if (xout_f) { *(f32x4*)(xout_f + off) = y0; *(f32x4*)(xout_f + off + 4) = y1; }
;                     else { u32x4 o; o.x = cvtpk(y0[0], y0[1]); o.y = cvtpk(y0[2], y0[3]); o.z = cvtpk(y1[0], y1[1]); o.w = cvtpk(y1[2], y1[3]); *(u32x4*)(xr + off) = o; } } }
	v_lshlrev_b32_e32 v52, 16, v48
	v_and_b32_e32 v53, 0xffff0000, v48
	v_lshlrev_b32_e32 v48, 16, v49
	v_and_b32_e32 v49, 0xffff0000, v49
	v_pk_fma_f32 v[46:47], v[46:47], v[70:71], v[48:49]
	v_lshlrev_b32_e32 v48, 16, v50
	v_and_b32_e32 v49, 0xffff0000, v50
	v_lshlrev_b32_e32 v50, 16, v51
	v_and_b32_e32 v51, 0xffff0000, v51
	v_pk_fma_f32 v[44:45], v[44:45], v[68:69], v[52:53]
	v_pk_fma_f32 v[50:51], v[42:43], v[66:67], v[50:51]
	v_pk_fma_f32 v[42:43], v[40:41], v[64:65], v[48:49]
	v_cvt_pk_bf16_f32 v40, v44, v45
	v_cvt_pk_bf16_f32 v41, v46, v47
	v_cvt_pk_bf16_f32 v42, v42, v43
	v_cvt_pk_bf16_f32 v43, v50, v51
	global_store_dwordx4 v[114:115], v[40:43], off offset:256
	global_load_dwordx4 v[40:43], v[106:107], off offset:256
	s_waitcnt vmcnt(0) lgkmcnt(0)
	v_lshlrev_b32_e32 v44, 16, v40
	v_and_b32_e32 v45, 0xffff0000, v40
	v_lshlrev_b32_e32 v40, 16, v41
	v_and_b32_e32 v41, 0xffff0000, v41
	v_pk_fma_f32 v[38:39], v[38:39], v[70:71], v[40:41]
	v_lshlrev_b32_e32 v40, 16, v42
	v_and_b32_e32 v41, 0xffff0000, v42
	v_lshlrev_b32_e32 v42, 16, v43
	v_and_b32_e32 v43, 0xffff0000, v43
	v_pk_fma_f32 v[36:37], v[36:37], v[68:69], v[44:45]
	v_pk_fma_f32 v[42:43], v[34:35], v[66:67], v[42:43]
	v_pk_fma_f32 v[34:35], v[32:33], v[64:65], v[40:41]
	v_cvt_pk_bf16_f32 v32, v36, v37
	v_cvt_pk_bf16_f32 v33, v38, v39
	v_cvt_pk_bf16_f32 v34, v34, v35
	v_cvt_pk_bf16_f32 v35, v42, v43
	global_store_dwordx4 v[106:107], v[32:35], off offset:256
	global_load_dwordx4 v[32:35], v[98:99], off offset:256
	s_waitcnt vmcnt(0) lgkmcnt(0)
	v_lshlrev_b32_e32 v36, 16, v32
	v_and_b32_e32 v37, 0xffff0000, v32
	v_lshlrev_b32_e32 v32, 16, v33
	v_and_b32_e32 v33, 0xffff0000, v33
	v_pk_fma_f32 v[30:31], v[30:31], v[70:71], v[32:33]
	v_lshlrev_b32_e32 v32, 16, v34
	v_and_b32_e32 v33, 0xffff0000, v34
	v_lshlrev_b32_e32 v34, 16, v35
	v_and_b32_e32 v35, 0xffff0000, v35
	v_pk_fma_f32 v[28:29], v[28:29], v[68:69], v[36:37]
	v_pk_fma_f32 v[34:35], v[26:27], v[66:67], v[34:35]
	v_pk_fma_f32 v[26:27], v[24:25], v[64:65], v[32:33]
	v_cvt_pk_bf16_f32 v24, v28, v29
	v_cvt_pk_bf16_f32 v25, v30, v31
	v_cvt_pk_bf16_f32 v26, v26, v27
	v_cvt_pk_bf16_f32 v27, v34, v35
	global_store_dwordx4 v[98:99], v[24:27], off offset:256
	global_load_dwordx4 v[24:27], v[88:89], off offset:256
	s_waitcnt vmcnt(0) lgkmcnt(0)
	v_lshlrev_b32_e32 v28, 16, v24
	v_and_b32_e32 v29, 0xffff0000, v24
	v_lshlrev_b32_e32 v24, 16, v25
	v_and_b32_e32 v25, 0xffff0000, v25
	v_pk_fma_f32 v[22:23], v[22:23], v[70:71], v[24:25]
	v_lshlrev_b32_e32 v24, 16, v26
	v_and_b32_e32 v25, 0xffff0000, v26
	v_lshlrev_b32_e32 v26, 16, v27
	v_and_b32_e32 v27, 0xffff0000, v27
	v_pk_fma_f32 v[20:21], v[20:21], v[68:69], v[28:29]
	v_pk_fma_f32 v[26:27], v[18:19], v[66:67], v[26:27]
	v_pk_fma_f32 v[18:19], v[16:17], v[64:65], v[24:25]
	v_cvt_pk_bf16_f32 v16, v20, v21
	v_cvt_pk_bf16_f32 v17, v22, v23
	v_cvt_pk_bf16_f32 v18, v18, v19
	v_cvt_pk_bf16_f32 v19, v26, v27
	global_store_dwordx4 v[88:89], v[16:19], off offset:256
	global_load_dwordx4 v[16:19], v[80:81], off offset:256
	s_waitcnt vmcnt(0) lgkmcnt(0)
	v_lshlrev_b32_e32 v20, 16, v16
	v_and_b32_e32 v21, 0xffff0000, v16
	v_lshlrev_b32_e32 v16, 16, v17
	v_and_b32_e32 v17, 0xffff0000, v17
	v_pk_fma_f32 v[14:15], v[14:15], v[70:71], v[16:17]
	v_lshlrev_b32_e32 v16, 16, v18
	v_and_b32_e32 v17, 0xffff0000, v18
	v_lshlrev_b32_e32 v18, 16, v19
	v_and_b32_e32 v19, 0xffff0000, v19
	v_pk_fma_f32 v[12:13], v[12:13], v[68:69], v[20:21]
	v_pk_fma_f32 v[18:19], v[10:11], v[66:67], v[18:19]
	v_pk_fma_f32 v[10:11], v[8:9], v[64:65], v[16:17]
	v_cvt_pk_bf16_f32 v8, v12, v13
	v_cvt_pk_bf16_f32 v9, v14, v15
	v_cvt_pk_bf16_f32 v10, v10, v11
	v_cvt_pk_bf16_f32 v11, v18, v19
	global_store_dwordx4 v[80:81], v[8:11], off offset:256
	global_load_dwordx4 v[8:11], v[72:73], off offset:256
	s_waitcnt vmcnt(0) lgkmcnt(0)
	v_lshlrev_b32_e32 v12, 16, v8
	v_and_b32_e32 v13, 0xffff0000, v8
	v_lshlrev_b32_e32 v8, 16, v9
	v_and_b32_e32 v9, 0xffff0000, v9
	v_pk_fma_f32 v[6:7], v[6:7], v[70:71], v[8:9]
	v_lshlrev_b32_e32 v8, 16, v10
	v_and_b32_e32 v9, 0xffff0000, v10
	v_lshlrev_b32_e32 v10, 16, v11
	v_and_b32_e32 v11, 0xffff0000, v11
	v_pk_fma_f32 v[4:5], v[4:5], v[68:69], v[12:13]
	v_pk_fma_f32 v[10:11], v[2:3], v[66:67], v[10:11]
	v_pk_fma_f32 v[2:3], v[0:1], v[64:65], v[8:9]
	v_cvt_pk_bf16_f32 v0, v4, v5
	v_cvt_pk_bf16_f32 v1, v6, v7
	v_cvt_pk_bf16_f32 v2, v2, v3
	v_cvt_pk_bf16_f32 v3, v10, v11
	global_store_dwordx4 v[72:73], v[0:3], off offset:256
	s_cbranch_vccnz .LBB0_1380
	s_andn2_b64 vcc, exec, s[94:95]
	s_cbranch_vccnz .LBB0_1379
	s_barrier
	s_branch .LBB0_1379
